# GEMM kernels: per-segment s_setprio toggles removed, one static priority raise for the wave half that runs one barrier behind
# speedup vs baseline: 1.0032x; 1.0026x over previous
.LBB1_86:
	v_bfe_i32 v3, v0, 27, 1
	v_lshlrev_b32_e32 v2, 4, v0
	v_lshrrev_b32_e32 v3, 22, v3
	v_add_u32_e32 v3, v2, v3
	v_and_b32_e32 v3, 0xfffffc00, v3
	v_sub_u32_e32 v3, v2, v3
	v_lshrrev_b32_e32 v4, 4, v3
	v_ashrrev_i32_e32 v1, 31, v0
	v_bitop3_b32 v3, v4, v3, 32 bitop3:0x6c
	v_lshrrev_b32_e32 v1, 26, v1
	v_ashrrev_i32_e32 v5, 31, v3
	v_add_u32_e32 v1, v0, v1
	v_lshrrev_b32_e32 v5, 26, v5
	v_ashrrev_i32_e32 v1, 6, v1
	v_add_u32_e32 v5, v3, v5
	v_lshlrev_b32_e32 v4, 3, v1
	v_ashrrev_i32_e32 v10, 6, v5
	v_and_b32_e32 v5, 0xc0, v5
	v_and_b32_e32 v4, -16, v4
	v_sub_u32_e32 v3, v3, v5
	v_mov_b32_e32 v5, 1
	v_add_u32_e32 v4, v10, v4
	v_ashrrev_i16_sdwa v3, v5, sext(v3) dst_sel:DWORD dst_unused:UNUSED_PAD src0_sel:DWORD src1_sel:BYTE_0
	v_lshlrev_b32_e32 v6, 5, v1
	v_bfe_i32 v11, v3, 0, 16
	v_lshlrev_b32_e32 v3, 1, v4
	v_lshrrev_b32_e32 v7, 2, v4
	v_and_b32_e32 v8, 3, v10
	s_mov_b32 s5, 0x1fffe0
	v_and_b32_e32 v6, 32, v6
	v_and_b32_e32 v3, 24, v3
	v_and_b32_e32 v7, 4, v7
	v_and_or_b32 v8, v4, s5, v8
	v_or3_b32 v3, v8, v7, v3
	v_add_lshl_u32 v6, v6, v11, 1
	v_add_u32_e32 v2, 0x2000, v2
	v_lshl_add_u32 v130, v3, 11, v6
	v_ashrrev_i32_e32 v3, 31, v2
	v_lshrrev_b32_e32 v3, 22, v3
	v_add_u32_e32 v3, v2, v3
	v_ashrrev_i32_e32 v12, 10, v3
	v_mul_i32_i24_e32 v3, 0x400, v12
	v_sub_u32_e32 v2, v2, v3
	v_lshrrev_b32_e32 v3, 4, v2
	v_bitop3_b32 v2, v3, v2, 32 bitop3:0x6c
	v_lshl_add_u32 v128, v4, 11, v6
	v_ashrrev_i32_e32 v4, 31, v2
	v_lshrrev_b32_e32 v4, 26, v4
	v_add_u32_e32 v4, v2, v4
	s_add_u32 s33, s20, 0x3100000
	v_lshlrev_b32_e32 v3, 3, v12
	v_ashrrev_i32_e32 v13, 6, v4
	v_and_b32_e32 v4, 0xc0, v4
	s_addc_u32 s34, s21, 0
	v_and_b32_e32 v3, -16, v3
	v_sub_u32_e32 v2, v2, v4
	s_add_u32 s35, s20, 0x100000
	v_add_u32_e32 v3, v13, v3
	v_ashrrev_i16_sdwa v2, v5, sext(v2) dst_sel:DWORD dst_unused:UNUSED_PAD src0_sel:DWORD src1_sel:BYTE_0
	v_and_b32_e32 v5, 3, v13
	s_addc_u32 s36, s21, 0
	v_and_or_b32 v5, v3, s5, v5
	s_ashr_i32 s12, s14, 6
	s_ashr_i32 s5, s4, 31
	s_ashr_i32 s25, s24, 31
	s_ashr_i32 s8, s14, 8
	s_lshl_b32 s37, s12, 10
	s_lshl_b64 s[6:7], s[4:5], 19
	s_lshl_b64 s[10:11], s[24:25], 19
	s_add_u32 s28, s35, s10
	v_lshlrev_b32_e32 v6, 5, v12
	v_bfe_i32 v14, v2, 0, 16
	v_lshlrev_b32_e32 v2, 1, v3
	v_lshrrev_b32_e32 v4, 2, v3
	s_addc_u32 s29, s36, s11
	s_add_i32 s38, s37, 0
	v_and_b32_e32 v6, 32, v6
	v_and_b32_e32 v2, 24, v2
	v_and_b32_e32 v4, 4, v4
	s_add_i32 m0, s38, 0x10000
	v_or3_b32 v2, v5, v4, v2
	v_add_lshl_u32 v4, v6, v14, 1
	global_load_lds_dwordx4 v130, s[28:29]
	s_add_i32 m0, s38, 0x12000
	v_lshl_add_u32 v134, v2, 11, v4
	s_add_u32 s10, s28, 0x40000
	global_load_lds_dwordx4 v134, s[28:29]
	s_addc_u32 s11, s29, 0
	s_add_i32 m0, s38, 0x14000
	v_lshl_add_u32 v132, v3, 11, v4
	global_load_lds_dwordx4 v130, s[10:11]
	s_add_i32 m0, s38, 0x16000
	s_add_u32 s26, s33, s6
	s_addc_u32 s27, s34, s7
	s_add_i32 s39, s38, 0x2000
	global_load_lds_dwordx4 v134, s[10:11]
	s_mov_b32 m0, s38
	s_add_u32 s6, s26, 0x40000
	global_load_lds_dwordx4 v128, s[26:27]
	s_mov_b32 m0, s39
	s_addc_u32 s7, s27, 0
	s_add_i32 s40, s38, 0x4000
	global_load_lds_dwordx4 v132, s[26:27]
	s_mov_b32 m0, s40
	s_add_i32 s41, s38, 0x6000
	global_load_lds_dwordx4 v128, s[6:7]
	s_mov_b32 m0, s41
	v_mov_b32_e32 v131, 0
	global_load_lds_dwordx4 v132, s[6:7]
	s_load_dwordx2 s[6:7], s[0:1], 0xd0
	v_mov_b32_e32 v135, v131
	v_mov_b32_e32 v129, v131
	v_mov_b32_e32 v133, v131
	s_cmp_eq_u32 s8, 1
	s_mov_b32 s9, 0
	v_lshl_add_u64 v[8:9], s[28:29], 0, v[130:131]
	v_lshl_add_u64 v[6:7], s[28:29], 0, v[134:135]
	v_lshl_add_u64 v[2:3], s[26:27], 0, v[128:129]
	s_cselect_b64 s[10:11], -1, 0
	s_cmp_lg_u32 s8, 1
	v_lshl_add_u64 v[4:5], s[26:27], 0, v[132:133]
	s_cbranch_scc1 .LBB1_88
	s_barrier
	s_setprio 1

.LBB1_93:
	s_ashr_i32 s19, s18, 31
	s_lshl_b64 s[20:21], s[18:19], 19
	s_add_u32 s20, s33, s20
	s_addc_u32 s21, s34, s21
	s_and_b64 s[22:23], s[0:1], exec
	s_cselect_b32 s5, s21, s27
	s_cselect_b32 s19, s20, s26
	s_ashr_i32 s17, s16, 31
	s_lshl_b64 s[22:23], s[16:17], 19
	s_add_u32 s22, s35, s22
	s_addc_u32 s23, s36, s23
	s_and_b64 s[30:31], s[0:1], exec
	s_cselect_b32 s17, s23, s29
	s_cselect_b32 s25, s22, s28
	s_add_u32 s26, s26, 0x40080
	s_addc_u32 s27, s27, 0
	s_add_u32 s52, s28, 0x100
	s_addc_u32 s53, s29, 0
	s_mov_b32 s54, -2
	ds_read_b128 v[148:151], v153
	ds_read_b128 v[156:159], v153 offset:1024
	ds_read_b128 v[160:163], v153 offset:2048
	ds_read_b128 v[164:167], v153 offset:3072
	ds_read_b128 v[168:171], v154
	ds_read_b128 v[172:175], v154 offset:1024
	ds_read_b128 v[176:179], v154 offset:2048
	ds_read_b128 v[180:183], v154 offset:3072
	s_add_u32 s28, s26, 0xfffc0080
	s_addc_u32 s29, s27, -1
	s_cmp_eq_u32 s54, 12
	s_cselect_b32 s31, s5, s29
	s_cselect_b32 s30, s19, s28
	s_cselect_b32 s29, s17, s53
	s_cselect_b32 s28, s25, s52
	v_lshl_add_u64 v[216:217], s[26:27], 0, v[140:141]
	s_add_i32 m0, s38, 0xc000
	ds_read_b128 v[184:187], v155
	ds_read_b128 v[188:191], v155 offset:1024
	ds_read_b128 v[192:195], v155 offset:2048
	ds_read_b128 v[196:199], v155 offset:3072
	ds_read_b128 v[200:203], v155 offset:4096
	ds_read_b128 v[204:207], v155 offset:5120
	ds_read_b128 v[208:211], v155 offset:6144
	ds_read_b128 v[212:215], v155 offset:7168
	global_load_lds_dwordx4 v[216:217], off
	v_lshl_add_u64 v[216:217], s[26:27], 0, v[142:143]
	s_add_i32 m0, s38, 0xe000
	s_nop 0
	global_load_lds_dwordx4 v[216:217], off
	s_waitcnt vmcnt(8)
	s_waitcnt lgkmcnt(0)
	s_barrier
	s_waitcnt lgkmcnt(0)
	v_mfma_f32_16x16x32_bf16 v[124:127], v[148:151], v[184:187], 0
	v_mfma_f32_16x16x32_bf16 v[120:123], v[160:163], v[184:187], 0
	v_mfma_f32_16x16x32_bf16 v[108:111], v[148:151], v[192:195], 0
	v_mfma_f32_16x16x32_bf16 v[104:107], v[160:163], v[192:195], 0
	v_mfma_f32_16x16x32_bf16 v[92:95], v[148:151], v[200:203], 0
	v_mfma_f32_16x16x32_bf16 v[88:91], v[160:163], v[200:203], 0
	v_mfma_f32_16x16x32_bf16 v[76:79], v[148:151], v[208:211], 0
	v_mfma_f32_16x16x32_bf16 v[72:75], v[160:163], v[208:211], 0
	v_mfma_f32_16x16x32_bf16 v[124:127], v[156:159], v[188:191], v[124:127]
	v_mfma_f32_16x16x32_bf16 v[120:123], v[164:167], v[188:191], v[120:123]
	v_mfma_f32_16x16x32_bf16 v[108:111], v[156:159], v[196:199], v[108:111]
	v_mfma_f32_16x16x32_bf16 v[104:107], v[164:167], v[196:199], v[104:107]
	v_mfma_f32_16x16x32_bf16 v[92:95], v[156:159], v[204:207], v[92:95]
	v_mfma_f32_16x16x32_bf16 v[88:91], v[164:167], v[204:207], v[88:91]
	v_mfma_f32_16x16x32_bf16 v[76:79], v[156:159], v[212:215], v[76:79]
	v_mfma_f32_16x16x32_bf16 v[72:75], v[164:167], v[212:215], v[72:75]
	v_mfma_f32_16x16x32_bf16 v[116:119], v[168:171], v[184:187], 0
	v_mfma_f32_16x16x32_bf16 v[112:115], v[176:179], v[184:187], 0
	v_mfma_f32_16x16x32_bf16 v[100:103], v[168:171], v[192:195], 0
	v_mfma_f32_16x16x32_bf16 v[96:99], v[176:179], v[192:195], 0
	v_mfma_f32_16x16x32_bf16 v[84:87], v[168:171], v[200:203], 0
	v_mfma_f32_16x16x32_bf16 v[80:83], v[176:179], v[200:203], 0
	v_mfma_f32_16x16x32_bf16 v[68:71], v[168:171], v[208:211], 0
	v_mfma_f32_16x16x32_bf16 v[64:67], v[176:179], v[208:211], 0
	v_mfma_f32_16x16x32_bf16 v[116:119], v[172:175], v[188:191], v[116:119]
	v_mfma_f32_16x16x32_bf16 v[112:115], v[180:183], v[188:191], v[112:115]
	v_mfma_f32_16x16x32_bf16 v[100:103], v[172:175], v[196:199], v[100:103]
	v_mfma_f32_16x16x32_bf16 v[96:99], v[180:183], v[196:199], v[96:99]
	v_mfma_f32_16x16x32_bf16 v[84:87], v[172:175], v[204:207], v[84:87]
	v_mfma_f32_16x16x32_bf16 v[80:83], v[180:183], v[204:207], v[80:83]
	v_mfma_f32_16x16x32_bf16 v[68:71], v[172:175], v[212:215], v[68:71]
	v_mfma_f32_16x16x32_bf16 v[64:67], v[180:183], v[212:215], v[64:67]
	s_barrier
	s_add_i32 s55, s48, s37
	v_lshl_add_u64 v[216:217], s[28:29], 0, v[130:131]
	s_mov_b32 m0, s55
	ds_read_b128 v[184:187], v155 offset:16384
	ds_read_b128 v[188:191], v155 offset:17408
	ds_read_b128 v[192:195], v155 offset:18432
	ds_read_b128 v[196:199], v155 offset:19456
	ds_read_b128 v[200:203], v155 offset:20480
	ds_read_b128 v[204:207], v155 offset:21504
	ds_read_b128 v[208:211], v155 offset:22528
	ds_read_b128 v[212:215], v155 offset:23552
	global_load_lds_dwordx4 v[216:217], off
	s_add_i32 m0, s55, 0x2000
	s_add_u32 s56, s28, 0x40000
	v_lshl_add_u64 v[218:219], s[28:29], 0, v[134:135]
	s_addc_u32 s57, s29, 0
	s_add_i32 s55, s49, s37
	global_load_lds_dwordx4 v[218:219], off
	v_lshl_add_u64 v[220:221], s[56:57], 0, v[130:131]
	s_mov_b32 m0, s55
	v_lshl_add_u64 v[222:223], s[30:31], 0, v[132:133]
	global_load_lds_dwordx4 v[220:221], off
	v_lshl_add_u64 v[220:221], s[56:57], 0, v[134:135]
	s_add_i32 m0, s55, 0x2000
	s_nop 0
	global_load_lds_dwordx4 v[220:221], off
	v_lshl_add_u64 v[220:221], s[30:31], 0, v[128:129]
	s_mov_b32 m0, s38
	s_nop 0
	global_load_lds_dwordx4 v[220:221], off
	s_mov_b32 m0, s39
	s_nop 0
	global_load_lds_dwordx4 v[222:223], off
	s_waitcnt vmcnt(8)
	s_waitcnt lgkmcnt(0)
	s_barrier
	s_waitcnt lgkmcnt(0)
	v_mfma_f32_16x16x32_bf16 v[60:63], v[148:151], v[184:187], 0
	v_mfma_f32_16x16x32_bf16 v[56:59], v[160:163], v[184:187], 0
	v_mfma_f32_16x16x32_bf16 v[44:47], v[148:151], v[192:195], 0
	v_mfma_f32_16x16x32_bf16 v[40:43], v[160:163], v[192:195], 0
	v_mfma_f32_16x16x32_bf16 v[28:31], v[148:151], v[200:203], 0
	v_mfma_f32_16x16x32_bf16 v[24:27], v[160:163], v[200:203], 0
	v_mfma_f32_16x16x32_bf16 v[12:15], v[148:151], v[208:211], 0
	v_mfma_f32_16x16x32_bf16 v[8:11], v[160:163], v[208:211], 0
	v_mfma_f32_16x16x32_bf16 v[60:63], v[156:159], v[188:191], v[60:63]
	v_mfma_f32_16x16x32_bf16 v[56:59], v[164:167], v[188:191], v[56:59]
	v_mfma_f32_16x16x32_bf16 v[44:47], v[156:159], v[196:199], v[44:47]
	v_mfma_f32_16x16x32_bf16 v[40:43], v[164:167], v[196:199], v[40:43]
	v_mfma_f32_16x16x32_bf16 v[28:31], v[156:159], v[204:207], v[28:31]
	v_mfma_f32_16x16x32_bf16 v[24:27], v[164:167], v[204:207], v[24:27]
	v_mfma_f32_16x16x32_bf16 v[12:15], v[156:159], v[212:215], v[12:15]
	v_mfma_f32_16x16x32_bf16 v[8:11], v[164:167], v[212:215], v[8:11]
	v_mfma_f32_16x16x32_bf16 v[52:55], v[168:171], v[184:187], 0
	v_mfma_f32_16x16x32_bf16 v[48:51], v[176:179], v[184:187], 0
	v_mfma_f32_16x16x32_bf16 v[36:39], v[168:171], v[192:195], 0
	v_mfma_f32_16x16x32_bf16 v[32:35], v[176:179], v[192:195], 0
	v_mfma_f32_16x16x32_bf16 v[20:23], v[168:171], v[200:203], 0
	v_mfma_f32_16x16x32_bf16 v[16:19], v[176:179], v[200:203], 0
	v_mfma_f32_16x16x32_bf16 v[4:7], v[168:171], v[208:211], 0
	v_mfma_f32_16x16x32_bf16 v[0:3], v[176:179], v[208:211], 0
	v_mfma_f32_16x16x32_bf16 v[52:55], v[172:175], v[188:191], v[52:55]
	v_mfma_f32_16x16x32_bf16 v[48:51], v[180:183], v[188:191], v[48:51]
	v_mfma_f32_16x16x32_bf16 v[36:39], v[172:175], v[196:199], v[36:39]
	v_mfma_f32_16x16x32_bf16 v[32:35], v[180:183], v[196:199], v[32:35]
	v_mfma_f32_16x16x32_bf16 v[20:23], v[172:175], v[204:207], v[20:23]
	v_mfma_f32_16x16x32_bf16 v[16:19], v[180:183], v[204:207], v[16:19]
	v_mfma_f32_16x16x32_bf16 v[4:7], v[172:175], v[212:215], v[4:7]
	v_mfma_f32_16x16x32_bf16 v[0:3], v[180:183], v[212:215], v[0:3]
	s_barrier
	s_add_i32 s55, 0, 0x18000
	s_add_i32 s56, 0, 0x1c000
	v_add_u32_e32 v164, s55, v152
	v_add_u32_e32 v180, s56, v152
	ds_read_b128 v[148:151], v164
	ds_read_b128 v[156:159], v164 offset:1024
	ds_read_b128 v[160:163], v164 offset:2048
	ds_read_b128 v[164:167], v164 offset:3072
	ds_read_b128 v[168:171], v180
	ds_read_b128 v[172:175], v180 offset:1024
	ds_read_b128 v[176:179], v180 offset:2048
	ds_read_b128 v[180:183], v180 offset:3072
	s_add_u32 s30, s30, 0x40000
	s_addc_u32 s31, s31, 0
	s_mov_b32 m0, s40
	v_lshl_add_u64 v[224:225], s[30:31], 0, v[128:129]
	ds_read_b128 v[184:187], v155 offset:32768
	ds_read_b128 v[188:191], v155 offset:33792
	ds_read_b128 v[192:195], v155 offset:34816
	ds_read_b128 v[196:199], v155 offset:35840
	ds_read_b128 v[200:203], v155 offset:36864
	ds_read_b128 v[204:207], v155 offset:37888
	ds_read_b128 v[208:211], v155 offset:38912
	ds_read_b128 v[212:215], v155 offset:39936
	global_load_lds_dwordx4 v[224:225], off
	v_lshl_add_u64 v[224:225], s[30:31], 0, v[132:133]
	s_mov_b32 m0, s41
	s_nop 0
	global_load_lds_dwordx4 v[224:225], off
	s_waitcnt vmcnt(8)
	s_waitcnt lgkmcnt(0)
	s_barrier
	s_waitcnt lgkmcnt(0)
	v_mfma_f32_16x16x32_bf16 v[124:127], v[148:151], v[184:187], v[124:127]
	v_mfma_f32_16x16x32_bf16 v[120:123], v[160:163], v[184:187], v[120:123]
	v_mfma_f32_16x16x32_bf16 v[108:111], v[148:151], v[192:195], v[108:111]
	v_mfma_f32_16x16x32_bf16 v[104:107], v[160:163], v[192:195], v[104:107]
	v_mfma_f32_16x16x32_bf16 v[92:95], v[148:151], v[200:203], v[92:95]
	v_mfma_f32_16x16x32_bf16 v[88:91], v[160:163], v[200:203], v[88:91]
	v_mfma_f32_16x16x32_bf16 v[76:79], v[148:151], v[208:211], v[76:79]
	v_mfma_f32_16x16x32_bf16 v[72:75], v[160:163], v[208:211], v[72:75]
	v_mfma_f32_16x16x32_bf16 v[124:127], v[156:159], v[188:191], v[124:127]
	v_mfma_f32_16x16x32_bf16 v[120:123], v[164:167], v[188:191], v[120:123]
	v_mfma_f32_16x16x32_bf16 v[108:111], v[156:159], v[196:199], v[108:111]
	v_mfma_f32_16x16x32_bf16 v[104:107], v[164:167], v[196:199], v[104:107]
	v_mfma_f32_16x16x32_bf16 v[92:95], v[156:159], v[204:207], v[92:95]
	v_mfma_f32_16x16x32_bf16 v[88:91], v[164:167], v[204:207], v[88:91]
	v_mfma_f32_16x16x32_bf16 v[76:79], v[156:159], v[212:215], v[76:79]
	v_mfma_f32_16x16x32_bf16 v[72:75], v[164:167], v[212:215], v[72:75]
	v_mfma_f32_16x16x32_bf16 v[116:119], v[168:171], v[184:187], v[116:119]
	v_mfma_f32_16x16x32_bf16 v[112:115], v[176:179], v[184:187], v[112:115]
	v_mfma_f32_16x16x32_bf16 v[100:103], v[168:171], v[192:195], v[100:103]
	v_mfma_f32_16x16x32_bf16 v[96:99], v[176:179], v[192:195], v[96:99]
	v_mfma_f32_16x16x32_bf16 v[84:87], v[168:171], v[200:203], v[84:87]
	v_mfma_f32_16x16x32_bf16 v[80:83], v[176:179], v[200:203], v[80:83]
	v_mfma_f32_16x16x32_bf16 v[68:71], v[168:171], v[208:211], v[68:71]
	v_mfma_f32_16x16x32_bf16 v[64:67], v[176:179], v[208:211], v[64:67]
	v_mfma_f32_16x16x32_bf16 v[116:119], v[172:175], v[188:191], v[116:119]
	v_mfma_f32_16x16x32_bf16 v[112:115], v[180:183], v[188:191], v[112:115]
	v_mfma_f32_16x16x32_bf16 v[100:103], v[172:175], v[196:199], v[100:103]
	v_mfma_f32_16x16x32_bf16 v[96:99], v[180:183], v[196:199], v[96:99]
	v_mfma_f32_16x16x32_bf16 v[84:87], v[172:175], v[204:207], v[84:87]
	v_mfma_f32_16x16x32_bf16 v[80:83], v[180:183], v[204:207], v[80:83]
	v_mfma_f32_16x16x32_bf16 v[68:71], v[172:175], v[212:215], v[68:71]
	v_mfma_f32_16x16x32_bf16 v[64:67], v[180:183], v[212:215], v[64:67]
	s_barrier
	s_add_i32 s30, s55, s37
	v_lshl_add_u64 v[216:217], v[216:217], 0, s[12:13]
	s_mov_b32 m0, s30
	ds_read_b128 v[184:187], v155 offset:49152
	ds_read_b128 v[188:191], v155 offset:50176
	ds_read_b128 v[192:195], v155 offset:51200
	ds_read_b128 v[196:199], v155 offset:52224
	ds_read_b128 v[200:203], v155 offset:53248
	ds_read_b128 v[204:207], v155 offset:54272
	ds_read_b128 v[208:211], v155 offset:55296
	ds_read_b128 v[212:215], v155 offset:56320
	global_load_lds_dwordx4 v[216:217], off
	s_add_i32 m0, s30, 0x2000
	s_add_u32 s28, s28, 0x40080
	v_lshl_add_u64 v[216:217], v[218:219], 0, s[12:13]
	s_addc_u32 s29, s29, 0
	s_add_i32 s30, s56, s37
	global_load_lds_dwordx4 v[216:217], off
	v_lshl_add_u64 v[216:217], s[28:29], 0, v[130:131]
	s_mov_b32 m0, s30
	s_nop 0
	global_load_lds_dwordx4 v[216:217], off
	v_lshl_add_u64 v[216:217], s[28:29], 0, v[134:135]
	s_add_i32 m0, s30, 0x2000
	s_nop 0
	global_load_lds_dwordx4 v[216:217], off
	v_lshl_add_u64 v[216:217], v[220:221], 0, s[12:13]
	s_mov_b32 m0, s43
	s_nop 0
	global_load_lds_dwordx4 v[216:217], off
	v_lshl_add_u64 v[216:217], v[222:223], 0, s[12:13]
	s_mov_b32 m0, s44
	s_nop 0
	global_load_lds_dwordx4 v[216:217], off
	s_waitcnt vmcnt(8)
	s_waitcnt lgkmcnt(0)
	s_barrier
	s_waitcnt lgkmcnt(0)
	v_mfma_f32_16x16x32_bf16 v[60:63], v[148:151], v[184:187], v[60:63]
	v_mfma_f32_16x16x32_bf16 v[56:59], v[160:163], v[184:187], v[56:59]
	v_mfma_f32_16x16x32_bf16 v[44:47], v[148:151], v[192:195], v[44:47]
	v_mfma_f32_16x16x32_bf16 v[40:43], v[160:163], v[192:195], v[40:43]
	v_mfma_f32_16x16x32_bf16 v[28:31], v[148:151], v[200:203], v[28:31]
	v_mfma_f32_16x16x32_bf16 v[24:27], v[160:163], v[200:203], v[24:27]
	v_mfma_f32_16x16x32_bf16 v[12:15], v[148:151], v[208:211], v[12:15]
	v_mfma_f32_16x16x32_bf16 v[8:11], v[160:163], v[208:211], v[8:11]
	v_mfma_f32_16x16x32_bf16 v[60:63], v[156:159], v[188:191], v[60:63]
	v_mfma_f32_16x16x32_bf16 v[56:59], v[164:167], v[188:191], v[56:59]
	v_mfma_f32_16x16x32_bf16 v[44:47], v[156:159], v[196:199], v[44:47]
	v_mfma_f32_16x16x32_bf16 v[40:43], v[164:167], v[196:199], v[40:43]
	v_mfma_f32_16x16x32_bf16 v[28:31], v[156:159], v[204:207], v[28:31]
	v_mfma_f32_16x16x32_bf16 v[24:27], v[164:167], v[204:207], v[24:27]
	v_mfma_f32_16x16x32_bf16 v[12:15], v[156:159], v[212:215], v[12:15]
	v_mfma_f32_16x16x32_bf16 v[8:11], v[164:167], v[212:215], v[8:11]
	v_mfma_f32_16x16x32_bf16 v[52:55], v[168:171], v[184:187], v[52:55]
	v_mfma_f32_16x16x32_bf16 v[48:51], v[176:179], v[184:187], v[48:51]
	v_mfma_f32_16x16x32_bf16 v[36:39], v[168:171], v[192:195], v[36:39]
	v_mfma_f32_16x16x32_bf16 v[32:35], v[176:179], v[192:195], v[32:35]
	v_mfma_f32_16x16x32_bf16 v[20:23], v[168:171], v[200:203], v[20:23]
	v_mfma_f32_16x16x32_bf16 v[16:19], v[176:179], v[200:203], v[16:19]
	v_mfma_f32_16x16x32_bf16 v[4:7], v[168:171], v[208:211], v[4:7]
	v_mfma_f32_16x16x32_bf16 v[0:3], v[176:179], v[208:211], v[0:3]
	v_mfma_f32_16x16x32_bf16 v[52:55], v[172:175], v[188:191], v[52:55]
	v_mfma_f32_16x16x32_bf16 v[48:51], v[180:183], v[188:191], v[48:51]
	v_mfma_f32_16x16x32_bf16 v[36:39], v[172:175], v[196:199], v[36:39]
	v_mfma_f32_16x16x32_bf16 v[32:35], v[180:183], v[196:199], v[32:35]
	v_mfma_f32_16x16x32_bf16 v[20:23], v[172:175], v[204:207], v[20:23]
	v_mfma_f32_16x16x32_bf16 v[16:19], v[180:183], v[204:207], v[16:19]
	v_mfma_f32_16x16x32_bf16 v[4:7], v[172:175], v[212:215], v[4:7]
	v_mfma_f32_16x16x32_bf16 v[0:3], v[180:183], v[212:215], v[0:3]
	s_barrier
	s_add_i32 s54, s54, 2
	s_add_u32 s26, s26, 0x100
	s_addc_u32 s27, s27, 0
	s_add_u32 s52, s52, 0x100
	s_addc_u32 s53, s53, 0
	s_cmp_gt_u32 s54, 13
.LBB1_94:
	ds_read_b128 v[148:151], v153
	ds_read_b128 v[156:159], v153 offset:1024
	ds_read_b128 v[160:163], v153 offset:2048
	ds_read_b128 v[164:167], v153 offset:3072
	ds_read_b128 v[168:171], v154
	ds_read_b128 v[172:175], v154 offset:1024
	ds_read_b128 v[176:179], v154 offset:2048
	ds_read_b128 v[180:183], v154 offset:3072
	s_add_u32 s28, s26, 0xfffc0080
	s_addc_u32 s29, s27, -1
	s_cmp_eq_u32 s54, 12
	s_cselect_b32 s31, s5, s29
	s_cselect_b32 s30, s19, s28
	s_cselect_b32 s29, s17, s53
	s_cselect_b32 s28, s25, s52
	v_lshl_add_u64 v[216:217], s[26:27], 0, v[140:141]
	s_add_i32 m0, s38, 0xc000
	ds_read_b128 v[184:187], v155
	ds_read_b128 v[188:191], v155 offset:1024
	ds_read_b128 v[192:195], v155 offset:2048
	ds_read_b128 v[196:199], v155 offset:3072
	ds_read_b128 v[200:203], v155 offset:4096
	ds_read_b128 v[204:207], v155 offset:5120
	ds_read_b128 v[208:211], v155 offset:6144
	ds_read_b128 v[212:215], v155 offset:7168
	global_load_lds_dwordx4 v[216:217], off
	v_lshl_add_u64 v[216:217], s[26:27], 0, v[142:143]
	s_add_i32 m0, s38, 0xe000
	s_nop 0
	global_load_lds_dwordx4 v[216:217], off
	s_waitcnt vmcnt(8)
	s_waitcnt lgkmcnt(0)
	s_barrier
	s_waitcnt lgkmcnt(0)
	v_mfma_f32_16x16x32_bf16 v[124:127], v[148:151], v[184:187], v[124:127]
	v_mfma_f32_16x16x32_bf16 v[120:123], v[160:163], v[184:187], v[120:123]
	v_mfma_f32_16x16x32_bf16 v[108:111], v[148:151], v[192:195], v[108:111]
	v_mfma_f32_16x16x32_bf16 v[104:107], v[160:163], v[192:195], v[104:107]
	v_mfma_f32_16x16x32_bf16 v[92:95], v[148:151], v[200:203], v[92:95]
	v_mfma_f32_16x16x32_bf16 v[88:91], v[160:163], v[200:203], v[88:91]
	v_mfma_f32_16x16x32_bf16 v[76:79], v[148:151], v[208:211], v[76:79]
	v_mfma_f32_16x16x32_bf16 v[72:75], v[160:163], v[208:211], v[72:75]
	v_mfma_f32_16x16x32_bf16 v[124:127], v[156:159], v[188:191], v[124:127]
	v_mfma_f32_16x16x32_bf16 v[120:123], v[164:167], v[188:191], v[120:123]
	v_mfma_f32_16x16x32_bf16 v[108:111], v[156:159], v[196:199], v[108:111]
	v_mfma_f32_16x16x32_bf16 v[104:107], v[164:167], v[196:199], v[104:107]
	v_mfma_f32_16x16x32_bf16 v[92:95], v[156:159], v[204:207], v[92:95]
	v_mfma_f32_16x16x32_bf16 v[88:91], v[164:167], v[204:207], v[88:91]
	v_mfma_f32_16x16x32_bf16 v[76:79], v[156:159], v[212:215], v[76:79]
	v_mfma_f32_16x16x32_bf16 v[72:75], v[164:167], v[212:215], v[72:75]
	v_mfma_f32_16x16x32_bf16 v[116:119], v[168:171], v[184:187], v[116:119]
	v_mfma_f32_16x16x32_bf16 v[112:115], v[176:179], v[184:187], v[112:115]
	v_mfma_f32_16x16x32_bf16 v[100:103], v[168:171], v[192:195], v[100:103]
	v_mfma_f32_16x16x32_bf16 v[96:99], v[176:179], v[192:195], v[96:99]
	v_mfma_f32_16x16x32_bf16 v[84:87], v[168:171], v[200:203], v[84:87]
	v_mfma_f32_16x16x32_bf16 v[80:83], v[176:179], v[200:203], v[80:83]
	v_mfma_f32_16x16x32_bf16 v[68:71], v[168:171], v[208:211], v[68:71]
	v_mfma_f32_16x16x32_bf16 v[64:67], v[176:179], v[208:211], v[64:67]
	v_mfma_f32_16x16x32_bf16 v[116:119], v[172:175], v[188:191], v[116:119]
	v_mfma_f32_16x16x32_bf16 v[112:115], v[180:183], v[188:191], v[112:115]
	v_mfma_f32_16x16x32_bf16 v[100:103], v[172:175], v[196:199], v[100:103]
	v_mfma_f32_16x16x32_bf16 v[96:99], v[180:183], v[196:199], v[96:99]
	v_mfma_f32_16x16x32_bf16 v[84:87], v[172:175], v[204:207], v[84:87]
	v_mfma_f32_16x16x32_bf16 v[80:83], v[180:183], v[204:207], v[80:83]
	v_mfma_f32_16x16x32_bf16 v[68:71], v[172:175], v[212:215], v[68:71]
	v_mfma_f32_16x16x32_bf16 v[64:67], v[180:183], v[212:215], v[64:67]
	s_barrier
	s_add_i32 s55, s48, s37
	v_lshl_add_u64 v[216:217], s[28:29], 0, v[130:131]
	s_mov_b32 m0, s55
	ds_read_b128 v[184:187], v155 offset:16384
	ds_read_b128 v[188:191], v155 offset:17408
	ds_read_b128 v[192:195], v155 offset:18432
	ds_read_b128 v[196:199], v155 offset:19456
	ds_read_b128 v[200:203], v155 offset:20480
	ds_read_b128 v[204:207], v155 offset:21504
	ds_read_b128 v[208:211], v155 offset:22528
	ds_read_b128 v[212:215], v155 offset:23552
	global_load_lds_dwordx4 v[216:217], off
	s_add_i32 m0, s55, 0x2000
	s_add_u32 s56, s28, 0x40000
	v_lshl_add_u64 v[218:219], s[28:29], 0, v[134:135]
	s_addc_u32 s57, s29, 0
	s_add_i32 s55, s49, s37
	global_load_lds_dwordx4 v[218:219], off
	v_lshl_add_u64 v[220:221], s[56:57], 0, v[130:131]
	s_mov_b32 m0, s55
	v_lshl_add_u64 v[222:223], s[30:31], 0, v[132:133]
	global_load_lds_dwordx4 v[220:221], off
	v_lshl_add_u64 v[220:221], s[56:57], 0, v[134:135]
	s_add_i32 m0, s55, 0x2000
	s_nop 0
	global_load_lds_dwordx4 v[220:221], off
	v_lshl_add_u64 v[220:221], s[30:31], 0, v[128:129]
	s_mov_b32 m0, s38
	s_nop 0
	global_load_lds_dwordx4 v[220:221], off
	s_mov_b32 m0, s39
	s_nop 0
	global_load_lds_dwordx4 v[222:223], off
	s_waitcnt vmcnt(8)
	s_waitcnt lgkmcnt(0)
	s_barrier
	s_waitcnt lgkmcnt(0)
	v_mfma_f32_16x16x32_bf16 v[60:63], v[148:151], v[184:187], v[60:63]
	v_mfma_f32_16x16x32_bf16 v[56:59], v[160:163], v[184:187], v[56:59]
	v_mfma_f32_16x16x32_bf16 v[44:47], v[148:151], v[192:195], v[44:47]
	v_mfma_f32_16x16x32_bf16 v[40:43], v[160:163], v[192:195], v[40:43]
	v_mfma_f32_16x16x32_bf16 v[28:31], v[148:151], v[200:203], v[28:31]
	v_mfma_f32_16x16x32_bf16 v[24:27], v[160:163], v[200:203], v[24:27]
	v_mfma_f32_16x16x32_bf16 v[12:15], v[148:151], v[208:211], v[12:15]
	v_mfma_f32_16x16x32_bf16 v[8:11], v[160:163], v[208:211], v[8:11]
	v_mfma_f32_16x16x32_bf16 v[60:63], v[156:159], v[188:191], v[60:63]
	v_mfma_f32_16x16x32_bf16 v[56:59], v[164:167], v[188:191], v[56:59]
	v_mfma_f32_16x16x32_bf16 v[44:47], v[156:159], v[196:199], v[44:47]
	v_mfma_f32_16x16x32_bf16 v[40:43], v[164:167], v[196:199], v[40:43]
	v_mfma_f32_16x16x32_bf16 v[28:31], v[156:159], v[204:207], v[28:31]
	v_mfma_f32_16x16x32_bf16 v[24:27], v[164:167], v[204:207], v[24:27]
	v_mfma_f32_16x16x32_bf16 v[12:15], v[156:159], v[212:215], v[12:15]
	v_mfma_f32_16x16x32_bf16 v[8:11], v[164:167], v[212:215], v[8:11]
	v_mfma_f32_16x16x32_bf16 v[52:55], v[168:171], v[184:187], v[52:55]
	v_mfma_f32_16x16x32_bf16 v[48:51], v[176:179], v[184:187], v[48:51]
	v_mfma_f32_16x16x32_bf16 v[36:39], v[168:171], v[192:195], v[36:39]
	v_mfma_f32_16x16x32_bf16 v[32:35], v[176:179], v[192:195], v[32:35]
	v_mfma_f32_16x16x32_bf16 v[20:23], v[168:171], v[200:203], v[20:23]
	v_mfma_f32_16x16x32_bf16 v[16:19], v[176:179], v[200:203], v[16:19]
	v_mfma_f32_16x16x32_bf16 v[4:7], v[168:171], v[208:211], v[4:7]
	v_mfma_f32_16x16x32_bf16 v[0:3], v[176:179], v[208:211], v[0:3]
	v_mfma_f32_16x16x32_bf16 v[52:55], v[172:175], v[188:191], v[52:55]
	v_mfma_f32_16x16x32_bf16 v[48:51], v[180:183], v[188:191], v[48:51]
	v_mfma_f32_16x16x32_bf16 v[36:39], v[172:175], v[196:199], v[36:39]
	v_mfma_f32_16x16x32_bf16 v[32:35], v[180:183], v[196:199], v[32:35]
	v_mfma_f32_16x16x32_bf16 v[20:23], v[172:175], v[204:207], v[20:23]
	v_mfma_f32_16x16x32_bf16 v[16:19], v[180:183], v[204:207], v[16:19]
	v_mfma_f32_16x16x32_bf16 v[4:7], v[172:175], v[212:215], v[4:7]
	v_mfma_f32_16x16x32_bf16 v[0:3], v[180:183], v[212:215], v[0:3]
	s_barrier
	s_add_i32 s55, 0, 0x18000
	s_add_i32 s56, 0, 0x1c000
	v_add_u32_e32 v164, s55, v152
	v_add_u32_e32 v180, s56, v152
	ds_read_b128 v[148:151], v164
	ds_read_b128 v[156:159], v164 offset:1024
	ds_read_b128 v[160:163], v164 offset:2048
	ds_read_b128 v[164:167], v164 offset:3072
	ds_read_b128 v[168:171], v180
	ds_read_b128 v[172:175], v180 offset:1024
	ds_read_b128 v[176:179], v180 offset:2048
	ds_read_b128 v[180:183], v180 offset:3072
	s_add_u32 s30, s30, 0x40000
	s_addc_u32 s31, s31, 0
	s_mov_b32 m0, s40
	v_lshl_add_u64 v[224:225], s[30:31], 0, v[128:129]
	ds_read_b128 v[184:187], v155 offset:32768
	ds_read_b128 v[188:191], v155 offset:33792
	ds_read_b128 v[192:195], v155 offset:34816
	ds_read_b128 v[196:199], v155 offset:35840
	ds_read_b128 v[200:203], v155 offset:36864
	ds_read_b128 v[204:207], v155 offset:37888
	ds_read_b128 v[208:211], v155 offset:38912
	ds_read_b128 v[212:215], v155 offset:39936
	global_load_lds_dwordx4 v[224:225], off
	v_lshl_add_u64 v[224:225], s[30:31], 0, v[132:133]
	s_mov_b32 m0, s41
	s_nop 0
	global_load_lds_dwordx4 v[224:225], off
	s_waitcnt vmcnt(8)
	s_waitcnt lgkmcnt(0)
	s_barrier
	s_waitcnt lgkmcnt(0)
	v_mfma_f32_16x16x32_bf16 v[124:127], v[148:151], v[184:187], v[124:127]
	v_mfma_f32_16x16x32_bf16 v[120:123], v[160:163], v[184:187], v[120:123]
	v_mfma_f32_16x16x32_bf16 v[108:111], v[148:151], v[192:195], v[108:111]
	v_mfma_f32_16x16x32_bf16 v[104:107], v[160:163], v[192:195], v[104:107]
	v_mfma_f32_16x16x32_bf16 v[92:95], v[148:151], v[200:203], v[92:95]
	v_mfma_f32_16x16x32_bf16 v[88:91], v[160:163], v[200:203], v[88:91]
	v_mfma_f32_16x16x32_bf16 v[76:79], v[148:151], v[208:211], v[76:79]
	v_mfma_f32_16x16x32_bf16 v[72:75], v[160:163], v[208:211], v[72:75]
	v_mfma_f32_16x16x32_bf16 v[124:127], v[156:159], v[188:191], v[124:127]
	v_mfma_f32_16x16x32_bf16 v[120:123], v[164:167], v[188:191], v[120:123]
	v_mfma_f32_16x16x32_bf16 v[108:111], v[156:159], v[196:199], v[108:111]
	v_mfma_f32_16x16x32_bf16 v[104:107], v[164:167], v[196:199], v[104:107]
	v_mfma_f32_16x16x32_bf16 v[92:95], v[156:159], v[204:207], v[92:95]
	v_mfma_f32_16x16x32_bf16 v[88:91], v[164:167], v[204:207], v[88:91]
	v_mfma_f32_16x16x32_bf16 v[76:79], v[156:159], v[212:215], v[76:79]
	v_mfma_f32_16x16x32_bf16 v[72:75], v[164:167], v[212:215], v[72:75]
	v_mfma_f32_16x16x32_bf16 v[116:119], v[168:171], v[184:187], v[116:119]
	v_mfma_f32_16x16x32_bf16 v[112:115], v[176:179], v[184:187], v[112:115]
	v_mfma_f32_16x16x32_bf16 v[100:103], v[168:171], v[192:195], v[100:103]
	v_mfma_f32_16x16x32_bf16 v[96:99], v[176:179], v[192:195], v[96:99]
	v_mfma_f32_16x16x32_bf16 v[84:87], v[168:171], v[200:203], v[84:87]
	v_mfma_f32_16x16x32_bf16 v[80:83], v[176:179], v[200:203], v[80:83]
	v_mfma_f32_16x16x32_bf16 v[68:71], v[168:171], v[208:211], v[68:71]
	v_mfma_f32_16x16x32_bf16 v[64:67], v[176:179], v[208:211], v[64:67]
	v_mfma_f32_16x16x32_bf16 v[116:119], v[172:175], v[188:191], v[116:119]
	v_mfma_f32_16x16x32_bf16 v[112:115], v[180:183], v[188:191], v[112:115]
	v_mfma_f32_16x16x32_bf16 v[100:103], v[172:175], v[196:199], v[100:103]
	v_mfma_f32_16x16x32_bf16 v[96:99], v[180:183], v[196:199], v[96:99]
	v_mfma_f32_16x16x32_bf16 v[84:87], v[172:175], v[204:207], v[84:87]
	v_mfma_f32_16x16x32_bf16 v[80:83], v[180:183], v[204:207], v[80:83]
	v_mfma_f32_16x16x32_bf16 v[68:71], v[172:175], v[212:215], v[68:71]
	v_mfma_f32_16x16x32_bf16 v[64:67], v[180:183], v[212:215], v[64:67]
	s_barrier
	s_add_i32 s30, s55, s37
	v_lshl_add_u64 v[216:217], v[216:217], 0, s[12:13]
	s_mov_b32 m0, s30
	ds_read_b128 v[184:187], v155 offset:49152
	ds_read_b128 v[188:191], v155 offset:50176
	ds_read_b128 v[192:195], v155 offset:51200
	ds_read_b128 v[196:199], v155 offset:52224
	ds_read_b128 v[200:203], v155 offset:53248
	ds_read_b128 v[204:207], v155 offset:54272
	ds_read_b128 v[208:211], v155 offset:55296
	ds_read_b128 v[212:215], v155 offset:56320
	global_load_lds_dwordx4 v[216:217], off
	s_add_i32 m0, s30, 0x2000
	s_add_u32 s28, s28, 0x40080
	v_lshl_add_u64 v[216:217], v[218:219], 0, s[12:13]
	s_addc_u32 s29, s29, 0
	s_add_i32 s30, s56, s37
	global_load_lds_dwordx4 v[216:217], off
	v_lshl_add_u64 v[216:217], s[28:29], 0, v[130:131]
	s_mov_b32 m0, s30
	s_nop 0
	global_load_lds_dwordx4 v[216:217], off
	v_lshl_add_u64 v[216:217], s[28:29], 0, v[134:135]
	s_add_i32 m0, s30, 0x2000
	s_nop 0
	global_load_lds_dwordx4 v[216:217], off
	v_lshl_add_u64 v[216:217], v[220:221], 0, s[12:13]
	s_mov_b32 m0, s43
	s_nop 0
	global_load_lds_dwordx4 v[216:217], off
	v_lshl_add_u64 v[216:217], v[222:223], 0, s[12:13]
	s_mov_b32 m0, s44
	s_nop 0
	global_load_lds_dwordx4 v[216:217], off
	s_waitcnt vmcnt(8)
	s_waitcnt lgkmcnt(0)
	s_barrier
	s_waitcnt lgkmcnt(0)
	v_mfma_f32_16x16x32_bf16 v[60:63], v[148:151], v[184:187], v[60:63]
	v_mfma_f32_16x16x32_bf16 v[56:59], v[160:163], v[184:187], v[56:59]
	v_mfma_f32_16x16x32_bf16 v[44:47], v[148:151], v[192:195], v[44:47]
	v_mfma_f32_16x16x32_bf16 v[40:43], v[160:163], v[192:195], v[40:43]
	v_mfma_f32_16x16x32_bf16 v[28:31], v[148:151], v[200:203], v[28:31]
	v_mfma_f32_16x16x32_bf16 v[24:27], v[160:163], v[200:203], v[24:27]
	v_mfma_f32_16x16x32_bf16 v[12:15], v[148:151], v[208:211], v[12:15]
	v_mfma_f32_16x16x32_bf16 v[8:11], v[160:163], v[208:211], v[8:11]
	v_mfma_f32_16x16x32_bf16 v[60:63], v[156:159], v[188:191], v[60:63]
	v_mfma_f32_16x16x32_bf16 v[56:59], v[164:167], v[188:191], v[56:59]
	v_mfma_f32_16x16x32_bf16 v[44:47], v[156:159], v[196:199], v[44:47]
	v_mfma_f32_16x16x32_bf16 v[40:43], v[164:167], v[196:199], v[40:43]
	v_mfma_f32_16x16x32_bf16 v[28:31], v[156:159], v[204:207], v[28:31]
	v_mfma_f32_16x16x32_bf16 v[24:27], v[164:167], v[204:207], v[24:27]
	v_mfma_f32_16x16x32_bf16 v[12:15], v[156:159], v[212:215], v[12:15]
	v_mfma_f32_16x16x32_bf16 v[8:11], v[164:167], v[212:215], v[8:11]
	v_mfma_f32_16x16x32_bf16 v[52:55], v[168:171], v[184:187], v[52:55]
	v_mfma_f32_16x16x32_bf16 v[48:51], v[176:179], v[184:187], v[48:51]
	v_mfma_f32_16x16x32_bf16 v[36:39], v[168:171], v[192:195], v[36:39]
	v_mfma_f32_16x16x32_bf16 v[32:35], v[176:179], v[192:195], v[32:35]
	v_mfma_f32_16x16x32_bf16 v[20:23], v[168:171], v[200:203], v[20:23]
	v_mfma_f32_16x16x32_bf16 v[16:19], v[176:179], v[200:203], v[16:19]
	v_mfma_f32_16x16x32_bf16 v[4:7], v[168:171], v[208:211], v[4:7]
	v_mfma_f32_16x16x32_bf16 v[0:3], v[176:179], v[208:211], v[0:3]
	v_mfma_f32_16x16x32_bf16 v[52:55], v[172:175], v[188:191], v[52:55]
	v_mfma_f32_16x16x32_bf16 v[48:51], v[180:183], v[188:191], v[48:51]
	v_mfma_f32_16x16x32_bf16 v[36:39], v[172:175], v[196:199], v[36:39]
	v_mfma_f32_16x16x32_bf16 v[32:35], v[180:183], v[196:199], v[32:35]
	v_mfma_f32_16x16x32_bf16 v[20:23], v[172:175], v[204:207], v[20:23]
	v_mfma_f32_16x16x32_bf16 v[16:19], v[180:183], v[204:207], v[16:19]
	v_mfma_f32_16x16x32_bf16 v[4:7], v[172:175], v[212:215], v[4:7]
	v_mfma_f32_16x16x32_bf16 v[0:3], v[180:183], v[212:215], v[0:3]
	s_barrier
	s_add_i32 s54, s54, 2
	s_add_u32 s26, s26, 0x100
	s_addc_u32 s27, s27, 0
	s_add_u32 s52, s52, 0x100
	s_addc_u32 s53, s53, 0
	s_cmp_gt_u32 s54, 13
	s_cbranch_scc0 .LBB1_94
	s_and_b64 vcc, exec, s[14:15]
	s_cbranch_vccz .LBB1_97
	s_barrier

.LBB3_8:
	v_bfe_i32 v3, v0, 27, 1
	v_lshlrev_b32_e32 v2, 4, v0
	v_lshrrev_b32_e32 v3, 22, v3
	v_add_u32_e32 v3, v2, v3
	v_and_b32_e32 v3, 0xfffffc00, v3
	v_sub_u32_e32 v3, v2, v3
	v_lshrrev_b32_e32 v4, 4, v3
	v_ashrrev_i32_e32 v1, 31, v0
	v_bitop3_b32 v3, v4, v3, 32 bitop3:0x6c
	v_lshrrev_b32_e32 v1, 26, v1
	v_ashrrev_i32_e32 v5, 31, v3
	v_add_u32_e32 v1, v0, v1
	v_lshrrev_b32_e32 v5, 26, v5
	v_ashrrev_i32_e32 v1, 6, v1
	v_add_u32_e32 v5, v3, v5
	v_lshlrev_b32_e32 v4, 3, v1
	v_ashrrev_i32_e32 v10, 6, v5
	v_and_b32_e32 v5, 0xc0, v5
	v_and_b32_e32 v4, -16, v4
	v_sub_u32_e32 v3, v3, v5
	v_mov_b32_e32 v5, 1
	v_add_u32_e32 v4, v10, v4
	v_ashrrev_i16_sdwa v3, v5, sext(v3) dst_sel:DWORD dst_unused:UNUSED_PAD src0_sel:DWORD src1_sel:BYTE_0
	v_lshlrev_b32_e32 v6, 5, v1
	v_bfe_i32 v11, v3, 0, 16
	v_lshlrev_b32_e32 v3, 1, v4
	v_lshrrev_b32_e32 v7, 2, v4
	v_and_b32_e32 v8, 3, v10
	s_mov_b32 s8, 0x1fffe0
	v_and_b32_e32 v6, 32, v6
	v_and_b32_e32 v3, 24, v3
	v_and_b32_e32 v7, 4, v7
	v_and_or_b32 v8, v4, s8, v8
	v_or3_b32 v3, v8, v7, v3
	v_add_lshl_u32 v6, v6, v11, 1
	v_add_u32_e32 v2, 0x2000, v2
	v_lshl_add_u32 v130, v3, 11, v6
	v_ashrrev_i32_e32 v3, 31, v2
	v_lshrrev_b32_e32 v3, 22, v3
	v_add_u32_e32 v3, v2, v3
	v_ashrrev_i32_e32 v12, 10, v3
	v_mul_i32_i24_e32 v3, 0x400, v12
	v_sub_u32_e32 v2, v2, v3
	v_lshrrev_b32_e32 v3, 4, v2
	v_bitop3_b32 v2, v3, v2, 32 bitop3:0x6c
	v_lshl_add_u32 v128, v4, 11, v6
	v_ashrrev_i32_e32 v4, 31, v2
	v_lshrrev_b32_e32 v4, 26, v4
	v_add_u32_e32 v4, v2, v4
	v_lshlrev_b32_e32 v3, 3, v12
	v_ashrrev_i32_e32 v13, 6, v4
	v_and_b32_e32 v4, 0xc0, v4
	v_and_b32_e32 v3, -16, v3
	v_sub_u32_e32 v2, v2, v4
	v_add_u32_e32 v3, v13, v3
	v_ashrrev_i16_sdwa v2, v5, sext(v2) dst_sel:DWORD dst_unused:UNUSED_PAD src0_sel:DWORD src1_sel:BYTE_0
	v_and_b32_e32 v5, 3, v13
	v_and_or_b32 v5, v3, s8, v5
	s_ashr_i32 s8, s14, 6
	s_ashr_i32 s5, s14, 8
	s_lshl_b32 s31, s8, 10
	s_add_u32 s33, s0, 0xd700000
	s_addc_u32 s34, s1, 0
	s_add_i32 s4, s9, s4
	s_ashr_i32 s9, s4, 31
	s_lshr_b32 s9, s9, 27
	s_add_i32 s9, s4, s9
	s_ashr_i32 s10, s9, 5
	s_and_b32 s9, s9, 0xffe0
	s_sub_i32 s9, s4, s9
	s_bfe_i32 s4, s9, 0x80000
	s_bfe_u32 s4, s4, 0x3000c
	s_add_i32 s11, s9, s4
	s_bfe_i32 s4, s11, 0x80000
	s_and_b32 s11, s11, 0xf8
	s_sub_i32 s9, s9, s11
	s_lshl_b32 s10, s10, 3
	s_sext_i32_i16 s4, s4
	s_sext_i32_i8 s9, s9
	s_lshr_b32 s4, s4, 3
	s_add_i32 s22, s10, s9
	s_ashr_i32 s23, s22, 31
	s_bfe_i64 s[12:13], s[4:5], 0x100000
	s_lshl_b64 s[10:11], s[22:23], 19
	s_lshl_b64 s[12:13], s[12:13], 19
	s_add_u32 s26, s6, s12
	v_lshlrev_b32_e32 v6, 5, v12
	v_bfe_i32 v14, v2, 0, 16
	v_lshlrev_b32_e32 v2, 1, v3
	v_lshrrev_b32_e32 v4, 2, v3
	s_addc_u32 s27, s7, s13
	s_add_i32 s23, s31, 0
	v_and_b32_e32 v6, 32, v6
	v_and_b32_e32 v2, 24, v2
	v_and_b32_e32 v4, 4, v4
	s_add_i32 m0, s23, 0x10000
	v_or3_b32 v2, v5, v4, v2
	v_add_lshl_u32 v4, v6, v14, 1
	global_load_lds_dwordx4 v130, s[26:27]
	s_add_i32 m0, s23, 0x12000
	v_lshl_add_u32 v134, v2, 11, v4
	s_add_u32 s12, s26, 0x40000
	global_load_lds_dwordx4 v134, s[26:27]
	s_addc_u32 s13, s27, 0
	s_add_i32 m0, s23, 0x14000
	v_lshl_add_u32 v132, v3, 11, v4
	global_load_lds_dwordx4 v130, s[12:13]
	s_add_i32 m0, s23, 0x16000
	s_add_u32 s24, s33, s10
	s_addc_u32 s25, s34, s11
	s_add_i32 s35, s23, 0x2000
	global_load_lds_dwordx4 v134, s[12:13]
	s_mov_b32 m0, s23
	s_add_u32 s10, s24, 0x40000
	global_load_lds_dwordx4 v128, s[24:25]
	s_mov_b32 m0, s35
	s_addc_u32 s11, s25, 0
	s_add_i32 s36, s23, 0x4000
	global_load_lds_dwordx4 v132, s[24:25]
	s_mov_b32 m0, s36
	s_add_i32 s37, s23, 0x6000
	global_load_lds_dwordx4 v128, s[10:11]
	s_mov_b32 m0, s37
	v_mov_b32_e32 v131, 0
	global_load_lds_dwordx4 v132, s[10:11]
	v_mov_b32_e32 v135, v131
	v_mov_b32_e32 v129, v131
	v_mov_b32_e32 v133, v131
	s_cmp_eq_u32 s5, 1
	s_mov_b32 s9, 0
	s_mov_b32 s38, 0x10000
	v_lshl_add_u64 v[8:9], s[26:27], 0, v[130:131]
	v_lshl_add_u64 v[6:7], s[26:27], 0, v[134:135]
	v_lshl_add_u64 v[2:3], s[24:25], 0, v[128:129]
	s_cselect_b64 s[10:11], -1, 0
	s_cmp_lg_u32 s5, 1
	v_lshl_add_u64 v[4:5], s[24:25], 0, v[132:133]
	s_cbranch_scc1 .LBB3_10
	s_barrier
	s_setprio 1

.LBB3_19:
	s_ashr_i32 s17, s16, 31
	s_lshl_b64 s[18:19], s[16:17], 19
	s_add_u32 s18, s33, s18
	v_cmp_lt_i64_e64 s[4:5], s[4:5], v[142:143]
	s_addc_u32 s19, s34, s19
	s_and_b64 s[20:21], s[4:5], exec
	s_cselect_b32 s17, s19, s25
	s_cselect_b32 s53, s18, s24
	s_ashr_i32 s15, s14, 31
	s_lshl_b64 s[20:21], s[14:15], 19
	s_add_u32 s20, s6, s20
	s_addc_u32 s21, s7, s21
	s_and_b64 s[28:29], s[4:5], exec
	s_cselect_b32 s15, s21, s27
	s_cselect_b32 s54, s20, s26
	s_add_u32 s24, s24, 0x40080
	s_addc_u32 s25, s25, 0
	s_add_u32 s55, s26, 0x100
	s_addc_u32 s56, s27, 0
	s_mov_b32 s57, -2
	ds_read_b128 v[152:155], v149
	ds_read_b128 v[156:159], v149 offset:1024
	ds_read_b128 v[160:163], v149 offset:2048
	ds_read_b128 v[164:167], v149 offset:3072
	ds_read_b128 v[168:171], v150
	ds_read_b128 v[172:175], v150 offset:1024
	ds_read_b128 v[176:179], v150 offset:2048
	ds_read_b128 v[180:183], v150 offset:3072
	s_add_u32 s26, s24, 0xfffc0080
	s_addc_u32 s27, s25, -1
	s_cmp_eq_u32 s57, 12
	s_cselect_b32 s29, s17, s27
	s_cselect_b32 s28, s53, s26
	s_cselect_b32 s27, s15, s56
	s_cselect_b32 s26, s54, s55
	v_lshl_add_u64 v[146:147], s[24:25], 0, v[138:139]
	s_add_i32 m0, s23, 0xc000
	ds_read_b128 v[184:187], v151
	ds_read_b128 v[188:191], v151 offset:1024
	ds_read_b128 v[192:195], v151 offset:2048
	ds_read_b128 v[196:199], v151 offset:3072
	ds_read_b128 v[200:203], v151 offset:4096
	ds_read_b128 v[204:207], v151 offset:5120
	ds_read_b128 v[208:211], v151 offset:6144
	ds_read_b128 v[212:215], v151 offset:7168
	global_load_lds_dwordx4 v[146:147], off
	v_lshl_add_u64 v[146:147], s[24:25], 0, v[140:141]
	s_add_i32 m0, s23, 0xe000
	s_nop 0
	global_load_lds_dwordx4 v[146:147], off
	s_waitcnt vmcnt(8)
	s_waitcnt lgkmcnt(0)
	s_barrier
	s_waitcnt lgkmcnt(0)
	v_mfma_f32_16x16x32_bf16 v[124:127], v[152:155], v[184:187], 0
	v_mfma_f32_16x16x32_bf16 v[120:123], v[160:163], v[184:187], 0
	v_mfma_f32_16x16x32_bf16 v[116:119], v[152:155], v[192:195], 0
	v_mfma_f32_16x16x32_bf16 v[108:111], v[160:163], v[192:195], 0
	v_mfma_f32_16x16x32_bf16 v[100:103], v[152:155], v[200:203], 0
	v_mfma_f32_16x16x32_bf16 v[92:95], v[160:163], v[200:203], 0
	v_mfma_f32_16x16x32_bf16 v[84:87], v[152:155], v[208:211], 0
	v_mfma_f32_16x16x32_bf16 v[76:79], v[160:163], v[208:211], 0
	v_mfma_f32_16x16x32_bf16 v[124:127], v[156:159], v[188:191], v[124:127]
	v_mfma_f32_16x16x32_bf16 v[120:123], v[164:167], v[188:191], v[120:123]
	v_mfma_f32_16x16x32_bf16 v[116:119], v[156:159], v[196:199], v[116:119]
	v_mfma_f32_16x16x32_bf16 v[108:111], v[164:167], v[196:199], v[108:111]
	v_mfma_f32_16x16x32_bf16 v[100:103], v[156:159], v[204:207], v[100:103]
	v_mfma_f32_16x16x32_bf16 v[92:95], v[164:167], v[204:207], v[92:95]
	v_mfma_f32_16x16x32_bf16 v[84:87], v[156:159], v[212:215], v[84:87]
	v_mfma_f32_16x16x32_bf16 v[76:79], v[164:167], v[212:215], v[76:79]
	v_mfma_f32_16x16x32_bf16 v[112:115], v[168:171], v[184:187], 0
	v_mfma_f32_16x16x32_bf16 v[104:107], v[176:179], v[184:187], 0
	v_mfma_f32_16x16x32_bf16 v[96:99], v[168:171], v[192:195], 0
	v_mfma_f32_16x16x32_bf16 v[88:91], v[176:179], v[192:195], 0
	v_mfma_f32_16x16x32_bf16 v[80:83], v[168:171], v[200:203], 0
	v_mfma_f32_16x16x32_bf16 v[72:75], v[176:179], v[200:203], 0
	v_mfma_f32_16x16x32_bf16 v[68:71], v[168:171], v[208:211], 0
	v_mfma_f32_16x16x32_bf16 v[64:67], v[176:179], v[208:211], 0
	v_mfma_f32_16x16x32_bf16 v[112:115], v[172:175], v[188:191], v[112:115]
	v_mfma_f32_16x16x32_bf16 v[104:107], v[180:183], v[188:191], v[104:107]
	v_mfma_f32_16x16x32_bf16 v[96:99], v[172:175], v[196:199], v[96:99]
	v_mfma_f32_16x16x32_bf16 v[88:91], v[180:183], v[196:199], v[88:91]
	v_mfma_f32_16x16x32_bf16 v[80:83], v[172:175], v[204:207], v[80:83]
	v_mfma_f32_16x16x32_bf16 v[72:75], v[180:183], v[204:207], v[72:75]
	v_mfma_f32_16x16x32_bf16 v[68:71], v[172:175], v[212:215], v[68:71]
	v_mfma_f32_16x16x32_bf16 v[64:67], v[180:183], v[212:215], v[64:67]
	s_barrier
	s_add_i32 s58, s45, s31
	v_lshl_add_u64 v[146:147], s[26:27], 0, v[130:131]
	s_mov_b32 m0, s58
	ds_read_b128 v[184:187], v151 offset:16384
	ds_read_b128 v[188:191], v151 offset:17408
	ds_read_b128 v[192:195], v151 offset:18432
	ds_read_b128 v[196:199], v151 offset:19456
	ds_read_b128 v[200:203], v151 offset:20480
	ds_read_b128 v[204:207], v151 offset:21504
	ds_read_b128 v[208:211], v151 offset:22528
	ds_read_b128 v[212:215], v151 offset:23552
	global_load_lds_dwordx4 v[146:147], off
	s_add_i32 m0, s58, 0x2000
	s_add_u32 s58, s26, 0x40000
	v_lshl_add_u64 v[216:217], s[26:27], 0, v[134:135]
	s_addc_u32 s59, s27, 0
	s_add_i32 s60, s46, s31
	global_load_lds_dwordx4 v[216:217], off
	v_lshl_add_u64 v[218:219], s[58:59], 0, v[130:131]
	s_mov_b32 m0, s60
	v_lshl_add_u64 v[220:221], s[28:29], 0, v[132:133]
	global_load_lds_dwordx4 v[218:219], off
	v_lshl_add_u64 v[218:219], s[58:59], 0, v[134:135]
	s_add_i32 m0, s60, 0x2000
	s_nop 0
	global_load_lds_dwordx4 v[218:219], off
	v_lshl_add_u64 v[218:219], s[28:29], 0, v[128:129]
	s_mov_b32 m0, s23
	s_nop 0
	global_load_lds_dwordx4 v[218:219], off
	s_mov_b32 m0, s35
	s_nop 0
	global_load_lds_dwordx4 v[220:221], off
	s_waitcnt vmcnt(8)
	s_waitcnt lgkmcnt(0)
	s_barrier
	s_waitcnt lgkmcnt(0)
	v_mfma_f32_16x16x32_bf16 v[60:63], v[152:155], v[184:187], 0
	v_mfma_f32_16x16x32_bf16 v[56:59], v[160:163], v[184:187], 0
	v_mfma_f32_16x16x32_bf16 v[52:55], v[152:155], v[192:195], 0
	v_mfma_f32_16x16x32_bf16 v[44:47], v[160:163], v[192:195], 0
	v_mfma_f32_16x16x32_bf16 v[36:39], v[152:155], v[200:203], 0
	v_mfma_f32_16x16x32_bf16 v[28:31], v[160:163], v[200:203], 0
	v_mfma_f32_16x16x32_bf16 v[20:23], v[152:155], v[208:211], 0
	v_mfma_f32_16x16x32_bf16 v[12:15], v[160:163], v[208:211], 0
	v_mfma_f32_16x16x32_bf16 v[60:63], v[156:159], v[188:191], v[60:63]
	v_mfma_f32_16x16x32_bf16 v[56:59], v[164:167], v[188:191], v[56:59]
	v_mfma_f32_16x16x32_bf16 v[52:55], v[156:159], v[196:199], v[52:55]
	v_mfma_f32_16x16x32_bf16 v[44:47], v[164:167], v[196:199], v[44:47]
	v_mfma_f32_16x16x32_bf16 v[36:39], v[156:159], v[204:207], v[36:39]
	v_mfma_f32_16x16x32_bf16 v[28:31], v[164:167], v[204:207], v[28:31]
	v_mfma_f32_16x16x32_bf16 v[20:23], v[156:159], v[212:215], v[20:23]
	v_mfma_f32_16x16x32_bf16 v[12:15], v[164:167], v[212:215], v[12:15]
	v_mfma_f32_16x16x32_bf16 v[48:51], v[168:171], v[184:187], 0
	v_mfma_f32_16x16x32_bf16 v[40:43], v[176:179], v[184:187], 0
	v_mfma_f32_16x16x32_bf16 v[32:35], v[168:171], v[192:195], 0
	v_mfma_f32_16x16x32_bf16 v[24:27], v[176:179], v[192:195], 0
	v_mfma_f32_16x16x32_bf16 v[16:19], v[168:171], v[200:203], 0
	v_mfma_f32_16x16x32_bf16 v[8:11], v[176:179], v[200:203], 0
	v_mfma_f32_16x16x32_bf16 v[4:7], v[168:171], v[208:211], 0
	v_mfma_f32_16x16x32_bf16 v[0:3], v[176:179], v[208:211], 0
	v_mfma_f32_16x16x32_bf16 v[48:51], v[172:175], v[188:191], v[48:51]
	v_mfma_f32_16x16x32_bf16 v[40:43], v[180:183], v[188:191], v[40:43]
	v_mfma_f32_16x16x32_bf16 v[32:35], v[172:175], v[196:199], v[32:35]
	v_mfma_f32_16x16x32_bf16 v[24:27], v[180:183], v[196:199], v[24:27]
	v_mfma_f32_16x16x32_bf16 v[16:19], v[172:175], v[204:207], v[16:19]
	v_mfma_f32_16x16x32_bf16 v[8:11], v[180:183], v[204:207], v[8:11]
	v_mfma_f32_16x16x32_bf16 v[4:7], v[172:175], v[212:215], v[4:7]
	v_mfma_f32_16x16x32_bf16 v[0:3], v[180:183], v[212:215], v[0:3]
	s_barrier
	s_add_i32 s58, 0, 0x18000
	s_add_i32 s59, 0, 0x1c000
	v_add_u32_e32 v164, s58, v148
	v_add_u32_e32 v180, s59, v148
	ds_read_b128 v[152:155], v164
	ds_read_b128 v[156:159], v164 offset:1024
	ds_read_b128 v[160:163], v164 offset:2048
	ds_read_b128 v[164:167], v164 offset:3072
	ds_read_b128 v[168:171], v180
	ds_read_b128 v[172:175], v180 offset:1024
	ds_read_b128 v[176:179], v180 offset:2048
	ds_read_b128 v[180:183], v180 offset:3072
	s_add_u32 s28, s28, 0x40000
	s_addc_u32 s29, s29, 0
	s_mov_b32 m0, s36
	v_lshl_add_u64 v[222:223], s[28:29], 0, v[128:129]
	ds_read_b128 v[184:187], v151 offset:32768
	ds_read_b128 v[188:191], v151 offset:33792
	ds_read_b128 v[192:195], v151 offset:34816
	ds_read_b128 v[196:199], v151 offset:35840
	ds_read_b128 v[200:203], v151 offset:36864
	ds_read_b128 v[204:207], v151 offset:37888
	ds_read_b128 v[208:211], v151 offset:38912
	ds_read_b128 v[212:215], v151 offset:39936
	global_load_lds_dwordx4 v[222:223], off
	v_lshl_add_u64 v[222:223], s[28:29], 0, v[132:133]
	s_mov_b32 m0, s37
	s_nop 0
	global_load_lds_dwordx4 v[222:223], off
	s_waitcnt vmcnt(8)
	s_waitcnt lgkmcnt(0)
	s_barrier
	s_waitcnt lgkmcnt(0)
	v_mfma_f32_16x16x32_bf16 v[124:127], v[152:155], v[184:187], v[124:127]
	v_mfma_f32_16x16x32_bf16 v[120:123], v[160:163], v[184:187], v[120:123]
	v_mfma_f32_16x16x32_bf16 v[116:119], v[152:155], v[192:195], v[116:119]
	v_mfma_f32_16x16x32_bf16 v[108:111], v[160:163], v[192:195], v[108:111]
	v_mfma_f32_16x16x32_bf16 v[100:103], v[152:155], v[200:203], v[100:103]
	v_mfma_f32_16x16x32_bf16 v[92:95], v[160:163], v[200:203], v[92:95]
	v_mfma_f32_16x16x32_bf16 v[84:87], v[152:155], v[208:211], v[84:87]
	v_mfma_f32_16x16x32_bf16 v[76:79], v[160:163], v[208:211], v[76:79]
	v_mfma_f32_16x16x32_bf16 v[124:127], v[156:159], v[188:191], v[124:127]
	v_mfma_f32_16x16x32_bf16 v[120:123], v[164:167], v[188:191], v[120:123]
	v_mfma_f32_16x16x32_bf16 v[116:119], v[156:159], v[196:199], v[116:119]
	v_mfma_f32_16x16x32_bf16 v[108:111], v[164:167], v[196:199], v[108:111]
	v_mfma_f32_16x16x32_bf16 v[100:103], v[156:159], v[204:207], v[100:103]
	v_mfma_f32_16x16x32_bf16 v[92:95], v[164:167], v[204:207], v[92:95]
	v_mfma_f32_16x16x32_bf16 v[84:87], v[156:159], v[212:215], v[84:87]
	v_mfma_f32_16x16x32_bf16 v[76:79], v[164:167], v[212:215], v[76:79]
	v_mfma_f32_16x16x32_bf16 v[112:115], v[168:171], v[184:187], v[112:115]
	v_mfma_f32_16x16x32_bf16 v[104:107], v[176:179], v[184:187], v[104:107]
	v_mfma_f32_16x16x32_bf16 v[96:99], v[168:171], v[192:195], v[96:99]
	v_mfma_f32_16x16x32_bf16 v[88:91], v[176:179], v[192:195], v[88:91]
	v_mfma_f32_16x16x32_bf16 v[80:83], v[168:171], v[200:203], v[80:83]
	v_mfma_f32_16x16x32_bf16 v[72:75], v[176:179], v[200:203], v[72:75]
	v_mfma_f32_16x16x32_bf16 v[68:71], v[168:171], v[208:211], v[68:71]
	v_mfma_f32_16x16x32_bf16 v[64:67], v[176:179], v[208:211], v[64:67]
	v_mfma_f32_16x16x32_bf16 v[112:115], v[172:175], v[188:191], v[112:115]
	v_mfma_f32_16x16x32_bf16 v[104:107], v[180:183], v[188:191], v[104:107]
	v_mfma_f32_16x16x32_bf16 v[96:99], v[172:175], v[196:199], v[96:99]
	v_mfma_f32_16x16x32_bf16 v[88:91], v[180:183], v[196:199], v[88:91]
	v_mfma_f32_16x16x32_bf16 v[80:83], v[172:175], v[204:207], v[80:83]
	v_mfma_f32_16x16x32_bf16 v[72:75], v[180:183], v[204:207], v[72:75]
	v_mfma_f32_16x16x32_bf16 v[68:71], v[172:175], v[212:215], v[68:71]
	v_mfma_f32_16x16x32_bf16 v[64:67], v[180:183], v[212:215], v[64:67]
	s_barrier
	s_add_i32 s28, s58, s31
	v_lshl_add_u64 v[146:147], v[146:147], 0, s[12:13]
	s_mov_b32 m0, s28
	ds_read_b128 v[184:187], v151 offset:49152
	ds_read_b128 v[188:191], v151 offset:50176
	ds_read_b128 v[192:195], v151 offset:51200
	ds_read_b128 v[196:199], v151 offset:52224
	ds_read_b128 v[200:203], v151 offset:53248
	ds_read_b128 v[204:207], v151 offset:54272
	ds_read_b128 v[208:211], v151 offset:55296
	ds_read_b128 v[212:215], v151 offset:56320
	global_load_lds_dwordx4 v[146:147], off
	s_add_i32 m0, s28, 0x2000
	s_add_u32 s26, s26, 0x40080
	v_lshl_add_u64 v[146:147], v[216:217], 0, s[12:13]
	s_addc_u32 s27, s27, 0
	s_add_i32 s28, s59, s31
	global_load_lds_dwordx4 v[146:147], off
	v_lshl_add_u64 v[146:147], s[26:27], 0, v[130:131]
	s_mov_b32 m0, s28
	s_nop 0
	global_load_lds_dwordx4 v[146:147], off
	v_lshl_add_u64 v[146:147], s[26:27], 0, v[134:135]
	s_add_i32 m0, s28, 0x2000
	s_nop 0
	global_load_lds_dwordx4 v[146:147], off
	v_lshl_add_u64 v[146:147], v[218:219], 0, s[12:13]
	s_mov_b32 m0, s40
	s_nop 0
	global_load_lds_dwordx4 v[146:147], off
	v_lshl_add_u64 v[146:147], v[220:221], 0, s[12:13]
	s_mov_b32 m0, s41
	s_nop 0
	global_load_lds_dwordx4 v[146:147], off
	s_waitcnt vmcnt(8)
	s_waitcnt lgkmcnt(0)
	s_barrier
	s_waitcnt lgkmcnt(0)
	v_mfma_f32_16x16x32_bf16 v[60:63], v[152:155], v[184:187], v[60:63]
	v_mfma_f32_16x16x32_bf16 v[56:59], v[160:163], v[184:187], v[56:59]
	v_mfma_f32_16x16x32_bf16 v[52:55], v[152:155], v[192:195], v[52:55]
	v_mfma_f32_16x16x32_bf16 v[44:47], v[160:163], v[192:195], v[44:47]
	v_mfma_f32_16x16x32_bf16 v[36:39], v[152:155], v[200:203], v[36:39]
	v_mfma_f32_16x16x32_bf16 v[28:31], v[160:163], v[200:203], v[28:31]
	v_mfma_f32_16x16x32_bf16 v[20:23], v[152:155], v[208:211], v[20:23]
	v_mfma_f32_16x16x32_bf16 v[12:15], v[160:163], v[208:211], v[12:15]
	v_mfma_f32_16x16x32_bf16 v[60:63], v[156:159], v[188:191], v[60:63]
	v_mfma_f32_16x16x32_bf16 v[56:59], v[164:167], v[188:191], v[56:59]
	v_mfma_f32_16x16x32_bf16 v[52:55], v[156:159], v[196:199], v[52:55]
	v_mfma_f32_16x16x32_bf16 v[44:47], v[164:167], v[196:199], v[44:47]
	v_mfma_f32_16x16x32_bf16 v[36:39], v[156:159], v[204:207], v[36:39]
	v_mfma_f32_16x16x32_bf16 v[28:31], v[164:167], v[204:207], v[28:31]
	v_mfma_f32_16x16x32_bf16 v[20:23], v[156:159], v[212:215], v[20:23]
	v_mfma_f32_16x16x32_bf16 v[12:15], v[164:167], v[212:215], v[12:15]
	v_mfma_f32_16x16x32_bf16 v[48:51], v[168:171], v[184:187], v[48:51]
	v_mfma_f32_16x16x32_bf16 v[40:43], v[176:179], v[184:187], v[40:43]
	v_mfma_f32_16x16x32_bf16 v[32:35], v[168:171], v[192:195], v[32:35]
	v_mfma_f32_16x16x32_bf16 v[24:27], v[176:179], v[192:195], v[24:27]
	v_mfma_f32_16x16x32_bf16 v[16:19], v[168:171], v[200:203], v[16:19]
	v_mfma_f32_16x16x32_bf16 v[8:11], v[176:179], v[200:203], v[8:11]
	v_mfma_f32_16x16x32_bf16 v[4:7], v[168:171], v[208:211], v[4:7]
	v_mfma_f32_16x16x32_bf16 v[0:3], v[176:179], v[208:211], v[0:3]
	v_mfma_f32_16x16x32_bf16 v[48:51], v[172:175], v[188:191], v[48:51]
	v_mfma_f32_16x16x32_bf16 v[40:43], v[180:183], v[188:191], v[40:43]
	v_mfma_f32_16x16x32_bf16 v[32:35], v[172:175], v[196:199], v[32:35]
	v_mfma_f32_16x16x32_bf16 v[24:27], v[180:183], v[196:199], v[24:27]
	v_mfma_f32_16x16x32_bf16 v[16:19], v[172:175], v[204:207], v[16:19]
	v_mfma_f32_16x16x32_bf16 v[8:11], v[180:183], v[204:207], v[8:11]
	v_mfma_f32_16x16x32_bf16 v[4:7], v[172:175], v[212:215], v[4:7]
	v_mfma_f32_16x16x32_bf16 v[0:3], v[180:183], v[212:215], v[0:3]
	s_barrier
	s_add_i32 s57, s57, 2
	s_add_u32 s24, s24, 0x100
	s_addc_u32 s25, s25, 0
	s_add_u32 s55, s55, 0x100
	s_addc_u32 s56, s56, 0
	s_cmp_gt_u32 s57, 13
.LBB3_20:
	ds_read_b128 v[152:155], v149
	ds_read_b128 v[156:159], v149 offset:1024
	ds_read_b128 v[160:163], v149 offset:2048
	ds_read_b128 v[164:167], v149 offset:3072
	ds_read_b128 v[168:171], v150
	ds_read_b128 v[172:175], v150 offset:1024
	ds_read_b128 v[176:179], v150 offset:2048
	ds_read_b128 v[180:183], v150 offset:3072
	s_add_u32 s26, s24, 0xfffc0080
	s_addc_u32 s27, s25, -1
	s_cmp_eq_u32 s57, 12
	s_cselect_b32 s29, s17, s27
	s_cselect_b32 s28, s53, s26
	s_cselect_b32 s27, s15, s56
	s_cselect_b32 s26, s54, s55
	v_lshl_add_u64 v[146:147], s[24:25], 0, v[138:139]
	s_add_i32 m0, s23, 0xc000
	ds_read_b128 v[184:187], v151
	ds_read_b128 v[188:191], v151 offset:1024
	ds_read_b128 v[192:195], v151 offset:2048
	ds_read_b128 v[196:199], v151 offset:3072
	ds_read_b128 v[200:203], v151 offset:4096
	ds_read_b128 v[204:207], v151 offset:5120
	ds_read_b128 v[208:211], v151 offset:6144
	ds_read_b128 v[212:215], v151 offset:7168
	global_load_lds_dwordx4 v[146:147], off
	v_lshl_add_u64 v[146:147], s[24:25], 0, v[140:141]
	s_add_i32 m0, s23, 0xe000
	s_nop 0
	global_load_lds_dwordx4 v[146:147], off
	s_waitcnt vmcnt(8)
	s_waitcnt lgkmcnt(0)
	s_barrier
	s_waitcnt lgkmcnt(0)
	v_mfma_f32_16x16x32_bf16 v[124:127], v[152:155], v[184:187], v[124:127]
	v_mfma_f32_16x16x32_bf16 v[120:123], v[160:163], v[184:187], v[120:123]
	v_mfma_f32_16x16x32_bf16 v[116:119], v[152:155], v[192:195], v[116:119]
	v_mfma_f32_16x16x32_bf16 v[108:111], v[160:163], v[192:195], v[108:111]
	v_mfma_f32_16x16x32_bf16 v[100:103], v[152:155], v[200:203], v[100:103]
	v_mfma_f32_16x16x32_bf16 v[92:95], v[160:163], v[200:203], v[92:95]
	v_mfma_f32_16x16x32_bf16 v[84:87], v[152:155], v[208:211], v[84:87]
	v_mfma_f32_16x16x32_bf16 v[76:79], v[160:163], v[208:211], v[76:79]
	v_mfma_f32_16x16x32_bf16 v[124:127], v[156:159], v[188:191], v[124:127]
	v_mfma_f32_16x16x32_bf16 v[120:123], v[164:167], v[188:191], v[120:123]
	v_mfma_f32_16x16x32_bf16 v[116:119], v[156:159], v[196:199], v[116:119]
	v_mfma_f32_16x16x32_bf16 v[108:111], v[164:167], v[196:199], v[108:111]
	v_mfma_f32_16x16x32_bf16 v[100:103], v[156:159], v[204:207], v[100:103]
	v_mfma_f32_16x16x32_bf16 v[92:95], v[164:167], v[204:207], v[92:95]
	v_mfma_f32_16x16x32_bf16 v[84:87], v[156:159], v[212:215], v[84:87]
	v_mfma_f32_16x16x32_bf16 v[76:79], v[164:167], v[212:215], v[76:79]
	v_mfma_f32_16x16x32_bf16 v[112:115], v[168:171], v[184:187], v[112:115]
	v_mfma_f32_16x16x32_bf16 v[104:107], v[176:179], v[184:187], v[104:107]
	v_mfma_f32_16x16x32_bf16 v[96:99], v[168:171], v[192:195], v[96:99]
	v_mfma_f32_16x16x32_bf16 v[88:91], v[176:179], v[192:195], v[88:91]
	v_mfma_f32_16x16x32_bf16 v[80:83], v[168:171], v[200:203], v[80:83]
	v_mfma_f32_16x16x32_bf16 v[72:75], v[176:179], v[200:203], v[72:75]
	v_mfma_f32_16x16x32_bf16 v[68:71], v[168:171], v[208:211], v[68:71]
	v_mfma_f32_16x16x32_bf16 v[64:67], v[176:179], v[208:211], v[64:67]
	v_mfma_f32_16x16x32_bf16 v[112:115], v[172:175], v[188:191], v[112:115]
	v_mfma_f32_16x16x32_bf16 v[104:107], v[180:183], v[188:191], v[104:107]
	v_mfma_f32_16x16x32_bf16 v[96:99], v[172:175], v[196:199], v[96:99]
	v_mfma_f32_16x16x32_bf16 v[88:91], v[180:183], v[196:199], v[88:91]
	v_mfma_f32_16x16x32_bf16 v[80:83], v[172:175], v[204:207], v[80:83]
	v_mfma_f32_16x16x32_bf16 v[72:75], v[180:183], v[204:207], v[72:75]
	v_mfma_f32_16x16x32_bf16 v[68:71], v[172:175], v[212:215], v[68:71]
	v_mfma_f32_16x16x32_bf16 v[64:67], v[180:183], v[212:215], v[64:67]
	s_barrier
	s_add_i32 s58, s45, s31
	v_lshl_add_u64 v[146:147], s[26:27], 0, v[130:131]
	s_mov_b32 m0, s58
	ds_read_b128 v[184:187], v151 offset:16384
	ds_read_b128 v[188:191], v151 offset:17408
	ds_read_b128 v[192:195], v151 offset:18432
	ds_read_b128 v[196:199], v151 offset:19456
	ds_read_b128 v[200:203], v151 offset:20480
	ds_read_b128 v[204:207], v151 offset:21504
	ds_read_b128 v[208:211], v151 offset:22528
	ds_read_b128 v[212:215], v151 offset:23552
	global_load_lds_dwordx4 v[146:147], off
	s_add_i32 m0, s58, 0x2000
	s_add_u32 s58, s26, 0x40000
	v_lshl_add_u64 v[216:217], s[26:27], 0, v[134:135]
	s_addc_u32 s59, s27, 0
	s_add_i32 s60, s46, s31
	global_load_lds_dwordx4 v[216:217], off
	v_lshl_add_u64 v[218:219], s[58:59], 0, v[130:131]
	s_mov_b32 m0, s60
	v_lshl_add_u64 v[220:221], s[28:29], 0, v[132:133]
	global_load_lds_dwordx4 v[218:219], off
	v_lshl_add_u64 v[218:219], s[58:59], 0, v[134:135]
	s_add_i32 m0, s60, 0x2000
	s_nop 0
	global_load_lds_dwordx4 v[218:219], off
	v_lshl_add_u64 v[218:219], s[28:29], 0, v[128:129]
	s_mov_b32 m0, s23
	s_nop 0
	global_load_lds_dwordx4 v[218:219], off
	s_mov_b32 m0, s35
	s_nop 0
	global_load_lds_dwordx4 v[220:221], off
	s_waitcnt vmcnt(8)
	s_waitcnt lgkmcnt(0)
	s_barrier
	s_waitcnt lgkmcnt(0)
	v_mfma_f32_16x16x32_bf16 v[60:63], v[152:155], v[184:187], v[60:63]
	v_mfma_f32_16x16x32_bf16 v[56:59], v[160:163], v[184:187], v[56:59]
	v_mfma_f32_16x16x32_bf16 v[52:55], v[152:155], v[192:195], v[52:55]
	v_mfma_f32_16x16x32_bf16 v[44:47], v[160:163], v[192:195], v[44:47]
	v_mfma_f32_16x16x32_bf16 v[36:39], v[152:155], v[200:203], v[36:39]
	v_mfma_f32_16x16x32_bf16 v[28:31], v[160:163], v[200:203], v[28:31]
	v_mfma_f32_16x16x32_bf16 v[20:23], v[152:155], v[208:211], v[20:23]
	v_mfma_f32_16x16x32_bf16 v[12:15], v[160:163], v[208:211], v[12:15]
	v_mfma_f32_16x16x32_bf16 v[60:63], v[156:159], v[188:191], v[60:63]
	v_mfma_f32_16x16x32_bf16 v[56:59], v[164:167], v[188:191], v[56:59]
	v_mfma_f32_16x16x32_bf16 v[52:55], v[156:159], v[196:199], v[52:55]
	v_mfma_f32_16x16x32_bf16 v[44:47], v[164:167], v[196:199], v[44:47]
	v_mfma_f32_16x16x32_bf16 v[36:39], v[156:159], v[204:207], v[36:39]
	v_mfma_f32_16x16x32_bf16 v[28:31], v[164:167], v[204:207], v[28:31]
	v_mfma_f32_16x16x32_bf16 v[20:23], v[156:159], v[212:215], v[20:23]
	v_mfma_f32_16x16x32_bf16 v[12:15], v[164:167], v[212:215], v[12:15]
	v_mfma_f32_16x16x32_bf16 v[48:51], v[168:171], v[184:187], v[48:51]
	v_mfma_f32_16x16x32_bf16 v[40:43], v[176:179], v[184:187], v[40:43]
	v_mfma_f32_16x16x32_bf16 v[32:35], v[168:171], v[192:195], v[32:35]
	v_mfma_f32_16x16x32_bf16 v[24:27], v[176:179], v[192:195], v[24:27]
	v_mfma_f32_16x16x32_bf16 v[16:19], v[168:171], v[200:203], v[16:19]
	v_mfma_f32_16x16x32_bf16 v[8:11], v[176:179], v[200:203], v[8:11]
	v_mfma_f32_16x16x32_bf16 v[4:7], v[168:171], v[208:211], v[4:7]
	v_mfma_f32_16x16x32_bf16 v[0:3], v[176:179], v[208:211], v[0:3]
	v_mfma_f32_16x16x32_bf16 v[48:51], v[172:175], v[188:191], v[48:51]
	v_mfma_f32_16x16x32_bf16 v[40:43], v[180:183], v[188:191], v[40:43]
	v_mfma_f32_16x16x32_bf16 v[32:35], v[172:175], v[196:199], v[32:35]
	v_mfma_f32_16x16x32_bf16 v[24:27], v[180:183], v[196:199], v[24:27]
	v_mfma_f32_16x16x32_bf16 v[16:19], v[172:175], v[204:207], v[16:19]
	v_mfma_f32_16x16x32_bf16 v[8:11], v[180:183], v[204:207], v[8:11]
	v_mfma_f32_16x16x32_bf16 v[4:7], v[172:175], v[212:215], v[4:7]
	v_mfma_f32_16x16x32_bf16 v[0:3], v[180:183], v[212:215], v[0:3]
	s_barrier
	s_add_i32 s58, 0, 0x18000
	s_add_i32 s59, 0, 0x1c000
	v_add_u32_e32 v164, s58, v148
	v_add_u32_e32 v180, s59, v148
	ds_read_b128 v[152:155], v164
	ds_read_b128 v[156:159], v164 offset:1024
	ds_read_b128 v[160:163], v164 offset:2048
	ds_read_b128 v[164:167], v164 offset:3072
	ds_read_b128 v[168:171], v180
	ds_read_b128 v[172:175], v180 offset:1024
	ds_read_b128 v[176:179], v180 offset:2048
	ds_read_b128 v[180:183], v180 offset:3072
	s_add_u32 s28, s28, 0x40000
	s_addc_u32 s29, s29, 0
	s_mov_b32 m0, s36
	v_lshl_add_u64 v[222:223], s[28:29], 0, v[128:129]
	ds_read_b128 v[184:187], v151 offset:32768
	ds_read_b128 v[188:191], v151 offset:33792
	ds_read_b128 v[192:195], v151 offset:34816
	ds_read_b128 v[196:199], v151 offset:35840
	ds_read_b128 v[200:203], v151 offset:36864
	ds_read_b128 v[204:207], v151 offset:37888
	ds_read_b128 v[208:211], v151 offset:38912
	ds_read_b128 v[212:215], v151 offset:39936
	global_load_lds_dwordx4 v[222:223], off
	v_lshl_add_u64 v[222:223], s[28:29], 0, v[132:133]
	s_mov_b32 m0, s37
	s_nop 0
	global_load_lds_dwordx4 v[222:223], off
	s_waitcnt vmcnt(8)
	s_waitcnt lgkmcnt(0)
	s_barrier
	s_waitcnt lgkmcnt(0)
	v_mfma_f32_16x16x32_bf16 v[124:127], v[152:155], v[184:187], v[124:127]
	v_mfma_f32_16x16x32_bf16 v[120:123], v[160:163], v[184:187], v[120:123]
	v_mfma_f32_16x16x32_bf16 v[116:119], v[152:155], v[192:195], v[116:119]
	v_mfma_f32_16x16x32_bf16 v[108:111], v[160:163], v[192:195], v[108:111]
	v_mfma_f32_16x16x32_bf16 v[100:103], v[152:155], v[200:203], v[100:103]
	v_mfma_f32_16x16x32_bf16 v[92:95], v[160:163], v[200:203], v[92:95]
	v_mfma_f32_16x16x32_bf16 v[84:87], v[152:155], v[208:211], v[84:87]
	v_mfma_f32_16x16x32_bf16 v[76:79], v[160:163], v[208:211], v[76:79]
	v_mfma_f32_16x16x32_bf16 v[124:127], v[156:159], v[188:191], v[124:127]
	v_mfma_f32_16x16x32_bf16 v[120:123], v[164:167], v[188:191], v[120:123]
	v_mfma_f32_16x16x32_bf16 v[116:119], v[156:159], v[196:199], v[116:119]
	v_mfma_f32_16x16x32_bf16 v[108:111], v[164:167], v[196:199], v[108:111]
	v_mfma_f32_16x16x32_bf16 v[100:103], v[156:159], v[204:207], v[100:103]
	v_mfma_f32_16x16x32_bf16 v[92:95], v[164:167], v[204:207], v[92:95]
	v_mfma_f32_16x16x32_bf16 v[84:87], v[156:159], v[212:215], v[84:87]
	v_mfma_f32_16x16x32_bf16 v[76:79], v[164:167], v[212:215], v[76:79]
	v_mfma_f32_16x16x32_bf16 v[112:115], v[168:171], v[184:187], v[112:115]
	v_mfma_f32_16x16x32_bf16 v[104:107], v[176:179], v[184:187], v[104:107]
	v_mfma_f32_16x16x32_bf16 v[96:99], v[168:171], v[192:195], v[96:99]
	v_mfma_f32_16x16x32_bf16 v[88:91], v[176:179], v[192:195], v[88:91]
	v_mfma_f32_16x16x32_bf16 v[80:83], v[168:171], v[200:203], v[80:83]
	v_mfma_f32_16x16x32_bf16 v[72:75], v[176:179], v[200:203], v[72:75]
	v_mfma_f32_16x16x32_bf16 v[68:71], v[168:171], v[208:211], v[68:71]
	v_mfma_f32_16x16x32_bf16 v[64:67], v[176:179], v[208:211], v[64:67]
	v_mfma_f32_16x16x32_bf16 v[112:115], v[172:175], v[188:191], v[112:115]
	v_mfma_f32_16x16x32_bf16 v[104:107], v[180:183], v[188:191], v[104:107]
	v_mfma_f32_16x16x32_bf16 v[96:99], v[172:175], v[196:199], v[96:99]
	v_mfma_f32_16x16x32_bf16 v[88:91], v[180:183], v[196:199], v[88:91]
	v_mfma_f32_16x16x32_bf16 v[80:83], v[172:175], v[204:207], v[80:83]
	v_mfma_f32_16x16x32_bf16 v[72:75], v[180:183], v[204:207], v[72:75]
	v_mfma_f32_16x16x32_bf16 v[68:71], v[172:175], v[212:215], v[68:71]
	v_mfma_f32_16x16x32_bf16 v[64:67], v[180:183], v[212:215], v[64:67]
	s_barrier
	s_add_i32 s28, s58, s31
	v_lshl_add_u64 v[146:147], v[146:147], 0, s[12:13]
	s_mov_b32 m0, s28
	ds_read_b128 v[184:187], v151 offset:49152
	ds_read_b128 v[188:191], v151 offset:50176
	ds_read_b128 v[192:195], v151 offset:51200
	ds_read_b128 v[196:199], v151 offset:52224
	ds_read_b128 v[200:203], v151 offset:53248
	ds_read_b128 v[204:207], v151 offset:54272
	ds_read_b128 v[208:211], v151 offset:55296
	ds_read_b128 v[212:215], v151 offset:56320
	global_load_lds_dwordx4 v[146:147], off
	s_add_i32 m0, s28, 0x2000
	s_add_u32 s26, s26, 0x40080
	v_lshl_add_u64 v[146:147], v[216:217], 0, s[12:13]
	s_addc_u32 s27, s27, 0
	s_add_i32 s28, s59, s31
	global_load_lds_dwordx4 v[146:147], off
	v_lshl_add_u64 v[146:147], s[26:27], 0, v[130:131]
	s_mov_b32 m0, s28
	s_nop 0
	global_load_lds_dwordx4 v[146:147], off
	v_lshl_add_u64 v[146:147], s[26:27], 0, v[134:135]
	s_add_i32 m0, s28, 0x2000
	s_nop 0
	global_load_lds_dwordx4 v[146:147], off
	v_lshl_add_u64 v[146:147], v[218:219], 0, s[12:13]
	s_mov_b32 m0, s40
	s_nop 0
	global_load_lds_dwordx4 v[146:147], off
	v_lshl_add_u64 v[146:147], v[220:221], 0, s[12:13]
	s_mov_b32 m0, s41
	s_nop 0
	global_load_lds_dwordx4 v[146:147], off
	s_waitcnt vmcnt(8)
	s_waitcnt lgkmcnt(0)
	s_barrier
	s_waitcnt lgkmcnt(0)
	v_mfma_f32_16x16x32_bf16 v[60:63], v[152:155], v[184:187], v[60:63]
	v_mfma_f32_16x16x32_bf16 v[56:59], v[160:163], v[184:187], v[56:59]
	v_mfma_f32_16x16x32_bf16 v[52:55], v[152:155], v[192:195], v[52:55]
	v_mfma_f32_16x16x32_bf16 v[44:47], v[160:163], v[192:195], v[44:47]
	v_mfma_f32_16x16x32_bf16 v[36:39], v[152:155], v[200:203], v[36:39]
	v_mfma_f32_16x16x32_bf16 v[28:31], v[160:163], v[200:203], v[28:31]
	v_mfma_f32_16x16x32_bf16 v[20:23], v[152:155], v[208:211], v[20:23]
	v_mfma_f32_16x16x32_bf16 v[12:15], v[160:163], v[208:211], v[12:15]
	v_mfma_f32_16x16x32_bf16 v[60:63], v[156:159], v[188:191], v[60:63]
	v_mfma_f32_16x16x32_bf16 v[56:59], v[164:167], v[188:191], v[56:59]
	v_mfma_f32_16x16x32_bf16 v[52:55], v[156:159], v[196:199], v[52:55]
	v_mfma_f32_16x16x32_bf16 v[44:47], v[164:167], v[196:199], v[44:47]
	v_mfma_f32_16x16x32_bf16 v[36:39], v[156:159], v[204:207], v[36:39]
	v_mfma_f32_16x16x32_bf16 v[28:31], v[164:167], v[204:207], v[28:31]
	v_mfma_f32_16x16x32_bf16 v[20:23], v[156:159], v[212:215], v[20:23]
	v_mfma_f32_16x16x32_bf16 v[12:15], v[164:167], v[212:215], v[12:15]
	v_mfma_f32_16x16x32_bf16 v[48:51], v[168:171], v[184:187], v[48:51]
	v_mfma_f32_16x16x32_bf16 v[40:43], v[176:179], v[184:187], v[40:43]
	v_mfma_f32_16x16x32_bf16 v[32:35], v[168:171], v[192:195], v[32:35]
	v_mfma_f32_16x16x32_bf16 v[24:27], v[176:179], v[192:195], v[24:27]
	v_mfma_f32_16x16x32_bf16 v[16:19], v[168:171], v[200:203], v[16:19]
	v_mfma_f32_16x16x32_bf16 v[8:11], v[176:179], v[200:203], v[8:11]
	v_mfma_f32_16x16x32_bf16 v[4:7], v[168:171], v[208:211], v[4:7]
	v_mfma_f32_16x16x32_bf16 v[0:3], v[176:179], v[208:211], v[0:3]
	v_mfma_f32_16x16x32_bf16 v[48:51], v[172:175], v[188:191], v[48:51]
	v_mfma_f32_16x16x32_bf16 v[40:43], v[180:183], v[188:191], v[40:43]
	v_mfma_f32_16x16x32_bf16 v[32:35], v[172:175], v[196:199], v[32:35]
	v_mfma_f32_16x16x32_bf16 v[24:27], v[180:183], v[196:199], v[24:27]
	v_mfma_f32_16x16x32_bf16 v[16:19], v[172:175], v[204:207], v[16:19]
	v_mfma_f32_16x16x32_bf16 v[8:11], v[180:183], v[204:207], v[8:11]
	v_mfma_f32_16x16x32_bf16 v[4:7], v[172:175], v[212:215], v[4:7]
	v_mfma_f32_16x16x32_bf16 v[0:3], v[180:183], v[212:215], v[0:3]
	s_barrier
	s_add_i32 s57, s57, 2
	s_add_u32 s24, s24, 0x100
	s_addc_u32 s25, s25, 0
	s_add_u32 s55, s55, 0x100
	s_addc_u32 s56, s56, 0
	s_cmp_gt_u32 s57, 13
	s_cbranch_scc0 .LBB3_20
	s_mov_b64 vcc, s[0:1]
	s_cbranch_vccz .LBB3_23
	s_barrier

.Lsmp5_done:
	s_cmpk_gt_i32 s2, 0x3ff
	v_readfirstlane_b32 s5, v0
	s_cbranch_scc1 .LBB5_16
	v_lshlrev_b32_e32 v2, 4, v0
	v_add_u32_e32 v3, 0x2000, v2
	v_ashrrev_i32_e32 v1, 31, v3
	v_lshrrev_b32_e32 v1, 22, v1
	v_add_u32_e32 v1, v3, v1
	v_ashrrev_i32_e32 v1, 10, v1
	v_mul_i32_i24_e32 v4, 0x400, v1
	v_sub_u32_e32 v3, v3, v4
	v_lshrrev_b32_e32 v4, 4, v3
	v_bitop3_b32 v3, v4, v3, 32 bitop3:0x6c
	v_ashrrev_i32_e32 v4, 31, v3
	v_lshrrev_b32_e32 v4, 26, v4
	v_add_u32_e32 v4, v3, v4
	v_lshlrev_b32_e32 v5, 3, v1
	v_ashrrev_i32_e32 v10, 6, v4
	v_and_b32_e32 v5, -16, v5
	v_add_u32_e32 v5, v10, v5
	v_and_b32_e32 v6, 3, v10
	s_mov_b32 s4, 0x1fffe0
	v_lshrrev_b32_e32 v7, 2, v5
	v_lshlrev_b32_e32 v8, 1, v5
	v_and_b32_e32 v4, 0xc0, v4
	v_and_or_b32 v6, v5, s4, v6
	v_and_b32_e32 v7, 4, v7
	v_and_b32_e32 v8, 24, v8
	v_sub_u32_e32 v3, v3, v4
	v_mov_b32_e32 v4, 1
	v_or3_b32 v6, v6, v7, v8
	v_lshlrev_b32_e32 v7, 5, v1
	v_ashrrev_i16_sdwa v3, v4, sext(v3) dst_sel:DWORD dst_unused:UNUSED_PAD src0_sel:DWORD src1_sel:BYTE_0
	v_and_b32_e32 v7, 32, v7
	v_bfe_i32 v11, v3, 0, 16
	v_add_lshl_u32 v3, v7, v11, 1
	v_lshl_add_u32 v128, v6, 11, v3
	v_lshl_add_u32 v130, v5, 11, v3
	v_bfe_i32 v3, v0, 27, 1
	v_lshrrev_b32_e32 v3, 22, v3
	v_add_u32_e32 v3, v2, v3
	s_load_dwordx2 s[0:1], s[0:1], 0xd8
	v_and_b32_e32 v3, 0xfffffc00, v3
	v_sub_u32_e32 v2, v2, v3
	v_lshrrev_b32_e32 v3, 4, v2
	v_ashrrev_i32_e32 v5, 31, v0
	v_bitop3_b32 v2, v3, v2, 32 bitop3:0x6c
	v_lshrrev_b32_e32 v5, 26, v5
	v_ashrrev_i32_e32 v3, 31, v2
	v_add_u32_e32 v5, v0, v5
	s_waitcnt lgkmcnt(0)
	s_add_u32 s28, s0, 0x3100000
	v_lshrrev_b32_e32 v3, 26, v3
	v_ashrrev_i32_e32 v13, 6, v5
	s_addc_u32 s29, s1, 0
	v_add_u32_e32 v3, v2, v3
	v_lshlrev_b32_e32 v5, 3, v13
	s_add_u32 s30, s0, 0x900000
	v_ashrrev_i32_e32 v12, 6, v3
	v_and_b32_e32 v5, -16, v5
	s_addc_u32 s31, s1, 0
	v_add_u32_e32 v5, v12, v5
	v_and_b32_e32 v6, 3, v12
	s_ashr_i32 s34, s2, 31
	v_and_or_b32 v6, v5, s4, v6
	s_lshr_b32 s4, s34, 29
	s_add_i32 s4, s2, s4
	s_ashr_i32 s6, s5, 6
	s_ashr_i32 s7, s4, 3
	s_and_b32 s4, s4, -8
	s_ashr_i32 s10, s5, 8
	s_lshl_b32 s33, s6, 10
	s_sub_i32 s4, s2, s4
	s_cmp_lt_i32 s4, 0
	s_movk_i32 s35, 0x81
	s_cselect_b32 s8, s35, 0x80
	s_mul_i32 s4, s4, s8
	s_add_i32 s4, s4, s7
	s_ashr_i32 s7, s4, 31
	s_lshr_b32 s7, s7, 25
	s_add_i32 s7, s4, s7
	v_lshrrev_b32_e32 v7, 2, v5
	v_lshlrev_b32_e32 v8, 1, v5
	v_and_b32_e32 v3, 0xc0, v3
	s_ashr_i32 s8, s7, 7
	v_and_b32_e32 v7, 4, v7
	v_and_b32_e32 v8, 24, v8
	v_sub_u32_e32 v2, v2, v3
	s_lshl_b32 s11, s8, 3
	v_or3_b32 v6, v6, v7, v8
	v_lshlrev_b32_e32 v7, 5, v13
	v_ashrrev_i16_sdwa v2, v4, sext(v2) dst_sel:DWORD dst_unused:UNUSED_PAD src0_sel:DWORD src1_sel:BYTE_0
	s_sub_i32 s8, 0x40, s11
	v_and_b32_e32 v7, 32, v7
	v_bfe_i32 v14, v2, 0, 16
	s_min_u32 s12, s8, 8
	s_and_b32 s7, s7, 0xffffff80
	v_add_lshl_u32 v2, v7, v14, 1
	s_sub_i32 s7, s4, s7
	v_cvt_f32_ubyte0_e32 v4, s12
	v_lshl_add_u32 v132, v6, 11, v2
	v_cvt_f32_i32_e32 v3, s7
	v_rcp_iflag_f32_e32 v6, v4
	v_lshl_add_u32 v134, v5, 11, v2
	s_ashr_i32 s4, s7, 30
	s_or_b32 s4, s4, 1
	v_mul_f32_e32 v2, v3, v6
	v_trunc_f32_e32 v2, v2
	v_fma_f32 v3, -v2, v4, v3
	v_cvt_i32_f32_e32 v2, v2
	v_cmp_ge_f32_e64 s[8:9], |v3|, v4
	s_and_b64 s[8:9], s[8:9], exec
	s_cselect_b32 s4, s4, 0
	v_readfirstlane_b32 s8, v2
	s_add_i32 s4, s8, s4
	s_mul_i32 s8, s4, s12
	s_sub_i32 s7, s7, s8
	s_sext_i32_i8 s7, s7
	s_add_i32 s20, s11, s7
	s_ashr_i32 s21, s20, 31
	s_bfe_i64 s[12:13], s[4:5], 0x80000
	s_lshl_b64 s[8:9], s[20:21], 19
	s_lshl_b64 s[12:13], s[12:13], 19
	s_add_u32 s24, s30, s12
	s_addc_u32 s25, s31, s13
	s_add_i32 s21, s33, 0
	s_add_i32 m0, s21, 0x10000
	v_mov_b32_e32 v133, 0
	global_load_lds_dwordx4 v132, s[24:25]
	s_add_i32 m0, s21, 0x12000
	s_add_u32 s12, s24, 0x40000
	global_load_lds_dwordx4 v128, s[24:25]
	s_addc_u32 s13, s25, 0
	s_add_i32 m0, s21, 0x14000
	v_mov_b32_e32 v129, v133
	global_load_lds_dwordx4 v132, s[12:13]
	s_add_i32 m0, s21, 0x16000
	s_add_u32 s22, s28, s8
	s_addc_u32 s23, s29, s9
	s_add_i32 s36, s21, 0x2000
	global_load_lds_dwordx4 v128, s[12:13]
	s_mov_b32 m0, s21
	s_add_u32 s8, s22, 0x40000
	global_load_lds_dwordx4 v134, s[22:23]
	s_mov_b32 m0, s36
	s_addc_u32 s9, s23, 0
	s_add_i32 s37, s21, 0x4000
	global_load_lds_dwordx4 v130, s[22:23]
	s_mov_b32 m0, s37
	s_add_i32 s38, s21, 0x6000
	global_load_lds_dwordx4 v134, s[8:9]
	s_mov_b32 m0, s38
	v_mov_b32_e32 v135, v133
	global_load_lds_dwordx4 v130, s[8:9]
	v_mov_b32_e32 v131, v133
	s_cmp_eq_u32 s10, 1
	s_mov_b32 s7, 0
	v_lshl_add_u64 v[8:9], s[24:25], 0, v[132:133]
	v_lshl_add_u64 v[6:7], s[24:25], 0, v[128:129]
	v_lshl_add_u64 v[2:3], s[22:23], 0, v[134:135]
	s_cselect_b64 s[8:9], -1, 0
	s_cmp_lg_u32 s10, 1
	v_lshl_add_u64 v[4:5], s[22:23], 0, v[130:131]
	s_cbranch_scc1 .LBB5_3
	s_barrier
	s_setprio 1

.LBB5_8:
	s_ashr_i32 s15, s14, 31
	s_lshl_b64 s[16:17], s[14:15], 19
	s_add_u32 s16, s28, s16
	v_cmp_lt_i64_e64 s[4:5], s[4:5], v[142:143]
	s_addc_u32 s17, s29, s17
	s_and_b64 s[18:19], s[4:5], exec
	s_cselect_b32 s15, s17, s23
	s_cselect_b32 s54, s16, s22
	s_ashr_i32 s13, s12, 31
	s_lshl_b64 s[18:19], s[12:13], 19
	s_add_u32 s18, s30, s18
	s_addc_u32 s19, s31, s19
	s_and_b64 s[26:27], s[4:5], exec
	s_cselect_b32 s13, s19, s25
	s_cselect_b32 s55, s18, s24
	s_add_u32 s22, s22, 0x40080
	s_addc_u32 s23, s23, 0
	s_add_u32 s56, s24, 0x100
	s_addc_u32 s57, s25, 0
	s_mov_b32 s58, -2
	ds_read_b128 v[152:155], v149
	ds_read_b128 v[156:159], v149 offset:1024
	ds_read_b128 v[160:163], v149 offset:2048
	ds_read_b128 v[164:167], v149 offset:3072
	ds_read_b128 v[168:171], v150
	ds_read_b128 v[172:175], v150 offset:1024
	ds_read_b128 v[176:179], v150 offset:2048
	ds_read_b128 v[180:183], v150 offset:3072
	s_add_u32 s24, s22, 0xfffc0080
	s_addc_u32 s25, s23, -1
	s_cmp_eq_u32 s58, 12
	s_cselect_b32 s27, s15, s25
	s_cselect_b32 s26, s54, s24
	s_cselect_b32 s25, s13, s57
	s_cselect_b32 s24, s55, s56
	v_lshl_add_u64 v[146:147], s[22:23], 0, v[138:139]
	s_add_i32 m0, s21, 0xc000
	ds_read_b128 v[184:187], v151
	ds_read_b128 v[188:191], v151 offset:1024
	ds_read_b128 v[192:195], v151 offset:2048
	ds_read_b128 v[196:199], v151 offset:3072
	ds_read_b128 v[200:203], v151 offset:4096
	ds_read_b128 v[204:207], v151 offset:5120
	ds_read_b128 v[208:211], v151 offset:6144
	ds_read_b128 v[212:215], v151 offset:7168
	global_load_lds_dwordx4 v[146:147], off
	v_lshl_add_u64 v[146:147], s[22:23], 0, v[140:141]
	s_add_i32 m0, s21, 0xe000
	s_nop 0
	global_load_lds_dwordx4 v[146:147], off
	s_waitcnt vmcnt(8)
	s_waitcnt lgkmcnt(0)
	s_barrier
	s_waitcnt lgkmcnt(0)
	v_mfma_f32_16x16x32_bf16 v[124:127], v[152:155], v[184:187], 0
	v_mfma_f32_16x16x32_bf16 v[120:123], v[160:163], v[184:187], 0
	v_mfma_f32_16x16x32_bf16 v[108:111], v[152:155], v[192:195], 0
	v_mfma_f32_16x16x32_bf16 v[104:107], v[160:163], v[192:195], 0
	v_mfma_f32_16x16x32_bf16 v[92:95], v[152:155], v[200:203], 0
	v_mfma_f32_16x16x32_bf16 v[88:91], v[160:163], v[200:203], 0
	v_mfma_f32_16x16x32_bf16 v[76:79], v[152:155], v[208:211], 0
	v_mfma_f32_16x16x32_bf16 v[72:75], v[160:163], v[208:211], 0
	v_mfma_f32_16x16x32_bf16 v[124:127], v[156:159], v[188:191], v[124:127]
	v_mfma_f32_16x16x32_bf16 v[120:123], v[164:167], v[188:191], v[120:123]
	v_mfma_f32_16x16x32_bf16 v[108:111], v[156:159], v[196:199], v[108:111]
	v_mfma_f32_16x16x32_bf16 v[104:107], v[164:167], v[196:199], v[104:107]
	v_mfma_f32_16x16x32_bf16 v[92:95], v[156:159], v[204:207], v[92:95]
	v_mfma_f32_16x16x32_bf16 v[88:91], v[164:167], v[204:207], v[88:91]
	v_mfma_f32_16x16x32_bf16 v[76:79], v[156:159], v[212:215], v[76:79]
	v_mfma_f32_16x16x32_bf16 v[72:75], v[164:167], v[212:215], v[72:75]
	v_mfma_f32_16x16x32_bf16 v[116:119], v[168:171], v[184:187], 0
	v_mfma_f32_16x16x32_bf16 v[112:115], v[176:179], v[184:187], 0
	v_mfma_f32_16x16x32_bf16 v[100:103], v[168:171], v[192:195], 0
	v_mfma_f32_16x16x32_bf16 v[96:99], v[176:179], v[192:195], 0
	v_mfma_f32_16x16x32_bf16 v[84:87], v[168:171], v[200:203], 0
	v_mfma_f32_16x16x32_bf16 v[80:83], v[176:179], v[200:203], 0
	v_mfma_f32_16x16x32_bf16 v[68:71], v[168:171], v[208:211], 0
	v_mfma_f32_16x16x32_bf16 v[64:67], v[176:179], v[208:211], 0
	v_mfma_f32_16x16x32_bf16 v[116:119], v[172:175], v[188:191], v[116:119]
	v_mfma_f32_16x16x32_bf16 v[112:115], v[180:183], v[188:191], v[112:115]
	v_mfma_f32_16x16x32_bf16 v[100:103], v[172:175], v[196:199], v[100:103]
	v_mfma_f32_16x16x32_bf16 v[96:99], v[180:183], v[196:199], v[96:99]
	v_mfma_f32_16x16x32_bf16 v[84:87], v[172:175], v[204:207], v[84:87]
	v_mfma_f32_16x16x32_bf16 v[80:83], v[180:183], v[204:207], v[80:83]
	v_mfma_f32_16x16x32_bf16 v[68:71], v[172:175], v[212:215], v[68:71]
	v_mfma_f32_16x16x32_bf16 v[64:67], v[180:183], v[212:215], v[64:67]
	s_barrier
	s_add_i32 s59, s43, s33
	v_lshl_add_u64 v[146:147], s[24:25], 0, v[132:133]
	s_mov_b32 m0, s59
	ds_read_b128 v[184:187], v151 offset:16384
	ds_read_b128 v[188:191], v151 offset:17408
	ds_read_b128 v[192:195], v151 offset:18432
	ds_read_b128 v[196:199], v151 offset:19456
	ds_read_b128 v[200:203], v151 offset:20480
	ds_read_b128 v[204:207], v151 offset:21504
	ds_read_b128 v[208:211], v151 offset:22528
	ds_read_b128 v[212:215], v151 offset:23552
	global_load_lds_dwordx4 v[146:147], off
	s_add_i32 m0, s59, 0x2000
	s_add_u32 s60, s24, 0x40000
	v_lshl_add_u64 v[216:217], s[24:25], 0, v[128:129]
	s_addc_u32 s61, s25, 0
	s_add_i32 s59, s44, s33
	global_load_lds_dwordx4 v[216:217], off
	v_lshl_add_u64 v[218:219], s[60:61], 0, v[132:133]
	s_mov_b32 m0, s59
	v_lshl_add_u64 v[220:221], s[26:27], 0, v[130:131]
	global_load_lds_dwordx4 v[218:219], off
	v_lshl_add_u64 v[218:219], s[60:61], 0, v[128:129]
	s_add_i32 m0, s59, 0x2000
	s_nop 0
	global_load_lds_dwordx4 v[218:219], off
	v_lshl_add_u64 v[218:219], s[26:27], 0, v[134:135]
	s_mov_b32 m0, s21
	s_nop 0
	global_load_lds_dwordx4 v[218:219], off
	s_mov_b32 m0, s36
	s_nop 0
	global_load_lds_dwordx4 v[220:221], off
	s_waitcnt vmcnt(8)
	s_waitcnt lgkmcnt(0)
	s_barrier
	s_waitcnt lgkmcnt(0)
	v_mfma_f32_16x16x32_bf16 v[60:63], v[152:155], v[184:187], 0
	v_mfma_f32_16x16x32_bf16 v[56:59], v[160:163], v[184:187], 0
	v_mfma_f32_16x16x32_bf16 v[44:47], v[152:155], v[192:195], 0
	v_mfma_f32_16x16x32_bf16 v[40:43], v[160:163], v[192:195], 0
	v_mfma_f32_16x16x32_bf16 v[28:31], v[152:155], v[200:203], 0
	v_mfma_f32_16x16x32_bf16 v[24:27], v[160:163], v[200:203], 0
	v_mfma_f32_16x16x32_bf16 v[12:15], v[152:155], v[208:211], 0
	v_mfma_f32_16x16x32_bf16 v[8:11], v[160:163], v[208:211], 0
	v_mfma_f32_16x16x32_bf16 v[60:63], v[156:159], v[188:191], v[60:63]
	v_mfma_f32_16x16x32_bf16 v[56:59], v[164:167], v[188:191], v[56:59]
	v_mfma_f32_16x16x32_bf16 v[44:47], v[156:159], v[196:199], v[44:47]
	v_mfma_f32_16x16x32_bf16 v[40:43], v[164:167], v[196:199], v[40:43]
	v_mfma_f32_16x16x32_bf16 v[28:31], v[156:159], v[204:207], v[28:31]
	v_mfma_f32_16x16x32_bf16 v[24:27], v[164:167], v[204:207], v[24:27]
	v_mfma_f32_16x16x32_bf16 v[12:15], v[156:159], v[212:215], v[12:15]
	v_mfma_f32_16x16x32_bf16 v[8:11], v[164:167], v[212:215], v[8:11]
	v_mfma_f32_16x16x32_bf16 v[52:55], v[168:171], v[184:187], 0
	v_mfma_f32_16x16x32_bf16 v[48:51], v[176:179], v[184:187], 0
	v_mfma_f32_16x16x32_bf16 v[36:39], v[168:171], v[192:195], 0
	v_mfma_f32_16x16x32_bf16 v[32:35], v[176:179], v[192:195], 0
	v_mfma_f32_16x16x32_bf16 v[20:23], v[168:171], v[200:203], 0
	v_mfma_f32_16x16x32_bf16 v[16:19], v[176:179], v[200:203], 0
	v_mfma_f32_16x16x32_bf16 v[4:7], v[168:171], v[208:211], 0
	v_mfma_f32_16x16x32_bf16 v[0:3], v[176:179], v[208:211], 0
	v_mfma_f32_16x16x32_bf16 v[52:55], v[172:175], v[188:191], v[52:55]
	v_mfma_f32_16x16x32_bf16 v[48:51], v[180:183], v[188:191], v[48:51]
	v_mfma_f32_16x16x32_bf16 v[36:39], v[172:175], v[196:199], v[36:39]
	v_mfma_f32_16x16x32_bf16 v[32:35], v[180:183], v[196:199], v[32:35]
	v_mfma_f32_16x16x32_bf16 v[20:23], v[172:175], v[204:207], v[20:23]
	v_mfma_f32_16x16x32_bf16 v[16:19], v[180:183], v[204:207], v[16:19]
	v_mfma_f32_16x16x32_bf16 v[4:7], v[172:175], v[212:215], v[4:7]
	v_mfma_f32_16x16x32_bf16 v[0:3], v[180:183], v[212:215], v[0:3]
	s_barrier
	s_add_i32 s59, 0, 0x18000
	s_add_i32 s60, 0, 0x1c000
	v_add_u32_e32 v164, s59, v148
	v_add_u32_e32 v180, s60, v148
	ds_read_b128 v[152:155], v164
	ds_read_b128 v[156:159], v164 offset:1024
	ds_read_b128 v[160:163], v164 offset:2048
	ds_read_b128 v[164:167], v164 offset:3072
	ds_read_b128 v[168:171], v180
	ds_read_b128 v[172:175], v180 offset:1024
	ds_read_b128 v[176:179], v180 offset:2048
	ds_read_b128 v[180:183], v180 offset:3072
	s_add_u32 s26, s26, 0x40000
	s_addc_u32 s27, s27, 0
	s_mov_b32 m0, s37
	v_lshl_add_u64 v[222:223], s[26:27], 0, v[134:135]
	ds_read_b128 v[184:187], v151 offset:32768
	ds_read_b128 v[188:191], v151 offset:33792
	ds_read_b128 v[192:195], v151 offset:34816
	ds_read_b128 v[196:199], v151 offset:35840
	ds_read_b128 v[200:203], v151 offset:36864
	ds_read_b128 v[204:207], v151 offset:37888
	ds_read_b128 v[208:211], v151 offset:38912
	ds_read_b128 v[212:215], v151 offset:39936
	global_load_lds_dwordx4 v[222:223], off
	v_lshl_add_u64 v[222:223], s[26:27], 0, v[130:131]
	s_mov_b32 m0, s38
	s_nop 0
	global_load_lds_dwordx4 v[222:223], off
	s_waitcnt vmcnt(8)
	s_waitcnt lgkmcnt(0)
	s_barrier
	s_waitcnt lgkmcnt(0)
	v_mfma_f32_16x16x32_bf16 v[124:127], v[152:155], v[184:187], v[124:127]
	v_mfma_f32_16x16x32_bf16 v[120:123], v[160:163], v[184:187], v[120:123]
	v_mfma_f32_16x16x32_bf16 v[108:111], v[152:155], v[192:195], v[108:111]
	v_mfma_f32_16x16x32_bf16 v[104:107], v[160:163], v[192:195], v[104:107]
	v_mfma_f32_16x16x32_bf16 v[92:95], v[152:155], v[200:203], v[92:95]
	v_mfma_f32_16x16x32_bf16 v[88:91], v[160:163], v[200:203], v[88:91]
	v_mfma_f32_16x16x32_bf16 v[76:79], v[152:155], v[208:211], v[76:79]
	v_mfma_f32_16x16x32_bf16 v[72:75], v[160:163], v[208:211], v[72:75]
	v_mfma_f32_16x16x32_bf16 v[124:127], v[156:159], v[188:191], v[124:127]
	v_mfma_f32_16x16x32_bf16 v[120:123], v[164:167], v[188:191], v[120:123]
	v_mfma_f32_16x16x32_bf16 v[108:111], v[156:159], v[196:199], v[108:111]
	v_mfma_f32_16x16x32_bf16 v[104:107], v[164:167], v[196:199], v[104:107]
	v_mfma_f32_16x16x32_bf16 v[92:95], v[156:159], v[204:207], v[92:95]
	v_mfma_f32_16x16x32_bf16 v[88:91], v[164:167], v[204:207], v[88:91]
	v_mfma_f32_16x16x32_bf16 v[76:79], v[156:159], v[212:215], v[76:79]
	v_mfma_f32_16x16x32_bf16 v[72:75], v[164:167], v[212:215], v[72:75]
	v_mfma_f32_16x16x32_bf16 v[116:119], v[168:171], v[184:187], v[116:119]
	v_mfma_f32_16x16x32_bf16 v[112:115], v[176:179], v[184:187], v[112:115]
	v_mfma_f32_16x16x32_bf16 v[100:103], v[168:171], v[192:195], v[100:103]
	v_mfma_f32_16x16x32_bf16 v[96:99], v[176:179], v[192:195], v[96:99]
	v_mfma_f32_16x16x32_bf16 v[84:87], v[168:171], v[200:203], v[84:87]
	v_mfma_f32_16x16x32_bf16 v[80:83], v[176:179], v[200:203], v[80:83]
	v_mfma_f32_16x16x32_bf16 v[68:71], v[168:171], v[208:211], v[68:71]
	v_mfma_f32_16x16x32_bf16 v[64:67], v[176:179], v[208:211], v[64:67]
	v_mfma_f32_16x16x32_bf16 v[116:119], v[172:175], v[188:191], v[116:119]
	v_mfma_f32_16x16x32_bf16 v[112:115], v[180:183], v[188:191], v[112:115]
	v_mfma_f32_16x16x32_bf16 v[100:103], v[172:175], v[196:199], v[100:103]
	v_mfma_f32_16x16x32_bf16 v[96:99], v[180:183], v[196:199], v[96:99]
	v_mfma_f32_16x16x32_bf16 v[84:87], v[172:175], v[204:207], v[84:87]
	v_mfma_f32_16x16x32_bf16 v[80:83], v[180:183], v[204:207], v[80:83]
	v_mfma_f32_16x16x32_bf16 v[68:71], v[172:175], v[212:215], v[68:71]
	v_mfma_f32_16x16x32_bf16 v[64:67], v[180:183], v[212:215], v[64:67]
	s_barrier
	s_add_i32 s26, s59, s33
	v_lshl_add_u64 v[146:147], v[146:147], 0, s[10:11]
	s_mov_b32 m0, s26
	ds_read_b128 v[184:187], v151 offset:49152
	ds_read_b128 v[188:191], v151 offset:50176
	ds_read_b128 v[192:195], v151 offset:51200
	ds_read_b128 v[196:199], v151 offset:52224
	ds_read_b128 v[200:203], v151 offset:53248
	ds_read_b128 v[204:207], v151 offset:54272
	ds_read_b128 v[208:211], v151 offset:55296
	ds_read_b128 v[212:215], v151 offset:56320
	global_load_lds_dwordx4 v[146:147], off
	s_add_i32 m0, s26, 0x2000
	s_add_u32 s24, s24, 0x40080
	v_lshl_add_u64 v[146:147], v[216:217], 0, s[10:11]
	s_addc_u32 s25, s25, 0
	s_add_i32 s26, s60, s33
	global_load_lds_dwordx4 v[146:147], off
	v_lshl_add_u64 v[146:147], s[24:25], 0, v[132:133]
	s_mov_b32 m0, s26
	s_nop 0
	global_load_lds_dwordx4 v[146:147], off
	v_lshl_add_u64 v[146:147], s[24:25], 0, v[128:129]
	s_add_i32 m0, s26, 0x2000
	s_nop 0
	global_load_lds_dwordx4 v[146:147], off
	v_lshl_add_u64 v[146:147], v[218:219], 0, s[10:11]
	s_mov_b32 m0, s40
	s_nop 0
	global_load_lds_dwordx4 v[146:147], off
	v_lshl_add_u64 v[146:147], v[220:221], 0, s[10:11]
	s_mov_b32 m0, s41
	s_nop 0
	global_load_lds_dwordx4 v[146:147], off
	s_waitcnt vmcnt(8)
	s_waitcnt lgkmcnt(0)
	s_barrier
	s_waitcnt lgkmcnt(0)
	v_mfma_f32_16x16x32_bf16 v[60:63], v[152:155], v[184:187], v[60:63]
	v_mfma_f32_16x16x32_bf16 v[56:59], v[160:163], v[184:187], v[56:59]
	v_mfma_f32_16x16x32_bf16 v[44:47], v[152:155], v[192:195], v[44:47]
	v_mfma_f32_16x16x32_bf16 v[40:43], v[160:163], v[192:195], v[40:43]
	v_mfma_f32_16x16x32_bf16 v[28:31], v[152:155], v[200:203], v[28:31]
	v_mfma_f32_16x16x32_bf16 v[24:27], v[160:163], v[200:203], v[24:27]
	v_mfma_f32_16x16x32_bf16 v[12:15], v[152:155], v[208:211], v[12:15]
	v_mfma_f32_16x16x32_bf16 v[8:11], v[160:163], v[208:211], v[8:11]
	v_mfma_f32_16x16x32_bf16 v[60:63], v[156:159], v[188:191], v[60:63]
	v_mfma_f32_16x16x32_bf16 v[56:59], v[164:167], v[188:191], v[56:59]
	v_mfma_f32_16x16x32_bf16 v[44:47], v[156:159], v[196:199], v[44:47]
	v_mfma_f32_16x16x32_bf16 v[40:43], v[164:167], v[196:199], v[40:43]
	v_mfma_f32_16x16x32_bf16 v[28:31], v[156:159], v[204:207], v[28:31]
	v_mfma_f32_16x16x32_bf16 v[24:27], v[164:167], v[204:207], v[24:27]
	v_mfma_f32_16x16x32_bf16 v[12:15], v[156:159], v[212:215], v[12:15]
	v_mfma_f32_16x16x32_bf16 v[8:11], v[164:167], v[212:215], v[8:11]
	v_mfma_f32_16x16x32_bf16 v[52:55], v[168:171], v[184:187], v[52:55]
	v_mfma_f32_16x16x32_bf16 v[48:51], v[176:179], v[184:187], v[48:51]
	v_mfma_f32_16x16x32_bf16 v[36:39], v[168:171], v[192:195], v[36:39]
	v_mfma_f32_16x16x32_bf16 v[32:35], v[176:179], v[192:195], v[32:35]
	v_mfma_f32_16x16x32_bf16 v[20:23], v[168:171], v[200:203], v[20:23]
	v_mfma_f32_16x16x32_bf16 v[16:19], v[176:179], v[200:203], v[16:19]
	v_mfma_f32_16x16x32_bf16 v[4:7], v[168:171], v[208:211], v[4:7]
	v_mfma_f32_16x16x32_bf16 v[0:3], v[176:179], v[208:211], v[0:3]
	v_mfma_f32_16x16x32_bf16 v[52:55], v[172:175], v[188:191], v[52:55]
	v_mfma_f32_16x16x32_bf16 v[48:51], v[180:183], v[188:191], v[48:51]
	v_mfma_f32_16x16x32_bf16 v[36:39], v[172:175], v[196:199], v[36:39]
	v_mfma_f32_16x16x32_bf16 v[32:35], v[180:183], v[196:199], v[32:35]
	v_mfma_f32_16x16x32_bf16 v[20:23], v[172:175], v[204:207], v[20:23]
	v_mfma_f32_16x16x32_bf16 v[16:19], v[180:183], v[204:207], v[16:19]
	v_mfma_f32_16x16x32_bf16 v[4:7], v[172:175], v[212:215], v[4:7]
	v_mfma_f32_16x16x32_bf16 v[0:3], v[180:183], v[212:215], v[0:3]
	s_barrier
	s_add_i32 s58, s58, 2
	s_add_u32 s22, s22, 0x100
	s_addc_u32 s23, s23, 0
	s_add_u32 s56, s56, 0x100
	s_addc_u32 s57, s57, 0
	s_cmp_gt_u32 s58, 13
.LBB5_9:
	ds_read_b128 v[152:155], v149
	ds_read_b128 v[156:159], v149 offset:1024
	ds_read_b128 v[160:163], v149 offset:2048
	ds_read_b128 v[164:167], v149 offset:3072
	ds_read_b128 v[168:171], v150
	ds_read_b128 v[172:175], v150 offset:1024
	ds_read_b128 v[176:179], v150 offset:2048
	ds_read_b128 v[180:183], v150 offset:3072
	s_add_u32 s24, s22, 0xfffc0080
	s_addc_u32 s25, s23, -1
	s_cmp_eq_u32 s58, 12
	s_cselect_b32 s27, s15, s25
	s_cselect_b32 s26, s54, s24
	s_cselect_b32 s25, s13, s57
	s_cselect_b32 s24, s55, s56
	v_lshl_add_u64 v[146:147], s[22:23], 0, v[138:139]
	s_add_i32 m0, s21, 0xc000
	ds_read_b128 v[184:187], v151
	ds_read_b128 v[188:191], v151 offset:1024
	ds_read_b128 v[192:195], v151 offset:2048
	ds_read_b128 v[196:199], v151 offset:3072
	ds_read_b128 v[200:203], v151 offset:4096
	ds_read_b128 v[204:207], v151 offset:5120
	ds_read_b128 v[208:211], v151 offset:6144
	ds_read_b128 v[212:215], v151 offset:7168
	global_load_lds_dwordx4 v[146:147], off
	v_lshl_add_u64 v[146:147], s[22:23], 0, v[140:141]
	s_add_i32 m0, s21, 0xe000
	s_nop 0
	global_load_lds_dwordx4 v[146:147], off
	s_waitcnt vmcnt(8)
	s_waitcnt lgkmcnt(0)
	s_barrier
	s_waitcnt lgkmcnt(0)
	v_mfma_f32_16x16x32_bf16 v[124:127], v[152:155], v[184:187], v[124:127]
	v_mfma_f32_16x16x32_bf16 v[120:123], v[160:163], v[184:187], v[120:123]
	v_mfma_f32_16x16x32_bf16 v[108:111], v[152:155], v[192:195], v[108:111]
	v_mfma_f32_16x16x32_bf16 v[104:107], v[160:163], v[192:195], v[104:107]
	v_mfma_f32_16x16x32_bf16 v[92:95], v[152:155], v[200:203], v[92:95]
	v_mfma_f32_16x16x32_bf16 v[88:91], v[160:163], v[200:203], v[88:91]
	v_mfma_f32_16x16x32_bf16 v[76:79], v[152:155], v[208:211], v[76:79]
	v_mfma_f32_16x16x32_bf16 v[72:75], v[160:163], v[208:211], v[72:75]
	v_mfma_f32_16x16x32_bf16 v[124:127], v[156:159], v[188:191], v[124:127]
	v_mfma_f32_16x16x32_bf16 v[120:123], v[164:167], v[188:191], v[120:123]
	v_mfma_f32_16x16x32_bf16 v[108:111], v[156:159], v[196:199], v[108:111]
	v_mfma_f32_16x16x32_bf16 v[104:107], v[164:167], v[196:199], v[104:107]
	v_mfma_f32_16x16x32_bf16 v[92:95], v[156:159], v[204:207], v[92:95]
	v_mfma_f32_16x16x32_bf16 v[88:91], v[164:167], v[204:207], v[88:91]
	v_mfma_f32_16x16x32_bf16 v[76:79], v[156:159], v[212:215], v[76:79]
	v_mfma_f32_16x16x32_bf16 v[72:75], v[164:167], v[212:215], v[72:75]
	v_mfma_f32_16x16x32_bf16 v[116:119], v[168:171], v[184:187], v[116:119]
	v_mfma_f32_16x16x32_bf16 v[112:115], v[176:179], v[184:187], v[112:115]
	v_mfma_f32_16x16x32_bf16 v[100:103], v[168:171], v[192:195], v[100:103]
	v_mfma_f32_16x16x32_bf16 v[96:99], v[176:179], v[192:195], v[96:99]
	v_mfma_f32_16x16x32_bf16 v[84:87], v[168:171], v[200:203], v[84:87]
	v_mfma_f32_16x16x32_bf16 v[80:83], v[176:179], v[200:203], v[80:83]
	v_mfma_f32_16x16x32_bf16 v[68:71], v[168:171], v[208:211], v[68:71]
	v_mfma_f32_16x16x32_bf16 v[64:67], v[176:179], v[208:211], v[64:67]
	v_mfma_f32_16x16x32_bf16 v[116:119], v[172:175], v[188:191], v[116:119]
	v_mfma_f32_16x16x32_bf16 v[112:115], v[180:183], v[188:191], v[112:115]
	v_mfma_f32_16x16x32_bf16 v[100:103], v[172:175], v[196:199], v[100:103]
	v_mfma_f32_16x16x32_bf16 v[96:99], v[180:183], v[196:199], v[96:99]
	v_mfma_f32_16x16x32_bf16 v[84:87], v[172:175], v[204:207], v[84:87]
	v_mfma_f32_16x16x32_bf16 v[80:83], v[180:183], v[204:207], v[80:83]
	v_mfma_f32_16x16x32_bf16 v[68:71], v[172:175], v[212:215], v[68:71]
	v_mfma_f32_16x16x32_bf16 v[64:67], v[180:183], v[212:215], v[64:67]
	s_barrier
	s_add_i32 s59, s43, s33
	v_lshl_add_u64 v[146:147], s[24:25], 0, v[132:133]
	s_mov_b32 m0, s59
	ds_read_b128 v[184:187], v151 offset:16384
	ds_read_b128 v[188:191], v151 offset:17408
	ds_read_b128 v[192:195], v151 offset:18432
	ds_read_b128 v[196:199], v151 offset:19456
	ds_read_b128 v[200:203], v151 offset:20480
	ds_read_b128 v[204:207], v151 offset:21504
	ds_read_b128 v[208:211], v151 offset:22528
	ds_read_b128 v[212:215], v151 offset:23552
	global_load_lds_dwordx4 v[146:147], off
	s_add_i32 m0, s59, 0x2000
	s_add_u32 s60, s24, 0x40000
	v_lshl_add_u64 v[216:217], s[24:25], 0, v[128:129]
	s_addc_u32 s61, s25, 0
	s_add_i32 s59, s44, s33
	global_load_lds_dwordx4 v[216:217], off
	v_lshl_add_u64 v[218:219], s[60:61], 0, v[132:133]
	s_mov_b32 m0, s59
	v_lshl_add_u64 v[220:221], s[26:27], 0, v[130:131]
	global_load_lds_dwordx4 v[218:219], off
	v_lshl_add_u64 v[218:219], s[60:61], 0, v[128:129]
	s_add_i32 m0, s59, 0x2000
	s_nop 0
	global_load_lds_dwordx4 v[218:219], off
	v_lshl_add_u64 v[218:219], s[26:27], 0, v[134:135]
	s_mov_b32 m0, s21
	s_nop 0
	global_load_lds_dwordx4 v[218:219], off
	s_mov_b32 m0, s36
	s_nop 0
	global_load_lds_dwordx4 v[220:221], off
	s_waitcnt vmcnt(8)
	s_waitcnt lgkmcnt(0)
	s_barrier
	s_waitcnt lgkmcnt(0)
	v_mfma_f32_16x16x32_bf16 v[60:63], v[152:155], v[184:187], v[60:63]
	v_mfma_f32_16x16x32_bf16 v[56:59], v[160:163], v[184:187], v[56:59]
	v_mfma_f32_16x16x32_bf16 v[44:47], v[152:155], v[192:195], v[44:47]
	v_mfma_f32_16x16x32_bf16 v[40:43], v[160:163], v[192:195], v[40:43]
	v_mfma_f32_16x16x32_bf16 v[28:31], v[152:155], v[200:203], v[28:31]
	v_mfma_f32_16x16x32_bf16 v[24:27], v[160:163], v[200:203], v[24:27]
	v_mfma_f32_16x16x32_bf16 v[12:15], v[152:155], v[208:211], v[12:15]
	v_mfma_f32_16x16x32_bf16 v[8:11], v[160:163], v[208:211], v[8:11]
	v_mfma_f32_16x16x32_bf16 v[60:63], v[156:159], v[188:191], v[60:63]
	v_mfma_f32_16x16x32_bf16 v[56:59], v[164:167], v[188:191], v[56:59]
	v_mfma_f32_16x16x32_bf16 v[44:47], v[156:159], v[196:199], v[44:47]
	v_mfma_f32_16x16x32_bf16 v[40:43], v[164:167], v[196:199], v[40:43]
	v_mfma_f32_16x16x32_bf16 v[28:31], v[156:159], v[204:207], v[28:31]
	v_mfma_f32_16x16x32_bf16 v[24:27], v[164:167], v[204:207], v[24:27]
	v_mfma_f32_16x16x32_bf16 v[12:15], v[156:159], v[212:215], v[12:15]
	v_mfma_f32_16x16x32_bf16 v[8:11], v[164:167], v[212:215], v[8:11]
	v_mfma_f32_16x16x32_bf16 v[52:55], v[168:171], v[184:187], v[52:55]
	v_mfma_f32_16x16x32_bf16 v[48:51], v[176:179], v[184:187], v[48:51]
	v_mfma_f32_16x16x32_bf16 v[36:39], v[168:171], v[192:195], v[36:39]
	v_mfma_f32_16x16x32_bf16 v[32:35], v[176:179], v[192:195], v[32:35]
	v_mfma_f32_16x16x32_bf16 v[20:23], v[168:171], v[200:203], v[20:23]
	v_mfma_f32_16x16x32_bf16 v[16:19], v[176:179], v[200:203], v[16:19]
	v_mfma_f32_16x16x32_bf16 v[4:7], v[168:171], v[208:211], v[4:7]
	v_mfma_f32_16x16x32_bf16 v[0:3], v[176:179], v[208:211], v[0:3]
	v_mfma_f32_16x16x32_bf16 v[52:55], v[172:175], v[188:191], v[52:55]
	v_mfma_f32_16x16x32_bf16 v[48:51], v[180:183], v[188:191], v[48:51]
	v_mfma_f32_16x16x32_bf16 v[36:39], v[172:175], v[196:199], v[36:39]
	v_mfma_f32_16x16x32_bf16 v[32:35], v[180:183], v[196:199], v[32:35]
	v_mfma_f32_16x16x32_bf16 v[20:23], v[172:175], v[204:207], v[20:23]
	v_mfma_f32_16x16x32_bf16 v[16:19], v[180:183], v[204:207], v[16:19]
	v_mfma_f32_16x16x32_bf16 v[4:7], v[172:175], v[212:215], v[4:7]
	v_mfma_f32_16x16x32_bf16 v[0:3], v[180:183], v[212:215], v[0:3]
	s_barrier
	s_add_i32 s59, 0, 0x18000
	s_add_i32 s60, 0, 0x1c000
	v_add_u32_e32 v164, s59, v148
	v_add_u32_e32 v180, s60, v148
	ds_read_b128 v[152:155], v164
	ds_read_b128 v[156:159], v164 offset:1024
	ds_read_b128 v[160:163], v164 offset:2048
	ds_read_b128 v[164:167], v164 offset:3072
	ds_read_b128 v[168:171], v180
	ds_read_b128 v[172:175], v180 offset:1024
	ds_read_b128 v[176:179], v180 offset:2048
	ds_read_b128 v[180:183], v180 offset:3072
	s_add_u32 s26, s26, 0x40000
	s_addc_u32 s27, s27, 0
	s_mov_b32 m0, s37
	v_lshl_add_u64 v[222:223], s[26:27], 0, v[134:135]
	ds_read_b128 v[184:187], v151 offset:32768
	ds_read_b128 v[188:191], v151 offset:33792
	ds_read_b128 v[192:195], v151 offset:34816
	ds_read_b128 v[196:199], v151 offset:35840
	ds_read_b128 v[200:203], v151 offset:36864
	ds_read_b128 v[204:207], v151 offset:37888
	ds_read_b128 v[208:211], v151 offset:38912
	ds_read_b128 v[212:215], v151 offset:39936
	global_load_lds_dwordx4 v[222:223], off
	v_lshl_add_u64 v[222:223], s[26:27], 0, v[130:131]
	s_mov_b32 m0, s38
	s_nop 0
	global_load_lds_dwordx4 v[222:223], off
	s_waitcnt vmcnt(8)
	s_waitcnt lgkmcnt(0)
	s_barrier
	s_waitcnt lgkmcnt(0)
	v_mfma_f32_16x16x32_bf16 v[124:127], v[152:155], v[184:187], v[124:127]
	v_mfma_f32_16x16x32_bf16 v[120:123], v[160:163], v[184:187], v[120:123]
	v_mfma_f32_16x16x32_bf16 v[108:111], v[152:155], v[192:195], v[108:111]
	v_mfma_f32_16x16x32_bf16 v[104:107], v[160:163], v[192:195], v[104:107]
	v_mfma_f32_16x16x32_bf16 v[92:95], v[152:155], v[200:203], v[92:95]
	v_mfma_f32_16x16x32_bf16 v[88:91], v[160:163], v[200:203], v[88:91]
	v_mfma_f32_16x16x32_bf16 v[76:79], v[152:155], v[208:211], v[76:79]
	v_mfma_f32_16x16x32_bf16 v[72:75], v[160:163], v[208:211], v[72:75]
	v_mfma_f32_16x16x32_bf16 v[124:127], v[156:159], v[188:191], v[124:127]
	v_mfma_f32_16x16x32_bf16 v[120:123], v[164:167], v[188:191], v[120:123]
	v_mfma_f32_16x16x32_bf16 v[108:111], v[156:159], v[196:199], v[108:111]
	v_mfma_f32_16x16x32_bf16 v[104:107], v[164:167], v[196:199], v[104:107]
	v_mfma_f32_16x16x32_bf16 v[92:95], v[156:159], v[204:207], v[92:95]
	v_mfma_f32_16x16x32_bf16 v[88:91], v[164:167], v[204:207], v[88:91]
	v_mfma_f32_16x16x32_bf16 v[76:79], v[156:159], v[212:215], v[76:79]
	v_mfma_f32_16x16x32_bf16 v[72:75], v[164:167], v[212:215], v[72:75]
	v_mfma_f32_16x16x32_bf16 v[116:119], v[168:171], v[184:187], v[116:119]
	v_mfma_f32_16x16x32_bf16 v[112:115], v[176:179], v[184:187], v[112:115]
	v_mfma_f32_16x16x32_bf16 v[100:103], v[168:171], v[192:195], v[100:103]
	v_mfma_f32_16x16x32_bf16 v[96:99], v[176:179], v[192:195], v[96:99]
	v_mfma_f32_16x16x32_bf16 v[84:87], v[168:171], v[200:203], v[84:87]
	v_mfma_f32_16x16x32_bf16 v[80:83], v[176:179], v[200:203], v[80:83]
	v_mfma_f32_16x16x32_bf16 v[68:71], v[168:171], v[208:211], v[68:71]
	v_mfma_f32_16x16x32_bf16 v[64:67], v[176:179], v[208:211], v[64:67]
	v_mfma_f32_16x16x32_bf16 v[116:119], v[172:175], v[188:191], v[116:119]
	v_mfma_f32_16x16x32_bf16 v[112:115], v[180:183], v[188:191], v[112:115]
	v_mfma_f32_16x16x32_bf16 v[100:103], v[172:175], v[196:199], v[100:103]
	v_mfma_f32_16x16x32_bf16 v[96:99], v[180:183], v[196:199], v[96:99]
	v_mfma_f32_16x16x32_bf16 v[84:87], v[172:175], v[204:207], v[84:87]
	v_mfma_f32_16x16x32_bf16 v[80:83], v[180:183], v[204:207], v[80:83]
	v_mfma_f32_16x16x32_bf16 v[68:71], v[172:175], v[212:215], v[68:71]
	v_mfma_f32_16x16x32_bf16 v[64:67], v[180:183], v[212:215], v[64:67]
	s_barrier
	s_add_i32 s26, s59, s33
	v_lshl_add_u64 v[146:147], v[146:147], 0, s[10:11]
	s_mov_b32 m0, s26
	ds_read_b128 v[184:187], v151 offset:49152
	ds_read_b128 v[188:191], v151 offset:50176
	ds_read_b128 v[192:195], v151 offset:51200
	ds_read_b128 v[196:199], v151 offset:52224
	ds_read_b128 v[200:203], v151 offset:53248
	ds_read_b128 v[204:207], v151 offset:54272
	ds_read_b128 v[208:211], v151 offset:55296
	ds_read_b128 v[212:215], v151 offset:56320
	global_load_lds_dwordx4 v[146:147], off
	s_add_i32 m0, s26, 0x2000
	s_add_u32 s24, s24, 0x40080
	v_lshl_add_u64 v[146:147], v[216:217], 0, s[10:11]
	s_addc_u32 s25, s25, 0
	s_add_i32 s26, s60, s33
	global_load_lds_dwordx4 v[146:147], off
	v_lshl_add_u64 v[146:147], s[24:25], 0, v[132:133]
	s_mov_b32 m0, s26
	s_nop 0
	global_load_lds_dwordx4 v[146:147], off
	v_lshl_add_u64 v[146:147], s[24:25], 0, v[128:129]
	s_add_i32 m0, s26, 0x2000
	s_nop 0
	global_load_lds_dwordx4 v[146:147], off
	v_lshl_add_u64 v[146:147], v[218:219], 0, s[10:11]
	s_mov_b32 m0, s40
	s_nop 0
	global_load_lds_dwordx4 v[146:147], off
	v_lshl_add_u64 v[146:147], v[220:221], 0, s[10:11]
	s_mov_b32 m0, s41
	s_nop 0
	global_load_lds_dwordx4 v[146:147], off
	s_waitcnt vmcnt(8)
	s_waitcnt lgkmcnt(0)
	s_barrier
	s_waitcnt lgkmcnt(0)
	v_mfma_f32_16x16x32_bf16 v[60:63], v[152:155], v[184:187], v[60:63]
	v_mfma_f32_16x16x32_bf16 v[56:59], v[160:163], v[184:187], v[56:59]
	v_mfma_f32_16x16x32_bf16 v[44:47], v[152:155], v[192:195], v[44:47]
	v_mfma_f32_16x16x32_bf16 v[40:43], v[160:163], v[192:195], v[40:43]
	v_mfma_f32_16x16x32_bf16 v[28:31], v[152:155], v[200:203], v[28:31]
	v_mfma_f32_16x16x32_bf16 v[24:27], v[160:163], v[200:203], v[24:27]
	v_mfma_f32_16x16x32_bf16 v[12:15], v[152:155], v[208:211], v[12:15]
	v_mfma_f32_16x16x32_bf16 v[8:11], v[160:163], v[208:211], v[8:11]
	v_mfma_f32_16x16x32_bf16 v[60:63], v[156:159], v[188:191], v[60:63]
	v_mfma_f32_16x16x32_bf16 v[56:59], v[164:167], v[188:191], v[56:59]
	v_mfma_f32_16x16x32_bf16 v[44:47], v[156:159], v[196:199], v[44:47]
	v_mfma_f32_16x16x32_bf16 v[40:43], v[164:167], v[196:199], v[40:43]
	v_mfma_f32_16x16x32_bf16 v[28:31], v[156:159], v[204:207], v[28:31]
	v_mfma_f32_16x16x32_bf16 v[24:27], v[164:167], v[204:207], v[24:27]
	v_mfma_f32_16x16x32_bf16 v[12:15], v[156:159], v[212:215], v[12:15]
	v_mfma_f32_16x16x32_bf16 v[8:11], v[164:167], v[212:215], v[8:11]
	v_mfma_f32_16x16x32_bf16 v[52:55], v[168:171], v[184:187], v[52:55]
	v_mfma_f32_16x16x32_bf16 v[48:51], v[176:179], v[184:187], v[48:51]
	v_mfma_f32_16x16x32_bf16 v[36:39], v[168:171], v[192:195], v[36:39]
	v_mfma_f32_16x16x32_bf16 v[32:35], v[176:179], v[192:195], v[32:35]
	v_mfma_f32_16x16x32_bf16 v[20:23], v[168:171], v[200:203], v[20:23]
	v_mfma_f32_16x16x32_bf16 v[16:19], v[176:179], v[200:203], v[16:19]
	v_mfma_f32_16x16x32_bf16 v[4:7], v[168:171], v[208:211], v[4:7]
	v_mfma_f32_16x16x32_bf16 v[0:3], v[176:179], v[208:211], v[0:3]
	v_mfma_f32_16x16x32_bf16 v[52:55], v[172:175], v[188:191], v[52:55]
	v_mfma_f32_16x16x32_bf16 v[48:51], v[180:183], v[188:191], v[48:51]
	v_mfma_f32_16x16x32_bf16 v[36:39], v[172:175], v[196:199], v[36:39]
	v_mfma_f32_16x16x32_bf16 v[32:35], v[180:183], v[196:199], v[32:35]
	v_mfma_f32_16x16x32_bf16 v[20:23], v[172:175], v[204:207], v[20:23]
	v_mfma_f32_16x16x32_bf16 v[16:19], v[180:183], v[204:207], v[16:19]
	v_mfma_f32_16x16x32_bf16 v[4:7], v[172:175], v[212:215], v[4:7]
	v_mfma_f32_16x16x32_bf16 v[0:3], v[180:183], v[212:215], v[0:3]
	s_barrier
	s_add_i32 s58, s58, 2
	s_add_u32 s22, s22, 0x100
	s_addc_u32 s23, s23, 0
	s_add_u32 s56, s56, 0x100
	s_addc_u32 s57, s57, 0
	s_cmp_gt_u32 s58, 13
	s_cbranch_scc0 .LBB5_9
	s_mov_b64 vcc, s[0:1]
	s_cbranch_vccz .LBB5_12
	s_barrier

.LBB6_8:
	v_bfe_i32 v3, v0, 27, 1
	v_lshlrev_b32_e32 v2, 4, v0
	v_lshrrev_b32_e32 v3, 22, v3
	v_add_u32_e32 v3, v2, v3
	v_and_b32_e32 v3, 0xfffffc00, v3
	v_sub_u32_e32 v3, v2, v3
	v_lshrrev_b32_e32 v4, 4, v3
	v_ashrrev_i32_e32 v1, 31, v0
	v_bitop3_b32 v3, v4, v3, 32 bitop3:0x6c
	v_lshrrev_b32_e32 v1, 26, v1
	v_ashrrev_i32_e32 v5, 31, v3
	v_add_u32_e32 v1, v0, v1
	v_lshrrev_b32_e32 v5, 26, v5
	v_ashrrev_i32_e32 v1, 6, v1
	v_add_u32_e32 v5, v3, v5
	v_lshlrev_b32_e32 v4, 3, v1
	v_ashrrev_i32_e32 v10, 6, v5
	v_and_b32_e32 v5, 0xc0, v5
	v_and_b32_e32 v4, -16, v4
	v_sub_u32_e32 v3, v3, v5
	v_mov_b32_e32 v5, 1
	v_add_u32_e32 v4, v10, v4
	v_ashrrev_i16_sdwa v3, v5, sext(v3) dst_sel:DWORD dst_unused:UNUSED_PAD src0_sel:DWORD src1_sel:BYTE_0
	v_lshlrev_b32_e32 v6, 5, v1
	v_bfe_i32 v11, v3, 0, 16
	v_lshlrev_b32_e32 v3, 1, v4
	v_lshrrev_b32_e32 v7, 2, v4
	v_and_b32_e32 v8, 3, v10
	s_mov_b32 s8, 0x7ffe0
	v_and_b32_e32 v6, 32, v6
	v_and_b32_e32 v3, 24, v3
	v_and_b32_e32 v7, 4, v7
	v_and_or_b32 v8, v4, s8, v8
	v_or3_b32 v3, v8, v7, v3
	v_add_lshl_u32 v6, v6, v11, 1
	v_add_u32_e32 v2, 0x2000, v2
	v_lshl_add_u32 v130, v3, 13, v6
	v_ashrrev_i32_e32 v3, 31, v2
	v_lshrrev_b32_e32 v3, 22, v3
	v_add_u32_e32 v3, v2, v3
	v_ashrrev_i32_e32 v12, 10, v3
	v_mul_i32_i24_e32 v3, 0x400, v12
	v_sub_u32_e32 v2, v2, v3
	v_lshrrev_b32_e32 v3, 4, v2
	v_bitop3_b32 v2, v3, v2, 32 bitop3:0x6c
	v_lshl_add_u32 v128, v4, 13, v6
	v_ashrrev_i32_e32 v4, 31, v2
	v_lshrrev_b32_e32 v4, 26, v4
	v_add_u32_e32 v4, v2, v4
	v_lshlrev_b32_e32 v3, 3, v12
	v_ashrrev_i32_e32 v13, 6, v4
	v_and_b32_e32 v4, 0xc0, v4
	v_and_b32_e32 v3, -16, v3
	v_sub_u32_e32 v2, v2, v4
	v_add_u32_e32 v3, v13, v3
	v_ashrrev_i16_sdwa v2, v5, sext(v2) dst_sel:DWORD dst_unused:UNUSED_PAD src0_sel:DWORD src1_sel:BYTE_0
	v_and_b32_e32 v5, 3, v13
	v_and_or_b32 v5, v3, s8, v5
	s_ashr_i32 s8, s14, 6
	s_ashr_i32 s5, s14, 8
	s_lshl_b32 s31, s8, 10
	s_add_u32 s33, s0, 0x7400000
	s_addc_u32 s34, s1, 0
	s_add_i32 s4, s9, s4
	s_ashr_i32 s9, s4, 31
	s_lshr_b32 s9, s9, 27
	s_add_i32 s9, s4, s9
	s_ashr_i32 s10, s9, 5
	s_and_b32 s9, s9, 0xffe0
	s_sub_i32 s9, s4, s9
	s_bfe_i32 s4, s9, 0x80000
	s_bfe_u32 s4, s4, 0x3000c
	s_add_i32 s11, s9, s4
	s_bfe_i32 s4, s11, 0x80000
	s_and_b32 s11, s11, 0xf8
	s_sub_i32 s9, s9, s11
	s_lshl_b32 s10, s10, 3
	s_sext_i32_i16 s4, s4
	s_sext_i32_i8 s9, s9
	s_lshr_b32 s4, s4, 3
	s_add_i32 s22, s10, s9
	s_ashr_i32 s23, s22, 31
	s_bfe_i64 s[12:13], s[4:5], 0x100000
	s_lshl_b64 s[10:11], s[22:23], 21
	s_lshl_b64 s[12:13], s[12:13], 21
	s_add_u32 s26, s6, s12
	v_lshlrev_b32_e32 v6, 5, v12
	v_bfe_i32 v14, v2, 0, 16
	v_lshlrev_b32_e32 v2, 1, v3
	v_lshrrev_b32_e32 v4, 2, v3
	s_addc_u32 s27, s7, s13
	s_add_i32 s23, s31, 0
	v_and_b32_e32 v6, 32, v6
	v_and_b32_e32 v2, 24, v2
	v_and_b32_e32 v4, 4, v4
	s_add_i32 m0, s23, 0x10000
	v_or3_b32 v2, v5, v4, v2
	v_add_lshl_u32 v4, v6, v14, 1
	global_load_lds_dwordx4 v130, s[26:27]
	s_add_i32 m0, s23, 0x12000
	v_lshl_add_u32 v134, v2, 13, v4
	s_add_u32 s12, s26, 0x100000
	global_load_lds_dwordx4 v134, s[26:27]
	s_addc_u32 s13, s27, 0
	s_add_i32 m0, s23, 0x14000
	v_lshl_add_u32 v132, v3, 13, v4
	global_load_lds_dwordx4 v130, s[12:13]
	s_add_i32 m0, s23, 0x16000
	s_add_u32 s24, s33, s10
	s_addc_u32 s25, s34, s11
	s_add_i32 s35, s23, 0x2000
	global_load_lds_dwordx4 v134, s[12:13]
	s_mov_b32 m0, s23
	s_add_u32 s10, s24, 0x100000
	global_load_lds_dwordx4 v128, s[24:25]
	s_mov_b32 m0, s35
	s_addc_u32 s11, s25, 0
	s_add_i32 s36, s23, 0x4000
	global_load_lds_dwordx4 v132, s[24:25]
	s_mov_b32 m0, s36
	s_add_i32 s37, s23, 0x6000
	global_load_lds_dwordx4 v128, s[10:11]
	s_mov_b32 m0, s37
	v_mov_b32_e32 v131, 0
	global_load_lds_dwordx4 v132, s[10:11]
	v_mov_b32_e32 v135, v131
	v_mov_b32_e32 v129, v131
	v_mov_b32_e32 v133, v131
	s_cmp_eq_u32 s5, 1
	s_mov_b32 s9, 0
	s_mov_b32 s38, 0x10000
	v_lshl_add_u64 v[8:9], s[26:27], 0, v[130:131]
	v_lshl_add_u64 v[6:7], s[26:27], 0, v[134:135]
	v_lshl_add_u64 v[2:3], s[24:25], 0, v[128:129]
	s_cselect_b64 s[10:11], -1, 0
	s_cmp_lg_u32 s5, 1
	v_lshl_add_u64 v[4:5], s[24:25], 0, v[132:133]
	s_cbranch_scc1 .LBB6_10
	s_barrier
	s_setprio 1

.LBB6_19:
	s_ashr_i32 s17, s16, 31
	s_lshl_b64 s[18:19], s[16:17], 21
	s_add_u32 s18, s33, s18
	v_cmp_lt_i64_e64 s[4:5], s[4:5], v[142:143]
	s_addc_u32 s19, s34, s19
	s_and_b64 s[20:21], s[4:5], exec
	s_cselect_b32 s17, s19, s25
	s_cselect_b32 s53, s18, s24
	s_ashr_i32 s15, s14, 31
	s_lshl_b64 s[20:21], s[14:15], 21
	s_add_u32 s20, s6, s20
	s_addc_u32 s21, s7, s21
	s_and_b64 s[28:29], s[4:5], exec
	s_cselect_b32 s15, s21, s27
	s_cselect_b32 s54, s20, s26
	s_add_u32 s24, s24, 0x100080
	s_addc_u32 s25, s25, 0
	s_add_u32 s55, s26, 0x100
	s_addc_u32 s56, s27, 0
	s_mov_b32 s57, -2
	ds_read_b128 v[152:155], v149
	ds_read_b128 v[156:159], v149 offset:1024
	ds_read_b128 v[160:163], v149 offset:2048
	ds_read_b128 v[164:167], v149 offset:3072
	ds_read_b128 v[168:171], v150
	ds_read_b128 v[172:175], v150 offset:1024
	ds_read_b128 v[176:179], v150 offset:2048
	ds_read_b128 v[180:183], v150 offset:3072
	s_add_u32 s26, s24, 0xfff00080
	s_addc_u32 s27, s25, -1
	s_cmp_eq_u32 s57, 60
	s_cselect_b32 s29, s17, s27
	s_cselect_b32 s28, s53, s26
	s_cselect_b32 s27, s15, s56
	s_cselect_b32 s26, s54, s55
	v_lshl_add_u64 v[146:147], s[24:25], 0, v[138:139]
	s_add_i32 m0, s23, 0xc000
	ds_read_b128 v[184:187], v151
	ds_read_b128 v[188:191], v151 offset:1024
	ds_read_b128 v[192:195], v151 offset:2048
	ds_read_b128 v[196:199], v151 offset:3072
	ds_read_b128 v[200:203], v151 offset:4096
	ds_read_b128 v[204:207], v151 offset:5120
	ds_read_b128 v[208:211], v151 offset:6144
	ds_read_b128 v[212:215], v151 offset:7168
	global_load_lds_dwordx4 v[146:147], off
	v_lshl_add_u64 v[146:147], s[24:25], 0, v[140:141]
	s_add_i32 m0, s23, 0xe000
	s_nop 0
	global_load_lds_dwordx4 v[146:147], off
	s_waitcnt vmcnt(8)
	s_waitcnt lgkmcnt(0)
	s_barrier
	s_waitcnt lgkmcnt(0)
	v_mfma_f32_16x16x32_bf16 v[124:127], v[152:155], v[184:187], 0
	v_mfma_f32_16x16x32_bf16 v[120:123], v[160:163], v[184:187], 0
	v_mfma_f32_16x16x32_bf16 v[116:119], v[152:155], v[192:195], 0
	v_mfma_f32_16x16x32_bf16 v[108:111], v[160:163], v[192:195], 0
	v_mfma_f32_16x16x32_bf16 v[100:103], v[152:155], v[200:203], 0
	v_mfma_f32_16x16x32_bf16 v[92:95], v[160:163], v[200:203], 0
	v_mfma_f32_16x16x32_bf16 v[84:87], v[152:155], v[208:211], 0
	v_mfma_f32_16x16x32_bf16 v[76:79], v[160:163], v[208:211], 0
	v_mfma_f32_16x16x32_bf16 v[124:127], v[156:159], v[188:191], v[124:127]
	v_mfma_f32_16x16x32_bf16 v[120:123], v[164:167], v[188:191], v[120:123]
	v_mfma_f32_16x16x32_bf16 v[116:119], v[156:159], v[196:199], v[116:119]
	v_mfma_f32_16x16x32_bf16 v[108:111], v[164:167], v[196:199], v[108:111]
	v_mfma_f32_16x16x32_bf16 v[100:103], v[156:159], v[204:207], v[100:103]
	v_mfma_f32_16x16x32_bf16 v[92:95], v[164:167], v[204:207], v[92:95]
	v_mfma_f32_16x16x32_bf16 v[84:87], v[156:159], v[212:215], v[84:87]
	v_mfma_f32_16x16x32_bf16 v[76:79], v[164:167], v[212:215], v[76:79]
	v_mfma_f32_16x16x32_bf16 v[112:115], v[168:171], v[184:187], 0
	v_mfma_f32_16x16x32_bf16 v[104:107], v[176:179], v[184:187], 0
	v_mfma_f32_16x16x32_bf16 v[96:99], v[168:171], v[192:195], 0
	v_mfma_f32_16x16x32_bf16 v[88:91], v[176:179], v[192:195], 0
	v_mfma_f32_16x16x32_bf16 v[80:83], v[168:171], v[200:203], 0
	v_mfma_f32_16x16x32_bf16 v[72:75], v[176:179], v[200:203], 0
	v_mfma_f32_16x16x32_bf16 v[68:71], v[168:171], v[208:211], 0
	v_mfma_f32_16x16x32_bf16 v[64:67], v[176:179], v[208:211], 0
	v_mfma_f32_16x16x32_bf16 v[112:115], v[172:175], v[188:191], v[112:115]
	v_mfma_f32_16x16x32_bf16 v[104:107], v[180:183], v[188:191], v[104:107]
	v_mfma_f32_16x16x32_bf16 v[96:99], v[172:175], v[196:199], v[96:99]
	v_mfma_f32_16x16x32_bf16 v[88:91], v[180:183], v[196:199], v[88:91]
	v_mfma_f32_16x16x32_bf16 v[80:83], v[172:175], v[204:207], v[80:83]
	v_mfma_f32_16x16x32_bf16 v[72:75], v[180:183], v[204:207], v[72:75]
	v_mfma_f32_16x16x32_bf16 v[68:71], v[172:175], v[212:215], v[68:71]
	v_mfma_f32_16x16x32_bf16 v[64:67], v[180:183], v[212:215], v[64:67]
	s_barrier
	s_add_i32 s58, s45, s31
	v_lshl_add_u64 v[146:147], s[26:27], 0, v[130:131]
	s_mov_b32 m0, s58
	ds_read_b128 v[184:187], v151 offset:16384
	ds_read_b128 v[188:191], v151 offset:17408
	ds_read_b128 v[192:195], v151 offset:18432
	ds_read_b128 v[196:199], v151 offset:19456
	ds_read_b128 v[200:203], v151 offset:20480
	ds_read_b128 v[204:207], v151 offset:21504
	ds_read_b128 v[208:211], v151 offset:22528
	ds_read_b128 v[212:215], v151 offset:23552
	global_load_lds_dwordx4 v[146:147], off
	s_add_i32 m0, s58, 0x2000
	s_add_u32 s58, s26, 0x100000
	v_lshl_add_u64 v[216:217], s[26:27], 0, v[134:135]
	s_addc_u32 s59, s27, 0
	s_add_i32 s60, s46, s31
	global_load_lds_dwordx4 v[216:217], off
	v_lshl_add_u64 v[218:219], s[58:59], 0, v[130:131]
	s_mov_b32 m0, s60
	v_lshl_add_u64 v[220:221], s[28:29], 0, v[132:133]
	global_load_lds_dwordx4 v[218:219], off
	v_lshl_add_u64 v[218:219], s[58:59], 0, v[134:135]
	s_add_i32 m0, s60, 0x2000
	s_nop 0
	global_load_lds_dwordx4 v[218:219], off
	v_lshl_add_u64 v[218:219], s[28:29], 0, v[128:129]
	s_mov_b32 m0, s23
	s_nop 0
	global_load_lds_dwordx4 v[218:219], off
	s_mov_b32 m0, s35
	s_nop 0
	global_load_lds_dwordx4 v[220:221], off
	s_waitcnt vmcnt(8)
	s_waitcnt lgkmcnt(0)
	s_barrier
	s_waitcnt lgkmcnt(0)
	v_mfma_f32_16x16x32_bf16 v[60:63], v[152:155], v[184:187], 0
	v_mfma_f32_16x16x32_bf16 v[56:59], v[160:163], v[184:187], 0
	v_mfma_f32_16x16x32_bf16 v[52:55], v[152:155], v[192:195], 0
	v_mfma_f32_16x16x32_bf16 v[44:47], v[160:163], v[192:195], 0
	v_mfma_f32_16x16x32_bf16 v[36:39], v[152:155], v[200:203], 0
	v_mfma_f32_16x16x32_bf16 v[28:31], v[160:163], v[200:203], 0
	v_mfma_f32_16x16x32_bf16 v[20:23], v[152:155], v[208:211], 0
	v_mfma_f32_16x16x32_bf16 v[12:15], v[160:163], v[208:211], 0
	v_mfma_f32_16x16x32_bf16 v[60:63], v[156:159], v[188:191], v[60:63]
	v_mfma_f32_16x16x32_bf16 v[56:59], v[164:167], v[188:191], v[56:59]
	v_mfma_f32_16x16x32_bf16 v[52:55], v[156:159], v[196:199], v[52:55]
	v_mfma_f32_16x16x32_bf16 v[44:47], v[164:167], v[196:199], v[44:47]
	v_mfma_f32_16x16x32_bf16 v[36:39], v[156:159], v[204:207], v[36:39]
	v_mfma_f32_16x16x32_bf16 v[28:31], v[164:167], v[204:207], v[28:31]
	v_mfma_f32_16x16x32_bf16 v[20:23], v[156:159], v[212:215], v[20:23]
	v_mfma_f32_16x16x32_bf16 v[12:15], v[164:167], v[212:215], v[12:15]
	v_mfma_f32_16x16x32_bf16 v[48:51], v[168:171], v[184:187], 0
	v_mfma_f32_16x16x32_bf16 v[40:43], v[176:179], v[184:187], 0
	v_mfma_f32_16x16x32_bf16 v[32:35], v[168:171], v[192:195], 0
	v_mfma_f32_16x16x32_bf16 v[24:27], v[176:179], v[192:195], 0
	v_mfma_f32_16x16x32_bf16 v[16:19], v[168:171], v[200:203], 0
	v_mfma_f32_16x16x32_bf16 v[8:11], v[176:179], v[200:203], 0
	v_mfma_f32_16x16x32_bf16 v[4:7], v[168:171], v[208:211], 0
	v_mfma_f32_16x16x32_bf16 v[0:3], v[176:179], v[208:211], 0
	v_mfma_f32_16x16x32_bf16 v[48:51], v[172:175], v[188:191], v[48:51]
	v_mfma_f32_16x16x32_bf16 v[40:43], v[180:183], v[188:191], v[40:43]
	v_mfma_f32_16x16x32_bf16 v[32:35], v[172:175], v[196:199], v[32:35]
	v_mfma_f32_16x16x32_bf16 v[24:27], v[180:183], v[196:199], v[24:27]
	v_mfma_f32_16x16x32_bf16 v[16:19], v[172:175], v[204:207], v[16:19]
	v_mfma_f32_16x16x32_bf16 v[8:11], v[180:183], v[204:207], v[8:11]
	v_mfma_f32_16x16x32_bf16 v[4:7], v[172:175], v[212:215], v[4:7]
	v_mfma_f32_16x16x32_bf16 v[0:3], v[180:183], v[212:215], v[0:3]
	s_barrier
	s_add_i32 s58, 0, 0x18000
	s_add_i32 s59, 0, 0x1c000
	v_add_u32_e32 v164, s58, v148
	v_add_u32_e32 v180, s59, v148
	ds_read_b128 v[152:155], v164
	ds_read_b128 v[156:159], v164 offset:1024
	ds_read_b128 v[160:163], v164 offset:2048
	ds_read_b128 v[164:167], v164 offset:3072
	ds_read_b128 v[168:171], v180
	ds_read_b128 v[172:175], v180 offset:1024
	ds_read_b128 v[176:179], v180 offset:2048
	ds_read_b128 v[180:183], v180 offset:3072
	s_add_u32 s28, s28, 0x100000
	s_addc_u32 s29, s29, 0
	s_mov_b32 m0, s36
	v_lshl_add_u64 v[222:223], s[28:29], 0, v[128:129]
	ds_read_b128 v[184:187], v151 offset:32768
	ds_read_b128 v[188:191], v151 offset:33792
	ds_read_b128 v[192:195], v151 offset:34816
	ds_read_b128 v[196:199], v151 offset:35840
	ds_read_b128 v[200:203], v151 offset:36864
	ds_read_b128 v[204:207], v151 offset:37888
	ds_read_b128 v[208:211], v151 offset:38912
	ds_read_b128 v[212:215], v151 offset:39936
	global_load_lds_dwordx4 v[222:223], off
	v_lshl_add_u64 v[222:223], s[28:29], 0, v[132:133]
	s_mov_b32 m0, s37
	s_nop 0
	global_load_lds_dwordx4 v[222:223], off
	s_waitcnt vmcnt(8)
	s_waitcnt lgkmcnt(0)
	s_barrier
	s_waitcnt lgkmcnt(0)
	v_mfma_f32_16x16x32_bf16 v[124:127], v[152:155], v[184:187], v[124:127]
	v_mfma_f32_16x16x32_bf16 v[120:123], v[160:163], v[184:187], v[120:123]
	v_mfma_f32_16x16x32_bf16 v[116:119], v[152:155], v[192:195], v[116:119]
	v_mfma_f32_16x16x32_bf16 v[108:111], v[160:163], v[192:195], v[108:111]
	v_mfma_f32_16x16x32_bf16 v[100:103], v[152:155], v[200:203], v[100:103]
	v_mfma_f32_16x16x32_bf16 v[92:95], v[160:163], v[200:203], v[92:95]
	v_mfma_f32_16x16x32_bf16 v[84:87], v[152:155], v[208:211], v[84:87]
	v_mfma_f32_16x16x32_bf16 v[76:79], v[160:163], v[208:211], v[76:79]
	v_mfma_f32_16x16x32_bf16 v[124:127], v[156:159], v[188:191], v[124:127]
	v_mfma_f32_16x16x32_bf16 v[120:123], v[164:167], v[188:191], v[120:123]
	v_mfma_f32_16x16x32_bf16 v[116:119], v[156:159], v[196:199], v[116:119]
	v_mfma_f32_16x16x32_bf16 v[108:111], v[164:167], v[196:199], v[108:111]
	v_mfma_f32_16x16x32_bf16 v[100:103], v[156:159], v[204:207], v[100:103]
	v_mfma_f32_16x16x32_bf16 v[92:95], v[164:167], v[204:207], v[92:95]
	v_mfma_f32_16x16x32_bf16 v[84:87], v[156:159], v[212:215], v[84:87]
	v_mfma_f32_16x16x32_bf16 v[76:79], v[164:167], v[212:215], v[76:79]
	v_mfma_f32_16x16x32_bf16 v[112:115], v[168:171], v[184:187], v[112:115]
	v_mfma_f32_16x16x32_bf16 v[104:107], v[176:179], v[184:187], v[104:107]
	v_mfma_f32_16x16x32_bf16 v[96:99], v[168:171], v[192:195], v[96:99]
	v_mfma_f32_16x16x32_bf16 v[88:91], v[176:179], v[192:195], v[88:91]
	v_mfma_f32_16x16x32_bf16 v[80:83], v[168:171], v[200:203], v[80:83]
	v_mfma_f32_16x16x32_bf16 v[72:75], v[176:179], v[200:203], v[72:75]
	v_mfma_f32_16x16x32_bf16 v[68:71], v[168:171], v[208:211], v[68:71]
	v_mfma_f32_16x16x32_bf16 v[64:67], v[176:179], v[208:211], v[64:67]
	v_mfma_f32_16x16x32_bf16 v[112:115], v[172:175], v[188:191], v[112:115]
	v_mfma_f32_16x16x32_bf16 v[104:107], v[180:183], v[188:191], v[104:107]
	v_mfma_f32_16x16x32_bf16 v[96:99], v[172:175], v[196:199], v[96:99]
	v_mfma_f32_16x16x32_bf16 v[88:91], v[180:183], v[196:199], v[88:91]
	v_mfma_f32_16x16x32_bf16 v[80:83], v[172:175], v[204:207], v[80:83]
	v_mfma_f32_16x16x32_bf16 v[72:75], v[180:183], v[204:207], v[72:75]
	v_mfma_f32_16x16x32_bf16 v[68:71], v[172:175], v[212:215], v[68:71]
	v_mfma_f32_16x16x32_bf16 v[64:67], v[180:183], v[212:215], v[64:67]
	s_barrier
	s_add_i32 s28, s58, s31
	v_lshl_add_u64 v[146:147], v[146:147], 0, s[12:13]
	s_mov_b32 m0, s28
	ds_read_b128 v[184:187], v151 offset:49152
	ds_read_b128 v[188:191], v151 offset:50176
	ds_read_b128 v[192:195], v151 offset:51200
	ds_read_b128 v[196:199], v151 offset:52224
	ds_read_b128 v[200:203], v151 offset:53248
	ds_read_b128 v[204:207], v151 offset:54272
	ds_read_b128 v[208:211], v151 offset:55296
	ds_read_b128 v[212:215], v151 offset:56320
	global_load_lds_dwordx4 v[146:147], off
	s_add_i32 m0, s28, 0x2000
	s_add_u32 s26, s26, 0x100080
	v_lshl_add_u64 v[146:147], v[216:217], 0, s[12:13]
	s_addc_u32 s27, s27, 0
	s_add_i32 s28, s59, s31
	global_load_lds_dwordx4 v[146:147], off
	v_lshl_add_u64 v[146:147], s[26:27], 0, v[130:131]
	s_mov_b32 m0, s28
	s_nop 0
	global_load_lds_dwordx4 v[146:147], off
	v_lshl_add_u64 v[146:147], s[26:27], 0, v[134:135]
	s_add_i32 m0, s28, 0x2000
	s_nop 0
	global_load_lds_dwordx4 v[146:147], off
	v_lshl_add_u64 v[146:147], v[218:219], 0, s[12:13]
	s_mov_b32 m0, s40
	s_nop 0
	global_load_lds_dwordx4 v[146:147], off
	v_lshl_add_u64 v[146:147], v[220:221], 0, s[12:13]
	s_mov_b32 m0, s41
	s_nop 0
	global_load_lds_dwordx4 v[146:147], off
	s_waitcnt vmcnt(8)
	s_waitcnt lgkmcnt(0)
	s_barrier
	s_waitcnt lgkmcnt(0)
	v_mfma_f32_16x16x32_bf16 v[60:63], v[152:155], v[184:187], v[60:63]
	v_mfma_f32_16x16x32_bf16 v[56:59], v[160:163], v[184:187], v[56:59]
	v_mfma_f32_16x16x32_bf16 v[52:55], v[152:155], v[192:195], v[52:55]
	v_mfma_f32_16x16x32_bf16 v[44:47], v[160:163], v[192:195], v[44:47]
	v_mfma_f32_16x16x32_bf16 v[36:39], v[152:155], v[200:203], v[36:39]
	v_mfma_f32_16x16x32_bf16 v[28:31], v[160:163], v[200:203], v[28:31]
	v_mfma_f32_16x16x32_bf16 v[20:23], v[152:155], v[208:211], v[20:23]
	v_mfma_f32_16x16x32_bf16 v[12:15], v[160:163], v[208:211], v[12:15]
	v_mfma_f32_16x16x32_bf16 v[60:63], v[156:159], v[188:191], v[60:63]
	v_mfma_f32_16x16x32_bf16 v[56:59], v[164:167], v[188:191], v[56:59]
	v_mfma_f32_16x16x32_bf16 v[52:55], v[156:159], v[196:199], v[52:55]
	v_mfma_f32_16x16x32_bf16 v[44:47], v[164:167], v[196:199], v[44:47]
	v_mfma_f32_16x16x32_bf16 v[36:39], v[156:159], v[204:207], v[36:39]
	v_mfma_f32_16x16x32_bf16 v[28:31], v[164:167], v[204:207], v[28:31]
	v_mfma_f32_16x16x32_bf16 v[20:23], v[156:159], v[212:215], v[20:23]
	v_mfma_f32_16x16x32_bf16 v[12:15], v[164:167], v[212:215], v[12:15]
	v_mfma_f32_16x16x32_bf16 v[48:51], v[168:171], v[184:187], v[48:51]
	v_mfma_f32_16x16x32_bf16 v[40:43], v[176:179], v[184:187], v[40:43]
	v_mfma_f32_16x16x32_bf16 v[32:35], v[168:171], v[192:195], v[32:35]
	v_mfma_f32_16x16x32_bf16 v[24:27], v[176:179], v[192:195], v[24:27]
	v_mfma_f32_16x16x32_bf16 v[16:19], v[168:171], v[200:203], v[16:19]
	v_mfma_f32_16x16x32_bf16 v[8:11], v[176:179], v[200:203], v[8:11]
	v_mfma_f32_16x16x32_bf16 v[4:7], v[168:171], v[208:211], v[4:7]
	v_mfma_f32_16x16x32_bf16 v[0:3], v[176:179], v[208:211], v[0:3]
	v_mfma_f32_16x16x32_bf16 v[48:51], v[172:175], v[188:191], v[48:51]
	v_mfma_f32_16x16x32_bf16 v[40:43], v[180:183], v[188:191], v[40:43]
	v_mfma_f32_16x16x32_bf16 v[32:35], v[172:175], v[196:199], v[32:35]
	v_mfma_f32_16x16x32_bf16 v[24:27], v[180:183], v[196:199], v[24:27]
	v_mfma_f32_16x16x32_bf16 v[16:19], v[172:175], v[204:207], v[16:19]
	v_mfma_f32_16x16x32_bf16 v[8:11], v[180:183], v[204:207], v[8:11]
	v_mfma_f32_16x16x32_bf16 v[4:7], v[172:175], v[212:215], v[4:7]
	v_mfma_f32_16x16x32_bf16 v[0:3], v[180:183], v[212:215], v[0:3]
	s_barrier
	s_add_i32 s57, s57, 2
	s_add_u32 s24, s24, 0x100
	s_addc_u32 s25, s25, 0
	s_add_u32 s55, s55, 0x100
	s_addc_u32 s56, s56, 0
	s_cmp_gt_u32 s57, 61
.LBB6_20:
	ds_read_b128 v[152:155], v149
	ds_read_b128 v[156:159], v149 offset:1024
	ds_read_b128 v[160:163], v149 offset:2048
	ds_read_b128 v[164:167], v149 offset:3072
	ds_read_b128 v[168:171], v150
	ds_read_b128 v[172:175], v150 offset:1024
	ds_read_b128 v[176:179], v150 offset:2048
	ds_read_b128 v[180:183], v150 offset:3072
	s_add_u32 s26, s24, 0xfff00080
	s_addc_u32 s27, s25, -1
	s_cmp_eq_u32 s57, 60
	s_cselect_b32 s29, s17, s27
	s_cselect_b32 s28, s53, s26
	s_cselect_b32 s27, s15, s56
	s_cselect_b32 s26, s54, s55
	v_lshl_add_u64 v[146:147], s[24:25], 0, v[138:139]
	s_add_i32 m0, s23, 0xc000
	ds_read_b128 v[184:187], v151
	ds_read_b128 v[188:191], v151 offset:1024
	ds_read_b128 v[192:195], v151 offset:2048
	ds_read_b128 v[196:199], v151 offset:3072
	ds_read_b128 v[200:203], v151 offset:4096
	ds_read_b128 v[204:207], v151 offset:5120
	ds_read_b128 v[208:211], v151 offset:6144
	ds_read_b128 v[212:215], v151 offset:7168
	global_load_lds_dwordx4 v[146:147], off
	v_lshl_add_u64 v[146:147], s[24:25], 0, v[140:141]
	s_add_i32 m0, s23, 0xe000
	s_nop 0
	global_load_lds_dwordx4 v[146:147], off
	s_waitcnt vmcnt(8)
	s_waitcnt lgkmcnt(0)
	s_barrier
	s_waitcnt lgkmcnt(0)
	v_mfma_f32_16x16x32_bf16 v[124:127], v[152:155], v[184:187], v[124:127]
	v_mfma_f32_16x16x32_bf16 v[120:123], v[160:163], v[184:187], v[120:123]
	v_mfma_f32_16x16x32_bf16 v[116:119], v[152:155], v[192:195], v[116:119]
	v_mfma_f32_16x16x32_bf16 v[108:111], v[160:163], v[192:195], v[108:111]
	v_mfma_f32_16x16x32_bf16 v[100:103], v[152:155], v[200:203], v[100:103]
	v_mfma_f32_16x16x32_bf16 v[92:95], v[160:163], v[200:203], v[92:95]
	v_mfma_f32_16x16x32_bf16 v[84:87], v[152:155], v[208:211], v[84:87]
	v_mfma_f32_16x16x32_bf16 v[76:79], v[160:163], v[208:211], v[76:79]
	v_mfma_f32_16x16x32_bf16 v[124:127], v[156:159], v[188:191], v[124:127]
	v_mfma_f32_16x16x32_bf16 v[120:123], v[164:167], v[188:191], v[120:123]
	v_mfma_f32_16x16x32_bf16 v[116:119], v[156:159], v[196:199], v[116:119]
	v_mfma_f32_16x16x32_bf16 v[108:111], v[164:167], v[196:199], v[108:111]
	v_mfma_f32_16x16x32_bf16 v[100:103], v[156:159], v[204:207], v[100:103]
	v_mfma_f32_16x16x32_bf16 v[92:95], v[164:167], v[204:207], v[92:95]
	v_mfma_f32_16x16x32_bf16 v[84:87], v[156:159], v[212:215], v[84:87]
	v_mfma_f32_16x16x32_bf16 v[76:79], v[164:167], v[212:215], v[76:79]
	v_mfma_f32_16x16x32_bf16 v[112:115], v[168:171], v[184:187], v[112:115]
	v_mfma_f32_16x16x32_bf16 v[104:107], v[176:179], v[184:187], v[104:107]
	v_mfma_f32_16x16x32_bf16 v[96:99], v[168:171], v[192:195], v[96:99]
	v_mfma_f32_16x16x32_bf16 v[88:91], v[176:179], v[192:195], v[88:91]
	v_mfma_f32_16x16x32_bf16 v[80:83], v[168:171], v[200:203], v[80:83]
	v_mfma_f32_16x16x32_bf16 v[72:75], v[176:179], v[200:203], v[72:75]
	v_mfma_f32_16x16x32_bf16 v[68:71], v[168:171], v[208:211], v[68:71]
	v_mfma_f32_16x16x32_bf16 v[64:67], v[176:179], v[208:211], v[64:67]
	v_mfma_f32_16x16x32_bf16 v[112:115], v[172:175], v[188:191], v[112:115]
	v_mfma_f32_16x16x32_bf16 v[104:107], v[180:183], v[188:191], v[104:107]
	v_mfma_f32_16x16x32_bf16 v[96:99], v[172:175], v[196:199], v[96:99]
	v_mfma_f32_16x16x32_bf16 v[88:91], v[180:183], v[196:199], v[88:91]
	v_mfma_f32_16x16x32_bf16 v[80:83], v[172:175], v[204:207], v[80:83]
	v_mfma_f32_16x16x32_bf16 v[72:75], v[180:183], v[204:207], v[72:75]
	v_mfma_f32_16x16x32_bf16 v[68:71], v[172:175], v[212:215], v[68:71]
	v_mfma_f32_16x16x32_bf16 v[64:67], v[180:183], v[212:215], v[64:67]
	s_barrier
	s_add_i32 s58, s45, s31
	v_lshl_add_u64 v[146:147], s[26:27], 0, v[130:131]
	s_mov_b32 m0, s58
	ds_read_b128 v[184:187], v151 offset:16384
	ds_read_b128 v[188:191], v151 offset:17408
	ds_read_b128 v[192:195], v151 offset:18432
	ds_read_b128 v[196:199], v151 offset:19456
	ds_read_b128 v[200:203], v151 offset:20480
	ds_read_b128 v[204:207], v151 offset:21504
	ds_read_b128 v[208:211], v151 offset:22528
	ds_read_b128 v[212:215], v151 offset:23552
	global_load_lds_dwordx4 v[146:147], off
	s_add_i32 m0, s58, 0x2000
	s_add_u32 s58, s26, 0x100000
	v_lshl_add_u64 v[216:217], s[26:27], 0, v[134:135]
	s_addc_u32 s59, s27, 0
	s_add_i32 s60, s46, s31
	global_load_lds_dwordx4 v[216:217], off
	v_lshl_add_u64 v[218:219], s[58:59], 0, v[130:131]
	s_mov_b32 m0, s60
	v_lshl_add_u64 v[220:221], s[28:29], 0, v[132:133]
	global_load_lds_dwordx4 v[218:219], off
	v_lshl_add_u64 v[218:219], s[58:59], 0, v[134:135]
	s_add_i32 m0, s60, 0x2000
	s_nop 0
	global_load_lds_dwordx4 v[218:219], off
	v_lshl_add_u64 v[218:219], s[28:29], 0, v[128:129]
	s_mov_b32 m0, s23
	s_nop 0
	global_load_lds_dwordx4 v[218:219], off
	s_mov_b32 m0, s35
	s_nop 0
	global_load_lds_dwordx4 v[220:221], off
	s_waitcnt vmcnt(8)
	s_waitcnt lgkmcnt(0)
	s_barrier
	s_waitcnt lgkmcnt(0)
	v_mfma_f32_16x16x32_bf16 v[60:63], v[152:155], v[184:187], v[60:63]
	v_mfma_f32_16x16x32_bf16 v[56:59], v[160:163], v[184:187], v[56:59]
	v_mfma_f32_16x16x32_bf16 v[52:55], v[152:155], v[192:195], v[52:55]
	v_mfma_f32_16x16x32_bf16 v[44:47], v[160:163], v[192:195], v[44:47]
	v_mfma_f32_16x16x32_bf16 v[36:39], v[152:155], v[200:203], v[36:39]
	v_mfma_f32_16x16x32_bf16 v[28:31], v[160:163], v[200:203], v[28:31]
	v_mfma_f32_16x16x32_bf16 v[20:23], v[152:155], v[208:211], v[20:23]
	v_mfma_f32_16x16x32_bf16 v[12:15], v[160:163], v[208:211], v[12:15]
	v_mfma_f32_16x16x32_bf16 v[60:63], v[156:159], v[188:191], v[60:63]
	v_mfma_f32_16x16x32_bf16 v[56:59], v[164:167], v[188:191], v[56:59]
	v_mfma_f32_16x16x32_bf16 v[52:55], v[156:159], v[196:199], v[52:55]
	v_mfma_f32_16x16x32_bf16 v[44:47], v[164:167], v[196:199], v[44:47]
	v_mfma_f32_16x16x32_bf16 v[36:39], v[156:159], v[204:207], v[36:39]
	v_mfma_f32_16x16x32_bf16 v[28:31], v[164:167], v[204:207], v[28:31]
	v_mfma_f32_16x16x32_bf16 v[20:23], v[156:159], v[212:215], v[20:23]
	v_mfma_f32_16x16x32_bf16 v[12:15], v[164:167], v[212:215], v[12:15]
	v_mfma_f32_16x16x32_bf16 v[48:51], v[168:171], v[184:187], v[48:51]
	v_mfma_f32_16x16x32_bf16 v[40:43], v[176:179], v[184:187], v[40:43]
	v_mfma_f32_16x16x32_bf16 v[32:35], v[168:171], v[192:195], v[32:35]
	v_mfma_f32_16x16x32_bf16 v[24:27], v[176:179], v[192:195], v[24:27]
	v_mfma_f32_16x16x32_bf16 v[16:19], v[168:171], v[200:203], v[16:19]
	v_mfma_f32_16x16x32_bf16 v[8:11], v[176:179], v[200:203], v[8:11]
	v_mfma_f32_16x16x32_bf16 v[4:7], v[168:171], v[208:211], v[4:7]
	v_mfma_f32_16x16x32_bf16 v[0:3], v[176:179], v[208:211], v[0:3]
	v_mfma_f32_16x16x32_bf16 v[48:51], v[172:175], v[188:191], v[48:51]
	v_mfma_f32_16x16x32_bf16 v[40:43], v[180:183], v[188:191], v[40:43]
	v_mfma_f32_16x16x32_bf16 v[32:35], v[172:175], v[196:199], v[32:35]
	v_mfma_f32_16x16x32_bf16 v[24:27], v[180:183], v[196:199], v[24:27]
	v_mfma_f32_16x16x32_bf16 v[16:19], v[172:175], v[204:207], v[16:19]
	v_mfma_f32_16x16x32_bf16 v[8:11], v[180:183], v[204:207], v[8:11]
	v_mfma_f32_16x16x32_bf16 v[4:7], v[172:175], v[212:215], v[4:7]
	v_mfma_f32_16x16x32_bf16 v[0:3], v[180:183], v[212:215], v[0:3]
	s_barrier
	s_add_i32 s58, 0, 0x18000
	s_add_i32 s59, 0, 0x1c000
	v_add_u32_e32 v164, s58, v148
	v_add_u32_e32 v180, s59, v148
	ds_read_b128 v[152:155], v164
	ds_read_b128 v[156:159], v164 offset:1024
	ds_read_b128 v[160:163], v164 offset:2048
	ds_read_b128 v[164:167], v164 offset:3072
	ds_read_b128 v[168:171], v180
	ds_read_b128 v[172:175], v180 offset:1024
	ds_read_b128 v[176:179], v180 offset:2048
	ds_read_b128 v[180:183], v180 offset:3072
	s_add_u32 s28, s28, 0x100000
	s_addc_u32 s29, s29, 0
	s_mov_b32 m0, s36
	v_lshl_add_u64 v[222:223], s[28:29], 0, v[128:129]
	ds_read_b128 v[184:187], v151 offset:32768
	ds_read_b128 v[188:191], v151 offset:33792
	ds_read_b128 v[192:195], v151 offset:34816
	ds_read_b128 v[196:199], v151 offset:35840
	ds_read_b128 v[200:203], v151 offset:36864
	ds_read_b128 v[204:207], v151 offset:37888
	ds_read_b128 v[208:211], v151 offset:38912
	ds_read_b128 v[212:215], v151 offset:39936
	global_load_lds_dwordx4 v[222:223], off
	v_lshl_add_u64 v[222:223], s[28:29], 0, v[132:133]
	s_mov_b32 m0, s37
	s_nop 0
	global_load_lds_dwordx4 v[222:223], off
	s_waitcnt vmcnt(8)
	s_waitcnt lgkmcnt(0)
	s_barrier
	s_waitcnt lgkmcnt(0)
	v_mfma_f32_16x16x32_bf16 v[124:127], v[152:155], v[184:187], v[124:127]
	v_mfma_f32_16x16x32_bf16 v[120:123], v[160:163], v[184:187], v[120:123]
	v_mfma_f32_16x16x32_bf16 v[116:119], v[152:155], v[192:195], v[116:119]
	v_mfma_f32_16x16x32_bf16 v[108:111], v[160:163], v[192:195], v[108:111]
	v_mfma_f32_16x16x32_bf16 v[100:103], v[152:155], v[200:203], v[100:103]
	v_mfma_f32_16x16x32_bf16 v[92:95], v[160:163], v[200:203], v[92:95]
	v_mfma_f32_16x16x32_bf16 v[84:87], v[152:155], v[208:211], v[84:87]
	v_mfma_f32_16x16x32_bf16 v[76:79], v[160:163], v[208:211], v[76:79]
	v_mfma_f32_16x16x32_bf16 v[124:127], v[156:159], v[188:191], v[124:127]
	v_mfma_f32_16x16x32_bf16 v[120:123], v[164:167], v[188:191], v[120:123]
	v_mfma_f32_16x16x32_bf16 v[116:119], v[156:159], v[196:199], v[116:119]
	v_mfma_f32_16x16x32_bf16 v[108:111], v[164:167], v[196:199], v[108:111]
	v_mfma_f32_16x16x32_bf16 v[100:103], v[156:159], v[204:207], v[100:103]
	v_mfma_f32_16x16x32_bf16 v[92:95], v[164:167], v[204:207], v[92:95]
	v_mfma_f32_16x16x32_bf16 v[84:87], v[156:159], v[212:215], v[84:87]
	v_mfma_f32_16x16x32_bf16 v[76:79], v[164:167], v[212:215], v[76:79]
	v_mfma_f32_16x16x32_bf16 v[112:115], v[168:171], v[184:187], v[112:115]
	v_mfma_f32_16x16x32_bf16 v[104:107], v[176:179], v[184:187], v[104:107]
	v_mfma_f32_16x16x32_bf16 v[96:99], v[168:171], v[192:195], v[96:99]
	v_mfma_f32_16x16x32_bf16 v[88:91], v[176:179], v[192:195], v[88:91]
	v_mfma_f32_16x16x32_bf16 v[80:83], v[168:171], v[200:203], v[80:83]
	v_mfma_f32_16x16x32_bf16 v[72:75], v[176:179], v[200:203], v[72:75]
	v_mfma_f32_16x16x32_bf16 v[68:71], v[168:171], v[208:211], v[68:71]
	v_mfma_f32_16x16x32_bf16 v[64:67], v[176:179], v[208:211], v[64:67]
	v_mfma_f32_16x16x32_bf16 v[112:115], v[172:175], v[188:191], v[112:115]
	v_mfma_f32_16x16x32_bf16 v[104:107], v[180:183], v[188:191], v[104:107]
	v_mfma_f32_16x16x32_bf16 v[96:99], v[172:175], v[196:199], v[96:99]
	v_mfma_f32_16x16x32_bf16 v[88:91], v[180:183], v[196:199], v[88:91]
	v_mfma_f32_16x16x32_bf16 v[80:83], v[172:175], v[204:207], v[80:83]
	v_mfma_f32_16x16x32_bf16 v[72:75], v[180:183], v[204:207], v[72:75]
	v_mfma_f32_16x16x32_bf16 v[68:71], v[172:175], v[212:215], v[68:71]
	v_mfma_f32_16x16x32_bf16 v[64:67], v[180:183], v[212:215], v[64:67]
	s_barrier
	s_add_i32 s28, s58, s31
	v_lshl_add_u64 v[146:147], v[146:147], 0, s[12:13]
	s_mov_b32 m0, s28
	ds_read_b128 v[184:187], v151 offset:49152
	ds_read_b128 v[188:191], v151 offset:50176
	ds_read_b128 v[192:195], v151 offset:51200
	ds_read_b128 v[196:199], v151 offset:52224
	ds_read_b128 v[200:203], v151 offset:53248
	ds_read_b128 v[204:207], v151 offset:54272
	ds_read_b128 v[208:211], v151 offset:55296
	ds_read_b128 v[212:215], v151 offset:56320
	global_load_lds_dwordx4 v[146:147], off
	s_add_i32 m0, s28, 0x2000
	s_add_u32 s26, s26, 0x100080
	v_lshl_add_u64 v[146:147], v[216:217], 0, s[12:13]
	s_addc_u32 s27, s27, 0
	s_add_i32 s28, s59, s31
	global_load_lds_dwordx4 v[146:147], off
	v_lshl_add_u64 v[146:147], s[26:27], 0, v[130:131]
	s_mov_b32 m0, s28
	s_nop 0
	global_load_lds_dwordx4 v[146:147], off
	v_lshl_add_u64 v[146:147], s[26:27], 0, v[134:135]
	s_add_i32 m0, s28, 0x2000
	s_nop 0
	global_load_lds_dwordx4 v[146:147], off
	v_lshl_add_u64 v[146:147], v[218:219], 0, s[12:13]
	s_mov_b32 m0, s40
	s_nop 0
	global_load_lds_dwordx4 v[146:147], off
	v_lshl_add_u64 v[146:147], v[220:221], 0, s[12:13]
	s_mov_b32 m0, s41
	s_nop 0
	global_load_lds_dwordx4 v[146:147], off
	s_waitcnt vmcnt(8)
	s_waitcnt lgkmcnt(0)
	s_barrier
	s_waitcnt lgkmcnt(0)
	v_mfma_f32_16x16x32_bf16 v[60:63], v[152:155], v[184:187], v[60:63]
	v_mfma_f32_16x16x32_bf16 v[56:59], v[160:163], v[184:187], v[56:59]
	v_mfma_f32_16x16x32_bf16 v[52:55], v[152:155], v[192:195], v[52:55]
	v_mfma_f32_16x16x32_bf16 v[44:47], v[160:163], v[192:195], v[44:47]
	v_mfma_f32_16x16x32_bf16 v[36:39], v[152:155], v[200:203], v[36:39]
	v_mfma_f32_16x16x32_bf16 v[28:31], v[160:163], v[200:203], v[28:31]
	v_mfma_f32_16x16x32_bf16 v[20:23], v[152:155], v[208:211], v[20:23]
	v_mfma_f32_16x16x32_bf16 v[12:15], v[160:163], v[208:211], v[12:15]
	v_mfma_f32_16x16x32_bf16 v[60:63], v[156:159], v[188:191], v[60:63]
	v_mfma_f32_16x16x32_bf16 v[56:59], v[164:167], v[188:191], v[56:59]
	v_mfma_f32_16x16x32_bf16 v[52:55], v[156:159], v[196:199], v[52:55]
	v_mfma_f32_16x16x32_bf16 v[44:47], v[164:167], v[196:199], v[44:47]
	v_mfma_f32_16x16x32_bf16 v[36:39], v[156:159], v[204:207], v[36:39]
	v_mfma_f32_16x16x32_bf16 v[28:31], v[164:167], v[204:207], v[28:31]
	v_mfma_f32_16x16x32_bf16 v[20:23], v[156:159], v[212:215], v[20:23]
	v_mfma_f32_16x16x32_bf16 v[12:15], v[164:167], v[212:215], v[12:15]
	v_mfma_f32_16x16x32_bf16 v[48:51], v[168:171], v[184:187], v[48:51]
	v_mfma_f32_16x16x32_bf16 v[40:43], v[176:179], v[184:187], v[40:43]
	v_mfma_f32_16x16x32_bf16 v[32:35], v[168:171], v[192:195], v[32:35]
	v_mfma_f32_16x16x32_bf16 v[24:27], v[176:179], v[192:195], v[24:27]
	v_mfma_f32_16x16x32_bf16 v[16:19], v[168:171], v[200:203], v[16:19]
	v_mfma_f32_16x16x32_bf16 v[8:11], v[176:179], v[200:203], v[8:11]
	v_mfma_f32_16x16x32_bf16 v[4:7], v[168:171], v[208:211], v[4:7]
	v_mfma_f32_16x16x32_bf16 v[0:3], v[176:179], v[208:211], v[0:3]
	v_mfma_f32_16x16x32_bf16 v[48:51], v[172:175], v[188:191], v[48:51]
	v_mfma_f32_16x16x32_bf16 v[40:43], v[180:183], v[188:191], v[40:43]
	v_mfma_f32_16x16x32_bf16 v[32:35], v[172:175], v[196:199], v[32:35]
	v_mfma_f32_16x16x32_bf16 v[24:27], v[180:183], v[196:199], v[24:27]
	v_mfma_f32_16x16x32_bf16 v[16:19], v[172:175], v[204:207], v[16:19]
	v_mfma_f32_16x16x32_bf16 v[8:11], v[180:183], v[204:207], v[8:11]
	v_mfma_f32_16x16x32_bf16 v[4:7], v[172:175], v[212:215], v[4:7]
	v_mfma_f32_16x16x32_bf16 v[0:3], v[180:183], v[212:215], v[0:3]
	s_barrier
	s_add_i32 s57, s57, 2
	s_add_u32 s24, s24, 0x100
	s_addc_u32 s25, s25, 0
	s_add_u32 s55, s55, 0x100
	s_addc_u32 s56, s56, 0
	s_cmp_gt_u32 s57, 61
	s_cbranch_scc0 .LBB6_20
	s_mov_b64 vcc, s[0:1]
	s_cbranch_vccz .LBB6_23
	s_barrier

.LBB8_4:
	v_bfe_i32 v3, v0, 27, 1
	v_lshlrev_b32_e32 v2, 4, v0
	v_lshrrev_b32_e32 v3, 22, v3
	v_add_u32_e32 v3, v2, v3
	v_and_b32_e32 v3, 0xfffffc00, v3
	v_sub_u32_e32 v3, v2, v3
	v_lshrrev_b32_e32 v4, 4, v3
	v_ashrrev_i32_e32 v1, 31, v0
	v_bitop3_b32 v3, v4, v3, 32 bitop3:0x6c
	v_lshrrev_b32_e32 v1, 26, v1
	v_ashrrev_i32_e32 v5, 31, v3
	v_add_u32_e32 v1, v0, v1
	v_lshrrev_b32_e32 v5, 26, v5
	v_ashrrev_i32_e32 v1, 6, v1
	v_add_u32_e32 v5, v3, v5
	v_lshlrev_b32_e32 v4, 3, v1
	v_ashrrev_i32_e32 v10, 6, v5
	v_and_b32_e32 v5, 0xc0, v5
	v_and_b32_e32 v4, -16, v4
	v_sub_u32_e32 v3, v3, v5
	v_mov_b32_e32 v5, 1
	v_add_u32_e32 v4, v10, v4
	v_ashrrev_i16_sdwa v3, v5, sext(v3) dst_sel:DWORD dst_unused:UNUSED_PAD src0_sel:DWORD src1_sel:BYTE_0
	s_load_dwordx4 s[8:11], s[0:1], 0xd0
	v_lshlrev_b32_e32 v6, 5, v1
	v_bfe_i32 v11, v3, 0, 16
	v_lshlrev_b32_e32 v3, 1, v4
	v_lshrrev_b32_e32 v7, 2, v4
	v_and_b32_e32 v8, 3, v10
	s_mov_b32 s1, 0x1fffe0
	v_and_b32_e32 v6, 32, v6
	v_and_b32_e32 v3, 24, v3
	v_and_b32_e32 v7, 4, v7
	v_and_or_b32 v8, v4, s1, v8
	v_or3_b32 v3, v8, v7, v3
	v_add_lshl_u32 v6, v6, v11, 1
	v_add_u32_e32 v2, 0x2000, v2
	v_lshl_add_u32 v130, v3, 11, v6
	v_ashrrev_i32_e32 v3, 31, v2
	v_lshrrev_b32_e32 v3, 22, v3
	v_add_u32_e32 v3, v2, v3
	v_ashrrev_i32_e32 v12, 10, v3
	v_mul_i32_i24_e32 v3, 0x400, v12
	v_sub_u32_e32 v2, v2, v3
	v_lshrrev_b32_e32 v3, 4, v2
	v_bitop3_b32 v2, v3, v2, 32 bitop3:0x6c
	v_lshl_add_u32 v128, v4, 11, v6
	v_ashrrev_i32_e32 v4, 31, v2
	v_lshrrev_b32_e32 v4, 26, v4
	v_add_u32_e32 v4, v2, v4
	s_waitcnt lgkmcnt(0)
	s_add_u32 s33, s10, 0x3100000
	v_lshlrev_b32_e32 v3, 3, v12
	v_ashrrev_i32_e32 v13, 6, v4
	v_and_b32_e32 v4, 0xc0, v4
	s_addc_u32 s36, s11, 0
	v_and_b32_e32 v3, -16, v3
	v_sub_u32_e32 v2, v2, v4
	s_add_u32 s37, s10, 0x1900000
	v_add_u32_e32 v3, v13, v3
	v_ashrrev_i16_sdwa v2, v5, sext(v2) dst_sel:DWORD dst_unused:UNUSED_PAD src0_sel:DWORD src1_sel:BYTE_0
	v_and_b32_e32 v5, 3, v13
	s_addc_u32 s38, s11, 0
	v_and_or_b32 v5, v3, s1, v5
	s_ashr_i32 s1, s16, 6
	s_ashr_i32 s5, s4, 31
	s_ashr_i32 s25, s24, 31
	s_ashr_i32 s0, s16, 8
	s_lshl_b32 s39, s1, 10
	s_lshl_b64 s[6:7], s[4:5], 19
	s_lshl_b64 s[12:13], s[24:25], 19
	s_add_u32 s26, s37, s12
	v_lshlrev_b32_e32 v6, 5, v12
	v_bfe_i32 v14, v2, 0, 16
	v_lshlrev_b32_e32 v2, 1, v3
	v_lshrrev_b32_e32 v4, 2, v3
	s_addc_u32 s27, s38, s13
	s_add_i32 s40, s39, 0
	v_and_b32_e32 v6, 32, v6
	v_and_b32_e32 v2, 24, v2
	v_and_b32_e32 v4, 4, v4
	s_add_i32 m0, s40, 0x10000
	v_or3_b32 v2, v5, v4, v2
	v_add_lshl_u32 v4, v6, v14, 1
	global_load_lds_dwordx4 v130, s[26:27]
	s_add_i32 m0, s40, 0x12000
	v_lshl_add_u32 v134, v2, 11, v4
	s_add_u32 s12, s26, 0x40000
	global_load_lds_dwordx4 v134, s[26:27]
	s_addc_u32 s13, s27, 0
	s_add_i32 m0, s40, 0x14000
	v_lshl_add_u32 v132, v3, 11, v4
	global_load_lds_dwordx4 v130, s[12:13]
	s_add_i32 m0, s40, 0x16000
	s_add_u32 s28, s33, s6
	s_addc_u32 s29, s36, s7
	s_add_i32 s41, s40, 0x2000
	global_load_lds_dwordx4 v134, s[12:13]
	s_mov_b32 m0, s40
	s_add_u32 s6, s28, 0x40000
	global_load_lds_dwordx4 v128, s[28:29]
	s_mov_b32 m0, s41
	s_addc_u32 s7, s29, 0
	s_add_i32 s42, s40, 0x4000
	global_load_lds_dwordx4 v132, s[28:29]
	s_mov_b32 m0, s42
	s_add_i32 s43, s40, 0x6000
	global_load_lds_dwordx4 v128, s[6:7]
	s_mov_b32 m0, s43
	v_mov_b32_e32 v131, 0
	global_load_lds_dwordx4 v132, s[6:7]
	v_mov_b32_e32 v135, v131
	v_mov_b32_e32 v129, v131
	v_mov_b32_e32 v133, v131
	s_cmp_eq_u32 s0, 1
	s_mov_b32 s7, 0
	v_lshl_add_u64 v[8:9], s[26:27], 0, v[130:131]
	v_lshl_add_u64 v[6:7], s[26:27], 0, v[134:135]
	v_lshl_add_u64 v[2:3], s[28:29], 0, v[128:129]
	s_cselect_b64 s[12:13], -1, 0
	s_cmp_lg_u32 s0, 1
	v_lshl_add_u64 v[4:5], s[28:29], 0, v[132:133]
	s_cbranch_scc1 .LBB8_6
	s_barrier
	s_setprio 1

.LBB8_11:
	s_ashr_i32 s19, s18, 31
	v_cmp_lt_i64_e32 vcc, s[0:1], v[144:145]
	s_lshl_b64 s[0:1], s[18:19], 19
	s_add_u32 s20, s33, s0
	s_addc_u32 s21, s36, s1
	s_and_b64 s[0:1], vcc, exec
	s_cselect_b32 s5, s21, s29
	s_cselect_b32 s19, s20, s28
	s_ashr_i32 s11, s10, 31
	s_lshl_b64 s[0:1], s[10:11], 19
	s_add_u32 s22, s37, s0
	s_addc_u32 s23, s38, s1
	s_and_b64 s[0:1], vcc, exec
	s_cselect_b32 s11, s23, s27
	s_cselect_b32 s25, s22, s26
	s_add_u32 s34, s26, 0x100
	s_addc_u32 s35, s27, 0
	s_add_u32 s26, s28, 0x40080
	s_addc_u32 s27, s29, 0
	s_mov_b32 s65, -2
	ds_read_b128 v[148:151], v153
	ds_read_b128 v[156:159], v153 offset:1024
	ds_read_b128 v[160:163], v153 offset:2048
	ds_read_b128 v[164:167], v153 offset:3072
	ds_read_b128 v[168:171], v154
	ds_read_b128 v[172:175], v154 offset:1024
	ds_read_b128 v[176:179], v154 offset:2048
	ds_read_b128 v[180:183], v154 offset:3072
	s_add_u32 s28, s26, 0xfffc0080
	s_addc_u32 s29, s27, -1
	s_cmp_eq_u32 s65, 12
	s_cselect_b32 s31, s5, s29
	s_cselect_b32 s30, s19, s28
	s_cselect_b32 s29, s11, s35
	s_cselect_b32 s28, s25, s34
	v_lshl_add_u64 v[216:217], s[26:27], 0, v[142:143]
	s_add_i32 m0, s40, 0xc000
	ds_read_b128 v[184:187], v155
	ds_read_b128 v[188:191], v155 offset:1024
	ds_read_b128 v[192:195], v155 offset:2048
	ds_read_b128 v[196:199], v155 offset:3072
	ds_read_b128 v[200:203], v155 offset:4096
	ds_read_b128 v[204:207], v155 offset:5120
	ds_read_b128 v[208:211], v155 offset:6144
	ds_read_b128 v[212:215], v155 offset:7168
	global_load_lds_dwordx4 v[216:217], off
	v_lshl_add_u64 v[216:217], s[26:27], 0, v[140:141]
	s_add_i32 m0, s40, 0xe000
	s_nop 0
	global_load_lds_dwordx4 v[216:217], off
	s_waitcnt vmcnt(8)
	s_waitcnt lgkmcnt(0)
	s_barrier
	s_waitcnt lgkmcnt(0)
	v_mfma_f32_16x16x32_bf16 v[124:127], v[148:151], v[184:187], 0
	v_mfma_f32_16x16x32_bf16 v[120:123], v[160:163], v[184:187], 0
	v_mfma_f32_16x16x32_bf16 v[108:111], v[148:151], v[192:195], 0
	v_mfma_f32_16x16x32_bf16 v[104:107], v[160:163], v[192:195], 0
	v_mfma_f32_16x16x32_bf16 v[92:95], v[148:151], v[200:203], 0
	v_mfma_f32_16x16x32_bf16 v[88:91], v[160:163], v[200:203], 0
	v_mfma_f32_16x16x32_bf16 v[76:79], v[148:151], v[208:211], 0
	v_mfma_f32_16x16x32_bf16 v[72:75], v[160:163], v[208:211], 0
	v_mfma_f32_16x16x32_bf16 v[124:127], v[156:159], v[188:191], v[124:127]
	v_mfma_f32_16x16x32_bf16 v[120:123], v[164:167], v[188:191], v[120:123]
	v_mfma_f32_16x16x32_bf16 v[108:111], v[156:159], v[196:199], v[108:111]
	v_mfma_f32_16x16x32_bf16 v[104:107], v[164:167], v[196:199], v[104:107]
	v_mfma_f32_16x16x32_bf16 v[92:95], v[156:159], v[204:207], v[92:95]
	v_mfma_f32_16x16x32_bf16 v[88:91], v[164:167], v[204:207], v[88:91]
	v_mfma_f32_16x16x32_bf16 v[76:79], v[156:159], v[212:215], v[76:79]
	v_mfma_f32_16x16x32_bf16 v[72:75], v[164:167], v[212:215], v[72:75]
	v_mfma_f32_16x16x32_bf16 v[116:119], v[168:171], v[184:187], 0
	v_mfma_f32_16x16x32_bf16 v[112:115], v[176:179], v[184:187], 0
	v_mfma_f32_16x16x32_bf16 v[100:103], v[168:171], v[192:195], 0
	v_mfma_f32_16x16x32_bf16 v[96:99], v[176:179], v[192:195], 0
	v_mfma_f32_16x16x32_bf16 v[84:87], v[168:171], v[200:203], 0
	v_mfma_f32_16x16x32_bf16 v[80:83], v[176:179], v[200:203], 0
	v_mfma_f32_16x16x32_bf16 v[68:71], v[168:171], v[208:211], 0
	v_mfma_f32_16x16x32_bf16 v[64:67], v[176:179], v[208:211], 0
	v_mfma_f32_16x16x32_bf16 v[116:119], v[172:175], v[188:191], v[116:119]
	v_mfma_f32_16x16x32_bf16 v[112:115], v[180:183], v[188:191], v[112:115]
	v_mfma_f32_16x16x32_bf16 v[100:103], v[172:175], v[196:199], v[100:103]
	v_mfma_f32_16x16x32_bf16 v[96:99], v[180:183], v[196:199], v[96:99]
	v_mfma_f32_16x16x32_bf16 v[84:87], v[172:175], v[204:207], v[84:87]
	v_mfma_f32_16x16x32_bf16 v[80:83], v[180:183], v[204:207], v[80:83]
	v_mfma_f32_16x16x32_bf16 v[68:71], v[172:175], v[212:215], v[68:71]
	v_mfma_f32_16x16x32_bf16 v[64:67], v[180:183], v[212:215], v[64:67]
	s_barrier
	s_add_i32 s66, s52, s39
	v_lshl_add_u64 v[216:217], s[28:29], 0, v[130:131]
	s_mov_b32 m0, s66
	ds_read_b128 v[184:187], v155 offset:16384
	ds_read_b128 v[188:191], v155 offset:17408
	ds_read_b128 v[192:195], v155 offset:18432
	ds_read_b128 v[196:199], v155 offset:19456
	ds_read_b128 v[200:203], v155 offset:20480
	ds_read_b128 v[204:207], v155 offset:21504
	ds_read_b128 v[208:211], v155 offset:22528
	ds_read_b128 v[212:215], v155 offset:23552
	global_load_lds_dwordx4 v[216:217], off
	s_add_i32 m0, s66, 0x2000
	s_add_u32 s66, s28, 0x40000
	v_lshl_add_u64 v[218:219], s[28:29], 0, v[134:135]
	s_addc_u32 s67, s29, 0
	s_add_i32 s68, s53, s39
	global_load_lds_dwordx4 v[218:219], off
	v_lshl_add_u64 v[220:221], s[66:67], 0, v[130:131]
	s_mov_b32 m0, s68
	v_lshl_add_u64 v[222:223], s[30:31], 0, v[132:133]
	global_load_lds_dwordx4 v[220:221], off
	v_lshl_add_u64 v[220:221], s[66:67], 0, v[134:135]
	s_add_i32 m0, s68, 0x2000
	s_nop 0
	global_load_lds_dwordx4 v[220:221], off
	v_lshl_add_u64 v[220:221], s[30:31], 0, v[128:129]
	s_mov_b32 m0, s40
	s_nop 0
	global_load_lds_dwordx4 v[220:221], off
	s_mov_b32 m0, s41
	s_nop 0
	global_load_lds_dwordx4 v[222:223], off
	s_waitcnt vmcnt(8)
	s_waitcnt lgkmcnt(0)
	s_barrier
	s_waitcnt lgkmcnt(0)
	v_mfma_f32_16x16x32_bf16 v[60:63], v[148:151], v[184:187], 0
	v_mfma_f32_16x16x32_bf16 v[56:59], v[160:163], v[184:187], 0
	v_mfma_f32_16x16x32_bf16 v[44:47], v[148:151], v[192:195], 0
	v_mfma_f32_16x16x32_bf16 v[40:43], v[160:163], v[192:195], 0
	v_mfma_f32_16x16x32_bf16 v[28:31], v[148:151], v[200:203], 0
	v_mfma_f32_16x16x32_bf16 v[24:27], v[160:163], v[200:203], 0
	v_mfma_f32_16x16x32_bf16 v[12:15], v[148:151], v[208:211], 0
	v_mfma_f32_16x16x32_bf16 v[8:11], v[160:163], v[208:211], 0
	v_mfma_f32_16x16x32_bf16 v[60:63], v[156:159], v[188:191], v[60:63]
	v_mfma_f32_16x16x32_bf16 v[56:59], v[164:167], v[188:191], v[56:59]
	v_mfma_f32_16x16x32_bf16 v[44:47], v[156:159], v[196:199], v[44:47]
	v_mfma_f32_16x16x32_bf16 v[40:43], v[164:167], v[196:199], v[40:43]
	v_mfma_f32_16x16x32_bf16 v[28:31], v[156:159], v[204:207], v[28:31]
	v_mfma_f32_16x16x32_bf16 v[24:27], v[164:167], v[204:207], v[24:27]
	v_mfma_f32_16x16x32_bf16 v[12:15], v[156:159], v[212:215], v[12:15]
	v_mfma_f32_16x16x32_bf16 v[8:11], v[164:167], v[212:215], v[8:11]
	v_mfma_f32_16x16x32_bf16 v[52:55], v[168:171], v[184:187], 0
	v_mfma_f32_16x16x32_bf16 v[48:51], v[176:179], v[184:187], 0
	v_mfma_f32_16x16x32_bf16 v[36:39], v[168:171], v[192:195], 0
	v_mfma_f32_16x16x32_bf16 v[32:35], v[176:179], v[192:195], 0
	v_mfma_f32_16x16x32_bf16 v[20:23], v[168:171], v[200:203], 0
	v_mfma_f32_16x16x32_bf16 v[16:19], v[176:179], v[200:203], 0
	v_mfma_f32_16x16x32_bf16 v[4:7], v[168:171], v[208:211], 0
	v_mfma_f32_16x16x32_bf16 v[0:3], v[176:179], v[208:211], 0
	v_mfma_f32_16x16x32_bf16 v[52:55], v[172:175], v[188:191], v[52:55]
	v_mfma_f32_16x16x32_bf16 v[48:51], v[180:183], v[188:191], v[48:51]
	v_mfma_f32_16x16x32_bf16 v[36:39], v[172:175], v[196:199], v[36:39]
	v_mfma_f32_16x16x32_bf16 v[32:35], v[180:183], v[196:199], v[32:35]
	v_mfma_f32_16x16x32_bf16 v[20:23], v[172:175], v[204:207], v[20:23]
	v_mfma_f32_16x16x32_bf16 v[16:19], v[180:183], v[204:207], v[16:19]
	v_mfma_f32_16x16x32_bf16 v[4:7], v[172:175], v[212:215], v[4:7]
	v_mfma_f32_16x16x32_bf16 v[0:3], v[180:183], v[212:215], v[0:3]
	s_barrier
	s_add_i32 s66, 0, 0x18000
	s_add_i32 s67, 0, 0x1c000
	v_add_u32_e32 v164, s66, v152
	v_add_u32_e32 v180, s67, v152
	ds_read_b128 v[148:151], v164
	ds_read_b128 v[156:159], v164 offset:1024
	ds_read_b128 v[160:163], v164 offset:2048
	ds_read_b128 v[164:167], v164 offset:3072
	ds_read_b128 v[168:171], v180
	ds_read_b128 v[172:175], v180 offset:1024
	ds_read_b128 v[176:179], v180 offset:2048
	ds_read_b128 v[180:183], v180 offset:3072
	s_add_u32 s30, s30, 0x40000
	s_addc_u32 s31, s31, 0
	s_mov_b32 m0, s42
	v_lshl_add_u64 v[224:225], s[30:31], 0, v[128:129]
	ds_read_b128 v[184:187], v155 offset:32768
	ds_read_b128 v[188:191], v155 offset:33792
	ds_read_b128 v[192:195], v155 offset:34816
	ds_read_b128 v[196:199], v155 offset:35840
	ds_read_b128 v[200:203], v155 offset:36864
	ds_read_b128 v[204:207], v155 offset:37888
	ds_read_b128 v[208:211], v155 offset:38912
	ds_read_b128 v[212:215], v155 offset:39936
	global_load_lds_dwordx4 v[224:225], off
	v_lshl_add_u64 v[224:225], s[30:31], 0, v[132:133]
	s_mov_b32 m0, s43
	s_nop 0
	global_load_lds_dwordx4 v[224:225], off
	s_waitcnt vmcnt(8)
	s_waitcnt lgkmcnt(0)
	s_barrier
	s_waitcnt lgkmcnt(0)
	v_mfma_f32_16x16x32_bf16 v[124:127], v[148:151], v[184:187], v[124:127]
	v_mfma_f32_16x16x32_bf16 v[120:123], v[160:163], v[184:187], v[120:123]
	v_mfma_f32_16x16x32_bf16 v[108:111], v[148:151], v[192:195], v[108:111]
	v_mfma_f32_16x16x32_bf16 v[104:107], v[160:163], v[192:195], v[104:107]
	v_mfma_f32_16x16x32_bf16 v[92:95], v[148:151], v[200:203], v[92:95]
	v_mfma_f32_16x16x32_bf16 v[88:91], v[160:163], v[200:203], v[88:91]
	v_mfma_f32_16x16x32_bf16 v[76:79], v[148:151], v[208:211], v[76:79]
	v_mfma_f32_16x16x32_bf16 v[72:75], v[160:163], v[208:211], v[72:75]
	v_mfma_f32_16x16x32_bf16 v[124:127], v[156:159], v[188:191], v[124:127]
	v_mfma_f32_16x16x32_bf16 v[120:123], v[164:167], v[188:191], v[120:123]
	v_mfma_f32_16x16x32_bf16 v[108:111], v[156:159], v[196:199], v[108:111]
	v_mfma_f32_16x16x32_bf16 v[104:107], v[164:167], v[196:199], v[104:107]
	v_mfma_f32_16x16x32_bf16 v[92:95], v[156:159], v[204:207], v[92:95]
	v_mfma_f32_16x16x32_bf16 v[88:91], v[164:167], v[204:207], v[88:91]
	v_mfma_f32_16x16x32_bf16 v[76:79], v[156:159], v[212:215], v[76:79]
	v_mfma_f32_16x16x32_bf16 v[72:75], v[164:167], v[212:215], v[72:75]
	v_mfma_f32_16x16x32_bf16 v[116:119], v[168:171], v[184:187], v[116:119]
	v_mfma_f32_16x16x32_bf16 v[112:115], v[176:179], v[184:187], v[112:115]
	v_mfma_f32_16x16x32_bf16 v[100:103], v[168:171], v[192:195], v[100:103]
	v_mfma_f32_16x16x32_bf16 v[96:99], v[176:179], v[192:195], v[96:99]
	v_mfma_f32_16x16x32_bf16 v[84:87], v[168:171], v[200:203], v[84:87]
	v_mfma_f32_16x16x32_bf16 v[80:83], v[176:179], v[200:203], v[80:83]
	v_mfma_f32_16x16x32_bf16 v[68:71], v[168:171], v[208:211], v[68:71]
	v_mfma_f32_16x16x32_bf16 v[64:67], v[176:179], v[208:211], v[64:67]
	v_mfma_f32_16x16x32_bf16 v[116:119], v[172:175], v[188:191], v[116:119]
	v_mfma_f32_16x16x32_bf16 v[112:115], v[180:183], v[188:191], v[112:115]
	v_mfma_f32_16x16x32_bf16 v[100:103], v[172:175], v[196:199], v[100:103]
	v_mfma_f32_16x16x32_bf16 v[96:99], v[180:183], v[196:199], v[96:99]
	v_mfma_f32_16x16x32_bf16 v[84:87], v[172:175], v[204:207], v[84:87]
	v_mfma_f32_16x16x32_bf16 v[80:83], v[180:183], v[204:207], v[80:83]
	v_mfma_f32_16x16x32_bf16 v[68:71], v[172:175], v[212:215], v[68:71]
	v_mfma_f32_16x16x32_bf16 v[64:67], v[180:183], v[212:215], v[64:67]
	s_barrier
	s_add_i32 s30, s66, s39
	v_lshl_add_u64 v[216:217], v[216:217], 0, s[14:15]
	s_mov_b32 m0, s30
	ds_read_b128 v[184:187], v155 offset:49152
	ds_read_b128 v[188:191], v155 offset:50176
	ds_read_b128 v[192:195], v155 offset:51200
	ds_read_b128 v[196:199], v155 offset:52224
	ds_read_b128 v[200:203], v155 offset:53248
	ds_read_b128 v[204:207], v155 offset:54272
	ds_read_b128 v[208:211], v155 offset:55296
	ds_read_b128 v[212:215], v155 offset:56320
	global_load_lds_dwordx4 v[216:217], off
	s_add_i32 m0, s30, 0x2000
	s_add_u32 s28, s28, 0x40080
	v_lshl_add_u64 v[216:217], v[218:219], 0, s[14:15]
	s_addc_u32 s29, s29, 0
	s_add_i32 s30, s67, s39
	global_load_lds_dwordx4 v[216:217], off
	v_lshl_add_u64 v[216:217], s[28:29], 0, v[130:131]
	s_mov_b32 m0, s30
	s_nop 0
	global_load_lds_dwordx4 v[216:217], off
	v_lshl_add_u64 v[216:217], s[28:29], 0, v[134:135]
	s_add_i32 m0, s30, 0x2000
	s_nop 0
	global_load_lds_dwordx4 v[216:217], off
	v_lshl_add_u64 v[216:217], v[220:221], 0, s[14:15]
	s_mov_b32 m0, s45
	s_nop 0
	global_load_lds_dwordx4 v[216:217], off
	v_lshl_add_u64 v[216:217], v[222:223], 0, s[14:15]
	s_mov_b32 m0, s46
	s_nop 0
	global_load_lds_dwordx4 v[216:217], off
	s_waitcnt vmcnt(8)
	s_waitcnt lgkmcnt(0)
	s_barrier
	s_waitcnt lgkmcnt(0)
	v_mfma_f32_16x16x32_bf16 v[60:63], v[148:151], v[184:187], v[60:63]
	v_mfma_f32_16x16x32_bf16 v[56:59], v[160:163], v[184:187], v[56:59]
	v_mfma_f32_16x16x32_bf16 v[44:47], v[148:151], v[192:195], v[44:47]
	v_mfma_f32_16x16x32_bf16 v[40:43], v[160:163], v[192:195], v[40:43]
	v_mfma_f32_16x16x32_bf16 v[28:31], v[148:151], v[200:203], v[28:31]
	v_mfma_f32_16x16x32_bf16 v[24:27], v[160:163], v[200:203], v[24:27]
	v_mfma_f32_16x16x32_bf16 v[12:15], v[148:151], v[208:211], v[12:15]
	v_mfma_f32_16x16x32_bf16 v[8:11], v[160:163], v[208:211], v[8:11]
	v_mfma_f32_16x16x32_bf16 v[60:63], v[156:159], v[188:191], v[60:63]
	v_mfma_f32_16x16x32_bf16 v[56:59], v[164:167], v[188:191], v[56:59]
	v_mfma_f32_16x16x32_bf16 v[44:47], v[156:159], v[196:199], v[44:47]
	v_mfma_f32_16x16x32_bf16 v[40:43], v[164:167], v[196:199], v[40:43]
	v_mfma_f32_16x16x32_bf16 v[28:31], v[156:159], v[204:207], v[28:31]
	v_mfma_f32_16x16x32_bf16 v[24:27], v[164:167], v[204:207], v[24:27]
	v_mfma_f32_16x16x32_bf16 v[12:15], v[156:159], v[212:215], v[12:15]
	v_mfma_f32_16x16x32_bf16 v[8:11], v[164:167], v[212:215], v[8:11]
	v_mfma_f32_16x16x32_bf16 v[52:55], v[168:171], v[184:187], v[52:55]
	v_mfma_f32_16x16x32_bf16 v[48:51], v[176:179], v[184:187], v[48:51]
	v_mfma_f32_16x16x32_bf16 v[36:39], v[168:171], v[192:195], v[36:39]
	v_mfma_f32_16x16x32_bf16 v[32:35], v[176:179], v[192:195], v[32:35]
	v_mfma_f32_16x16x32_bf16 v[20:23], v[168:171], v[200:203], v[20:23]
	v_mfma_f32_16x16x32_bf16 v[16:19], v[176:179], v[200:203], v[16:19]
	v_mfma_f32_16x16x32_bf16 v[4:7], v[168:171], v[208:211], v[4:7]
	v_mfma_f32_16x16x32_bf16 v[0:3], v[176:179], v[208:211], v[0:3]
	v_mfma_f32_16x16x32_bf16 v[52:55], v[172:175], v[188:191], v[52:55]
	v_mfma_f32_16x16x32_bf16 v[48:51], v[180:183], v[188:191], v[48:51]
	v_mfma_f32_16x16x32_bf16 v[36:39], v[172:175], v[196:199], v[36:39]
	v_mfma_f32_16x16x32_bf16 v[32:35], v[180:183], v[196:199], v[32:35]
	v_mfma_f32_16x16x32_bf16 v[20:23], v[172:175], v[204:207], v[20:23]
	v_mfma_f32_16x16x32_bf16 v[16:19], v[180:183], v[204:207], v[16:19]
	v_mfma_f32_16x16x32_bf16 v[4:7], v[172:175], v[212:215], v[4:7]
	v_mfma_f32_16x16x32_bf16 v[0:3], v[180:183], v[212:215], v[0:3]
	s_barrier
	s_add_i32 s65, s65, 2
	s_add_u32 s34, s34, 0x100
	s_addc_u32 s35, s35, 0
	s_add_u32 s26, s26, 0x100
	s_addc_u32 s27, s27, 0
	s_cmp_lt_u32 s65, 14
.LBB8_12:
	ds_read_b128 v[148:151], v153
	ds_read_b128 v[156:159], v153 offset:1024
	ds_read_b128 v[160:163], v153 offset:2048
	ds_read_b128 v[164:167], v153 offset:3072
	ds_read_b128 v[168:171], v154
	ds_read_b128 v[172:175], v154 offset:1024
	ds_read_b128 v[176:179], v154 offset:2048
	ds_read_b128 v[180:183], v154 offset:3072
	s_add_u32 s28, s26, 0xfffc0080
	s_addc_u32 s29, s27, -1
	s_cmp_eq_u32 s65, 12
	s_cselect_b32 s31, s5, s29
	s_cselect_b32 s30, s19, s28
	s_cselect_b32 s29, s11, s35
	s_cselect_b32 s28, s25, s34
	v_lshl_add_u64 v[216:217], s[26:27], 0, v[142:143]
	s_add_i32 m0, s40, 0xc000
	ds_read_b128 v[184:187], v155
	ds_read_b128 v[188:191], v155 offset:1024
	ds_read_b128 v[192:195], v155 offset:2048
	ds_read_b128 v[196:199], v155 offset:3072
	ds_read_b128 v[200:203], v155 offset:4096
	ds_read_b128 v[204:207], v155 offset:5120
	ds_read_b128 v[208:211], v155 offset:6144
	ds_read_b128 v[212:215], v155 offset:7168
	global_load_lds_dwordx4 v[216:217], off
	v_lshl_add_u64 v[216:217], s[26:27], 0, v[140:141]
	s_add_i32 m0, s40, 0xe000
	s_nop 0
	global_load_lds_dwordx4 v[216:217], off
	s_waitcnt vmcnt(8)
	s_waitcnt lgkmcnt(0)
	s_barrier
	s_waitcnt lgkmcnt(0)
	v_mfma_f32_16x16x32_bf16 v[124:127], v[148:151], v[184:187], v[124:127]
	v_mfma_f32_16x16x32_bf16 v[120:123], v[160:163], v[184:187], v[120:123]
	v_mfma_f32_16x16x32_bf16 v[108:111], v[148:151], v[192:195], v[108:111]
	v_mfma_f32_16x16x32_bf16 v[104:107], v[160:163], v[192:195], v[104:107]
	v_mfma_f32_16x16x32_bf16 v[92:95], v[148:151], v[200:203], v[92:95]
	v_mfma_f32_16x16x32_bf16 v[88:91], v[160:163], v[200:203], v[88:91]
	v_mfma_f32_16x16x32_bf16 v[76:79], v[148:151], v[208:211], v[76:79]
	v_mfma_f32_16x16x32_bf16 v[72:75], v[160:163], v[208:211], v[72:75]
	v_mfma_f32_16x16x32_bf16 v[124:127], v[156:159], v[188:191], v[124:127]
	v_mfma_f32_16x16x32_bf16 v[120:123], v[164:167], v[188:191], v[120:123]
	v_mfma_f32_16x16x32_bf16 v[108:111], v[156:159], v[196:199], v[108:111]
	v_mfma_f32_16x16x32_bf16 v[104:107], v[164:167], v[196:199], v[104:107]
	v_mfma_f32_16x16x32_bf16 v[92:95], v[156:159], v[204:207], v[92:95]
	v_mfma_f32_16x16x32_bf16 v[88:91], v[164:167], v[204:207], v[88:91]
	v_mfma_f32_16x16x32_bf16 v[76:79], v[156:159], v[212:215], v[76:79]
	v_mfma_f32_16x16x32_bf16 v[72:75], v[164:167], v[212:215], v[72:75]
	v_mfma_f32_16x16x32_bf16 v[116:119], v[168:171], v[184:187], v[116:119]
	v_mfma_f32_16x16x32_bf16 v[112:115], v[176:179], v[184:187], v[112:115]
	v_mfma_f32_16x16x32_bf16 v[100:103], v[168:171], v[192:195], v[100:103]
	v_mfma_f32_16x16x32_bf16 v[96:99], v[176:179], v[192:195], v[96:99]
	v_mfma_f32_16x16x32_bf16 v[84:87], v[168:171], v[200:203], v[84:87]
	v_mfma_f32_16x16x32_bf16 v[80:83], v[176:179], v[200:203], v[80:83]
	v_mfma_f32_16x16x32_bf16 v[68:71], v[168:171], v[208:211], v[68:71]
	v_mfma_f32_16x16x32_bf16 v[64:67], v[176:179], v[208:211], v[64:67]
	v_mfma_f32_16x16x32_bf16 v[116:119], v[172:175], v[188:191], v[116:119]
	v_mfma_f32_16x16x32_bf16 v[112:115], v[180:183], v[188:191], v[112:115]
	v_mfma_f32_16x16x32_bf16 v[100:103], v[172:175], v[196:199], v[100:103]
	v_mfma_f32_16x16x32_bf16 v[96:99], v[180:183], v[196:199], v[96:99]
	v_mfma_f32_16x16x32_bf16 v[84:87], v[172:175], v[204:207], v[84:87]
	v_mfma_f32_16x16x32_bf16 v[80:83], v[180:183], v[204:207], v[80:83]
	v_mfma_f32_16x16x32_bf16 v[68:71], v[172:175], v[212:215], v[68:71]
	v_mfma_f32_16x16x32_bf16 v[64:67], v[180:183], v[212:215], v[64:67]
	s_barrier
	s_add_i32 s66, s52, s39
	v_lshl_add_u64 v[216:217], s[28:29], 0, v[130:131]
	s_mov_b32 m0, s66
	ds_read_b128 v[184:187], v155 offset:16384
	ds_read_b128 v[188:191], v155 offset:17408
	ds_read_b128 v[192:195], v155 offset:18432
	ds_read_b128 v[196:199], v155 offset:19456
	ds_read_b128 v[200:203], v155 offset:20480
	ds_read_b128 v[204:207], v155 offset:21504
	ds_read_b128 v[208:211], v155 offset:22528
	ds_read_b128 v[212:215], v155 offset:23552
	global_load_lds_dwordx4 v[216:217], off
	s_add_i32 m0, s66, 0x2000
	s_add_u32 s66, s28, 0x40000
	v_lshl_add_u64 v[218:219], s[28:29], 0, v[134:135]
	s_addc_u32 s67, s29, 0
	s_add_i32 s68, s53, s39
	global_load_lds_dwordx4 v[218:219], off
	v_lshl_add_u64 v[220:221], s[66:67], 0, v[130:131]
	s_mov_b32 m0, s68
	v_lshl_add_u64 v[222:223], s[30:31], 0, v[132:133]
	global_load_lds_dwordx4 v[220:221], off
	v_lshl_add_u64 v[220:221], s[66:67], 0, v[134:135]
	s_add_i32 m0, s68, 0x2000
	s_nop 0
	global_load_lds_dwordx4 v[220:221], off
	v_lshl_add_u64 v[220:221], s[30:31], 0, v[128:129]
	s_mov_b32 m0, s40
	s_nop 0
	global_load_lds_dwordx4 v[220:221], off
	s_mov_b32 m0, s41
	s_nop 0
	global_load_lds_dwordx4 v[222:223], off
	s_waitcnt vmcnt(8)
	s_waitcnt lgkmcnt(0)
	s_barrier
	s_waitcnt lgkmcnt(0)
	v_mfma_f32_16x16x32_bf16 v[60:63], v[148:151], v[184:187], v[60:63]
	v_mfma_f32_16x16x32_bf16 v[56:59], v[160:163], v[184:187], v[56:59]
	v_mfma_f32_16x16x32_bf16 v[44:47], v[148:151], v[192:195], v[44:47]
	v_mfma_f32_16x16x32_bf16 v[40:43], v[160:163], v[192:195], v[40:43]
	v_mfma_f32_16x16x32_bf16 v[28:31], v[148:151], v[200:203], v[28:31]
	v_mfma_f32_16x16x32_bf16 v[24:27], v[160:163], v[200:203], v[24:27]
	v_mfma_f32_16x16x32_bf16 v[12:15], v[148:151], v[208:211], v[12:15]
	v_mfma_f32_16x16x32_bf16 v[8:11], v[160:163], v[208:211], v[8:11]
	v_mfma_f32_16x16x32_bf16 v[60:63], v[156:159], v[188:191], v[60:63]
	v_mfma_f32_16x16x32_bf16 v[56:59], v[164:167], v[188:191], v[56:59]
	v_mfma_f32_16x16x32_bf16 v[44:47], v[156:159], v[196:199], v[44:47]
	v_mfma_f32_16x16x32_bf16 v[40:43], v[164:167], v[196:199], v[40:43]
	v_mfma_f32_16x16x32_bf16 v[28:31], v[156:159], v[204:207], v[28:31]
	v_mfma_f32_16x16x32_bf16 v[24:27], v[164:167], v[204:207], v[24:27]
	v_mfma_f32_16x16x32_bf16 v[12:15], v[156:159], v[212:215], v[12:15]
	v_mfma_f32_16x16x32_bf16 v[8:11], v[164:167], v[212:215], v[8:11]
	v_mfma_f32_16x16x32_bf16 v[52:55], v[168:171], v[184:187], v[52:55]
	v_mfma_f32_16x16x32_bf16 v[48:51], v[176:179], v[184:187], v[48:51]
	v_mfma_f32_16x16x32_bf16 v[36:39], v[168:171], v[192:195], v[36:39]
	v_mfma_f32_16x16x32_bf16 v[32:35], v[176:179], v[192:195], v[32:35]
	v_mfma_f32_16x16x32_bf16 v[20:23], v[168:171], v[200:203], v[20:23]
	v_mfma_f32_16x16x32_bf16 v[16:19], v[176:179], v[200:203], v[16:19]
	v_mfma_f32_16x16x32_bf16 v[4:7], v[168:171], v[208:211], v[4:7]
	v_mfma_f32_16x16x32_bf16 v[0:3], v[176:179], v[208:211], v[0:3]
	v_mfma_f32_16x16x32_bf16 v[52:55], v[172:175], v[188:191], v[52:55]
	v_mfma_f32_16x16x32_bf16 v[48:51], v[180:183], v[188:191], v[48:51]
	v_mfma_f32_16x16x32_bf16 v[36:39], v[172:175], v[196:199], v[36:39]
	v_mfma_f32_16x16x32_bf16 v[32:35], v[180:183], v[196:199], v[32:35]
	v_mfma_f32_16x16x32_bf16 v[20:23], v[172:175], v[204:207], v[20:23]
	v_mfma_f32_16x16x32_bf16 v[16:19], v[180:183], v[204:207], v[16:19]
	v_mfma_f32_16x16x32_bf16 v[4:7], v[172:175], v[212:215], v[4:7]
	v_mfma_f32_16x16x32_bf16 v[0:3], v[180:183], v[212:215], v[0:3]
	s_barrier
	s_add_i32 s66, 0, 0x18000
	s_add_i32 s67, 0, 0x1c000
	v_add_u32_e32 v164, s66, v152
	v_add_u32_e32 v180, s67, v152
	ds_read_b128 v[148:151], v164
	ds_read_b128 v[156:159], v164 offset:1024
	ds_read_b128 v[160:163], v164 offset:2048
	ds_read_b128 v[164:167], v164 offset:3072
	ds_read_b128 v[168:171], v180
	ds_read_b128 v[172:175], v180 offset:1024
	ds_read_b128 v[176:179], v180 offset:2048
	ds_read_b128 v[180:183], v180 offset:3072
	s_add_u32 s30, s30, 0x40000
	s_addc_u32 s31, s31, 0
	s_mov_b32 m0, s42
	v_lshl_add_u64 v[224:225], s[30:31], 0, v[128:129]
	ds_read_b128 v[184:187], v155 offset:32768
	ds_read_b128 v[188:191], v155 offset:33792
	ds_read_b128 v[192:195], v155 offset:34816
	ds_read_b128 v[196:199], v155 offset:35840
	ds_read_b128 v[200:203], v155 offset:36864
	ds_read_b128 v[204:207], v155 offset:37888
	ds_read_b128 v[208:211], v155 offset:38912
	ds_read_b128 v[212:215], v155 offset:39936
	global_load_lds_dwordx4 v[224:225], off
	v_lshl_add_u64 v[224:225], s[30:31], 0, v[132:133]
	s_mov_b32 m0, s43
	s_nop 0
	global_load_lds_dwordx4 v[224:225], off
	s_waitcnt vmcnt(8)
	s_waitcnt lgkmcnt(0)
	s_barrier
	s_waitcnt lgkmcnt(0)
	v_mfma_f32_16x16x32_bf16 v[124:127], v[148:151], v[184:187], v[124:127]
	v_mfma_f32_16x16x32_bf16 v[120:123], v[160:163], v[184:187], v[120:123]
	v_mfma_f32_16x16x32_bf16 v[108:111], v[148:151], v[192:195], v[108:111]
	v_mfma_f32_16x16x32_bf16 v[104:107], v[160:163], v[192:195], v[104:107]
	v_mfma_f32_16x16x32_bf16 v[92:95], v[148:151], v[200:203], v[92:95]
	v_mfma_f32_16x16x32_bf16 v[88:91], v[160:163], v[200:203], v[88:91]
	v_mfma_f32_16x16x32_bf16 v[76:79], v[148:151], v[208:211], v[76:79]
	v_mfma_f32_16x16x32_bf16 v[72:75], v[160:163], v[208:211], v[72:75]
	v_mfma_f32_16x16x32_bf16 v[124:127], v[156:159], v[188:191], v[124:127]
	v_mfma_f32_16x16x32_bf16 v[120:123], v[164:167], v[188:191], v[120:123]
	v_mfma_f32_16x16x32_bf16 v[108:111], v[156:159], v[196:199], v[108:111]
	v_mfma_f32_16x16x32_bf16 v[104:107], v[164:167], v[196:199], v[104:107]
	v_mfma_f32_16x16x32_bf16 v[92:95], v[156:159], v[204:207], v[92:95]
	v_mfma_f32_16x16x32_bf16 v[88:91], v[164:167], v[204:207], v[88:91]
	v_mfma_f32_16x16x32_bf16 v[76:79], v[156:159], v[212:215], v[76:79]
	v_mfma_f32_16x16x32_bf16 v[72:75], v[164:167], v[212:215], v[72:75]
	v_mfma_f32_16x16x32_bf16 v[116:119], v[168:171], v[184:187], v[116:119]
	v_mfma_f32_16x16x32_bf16 v[112:115], v[176:179], v[184:187], v[112:115]
	v_mfma_f32_16x16x32_bf16 v[100:103], v[168:171], v[192:195], v[100:103]
	v_mfma_f32_16x16x32_bf16 v[96:99], v[176:179], v[192:195], v[96:99]
	v_mfma_f32_16x16x32_bf16 v[84:87], v[168:171], v[200:203], v[84:87]
	v_mfma_f32_16x16x32_bf16 v[80:83], v[176:179], v[200:203], v[80:83]
	v_mfma_f32_16x16x32_bf16 v[68:71], v[168:171], v[208:211], v[68:71]
	v_mfma_f32_16x16x32_bf16 v[64:67], v[176:179], v[208:211], v[64:67]
	v_mfma_f32_16x16x32_bf16 v[116:119], v[172:175], v[188:191], v[116:119]
	v_mfma_f32_16x16x32_bf16 v[112:115], v[180:183], v[188:191], v[112:115]
	v_mfma_f32_16x16x32_bf16 v[100:103], v[172:175], v[196:199], v[100:103]
	v_mfma_f32_16x16x32_bf16 v[96:99], v[180:183], v[196:199], v[96:99]
	v_mfma_f32_16x16x32_bf16 v[84:87], v[172:175], v[204:207], v[84:87]
	v_mfma_f32_16x16x32_bf16 v[80:83], v[180:183], v[204:207], v[80:83]
	v_mfma_f32_16x16x32_bf16 v[68:71], v[172:175], v[212:215], v[68:71]
	v_mfma_f32_16x16x32_bf16 v[64:67], v[180:183], v[212:215], v[64:67]
	s_barrier
	s_add_i32 s30, s66, s39
	v_lshl_add_u64 v[216:217], v[216:217], 0, s[14:15]
	s_mov_b32 m0, s30
	ds_read_b128 v[184:187], v155 offset:49152
	ds_read_b128 v[188:191], v155 offset:50176
	ds_read_b128 v[192:195], v155 offset:51200
	ds_read_b128 v[196:199], v155 offset:52224
	ds_read_b128 v[200:203], v155 offset:53248
	ds_read_b128 v[204:207], v155 offset:54272
	ds_read_b128 v[208:211], v155 offset:55296
	ds_read_b128 v[212:215], v155 offset:56320
	global_load_lds_dwordx4 v[216:217], off
	s_add_i32 m0, s30, 0x2000
	s_add_u32 s28, s28, 0x40080
	v_lshl_add_u64 v[216:217], v[218:219], 0, s[14:15]
	s_addc_u32 s29, s29, 0
	s_add_i32 s30, s67, s39
	global_load_lds_dwordx4 v[216:217], off
	v_lshl_add_u64 v[216:217], s[28:29], 0, v[130:131]
	s_mov_b32 m0, s30
	s_nop 0
	global_load_lds_dwordx4 v[216:217], off
	v_lshl_add_u64 v[216:217], s[28:29], 0, v[134:135]
	s_add_i32 m0, s30, 0x2000
	s_nop 0
	global_load_lds_dwordx4 v[216:217], off
	v_lshl_add_u64 v[216:217], v[220:221], 0, s[14:15]
	s_mov_b32 m0, s45
	s_nop 0
	global_load_lds_dwordx4 v[216:217], off
	v_lshl_add_u64 v[216:217], v[222:223], 0, s[14:15]
	s_mov_b32 m0, s46
	s_nop 0
	global_load_lds_dwordx4 v[216:217], off
	s_waitcnt vmcnt(8)
	s_waitcnt lgkmcnt(0)
	s_barrier
	s_waitcnt lgkmcnt(0)
	v_mfma_f32_16x16x32_bf16 v[60:63], v[148:151], v[184:187], v[60:63]
	v_mfma_f32_16x16x32_bf16 v[56:59], v[160:163], v[184:187], v[56:59]
	v_mfma_f32_16x16x32_bf16 v[44:47], v[148:151], v[192:195], v[44:47]
	v_mfma_f32_16x16x32_bf16 v[40:43], v[160:163], v[192:195], v[40:43]
	v_mfma_f32_16x16x32_bf16 v[28:31], v[148:151], v[200:203], v[28:31]
	v_mfma_f32_16x16x32_bf16 v[24:27], v[160:163], v[200:203], v[24:27]
	v_mfma_f32_16x16x32_bf16 v[12:15], v[148:151], v[208:211], v[12:15]
	v_mfma_f32_16x16x32_bf16 v[8:11], v[160:163], v[208:211], v[8:11]
	v_mfma_f32_16x16x32_bf16 v[60:63], v[156:159], v[188:191], v[60:63]
	v_mfma_f32_16x16x32_bf16 v[56:59], v[164:167], v[188:191], v[56:59]
	v_mfma_f32_16x16x32_bf16 v[44:47], v[156:159], v[196:199], v[44:47]
	v_mfma_f32_16x16x32_bf16 v[40:43], v[164:167], v[196:199], v[40:43]
	v_mfma_f32_16x16x32_bf16 v[28:31], v[156:159], v[204:207], v[28:31]
	v_mfma_f32_16x16x32_bf16 v[24:27], v[164:167], v[204:207], v[24:27]
	v_mfma_f32_16x16x32_bf16 v[12:15], v[156:159], v[212:215], v[12:15]
	v_mfma_f32_16x16x32_bf16 v[8:11], v[164:167], v[212:215], v[8:11]
	v_mfma_f32_16x16x32_bf16 v[52:55], v[168:171], v[184:187], v[52:55]
	v_mfma_f32_16x16x32_bf16 v[48:51], v[176:179], v[184:187], v[48:51]
	v_mfma_f32_16x16x32_bf16 v[36:39], v[168:171], v[192:195], v[36:39]
	v_mfma_f32_16x16x32_bf16 v[32:35], v[176:179], v[192:195], v[32:35]
	v_mfma_f32_16x16x32_bf16 v[20:23], v[168:171], v[200:203], v[20:23]
	v_mfma_f32_16x16x32_bf16 v[16:19], v[176:179], v[200:203], v[16:19]
	v_mfma_f32_16x16x32_bf16 v[4:7], v[168:171], v[208:211], v[4:7]
	v_mfma_f32_16x16x32_bf16 v[0:3], v[176:179], v[208:211], v[0:3]
	v_mfma_f32_16x16x32_bf16 v[52:55], v[172:175], v[188:191], v[52:55]
	v_mfma_f32_16x16x32_bf16 v[48:51], v[180:183], v[188:191], v[48:51]
	v_mfma_f32_16x16x32_bf16 v[36:39], v[172:175], v[196:199], v[36:39]
	v_mfma_f32_16x16x32_bf16 v[32:35], v[180:183], v[196:199], v[32:35]
	v_mfma_f32_16x16x32_bf16 v[20:23], v[172:175], v[204:207], v[20:23]
	v_mfma_f32_16x16x32_bf16 v[16:19], v[180:183], v[204:207], v[16:19]
	v_mfma_f32_16x16x32_bf16 v[4:7], v[172:175], v[212:215], v[4:7]
	v_mfma_f32_16x16x32_bf16 v[0:3], v[180:183], v[212:215], v[0:3]
	s_barrier
	s_add_i32 s65, s65, 2
	s_add_u32 s34, s34, 0x100
	s_addc_u32 s35, s35, 0
	s_add_u32 s26, s26, 0x100
	s_addc_u32 s27, s27, 0
	s_cmp_lt_u32 s65, 14
	s_cbranch_scc1 .LBB8_12
	s_andn2_b64 vcc, exec, s[16:17]
	s_cbranch_vccnz .LBB8_15
	s_barrier

.LBB10_8:
	v_bfe_i32 v3, v0, 27, 1
	v_lshlrev_b32_e32 v2, 4, v0
	v_lshrrev_b32_e32 v3, 22, v3
	v_add_u32_e32 v3, v2, v3
	v_and_b32_e32 v3, 0xfffffc00, v3
	v_sub_u32_e32 v3, v2, v3
	v_lshrrev_b32_e32 v4, 4, v3
	v_ashrrev_i32_e32 v1, 31, v0
	v_bitop3_b32 v3, v4, v3, 32 bitop3:0x6c
	v_lshrrev_b32_e32 v1, 26, v1
	v_ashrrev_i32_e32 v5, 31, v3
	v_add_u32_e32 v1, v0, v1
	v_lshrrev_b32_e32 v5, 26, v5
	v_ashrrev_i32_e32 v1, 6, v1
	v_add_u32_e32 v5, v3, v5
	v_lshlrev_b32_e32 v4, 3, v1
	v_ashrrev_i32_e32 v10, 6, v5
	v_and_b32_e32 v5, 0xc0, v5
	v_and_b32_e32 v4, -16, v4
	v_sub_u32_e32 v3, v3, v5
	v_mov_b32_e32 v5, 1
	v_add_u32_e32 v4, v10, v4
	v_ashrrev_i16_sdwa v3, v5, sext(v3) dst_sel:DWORD dst_unused:UNUSED_PAD src0_sel:DWORD src1_sel:BYTE_0
	v_lshlrev_b32_e32 v6, 5, v1
	v_bfe_i32 v11, v3, 0, 16
	v_lshlrev_b32_e32 v3, 1, v4
	v_lshrrev_b32_e32 v7, 2, v4
	v_and_b32_e32 v8, 3, v10
	s_mov_b32 s9, 0x1fffe0
	v_and_b32_e32 v6, 32, v6
	v_and_b32_e32 v3, 24, v3
	v_and_b32_e32 v7, 4, v7
	v_and_or_b32 v8, v4, s9, v8
	v_or3_b32 v3, v8, v7, v3
	v_add_lshl_u32 v6, v6, v11, 1
	v_add_u32_e32 v2, 0x2000, v2
	v_lshl_add_u32 v130, v3, 11, v6
	v_ashrrev_i32_e32 v3, 31, v2
	v_lshrrev_b32_e32 v3, 22, v3
	v_add_u32_e32 v3, v2, v3
	v_ashrrev_i32_e32 v12, 10, v3
	v_mul_i32_i24_e32 v3, 0x400, v12
	v_sub_u32_e32 v2, v2, v3
	v_lshrrev_b32_e32 v3, 4, v2
	v_bitop3_b32 v2, v3, v2, 32 bitop3:0x6c
	s_ashr_i32 s10, s13, 6
	s_ashr_i32 s6, s13, 8
	v_lshl_add_u32 v128, v4, 11, v6
	v_ashrrev_i32_e32 v4, 31, v2
	s_lshl_b32 s31, s10, 10
	v_lshrrev_b32_e32 v4, 26, v4
	s_add_u32 s33, s0, 0xd700000
	v_add_u32_e32 v4, v2, v4
	s_addc_u32 s34, s1, 0
	s_add_i32 s7, s8, s7
	v_lshlrev_b32_e32 v3, 3, v12
	v_ashrrev_i32_e32 v13, 6, v4
	v_and_b32_e32 v4, 0xc0, v4
	s_ashr_i32 s8, s7, 31
	v_and_b32_e32 v3, -16, v3
	v_sub_u32_e32 v2, v2, v4
	s_lshr_b32 s8, s8, 27
	v_add_u32_e32 v3, v13, v3
	v_ashrrev_i16_sdwa v2, v5, sext(v2) dst_sel:DWORD dst_unused:UNUSED_PAD src0_sel:DWORD src1_sel:BYTE_0
	v_and_b32_e32 v5, 3, v13
	s_add_i32 s8, s7, s8
	v_and_or_b32 v5, v3, s9, v5
	s_ashr_i32 s9, s8, 5
	s_and_b32 s8, s8, 0xffe0
	s_sub_i32 s7, s7, s8
	s_bfe_i32 s8, s7, 0x80000
	s_bfe_u32 s8, s8, 0x3000c
	s_add_i32 s8, s7, s8
	s_bfe_i32 s11, s8, 0x80000
	s_and_b32 s8, s8, 0xf8
	s_sub_i32 s7, s7, s8
	s_lshl_b32 s9, s9, 3
	s_sext_i32_i16 s11, s11
	s_sext_i32_i8 s7, s7
	s_lshr_b32 s12, s11, 3
	s_add_i32 s22, s9, s7
	s_ashr_i32 s23, s22, 31
	s_bfe_i64 s[14:15], s[12:13], 0x100000
	s_lshl_b64 s[8:9], s[22:23], 19
	s_lshl_b64 s[14:15], s[14:15], 19
	s_add_u32 s24, s4, s14
	v_lshlrev_b32_e32 v6, 5, v12
	v_bfe_i32 v14, v2, 0, 16
	v_lshlrev_b32_e32 v2, 1, v3
	v_lshrrev_b32_e32 v4, 2, v3
	s_addc_u32 s25, s5, s15
	s_add_i32 s35, s31, 0
	v_and_b32_e32 v6, 32, v6
	v_and_b32_e32 v2, 24, v2
	v_and_b32_e32 v4, 4, v4
	s_add_i32 m0, s35, 0x10000
	v_or3_b32 v2, v5, v4, v2
	v_add_lshl_u32 v4, v6, v14, 1
	global_load_lds_dwordx4 v130, s[24:25]
	s_add_i32 m0, s35, 0x12000
	v_lshl_add_u32 v134, v2, 11, v4
	s_add_u32 s14, s24, 0x40000
	global_load_lds_dwordx4 v134, s[24:25]
	s_addc_u32 s15, s25, 0
	s_add_i32 m0, s35, 0x14000
	v_lshl_add_u32 v132, v3, 11, v4
	global_load_lds_dwordx4 v130, s[14:15]
	s_add_i32 m0, s35, 0x16000
	s_add_u32 s26, s33, s8
	s_addc_u32 s27, s34, s9
	s_add_i32 s36, s35, 0x2000
	global_load_lds_dwordx4 v134, s[14:15]
	s_mov_b32 m0, s35
	s_add_u32 s8, s26, 0x40000
	global_load_lds_dwordx4 v128, s[26:27]
	s_mov_b32 m0, s36
	s_addc_u32 s9, s27, 0
	s_add_i32 s37, s35, 0x4000
	global_load_lds_dwordx4 v132, s[26:27]
	s_mov_b32 m0, s37
	s_add_i32 s38, s35, 0x6000
	global_load_lds_dwordx4 v128, s[8:9]
	s_mov_b32 m0, s38
	v_mov_b32_e32 v131, 0
	global_load_lds_dwordx4 v132, s[8:9]
	v_mov_b32_e32 v135, v131
	v_mov_b32_e32 v129, v131
	v_mov_b32_e32 v133, v131
	s_cmp_eq_u32 s6, 1
	s_mov_b32 s7, 0
	s_mov_b32 s39, 0x10000
	v_lshl_add_u64 v[8:9], s[24:25], 0, v[130:131]
	v_lshl_add_u64 v[6:7], s[24:25], 0, v[134:135]
	v_lshl_add_u64 v[2:3], s[26:27], 0, v[128:129]
	s_cselect_b64 s[8:9], -1, 0
	s_cmp_lg_u32 s6, 1
	v_lshl_add_u64 v[4:5], s[26:27], 0, v[132:133]
	s_cbranch_scc1 .LBB10_10
	s_barrier
	s_setprio 1

.LBB10_19:
	s_ashr_i32 s17, s16, 31
	v_cmp_lt_i64_e32 vcc, s[0:1], v[142:143]
	s_lshl_b64 s[0:1], s[16:17], 19
	s_add_u32 s18, s33, s0
	s_addc_u32 s19, s34, s1
	s_and_b64 s[0:1], vcc, exec
	s_cselect_b32 s17, s19, s27
	s_cselect_b32 s53, s18, s26
	s_ashr_i32 s15, s14, 31
	s_lshl_b64 s[0:1], s[14:15], 19
	s_add_u32 s20, s4, s0
	s_addc_u32 s21, s5, s1
	s_and_b64 s[0:1], vcc, exec
	s_cselect_b32 s15, s21, s25
	s_cselect_b32 s54, s20, s24
	s_add_u32 s55, s24, 0x100
	s_addc_u32 s56, s25, 0
	s_add_u32 s24, s26, 0x40080
	s_addc_u32 s25, s27, 0
	s_mov_b32 s57, -2
	ds_read_b128 v[152:155], v149
	ds_read_b128 v[156:159], v149 offset:1024
	ds_read_b128 v[160:163], v149 offset:2048
	ds_read_b128 v[164:167], v149 offset:3072
	ds_read_b128 v[168:171], v150
	ds_read_b128 v[172:175], v150 offset:1024
	ds_read_b128 v[176:179], v150 offset:2048
	ds_read_b128 v[180:183], v150 offset:3072
	s_add_u32 s26, s24, 0xfffc0080
	s_addc_u32 s27, s25, -1
	s_cmp_eq_u32 s57, 12
	s_cselect_b32 s29, s17, s27
	s_cselect_b32 s28, s53, s26
	s_cselect_b32 s27, s15, s56
	s_cselect_b32 s26, s54, s55
	v_lshl_add_u64 v[146:147], s[24:25], 0, v[140:141]
	s_add_i32 m0, s35, 0xc000
	ds_read_b128 v[184:187], v151
	ds_read_b128 v[188:191], v151 offset:1024
	ds_read_b128 v[192:195], v151 offset:2048
	ds_read_b128 v[196:199], v151 offset:3072
	ds_read_b128 v[200:203], v151 offset:4096
	ds_read_b128 v[204:207], v151 offset:5120
	ds_read_b128 v[208:211], v151 offset:6144
	ds_read_b128 v[212:215], v151 offset:7168
	global_load_lds_dwordx4 v[146:147], off
	v_lshl_add_u64 v[146:147], s[24:25], 0, v[138:139]
	s_add_i32 m0, s35, 0xe000
	s_nop 0
	global_load_lds_dwordx4 v[146:147], off
	s_waitcnt vmcnt(8)
	s_waitcnt lgkmcnt(0)
	s_barrier
	s_waitcnt lgkmcnt(0)
	v_mfma_f32_16x16x32_bf16 v[124:127], v[152:155], v[184:187], 0
	v_mfma_f32_16x16x32_bf16 v[120:123], v[160:163], v[184:187], 0
	v_mfma_f32_16x16x32_bf16 v[116:119], v[152:155], v[192:195], 0
	v_mfma_f32_16x16x32_bf16 v[108:111], v[160:163], v[192:195], 0
	v_mfma_f32_16x16x32_bf16 v[100:103], v[152:155], v[200:203], 0
	v_mfma_f32_16x16x32_bf16 v[92:95], v[160:163], v[200:203], 0
	v_mfma_f32_16x16x32_bf16 v[84:87], v[152:155], v[208:211], 0
	v_mfma_f32_16x16x32_bf16 v[76:79], v[160:163], v[208:211], 0
	v_mfma_f32_16x16x32_bf16 v[124:127], v[156:159], v[188:191], v[124:127]
	v_mfma_f32_16x16x32_bf16 v[120:123], v[164:167], v[188:191], v[120:123]
	v_mfma_f32_16x16x32_bf16 v[116:119], v[156:159], v[196:199], v[116:119]
	v_mfma_f32_16x16x32_bf16 v[108:111], v[164:167], v[196:199], v[108:111]
	v_mfma_f32_16x16x32_bf16 v[100:103], v[156:159], v[204:207], v[100:103]
	v_mfma_f32_16x16x32_bf16 v[92:95], v[164:167], v[204:207], v[92:95]
	v_mfma_f32_16x16x32_bf16 v[84:87], v[156:159], v[212:215], v[84:87]
	v_mfma_f32_16x16x32_bf16 v[76:79], v[164:167], v[212:215], v[76:79]
	v_mfma_f32_16x16x32_bf16 v[112:115], v[168:171], v[184:187], 0
	v_mfma_f32_16x16x32_bf16 v[104:107], v[176:179], v[184:187], 0
	v_mfma_f32_16x16x32_bf16 v[96:99], v[168:171], v[192:195], 0
	v_mfma_f32_16x16x32_bf16 v[88:91], v[176:179], v[192:195], 0
	v_mfma_f32_16x16x32_bf16 v[80:83], v[168:171], v[200:203], 0
	v_mfma_f32_16x16x32_bf16 v[72:75], v[176:179], v[200:203], 0
	v_mfma_f32_16x16x32_bf16 v[68:71], v[168:171], v[208:211], 0
	v_mfma_f32_16x16x32_bf16 v[64:67], v[176:179], v[208:211], 0
	v_mfma_f32_16x16x32_bf16 v[112:115], v[172:175], v[188:191], v[112:115]
	v_mfma_f32_16x16x32_bf16 v[104:107], v[180:183], v[188:191], v[104:107]
	v_mfma_f32_16x16x32_bf16 v[96:99], v[172:175], v[196:199], v[96:99]
	v_mfma_f32_16x16x32_bf16 v[88:91], v[180:183], v[196:199], v[88:91]
	v_mfma_f32_16x16x32_bf16 v[80:83], v[172:175], v[204:207], v[80:83]
	v_mfma_f32_16x16x32_bf16 v[72:75], v[180:183], v[204:207], v[72:75]
	v_mfma_f32_16x16x32_bf16 v[68:71], v[172:175], v[212:215], v[68:71]
	v_mfma_f32_16x16x32_bf16 v[64:67], v[180:183], v[212:215], v[64:67]
	s_barrier
	s_add_i32 s58, s46, s31
	v_lshl_add_u64 v[146:147], s[26:27], 0, v[130:131]
	s_mov_b32 m0, s58
	ds_read_b128 v[184:187], v151 offset:16384
	ds_read_b128 v[188:191], v151 offset:17408
	ds_read_b128 v[192:195], v151 offset:18432
	ds_read_b128 v[196:199], v151 offset:19456
	ds_read_b128 v[200:203], v151 offset:20480
	ds_read_b128 v[204:207], v151 offset:21504
	ds_read_b128 v[208:211], v151 offset:22528
	ds_read_b128 v[212:215], v151 offset:23552
	global_load_lds_dwordx4 v[146:147], off
	s_add_i32 m0, s58, 0x2000
	s_add_u32 s58, s26, 0x40000
	v_lshl_add_u64 v[216:217], s[26:27], 0, v[134:135]
	s_addc_u32 s59, s27, 0
	s_add_i32 s60, s47, s31
	global_load_lds_dwordx4 v[216:217], off
	v_lshl_add_u64 v[218:219], s[58:59], 0, v[130:131]
	s_mov_b32 m0, s60
	v_lshl_add_u64 v[220:221], s[28:29], 0, v[132:133]
	global_load_lds_dwordx4 v[218:219], off
	v_lshl_add_u64 v[218:219], s[58:59], 0, v[134:135]
	s_add_i32 m0, s60, 0x2000
	s_nop 0
	global_load_lds_dwordx4 v[218:219], off
	v_lshl_add_u64 v[218:219], s[28:29], 0, v[128:129]
	s_mov_b32 m0, s35
	s_nop 0
	global_load_lds_dwordx4 v[218:219], off
	s_mov_b32 m0, s36
	s_nop 0
	global_load_lds_dwordx4 v[220:221], off
	s_waitcnt vmcnt(8)
	s_waitcnt lgkmcnt(0)
	s_barrier
	s_waitcnt lgkmcnt(0)
	v_mfma_f32_16x16x32_bf16 v[60:63], v[152:155], v[184:187], 0
	v_mfma_f32_16x16x32_bf16 v[56:59], v[160:163], v[184:187], 0
	v_mfma_f32_16x16x32_bf16 v[52:55], v[152:155], v[192:195], 0
	v_mfma_f32_16x16x32_bf16 v[44:47], v[160:163], v[192:195], 0
	v_mfma_f32_16x16x32_bf16 v[36:39], v[152:155], v[200:203], 0
	v_mfma_f32_16x16x32_bf16 v[28:31], v[160:163], v[200:203], 0
	v_mfma_f32_16x16x32_bf16 v[20:23], v[152:155], v[208:211], 0
	v_mfma_f32_16x16x32_bf16 v[12:15], v[160:163], v[208:211], 0
	v_mfma_f32_16x16x32_bf16 v[60:63], v[156:159], v[188:191], v[60:63]
	v_mfma_f32_16x16x32_bf16 v[56:59], v[164:167], v[188:191], v[56:59]
	v_mfma_f32_16x16x32_bf16 v[52:55], v[156:159], v[196:199], v[52:55]
	v_mfma_f32_16x16x32_bf16 v[44:47], v[164:167], v[196:199], v[44:47]
	v_mfma_f32_16x16x32_bf16 v[36:39], v[156:159], v[204:207], v[36:39]
	v_mfma_f32_16x16x32_bf16 v[28:31], v[164:167], v[204:207], v[28:31]
	v_mfma_f32_16x16x32_bf16 v[20:23], v[156:159], v[212:215], v[20:23]
	v_mfma_f32_16x16x32_bf16 v[12:15], v[164:167], v[212:215], v[12:15]
	v_mfma_f32_16x16x32_bf16 v[48:51], v[168:171], v[184:187], 0
	v_mfma_f32_16x16x32_bf16 v[40:43], v[176:179], v[184:187], 0
	v_mfma_f32_16x16x32_bf16 v[32:35], v[168:171], v[192:195], 0
	v_mfma_f32_16x16x32_bf16 v[24:27], v[176:179], v[192:195], 0
	v_mfma_f32_16x16x32_bf16 v[16:19], v[168:171], v[200:203], 0
	v_mfma_f32_16x16x32_bf16 v[8:11], v[176:179], v[200:203], 0
	v_mfma_f32_16x16x32_bf16 v[4:7], v[168:171], v[208:211], 0
	v_mfma_f32_16x16x32_bf16 v[0:3], v[176:179], v[208:211], 0
	v_mfma_f32_16x16x32_bf16 v[48:51], v[172:175], v[188:191], v[48:51]
	v_mfma_f32_16x16x32_bf16 v[40:43], v[180:183], v[188:191], v[40:43]
	v_mfma_f32_16x16x32_bf16 v[32:35], v[172:175], v[196:199], v[32:35]
	v_mfma_f32_16x16x32_bf16 v[24:27], v[180:183], v[196:199], v[24:27]
	v_mfma_f32_16x16x32_bf16 v[16:19], v[172:175], v[204:207], v[16:19]
	v_mfma_f32_16x16x32_bf16 v[8:11], v[180:183], v[204:207], v[8:11]
	v_mfma_f32_16x16x32_bf16 v[4:7], v[172:175], v[212:215], v[4:7]
	v_mfma_f32_16x16x32_bf16 v[0:3], v[180:183], v[212:215], v[0:3]
	s_barrier
	s_add_i32 s58, 0, 0x18000
	s_add_i32 s59, 0, 0x1c000
	v_add_u32_e32 v164, s58, v148
	v_add_u32_e32 v180, s59, v148
	ds_read_b128 v[152:155], v164
	ds_read_b128 v[156:159], v164 offset:1024
	ds_read_b128 v[160:163], v164 offset:2048
	ds_read_b128 v[164:167], v164 offset:3072
	ds_read_b128 v[168:171], v180
	ds_read_b128 v[172:175], v180 offset:1024
	ds_read_b128 v[176:179], v180 offset:2048
	ds_read_b128 v[180:183], v180 offset:3072
	s_add_u32 s28, s28, 0x40000
	s_addc_u32 s29, s29, 0
	s_mov_b32 m0, s37
	v_lshl_add_u64 v[222:223], s[28:29], 0, v[128:129]
	ds_read_b128 v[184:187], v151 offset:32768
	ds_read_b128 v[188:191], v151 offset:33792
	ds_read_b128 v[192:195], v151 offset:34816
	ds_read_b128 v[196:199], v151 offset:35840
	ds_read_b128 v[200:203], v151 offset:36864
	ds_read_b128 v[204:207], v151 offset:37888
	ds_read_b128 v[208:211], v151 offset:38912
	ds_read_b128 v[212:215], v151 offset:39936
	global_load_lds_dwordx4 v[222:223], off
	v_lshl_add_u64 v[222:223], s[28:29], 0, v[132:133]
	s_mov_b32 m0, s38
	s_nop 0
	global_load_lds_dwordx4 v[222:223], off
	s_waitcnt vmcnt(8)
	s_waitcnt lgkmcnt(0)
	s_barrier
	s_waitcnt lgkmcnt(0)
	v_mfma_f32_16x16x32_bf16 v[124:127], v[152:155], v[184:187], v[124:127]
	v_mfma_f32_16x16x32_bf16 v[120:123], v[160:163], v[184:187], v[120:123]
	v_mfma_f32_16x16x32_bf16 v[116:119], v[152:155], v[192:195], v[116:119]
	v_mfma_f32_16x16x32_bf16 v[108:111], v[160:163], v[192:195], v[108:111]
	v_mfma_f32_16x16x32_bf16 v[100:103], v[152:155], v[200:203], v[100:103]
	v_mfma_f32_16x16x32_bf16 v[92:95], v[160:163], v[200:203], v[92:95]
	v_mfma_f32_16x16x32_bf16 v[84:87], v[152:155], v[208:211], v[84:87]
	v_mfma_f32_16x16x32_bf16 v[76:79], v[160:163], v[208:211], v[76:79]
	v_mfma_f32_16x16x32_bf16 v[124:127], v[156:159], v[188:191], v[124:127]
	v_mfma_f32_16x16x32_bf16 v[120:123], v[164:167], v[188:191], v[120:123]
	v_mfma_f32_16x16x32_bf16 v[116:119], v[156:159], v[196:199], v[116:119]
	v_mfma_f32_16x16x32_bf16 v[108:111], v[164:167], v[196:199], v[108:111]
	v_mfma_f32_16x16x32_bf16 v[100:103], v[156:159], v[204:207], v[100:103]
	v_mfma_f32_16x16x32_bf16 v[92:95], v[164:167], v[204:207], v[92:95]
	v_mfma_f32_16x16x32_bf16 v[84:87], v[156:159], v[212:215], v[84:87]
	v_mfma_f32_16x16x32_bf16 v[76:79], v[164:167], v[212:215], v[76:79]
	v_mfma_f32_16x16x32_bf16 v[112:115], v[168:171], v[184:187], v[112:115]
	v_mfma_f32_16x16x32_bf16 v[104:107], v[176:179], v[184:187], v[104:107]
	v_mfma_f32_16x16x32_bf16 v[96:99], v[168:171], v[192:195], v[96:99]
	v_mfma_f32_16x16x32_bf16 v[88:91], v[176:179], v[192:195], v[88:91]
	v_mfma_f32_16x16x32_bf16 v[80:83], v[168:171], v[200:203], v[80:83]
	v_mfma_f32_16x16x32_bf16 v[72:75], v[176:179], v[200:203], v[72:75]
	v_mfma_f32_16x16x32_bf16 v[68:71], v[168:171], v[208:211], v[68:71]
	v_mfma_f32_16x16x32_bf16 v[64:67], v[176:179], v[208:211], v[64:67]
	v_mfma_f32_16x16x32_bf16 v[112:115], v[172:175], v[188:191], v[112:115]
	v_mfma_f32_16x16x32_bf16 v[104:107], v[180:183], v[188:191], v[104:107]
	v_mfma_f32_16x16x32_bf16 v[96:99], v[172:175], v[196:199], v[96:99]
	v_mfma_f32_16x16x32_bf16 v[88:91], v[180:183], v[196:199], v[88:91]
	v_mfma_f32_16x16x32_bf16 v[80:83], v[172:175], v[204:207], v[80:83]
	v_mfma_f32_16x16x32_bf16 v[72:75], v[180:183], v[204:207], v[72:75]
	v_mfma_f32_16x16x32_bf16 v[68:71], v[172:175], v[212:215], v[68:71]
	v_mfma_f32_16x16x32_bf16 v[64:67], v[180:183], v[212:215], v[64:67]
	s_barrier
	s_add_i32 s28, s58, s31
	v_lshl_add_u64 v[146:147], v[146:147], 0, s[10:11]
	s_mov_b32 m0, s28
	ds_read_b128 v[184:187], v151 offset:49152
	ds_read_b128 v[188:191], v151 offset:50176
	ds_read_b128 v[192:195], v151 offset:51200
	ds_read_b128 v[196:199], v151 offset:52224
	ds_read_b128 v[200:203], v151 offset:53248
	ds_read_b128 v[204:207], v151 offset:54272
	ds_read_b128 v[208:211], v151 offset:55296
	ds_read_b128 v[212:215], v151 offset:56320
	global_load_lds_dwordx4 v[146:147], off
	s_add_i32 m0, s28, 0x2000
	s_add_u32 s26, s26, 0x40080
	v_lshl_add_u64 v[146:147], v[216:217], 0, s[10:11]
	s_addc_u32 s27, s27, 0
	s_add_i32 s28, s59, s31
	global_load_lds_dwordx4 v[146:147], off
	v_lshl_add_u64 v[146:147], s[26:27], 0, v[130:131]
	s_mov_b32 m0, s28
	s_nop 0
	global_load_lds_dwordx4 v[146:147], off
	v_lshl_add_u64 v[146:147], s[26:27], 0, v[134:135]
	s_add_i32 m0, s28, 0x2000
	s_nop 0
	global_load_lds_dwordx4 v[146:147], off
	v_lshl_add_u64 v[146:147], v[218:219], 0, s[10:11]
	s_mov_b32 m0, s41
	s_nop 0
	global_load_lds_dwordx4 v[146:147], off
	v_lshl_add_u64 v[146:147], v[220:221], 0, s[10:11]
	s_mov_b32 m0, s42
	s_nop 0
	global_load_lds_dwordx4 v[146:147], off
	s_waitcnt vmcnt(8)
	s_waitcnt lgkmcnt(0)
	s_barrier
	s_waitcnt lgkmcnt(0)
	v_mfma_f32_16x16x32_bf16 v[60:63], v[152:155], v[184:187], v[60:63]
	v_mfma_f32_16x16x32_bf16 v[56:59], v[160:163], v[184:187], v[56:59]
	v_mfma_f32_16x16x32_bf16 v[52:55], v[152:155], v[192:195], v[52:55]
	v_mfma_f32_16x16x32_bf16 v[44:47], v[160:163], v[192:195], v[44:47]
	v_mfma_f32_16x16x32_bf16 v[36:39], v[152:155], v[200:203], v[36:39]
	v_mfma_f32_16x16x32_bf16 v[28:31], v[160:163], v[200:203], v[28:31]
	v_mfma_f32_16x16x32_bf16 v[20:23], v[152:155], v[208:211], v[20:23]
	v_mfma_f32_16x16x32_bf16 v[12:15], v[160:163], v[208:211], v[12:15]
	v_mfma_f32_16x16x32_bf16 v[60:63], v[156:159], v[188:191], v[60:63]
	v_mfma_f32_16x16x32_bf16 v[56:59], v[164:167], v[188:191], v[56:59]
	v_mfma_f32_16x16x32_bf16 v[52:55], v[156:159], v[196:199], v[52:55]
	v_mfma_f32_16x16x32_bf16 v[44:47], v[164:167], v[196:199], v[44:47]
	v_mfma_f32_16x16x32_bf16 v[36:39], v[156:159], v[204:207], v[36:39]
	v_mfma_f32_16x16x32_bf16 v[28:31], v[164:167], v[204:207], v[28:31]
	v_mfma_f32_16x16x32_bf16 v[20:23], v[156:159], v[212:215], v[20:23]
	v_mfma_f32_16x16x32_bf16 v[12:15], v[164:167], v[212:215], v[12:15]
	v_mfma_f32_16x16x32_bf16 v[48:51], v[168:171], v[184:187], v[48:51]
	v_mfma_f32_16x16x32_bf16 v[40:43], v[176:179], v[184:187], v[40:43]
	v_mfma_f32_16x16x32_bf16 v[32:35], v[168:171], v[192:195], v[32:35]
	v_mfma_f32_16x16x32_bf16 v[24:27], v[176:179], v[192:195], v[24:27]
	v_mfma_f32_16x16x32_bf16 v[16:19], v[168:171], v[200:203], v[16:19]
	v_mfma_f32_16x16x32_bf16 v[8:11], v[176:179], v[200:203], v[8:11]
	v_mfma_f32_16x16x32_bf16 v[4:7], v[168:171], v[208:211], v[4:7]
	v_mfma_f32_16x16x32_bf16 v[0:3], v[176:179], v[208:211], v[0:3]
	v_mfma_f32_16x16x32_bf16 v[48:51], v[172:175], v[188:191], v[48:51]
	v_mfma_f32_16x16x32_bf16 v[40:43], v[180:183], v[188:191], v[40:43]
	v_mfma_f32_16x16x32_bf16 v[32:35], v[172:175], v[196:199], v[32:35]
	v_mfma_f32_16x16x32_bf16 v[24:27], v[180:183], v[196:199], v[24:27]
	v_mfma_f32_16x16x32_bf16 v[16:19], v[172:175], v[204:207], v[16:19]
	v_mfma_f32_16x16x32_bf16 v[8:11], v[180:183], v[204:207], v[8:11]
	v_mfma_f32_16x16x32_bf16 v[4:7], v[172:175], v[212:215], v[4:7]
	v_mfma_f32_16x16x32_bf16 v[0:3], v[180:183], v[212:215], v[0:3]
	s_barrier
	s_add_i32 s57, s57, 2
	s_add_u32 s55, s55, 0x100
	s_addc_u32 s56, s56, 0
	s_add_u32 s24, s24, 0x100
	s_addc_u32 s25, s25, 0
	s_cmp_lt_u32 s57, 14
.LBB10_20:
	ds_read_b128 v[152:155], v149
	ds_read_b128 v[156:159], v149 offset:1024
	ds_read_b128 v[160:163], v149 offset:2048
	ds_read_b128 v[164:167], v149 offset:3072
	ds_read_b128 v[168:171], v150
	ds_read_b128 v[172:175], v150 offset:1024
	ds_read_b128 v[176:179], v150 offset:2048
	ds_read_b128 v[180:183], v150 offset:3072
	s_add_u32 s26, s24, 0xfffc0080
	s_addc_u32 s27, s25, -1
	s_cmp_eq_u32 s57, 12
	s_cselect_b32 s29, s17, s27
	s_cselect_b32 s28, s53, s26
	s_cselect_b32 s27, s15, s56
	s_cselect_b32 s26, s54, s55
	v_lshl_add_u64 v[146:147], s[24:25], 0, v[140:141]
	s_add_i32 m0, s35, 0xc000
	ds_read_b128 v[184:187], v151
	ds_read_b128 v[188:191], v151 offset:1024
	ds_read_b128 v[192:195], v151 offset:2048
	ds_read_b128 v[196:199], v151 offset:3072
	ds_read_b128 v[200:203], v151 offset:4096
	ds_read_b128 v[204:207], v151 offset:5120
	ds_read_b128 v[208:211], v151 offset:6144
	ds_read_b128 v[212:215], v151 offset:7168
	global_load_lds_dwordx4 v[146:147], off
	v_lshl_add_u64 v[146:147], s[24:25], 0, v[138:139]
	s_add_i32 m0, s35, 0xe000
	s_nop 0
	global_load_lds_dwordx4 v[146:147], off
	s_waitcnt vmcnt(8)
	s_waitcnt lgkmcnt(0)
	s_barrier
	s_waitcnt lgkmcnt(0)
	v_mfma_f32_16x16x32_bf16 v[124:127], v[152:155], v[184:187], v[124:127]
	v_mfma_f32_16x16x32_bf16 v[120:123], v[160:163], v[184:187], v[120:123]
	v_mfma_f32_16x16x32_bf16 v[116:119], v[152:155], v[192:195], v[116:119]
	v_mfma_f32_16x16x32_bf16 v[108:111], v[160:163], v[192:195], v[108:111]
	v_mfma_f32_16x16x32_bf16 v[100:103], v[152:155], v[200:203], v[100:103]
	v_mfma_f32_16x16x32_bf16 v[92:95], v[160:163], v[200:203], v[92:95]
	v_mfma_f32_16x16x32_bf16 v[84:87], v[152:155], v[208:211], v[84:87]
	v_mfma_f32_16x16x32_bf16 v[76:79], v[160:163], v[208:211], v[76:79]
	v_mfma_f32_16x16x32_bf16 v[124:127], v[156:159], v[188:191], v[124:127]
	v_mfma_f32_16x16x32_bf16 v[120:123], v[164:167], v[188:191], v[120:123]
	v_mfma_f32_16x16x32_bf16 v[116:119], v[156:159], v[196:199], v[116:119]
	v_mfma_f32_16x16x32_bf16 v[108:111], v[164:167], v[196:199], v[108:111]
	v_mfma_f32_16x16x32_bf16 v[100:103], v[156:159], v[204:207], v[100:103]
	v_mfma_f32_16x16x32_bf16 v[92:95], v[164:167], v[204:207], v[92:95]
	v_mfma_f32_16x16x32_bf16 v[84:87], v[156:159], v[212:215], v[84:87]
	v_mfma_f32_16x16x32_bf16 v[76:79], v[164:167], v[212:215], v[76:79]
	v_mfma_f32_16x16x32_bf16 v[112:115], v[168:171], v[184:187], v[112:115]
	v_mfma_f32_16x16x32_bf16 v[104:107], v[176:179], v[184:187], v[104:107]
	v_mfma_f32_16x16x32_bf16 v[96:99], v[168:171], v[192:195], v[96:99]
	v_mfma_f32_16x16x32_bf16 v[88:91], v[176:179], v[192:195], v[88:91]
	v_mfma_f32_16x16x32_bf16 v[80:83], v[168:171], v[200:203], v[80:83]
	v_mfma_f32_16x16x32_bf16 v[72:75], v[176:179], v[200:203], v[72:75]
	v_mfma_f32_16x16x32_bf16 v[68:71], v[168:171], v[208:211], v[68:71]
	v_mfma_f32_16x16x32_bf16 v[64:67], v[176:179], v[208:211], v[64:67]
	v_mfma_f32_16x16x32_bf16 v[112:115], v[172:175], v[188:191], v[112:115]
	v_mfma_f32_16x16x32_bf16 v[104:107], v[180:183], v[188:191], v[104:107]
	v_mfma_f32_16x16x32_bf16 v[96:99], v[172:175], v[196:199], v[96:99]
	v_mfma_f32_16x16x32_bf16 v[88:91], v[180:183], v[196:199], v[88:91]
	v_mfma_f32_16x16x32_bf16 v[80:83], v[172:175], v[204:207], v[80:83]
	v_mfma_f32_16x16x32_bf16 v[72:75], v[180:183], v[204:207], v[72:75]
	v_mfma_f32_16x16x32_bf16 v[68:71], v[172:175], v[212:215], v[68:71]
	v_mfma_f32_16x16x32_bf16 v[64:67], v[180:183], v[212:215], v[64:67]
	s_barrier
	s_add_i32 s58, s46, s31
	v_lshl_add_u64 v[146:147], s[26:27], 0, v[130:131]
	s_mov_b32 m0, s58
	ds_read_b128 v[184:187], v151 offset:16384
	ds_read_b128 v[188:191], v151 offset:17408
	ds_read_b128 v[192:195], v151 offset:18432
	ds_read_b128 v[196:199], v151 offset:19456
	ds_read_b128 v[200:203], v151 offset:20480
	ds_read_b128 v[204:207], v151 offset:21504
	ds_read_b128 v[208:211], v151 offset:22528
	ds_read_b128 v[212:215], v151 offset:23552
	global_load_lds_dwordx4 v[146:147], off
	s_add_i32 m0, s58, 0x2000
	s_add_u32 s58, s26, 0x40000
	v_lshl_add_u64 v[216:217], s[26:27], 0, v[134:135]
	s_addc_u32 s59, s27, 0
	s_add_i32 s60, s47, s31
	global_load_lds_dwordx4 v[216:217], off
	v_lshl_add_u64 v[218:219], s[58:59], 0, v[130:131]
	s_mov_b32 m0, s60
	v_lshl_add_u64 v[220:221], s[28:29], 0, v[132:133]
	global_load_lds_dwordx4 v[218:219], off
	v_lshl_add_u64 v[218:219], s[58:59], 0, v[134:135]
	s_add_i32 m0, s60, 0x2000
	s_nop 0
	global_load_lds_dwordx4 v[218:219], off
	v_lshl_add_u64 v[218:219], s[28:29], 0, v[128:129]
	s_mov_b32 m0, s35
	s_nop 0
	global_load_lds_dwordx4 v[218:219], off
	s_mov_b32 m0, s36
	s_nop 0
	global_load_lds_dwordx4 v[220:221], off
	s_waitcnt vmcnt(8)
	s_waitcnt lgkmcnt(0)
	s_barrier
	s_waitcnt lgkmcnt(0)
	v_mfma_f32_16x16x32_bf16 v[60:63], v[152:155], v[184:187], v[60:63]
	v_mfma_f32_16x16x32_bf16 v[56:59], v[160:163], v[184:187], v[56:59]
	v_mfma_f32_16x16x32_bf16 v[52:55], v[152:155], v[192:195], v[52:55]
	v_mfma_f32_16x16x32_bf16 v[44:47], v[160:163], v[192:195], v[44:47]
	v_mfma_f32_16x16x32_bf16 v[36:39], v[152:155], v[200:203], v[36:39]
	v_mfma_f32_16x16x32_bf16 v[28:31], v[160:163], v[200:203], v[28:31]
	v_mfma_f32_16x16x32_bf16 v[20:23], v[152:155], v[208:211], v[20:23]
	v_mfma_f32_16x16x32_bf16 v[12:15], v[160:163], v[208:211], v[12:15]
	v_mfma_f32_16x16x32_bf16 v[60:63], v[156:159], v[188:191], v[60:63]
	v_mfma_f32_16x16x32_bf16 v[56:59], v[164:167], v[188:191], v[56:59]
	v_mfma_f32_16x16x32_bf16 v[52:55], v[156:159], v[196:199], v[52:55]
	v_mfma_f32_16x16x32_bf16 v[44:47], v[164:167], v[196:199], v[44:47]
	v_mfma_f32_16x16x32_bf16 v[36:39], v[156:159], v[204:207], v[36:39]
	v_mfma_f32_16x16x32_bf16 v[28:31], v[164:167], v[204:207], v[28:31]
	v_mfma_f32_16x16x32_bf16 v[20:23], v[156:159], v[212:215], v[20:23]
	v_mfma_f32_16x16x32_bf16 v[12:15], v[164:167], v[212:215], v[12:15]
	v_mfma_f32_16x16x32_bf16 v[48:51], v[168:171], v[184:187], v[48:51]
	v_mfma_f32_16x16x32_bf16 v[40:43], v[176:179], v[184:187], v[40:43]
	v_mfma_f32_16x16x32_bf16 v[32:35], v[168:171], v[192:195], v[32:35]
	v_mfma_f32_16x16x32_bf16 v[24:27], v[176:179], v[192:195], v[24:27]
	v_mfma_f32_16x16x32_bf16 v[16:19], v[168:171], v[200:203], v[16:19]
	v_mfma_f32_16x16x32_bf16 v[8:11], v[176:179], v[200:203], v[8:11]
	v_mfma_f32_16x16x32_bf16 v[4:7], v[168:171], v[208:211], v[4:7]
	v_mfma_f32_16x16x32_bf16 v[0:3], v[176:179], v[208:211], v[0:3]
	v_mfma_f32_16x16x32_bf16 v[48:51], v[172:175], v[188:191], v[48:51]
	v_mfma_f32_16x16x32_bf16 v[40:43], v[180:183], v[188:191], v[40:43]
	v_mfma_f32_16x16x32_bf16 v[32:35], v[172:175], v[196:199], v[32:35]
	v_mfma_f32_16x16x32_bf16 v[24:27], v[180:183], v[196:199], v[24:27]
	v_mfma_f32_16x16x32_bf16 v[16:19], v[172:175], v[204:207], v[16:19]
	v_mfma_f32_16x16x32_bf16 v[8:11], v[180:183], v[204:207], v[8:11]
	v_mfma_f32_16x16x32_bf16 v[4:7], v[172:175], v[212:215], v[4:7]
	v_mfma_f32_16x16x32_bf16 v[0:3], v[180:183], v[212:215], v[0:3]
	s_barrier
	s_add_i32 s58, 0, 0x18000
	s_add_i32 s59, 0, 0x1c000
	v_add_u32_e32 v164, s58, v148
	v_add_u32_e32 v180, s59, v148
	ds_read_b128 v[152:155], v164
	ds_read_b128 v[156:159], v164 offset:1024
	ds_read_b128 v[160:163], v164 offset:2048
	ds_read_b128 v[164:167], v164 offset:3072
	ds_read_b128 v[168:171], v180
	ds_read_b128 v[172:175], v180 offset:1024
	ds_read_b128 v[176:179], v180 offset:2048
	ds_read_b128 v[180:183], v180 offset:3072
	s_add_u32 s28, s28, 0x40000
	s_addc_u32 s29, s29, 0
	s_mov_b32 m0, s37
	v_lshl_add_u64 v[222:223], s[28:29], 0, v[128:129]
	ds_read_b128 v[184:187], v151 offset:32768
	ds_read_b128 v[188:191], v151 offset:33792
	ds_read_b128 v[192:195], v151 offset:34816
	ds_read_b128 v[196:199], v151 offset:35840
	ds_read_b128 v[200:203], v151 offset:36864
	ds_read_b128 v[204:207], v151 offset:37888
	ds_read_b128 v[208:211], v151 offset:38912
	ds_read_b128 v[212:215], v151 offset:39936
	global_load_lds_dwordx4 v[222:223], off
	v_lshl_add_u64 v[222:223], s[28:29], 0, v[132:133]
	s_mov_b32 m0, s38
	s_nop 0
	global_load_lds_dwordx4 v[222:223], off
	s_waitcnt vmcnt(8)
	s_waitcnt lgkmcnt(0)
	s_barrier
	s_waitcnt lgkmcnt(0)
	v_mfma_f32_16x16x32_bf16 v[124:127], v[152:155], v[184:187], v[124:127]
	v_mfma_f32_16x16x32_bf16 v[120:123], v[160:163], v[184:187], v[120:123]
	v_mfma_f32_16x16x32_bf16 v[116:119], v[152:155], v[192:195], v[116:119]
	v_mfma_f32_16x16x32_bf16 v[108:111], v[160:163], v[192:195], v[108:111]
	v_mfma_f32_16x16x32_bf16 v[100:103], v[152:155], v[200:203], v[100:103]
	v_mfma_f32_16x16x32_bf16 v[92:95], v[160:163], v[200:203], v[92:95]
	v_mfma_f32_16x16x32_bf16 v[84:87], v[152:155], v[208:211], v[84:87]
	v_mfma_f32_16x16x32_bf16 v[76:79], v[160:163], v[208:211], v[76:79]
	v_mfma_f32_16x16x32_bf16 v[124:127], v[156:159], v[188:191], v[124:127]
	v_mfma_f32_16x16x32_bf16 v[120:123], v[164:167], v[188:191], v[120:123]
	v_mfma_f32_16x16x32_bf16 v[116:119], v[156:159], v[196:199], v[116:119]
	v_mfma_f32_16x16x32_bf16 v[108:111], v[164:167], v[196:199], v[108:111]
	v_mfma_f32_16x16x32_bf16 v[100:103], v[156:159], v[204:207], v[100:103]
	v_mfma_f32_16x16x32_bf16 v[92:95], v[164:167], v[204:207], v[92:95]
	v_mfma_f32_16x16x32_bf16 v[84:87], v[156:159], v[212:215], v[84:87]
	v_mfma_f32_16x16x32_bf16 v[76:79], v[164:167], v[212:215], v[76:79]
	v_mfma_f32_16x16x32_bf16 v[112:115], v[168:171], v[184:187], v[112:115]
	v_mfma_f32_16x16x32_bf16 v[104:107], v[176:179], v[184:187], v[104:107]
	v_mfma_f32_16x16x32_bf16 v[96:99], v[168:171], v[192:195], v[96:99]
	v_mfma_f32_16x16x32_bf16 v[88:91], v[176:179], v[192:195], v[88:91]
	v_mfma_f32_16x16x32_bf16 v[80:83], v[168:171], v[200:203], v[80:83]
	v_mfma_f32_16x16x32_bf16 v[72:75], v[176:179], v[200:203], v[72:75]
	v_mfma_f32_16x16x32_bf16 v[68:71], v[168:171], v[208:211], v[68:71]
	v_mfma_f32_16x16x32_bf16 v[64:67], v[176:179], v[208:211], v[64:67]
	v_mfma_f32_16x16x32_bf16 v[112:115], v[172:175], v[188:191], v[112:115]
	v_mfma_f32_16x16x32_bf16 v[104:107], v[180:183], v[188:191], v[104:107]
	v_mfma_f32_16x16x32_bf16 v[96:99], v[172:175], v[196:199], v[96:99]
	v_mfma_f32_16x16x32_bf16 v[88:91], v[180:183], v[196:199], v[88:91]
	v_mfma_f32_16x16x32_bf16 v[80:83], v[172:175], v[204:207], v[80:83]
	v_mfma_f32_16x16x32_bf16 v[72:75], v[180:183], v[204:207], v[72:75]
	v_mfma_f32_16x16x32_bf16 v[68:71], v[172:175], v[212:215], v[68:71]
	v_mfma_f32_16x16x32_bf16 v[64:67], v[180:183], v[212:215], v[64:67]
	s_barrier
	s_add_i32 s28, s58, s31
	v_lshl_add_u64 v[146:147], v[146:147], 0, s[10:11]
	s_mov_b32 m0, s28
	ds_read_b128 v[184:187], v151 offset:49152
	ds_read_b128 v[188:191], v151 offset:50176
	ds_read_b128 v[192:195], v151 offset:51200
	ds_read_b128 v[196:199], v151 offset:52224
	ds_read_b128 v[200:203], v151 offset:53248
	ds_read_b128 v[204:207], v151 offset:54272
	ds_read_b128 v[208:211], v151 offset:55296
	ds_read_b128 v[212:215], v151 offset:56320
	global_load_lds_dwordx4 v[146:147], off
	s_add_i32 m0, s28, 0x2000
	s_add_u32 s26, s26, 0x40080
	v_lshl_add_u64 v[146:147], v[216:217], 0, s[10:11]
	s_addc_u32 s27, s27, 0
	s_add_i32 s28, s59, s31
	global_load_lds_dwordx4 v[146:147], off
	v_lshl_add_u64 v[146:147], s[26:27], 0, v[130:131]
	s_mov_b32 m0, s28
	s_nop 0
	global_load_lds_dwordx4 v[146:147], off
	v_lshl_add_u64 v[146:147], s[26:27], 0, v[134:135]
	s_add_i32 m0, s28, 0x2000
	s_nop 0
	global_load_lds_dwordx4 v[146:147], off
	v_lshl_add_u64 v[146:147], v[218:219], 0, s[10:11]
	s_mov_b32 m0, s41
	s_nop 0
	global_load_lds_dwordx4 v[146:147], off
	v_lshl_add_u64 v[146:147], v[220:221], 0, s[10:11]
	s_mov_b32 m0, s42
	s_nop 0
	global_load_lds_dwordx4 v[146:147], off
	s_waitcnt vmcnt(8)
	s_waitcnt lgkmcnt(0)
	s_barrier
	s_waitcnt lgkmcnt(0)
	v_mfma_f32_16x16x32_bf16 v[60:63], v[152:155], v[184:187], v[60:63]
	v_mfma_f32_16x16x32_bf16 v[56:59], v[160:163], v[184:187], v[56:59]
	v_mfma_f32_16x16x32_bf16 v[52:55], v[152:155], v[192:195], v[52:55]
	v_mfma_f32_16x16x32_bf16 v[44:47], v[160:163], v[192:195], v[44:47]
	v_mfma_f32_16x16x32_bf16 v[36:39], v[152:155], v[200:203], v[36:39]
	v_mfma_f32_16x16x32_bf16 v[28:31], v[160:163], v[200:203], v[28:31]
	v_mfma_f32_16x16x32_bf16 v[20:23], v[152:155], v[208:211], v[20:23]
	v_mfma_f32_16x16x32_bf16 v[12:15], v[160:163], v[208:211], v[12:15]
	v_mfma_f32_16x16x32_bf16 v[60:63], v[156:159], v[188:191], v[60:63]
	v_mfma_f32_16x16x32_bf16 v[56:59], v[164:167], v[188:191], v[56:59]
	v_mfma_f32_16x16x32_bf16 v[52:55], v[156:159], v[196:199], v[52:55]
	v_mfma_f32_16x16x32_bf16 v[44:47], v[164:167], v[196:199], v[44:47]
	v_mfma_f32_16x16x32_bf16 v[36:39], v[156:159], v[204:207], v[36:39]
	v_mfma_f32_16x16x32_bf16 v[28:31], v[164:167], v[204:207], v[28:31]
	v_mfma_f32_16x16x32_bf16 v[20:23], v[156:159], v[212:215], v[20:23]
	v_mfma_f32_16x16x32_bf16 v[12:15], v[164:167], v[212:215], v[12:15]
	v_mfma_f32_16x16x32_bf16 v[48:51], v[168:171], v[184:187], v[48:51]
	v_mfma_f32_16x16x32_bf16 v[40:43], v[176:179], v[184:187], v[40:43]
	v_mfma_f32_16x16x32_bf16 v[32:35], v[168:171], v[192:195], v[32:35]
	v_mfma_f32_16x16x32_bf16 v[24:27], v[176:179], v[192:195], v[24:27]
	v_mfma_f32_16x16x32_bf16 v[16:19], v[168:171], v[200:203], v[16:19]
	v_mfma_f32_16x16x32_bf16 v[8:11], v[176:179], v[200:203], v[8:11]
	v_mfma_f32_16x16x32_bf16 v[4:7], v[168:171], v[208:211], v[4:7]
	v_mfma_f32_16x16x32_bf16 v[0:3], v[176:179], v[208:211], v[0:3]
	v_mfma_f32_16x16x32_bf16 v[48:51], v[172:175], v[188:191], v[48:51]
	v_mfma_f32_16x16x32_bf16 v[40:43], v[180:183], v[188:191], v[40:43]
	v_mfma_f32_16x16x32_bf16 v[32:35], v[172:175], v[196:199], v[32:35]
	v_mfma_f32_16x16x32_bf16 v[24:27], v[180:183], v[196:199], v[24:27]
	v_mfma_f32_16x16x32_bf16 v[16:19], v[172:175], v[204:207], v[16:19]
	v_mfma_f32_16x16x32_bf16 v[8:11], v[180:183], v[204:207], v[8:11]
	v_mfma_f32_16x16x32_bf16 v[4:7], v[172:175], v[212:215], v[4:7]
	v_mfma_f32_16x16x32_bf16 v[0:3], v[180:183], v[212:215], v[0:3]
	s_barrier
	s_add_i32 s57, s57, 2
	s_add_u32 s55, s55, 0x100
	s_addc_u32 s56, s56, 0
	s_add_u32 s24, s24, 0x100
	s_addc_u32 s25, s25, 0
	s_cmp_lt_u32 s57, 14
	s_cbranch_scc1 .LBB10_20
	s_andn2_b64 vcc, exec, s[12:13]
	s_cbranch_vccnz .LBB10_23
	s_barrier

.Lsmp12_done:
	s_cmpk_gt_i32 s2, 0x3ff
	v_readfirstlane_b32 s11, v0
	s_cbranch_scc1 .LBB12_16
	v_lshlrev_b32_e32 v2, 4, v0
	v_add_u32_e32 v3, 0x2000, v2
	v_ashrrev_i32_e32 v1, 31, v3
	v_lshrrev_b32_e32 v1, 22, v1
	v_add_u32_e32 v1, v3, v1
	v_ashrrev_i32_e32 v1, 10, v1
	v_mul_i32_i24_e32 v4, 0x400, v1
	v_sub_u32_e32 v3, v3, v4
	v_lshrrev_b32_e32 v4, 4, v3
	v_bitop3_b32 v3, v4, v3, 32 bitop3:0x6c
	v_ashrrev_i32_e32 v4, 31, v3
	v_lshrrev_b32_e32 v4, 26, v4
	v_add_u32_e32 v4, v3, v4
	v_lshlrev_b32_e32 v5, 3, v1
	v_ashrrev_i32_e32 v10, 6, v4
	v_and_b32_e32 v5, -16, v5
	v_add_u32_e32 v5, v10, v5
	v_and_b32_e32 v6, 3, v10
	s_mov_b32 s5, 0x1fffe0
	v_lshrrev_b32_e32 v7, 2, v5
	v_lshlrev_b32_e32 v8, 1, v5
	v_and_b32_e32 v4, 0xc0, v4
	v_and_or_b32 v6, v5, s5, v6
	v_and_b32_e32 v7, 4, v7
	v_and_b32_e32 v8, 24, v8
	v_sub_u32_e32 v3, v3, v4
	v_mov_b32_e32 v4, 1
	v_or3_b32 v6, v6, v7, v8
	v_lshlrev_b32_e32 v7, 5, v1
	v_ashrrev_i16_sdwa v3, v4, sext(v3) dst_sel:DWORD dst_unused:UNUSED_PAD src0_sel:DWORD src1_sel:BYTE_0
	v_and_b32_e32 v7, 32, v7
	v_bfe_i32 v11, v3, 0, 16
	v_add_lshl_u32 v3, v7, v11, 1
	v_lshl_add_u32 v128, v6, 11, v3
	v_lshl_add_u32 v130, v5, 11, v3
	v_bfe_i32 v3, v0, 27, 1
	v_lshrrev_b32_e32 v3, 22, v3
	v_add_u32_e32 v3, v2, v3
	s_load_dwordx2 s[0:1], s[0:1], 0xd8
	v_and_b32_e32 v3, 0xfffffc00, v3
	v_sub_u32_e32 v2, v2, v3
	v_lshrrev_b32_e32 v3, 4, v2
	v_ashrrev_i32_e32 v5, 31, v0
	v_bitop3_b32 v2, v3, v2, 32 bitop3:0x6c
	v_lshrrev_b32_e32 v5, 26, v5
	v_ashrrev_i32_e32 v3, 31, v2
	v_add_u32_e32 v5, v0, v5
	s_waitcnt lgkmcnt(0)
	s_add_u32 s28, s0, 0x3100000
	v_lshrrev_b32_e32 v3, 26, v3
	v_ashrrev_i32_e32 v13, 6, v5
	s_addc_u32 s29, s1, 0
	v_add_u32_e32 v3, v2, v3
	v_lshlrev_b32_e32 v5, 3, v13
	s_add_u32 s30, s0, 0x2100000
	v_ashrrev_i32_e32 v12, 6, v3
	v_and_b32_e32 v5, -16, v5
	s_addc_u32 s31, s1, 0
	v_add_u32_e32 v5, v12, v5
	v_and_b32_e32 v6, 3, v12
	s_ashr_i32 s34, s2, 31
	v_and_or_b32 v6, v5, s5, v6
	s_lshr_b32 s5, s34, 29
	s_add_i32 s5, s2, s5
	s_ashr_i32 s4, s11, 6
	s_ashr_i32 s6, s5, 3
	s_and_b32 s5, s5, -8
	s_ashr_i32 s8, s11, 8
	s_lshl_b32 s33, s4, 10
	s_sub_i32 s5, s2, s5
	s_cmp_lt_i32 s5, 0
	s_movk_i32 s35, 0x81
	s_cselect_b32 s7, s35, 0x80
	s_mul_i32 s5, s5, s7
	s_add_i32 s5, s5, s6
	s_ashr_i32 s6, s5, 31
	s_lshr_b32 s6, s6, 25
	s_add_i32 s6, s5, s6
	v_lshrrev_b32_e32 v7, 2, v5
	v_lshlrev_b32_e32 v8, 1, v5
	v_and_b32_e32 v3, 0xc0, v3
	s_ashr_i32 s7, s6, 7
	v_and_b32_e32 v7, 4, v7
	v_and_b32_e32 v8, 24, v8
	v_sub_u32_e32 v2, v2, v3
	s_lshl_b32 s9, s7, 3
	v_or3_b32 v6, v6, v7, v8
	v_lshlrev_b32_e32 v7, 5, v13
	v_ashrrev_i16_sdwa v2, v4, sext(v2) dst_sel:DWORD dst_unused:UNUSED_PAD src0_sel:DWORD src1_sel:BYTE_0
	s_sub_i32 s7, 0x40, s9
	v_and_b32_e32 v7, 32, v7
	v_bfe_i32 v14, v2, 0, 16
	s_min_u32 s12, s7, 8
	s_and_b32 s6, s6, 0xffffff80
	v_add_lshl_u32 v2, v7, v14, 1
	s_sub_i32 s5, s5, s6
	v_cvt_f32_ubyte0_e32 v4, s12
	v_lshl_add_u32 v132, v6, 11, v2
	v_cvt_f32_i32_e32 v3, s5
	v_rcp_iflag_f32_e32 v6, v4
	v_lshl_add_u32 v134, v5, 11, v2
	s_ashr_i32 s6, s5, 30
	s_or_b32 s10, s6, 1
	v_mul_f32_e32 v2, v3, v6
	v_trunc_f32_e32 v2, v2
	v_fma_f32 v3, -v2, v4, v3
	v_cvt_i32_f32_e32 v2, v2
	v_cmp_ge_f32_e64 s[6:7], |v3|, v4
	s_and_b64 s[6:7], s[6:7], exec
	s_cselect_b32 s6, s10, 0
	v_readfirstlane_b32 s7, v2
	s_add_i32 s10, s7, s6
	s_mul_i32 s6, s10, s12
	s_sub_i32 s5, s5, s6
	s_sext_i32_i8 s5, s5
	s_add_i32 s20, s9, s5
	s_ashr_i32 s21, s20, 31
	s_bfe_i64 s[12:13], s[10:11], 0x80000
	s_lshl_b64 s[6:7], s[20:21], 19
	s_lshl_b64 s[12:13], s[12:13], 19
	s_add_u32 s22, s30, s12
	s_addc_u32 s23, s31, s13
	s_add_i32 s36, s33, 0
	s_add_i32 m0, s36, 0x10000
	v_mov_b32_e32 v133, 0
	global_load_lds_dwordx4 v132, s[22:23]
	s_add_i32 m0, s36, 0x12000
	s_add_u32 s12, s22, 0x40000
	global_load_lds_dwordx4 v128, s[22:23]
	s_addc_u32 s13, s23, 0
	s_add_i32 m0, s36, 0x14000
	v_mov_b32_e32 v129, v133
	global_load_lds_dwordx4 v132, s[12:13]
	s_add_i32 m0, s36, 0x16000
	s_add_u32 s24, s28, s6
	s_addc_u32 s25, s29, s7
	s_add_i32 s37, s36, 0x2000
	global_load_lds_dwordx4 v128, s[12:13]
	s_mov_b32 m0, s36
	s_add_u32 s6, s24, 0x40000
	global_load_lds_dwordx4 v134, s[24:25]
	s_mov_b32 m0, s37
	s_addc_u32 s7, s25, 0
	s_add_i32 s38, s36, 0x4000
	global_load_lds_dwordx4 v130, s[24:25]
	s_mov_b32 m0, s38
	s_add_i32 s39, s36, 0x6000
	global_load_lds_dwordx4 v134, s[6:7]
	s_mov_b32 m0, s39
	v_mov_b32_e32 v135, v133
	global_load_lds_dwordx4 v130, s[6:7]
	v_mov_b32_e32 v131, v133
	s_cmp_eq_u32 s8, 1
	s_mov_b32 s5, 0
	v_lshl_add_u64 v[8:9], s[22:23], 0, v[132:133]
	v_lshl_add_u64 v[6:7], s[22:23], 0, v[128:129]
	v_lshl_add_u64 v[2:3], s[24:25], 0, v[134:135]
	s_cselect_b64 s[6:7], -1, 0
	s_cmp_lg_u32 s8, 1
	v_lshl_add_u64 v[4:5], s[24:25], 0, v[130:131]
	s_cbranch_scc1 .LBB12_3
	s_barrier
	s_setprio 1

.LBB12_8:
	s_ashr_i32 s15, s14, 31
	v_cmp_lt_i64_e32 vcc, s[0:1], v[142:143]
	s_lshl_b64 s[0:1], s[14:15], 19
	s_add_u32 s16, s28, s0
	s_addc_u32 s17, s29, s1
	s_and_b64 s[0:1], vcc, exec
	s_cselect_b32 s15, s17, s25
	s_cselect_b32 s54, s16, s24
	s_ashr_i32 s13, s12, 31
	s_lshl_b64 s[0:1], s[12:13], 19
	s_add_u32 s18, s30, s0
	s_addc_u32 s19, s31, s1
	s_and_b64 s[0:1], vcc, exec
	s_cselect_b32 s13, s19, s23
	s_cselect_b32 s55, s18, s22
	s_add_u32 s56, s22, 0x100
	s_addc_u32 s57, s23, 0
	s_add_u32 s22, s24, 0x40080
	s_addc_u32 s23, s25, 0
	s_mov_b32 s58, -2
	ds_read_b128 v[152:155], v149
	ds_read_b128 v[156:159], v149 offset:1024
	ds_read_b128 v[160:163], v149 offset:2048
	ds_read_b128 v[164:167], v149 offset:3072
	ds_read_b128 v[168:171], v150
	ds_read_b128 v[172:175], v150 offset:1024
	ds_read_b128 v[176:179], v150 offset:2048
	ds_read_b128 v[180:183], v150 offset:3072
	s_add_u32 s24, s22, 0xfffc0080
	s_addc_u32 s25, s23, -1
	s_cmp_eq_u32 s58, 12
	s_cselect_b32 s27, s15, s25
	s_cselect_b32 s26, s54, s24
	s_cselect_b32 s25, s13, s57
	s_cselect_b32 s24, s55, s56
	v_lshl_add_u64 v[146:147], s[22:23], 0, v[140:141]
	s_add_i32 m0, s36, 0xc000
	ds_read_b128 v[184:187], v151
	ds_read_b128 v[188:191], v151 offset:1024
	ds_read_b128 v[192:195], v151 offset:2048
	ds_read_b128 v[196:199], v151 offset:3072
	ds_read_b128 v[200:203], v151 offset:4096
	ds_read_b128 v[204:207], v151 offset:5120
	ds_read_b128 v[208:211], v151 offset:6144
	ds_read_b128 v[212:215], v151 offset:7168
	global_load_lds_dwordx4 v[146:147], off
	v_lshl_add_u64 v[146:147], s[22:23], 0, v[138:139]
	s_add_i32 m0, s36, 0xe000
	s_nop 0
	global_load_lds_dwordx4 v[146:147], off
	s_waitcnt vmcnt(8)
	s_waitcnt lgkmcnt(0)
	s_barrier
	s_waitcnt lgkmcnt(0)
	v_mfma_f32_16x16x32_bf16 v[124:127], v[152:155], v[184:187], 0
	v_mfma_f32_16x16x32_bf16 v[120:123], v[160:163], v[184:187], 0
	v_mfma_f32_16x16x32_bf16 v[108:111], v[152:155], v[192:195], 0
	v_mfma_f32_16x16x32_bf16 v[104:107], v[160:163], v[192:195], 0
	v_mfma_f32_16x16x32_bf16 v[92:95], v[152:155], v[200:203], 0
	v_mfma_f32_16x16x32_bf16 v[88:91], v[160:163], v[200:203], 0
	v_mfma_f32_16x16x32_bf16 v[76:79], v[152:155], v[208:211], 0
	v_mfma_f32_16x16x32_bf16 v[72:75], v[160:163], v[208:211], 0
	v_mfma_f32_16x16x32_bf16 v[124:127], v[156:159], v[188:191], v[124:127]
	v_mfma_f32_16x16x32_bf16 v[120:123], v[164:167], v[188:191], v[120:123]
	v_mfma_f32_16x16x32_bf16 v[108:111], v[156:159], v[196:199], v[108:111]
	v_mfma_f32_16x16x32_bf16 v[104:107], v[164:167], v[196:199], v[104:107]
	v_mfma_f32_16x16x32_bf16 v[92:95], v[156:159], v[204:207], v[92:95]
	v_mfma_f32_16x16x32_bf16 v[88:91], v[164:167], v[204:207], v[88:91]
	v_mfma_f32_16x16x32_bf16 v[76:79], v[156:159], v[212:215], v[76:79]
	v_mfma_f32_16x16x32_bf16 v[72:75], v[164:167], v[212:215], v[72:75]
	v_mfma_f32_16x16x32_bf16 v[116:119], v[168:171], v[184:187], 0
	v_mfma_f32_16x16x32_bf16 v[112:115], v[176:179], v[184:187], 0
	v_mfma_f32_16x16x32_bf16 v[100:103], v[168:171], v[192:195], 0
	v_mfma_f32_16x16x32_bf16 v[96:99], v[176:179], v[192:195], 0
	v_mfma_f32_16x16x32_bf16 v[84:87], v[168:171], v[200:203], 0
	v_mfma_f32_16x16x32_bf16 v[80:83], v[176:179], v[200:203], 0
	v_mfma_f32_16x16x32_bf16 v[68:71], v[168:171], v[208:211], 0
	v_mfma_f32_16x16x32_bf16 v[64:67], v[176:179], v[208:211], 0
	v_mfma_f32_16x16x32_bf16 v[116:119], v[172:175], v[188:191], v[116:119]
	v_mfma_f32_16x16x32_bf16 v[112:115], v[180:183], v[188:191], v[112:115]
	v_mfma_f32_16x16x32_bf16 v[100:103], v[172:175], v[196:199], v[100:103]
	v_mfma_f32_16x16x32_bf16 v[96:99], v[180:183], v[196:199], v[96:99]
	v_mfma_f32_16x16x32_bf16 v[84:87], v[172:175], v[204:207], v[84:87]
	v_mfma_f32_16x16x32_bf16 v[80:83], v[180:183], v[204:207], v[80:83]
	v_mfma_f32_16x16x32_bf16 v[68:71], v[172:175], v[212:215], v[68:71]
	v_mfma_f32_16x16x32_bf16 v[64:67], v[180:183], v[212:215], v[64:67]
	s_barrier
	s_add_i32 s59, s44, s33
	v_lshl_add_u64 v[146:147], s[24:25], 0, v[132:133]
	s_mov_b32 m0, s59
	ds_read_b128 v[184:187], v151 offset:16384
	ds_read_b128 v[188:191], v151 offset:17408
	ds_read_b128 v[192:195], v151 offset:18432
	ds_read_b128 v[196:199], v151 offset:19456
	ds_read_b128 v[200:203], v151 offset:20480
	ds_read_b128 v[204:207], v151 offset:21504
	ds_read_b128 v[208:211], v151 offset:22528
	ds_read_b128 v[212:215], v151 offset:23552
	global_load_lds_dwordx4 v[146:147], off
	s_add_i32 m0, s59, 0x2000
	s_add_u32 s60, s24, 0x40000
	v_lshl_add_u64 v[216:217], s[24:25], 0, v[128:129]
	s_addc_u32 s61, s25, 0
	s_add_i32 s59, s45, s33
	global_load_lds_dwordx4 v[216:217], off
	v_lshl_add_u64 v[218:219], s[60:61], 0, v[132:133]
	s_mov_b32 m0, s59
	v_lshl_add_u64 v[220:221], s[26:27], 0, v[130:131]
	global_load_lds_dwordx4 v[218:219], off
	v_lshl_add_u64 v[218:219], s[60:61], 0, v[128:129]
	s_add_i32 m0, s59, 0x2000
	s_nop 0
	global_load_lds_dwordx4 v[218:219], off
	v_lshl_add_u64 v[218:219], s[26:27], 0, v[134:135]
	s_mov_b32 m0, s36
	s_nop 0
	global_load_lds_dwordx4 v[218:219], off
	s_mov_b32 m0, s37
	s_nop 0
	global_load_lds_dwordx4 v[220:221], off
	s_waitcnt vmcnt(8)
	s_waitcnt lgkmcnt(0)
	s_barrier
	s_waitcnt lgkmcnt(0)
	v_mfma_f32_16x16x32_bf16 v[60:63], v[152:155], v[184:187], 0
	v_mfma_f32_16x16x32_bf16 v[56:59], v[160:163], v[184:187], 0
	v_mfma_f32_16x16x32_bf16 v[44:47], v[152:155], v[192:195], 0
	v_mfma_f32_16x16x32_bf16 v[40:43], v[160:163], v[192:195], 0
	v_mfma_f32_16x16x32_bf16 v[28:31], v[152:155], v[200:203], 0
	v_mfma_f32_16x16x32_bf16 v[24:27], v[160:163], v[200:203], 0
	v_mfma_f32_16x16x32_bf16 v[12:15], v[152:155], v[208:211], 0
	v_mfma_f32_16x16x32_bf16 v[8:11], v[160:163], v[208:211], 0
	v_mfma_f32_16x16x32_bf16 v[60:63], v[156:159], v[188:191], v[60:63]
	v_mfma_f32_16x16x32_bf16 v[56:59], v[164:167], v[188:191], v[56:59]
	v_mfma_f32_16x16x32_bf16 v[44:47], v[156:159], v[196:199], v[44:47]
	v_mfma_f32_16x16x32_bf16 v[40:43], v[164:167], v[196:199], v[40:43]
	v_mfma_f32_16x16x32_bf16 v[28:31], v[156:159], v[204:207], v[28:31]
	v_mfma_f32_16x16x32_bf16 v[24:27], v[164:167], v[204:207], v[24:27]
	v_mfma_f32_16x16x32_bf16 v[12:15], v[156:159], v[212:215], v[12:15]
	v_mfma_f32_16x16x32_bf16 v[8:11], v[164:167], v[212:215], v[8:11]
	v_mfma_f32_16x16x32_bf16 v[52:55], v[168:171], v[184:187], 0
	v_mfma_f32_16x16x32_bf16 v[48:51], v[176:179], v[184:187], 0
	v_mfma_f32_16x16x32_bf16 v[36:39], v[168:171], v[192:195], 0
	v_mfma_f32_16x16x32_bf16 v[32:35], v[176:179], v[192:195], 0
	v_mfma_f32_16x16x32_bf16 v[20:23], v[168:171], v[200:203], 0
	v_mfma_f32_16x16x32_bf16 v[16:19], v[176:179], v[200:203], 0
	v_mfma_f32_16x16x32_bf16 v[4:7], v[168:171], v[208:211], 0
	v_mfma_f32_16x16x32_bf16 v[0:3], v[176:179], v[208:211], 0
	v_mfma_f32_16x16x32_bf16 v[52:55], v[172:175], v[188:191], v[52:55]
	v_mfma_f32_16x16x32_bf16 v[48:51], v[180:183], v[188:191], v[48:51]
	v_mfma_f32_16x16x32_bf16 v[36:39], v[172:175], v[196:199], v[36:39]
	v_mfma_f32_16x16x32_bf16 v[32:35], v[180:183], v[196:199], v[32:35]
	v_mfma_f32_16x16x32_bf16 v[20:23], v[172:175], v[204:207], v[20:23]
	v_mfma_f32_16x16x32_bf16 v[16:19], v[180:183], v[204:207], v[16:19]
	v_mfma_f32_16x16x32_bf16 v[4:7], v[172:175], v[212:215], v[4:7]
	v_mfma_f32_16x16x32_bf16 v[0:3], v[180:183], v[212:215], v[0:3]
	s_barrier
	s_add_i32 s59, 0, 0x18000
	s_add_i32 s60, 0, 0x1c000
	v_add_u32_e32 v164, s59, v148
	v_add_u32_e32 v180, s60, v148
	ds_read_b128 v[152:155], v164
	ds_read_b128 v[156:159], v164 offset:1024
	ds_read_b128 v[160:163], v164 offset:2048
	ds_read_b128 v[164:167], v164 offset:3072
	ds_read_b128 v[168:171], v180
	ds_read_b128 v[172:175], v180 offset:1024
	ds_read_b128 v[176:179], v180 offset:2048
	ds_read_b128 v[180:183], v180 offset:3072
	s_add_u32 s26, s26, 0x40000
	s_addc_u32 s27, s27, 0
	s_mov_b32 m0, s38
	v_lshl_add_u64 v[222:223], s[26:27], 0, v[134:135]
	ds_read_b128 v[184:187], v151 offset:32768
	ds_read_b128 v[188:191], v151 offset:33792
	ds_read_b128 v[192:195], v151 offset:34816
	ds_read_b128 v[196:199], v151 offset:35840
	ds_read_b128 v[200:203], v151 offset:36864
	ds_read_b128 v[204:207], v151 offset:37888
	ds_read_b128 v[208:211], v151 offset:38912
	ds_read_b128 v[212:215], v151 offset:39936
	global_load_lds_dwordx4 v[222:223], off
	v_lshl_add_u64 v[222:223], s[26:27], 0, v[130:131]
	s_mov_b32 m0, s39
	s_nop 0
	global_load_lds_dwordx4 v[222:223], off
	s_waitcnt vmcnt(8)
	s_waitcnt lgkmcnt(0)
	s_barrier
	s_waitcnt lgkmcnt(0)
	v_mfma_f32_16x16x32_bf16 v[124:127], v[152:155], v[184:187], v[124:127]
	v_mfma_f32_16x16x32_bf16 v[120:123], v[160:163], v[184:187], v[120:123]
	v_mfma_f32_16x16x32_bf16 v[108:111], v[152:155], v[192:195], v[108:111]
	v_mfma_f32_16x16x32_bf16 v[104:107], v[160:163], v[192:195], v[104:107]
	v_mfma_f32_16x16x32_bf16 v[92:95], v[152:155], v[200:203], v[92:95]
	v_mfma_f32_16x16x32_bf16 v[88:91], v[160:163], v[200:203], v[88:91]
	v_mfma_f32_16x16x32_bf16 v[76:79], v[152:155], v[208:211], v[76:79]
	v_mfma_f32_16x16x32_bf16 v[72:75], v[160:163], v[208:211], v[72:75]
	v_mfma_f32_16x16x32_bf16 v[124:127], v[156:159], v[188:191], v[124:127]
	v_mfma_f32_16x16x32_bf16 v[120:123], v[164:167], v[188:191], v[120:123]
	v_mfma_f32_16x16x32_bf16 v[108:111], v[156:159], v[196:199], v[108:111]
	v_mfma_f32_16x16x32_bf16 v[104:107], v[164:167], v[196:199], v[104:107]
	v_mfma_f32_16x16x32_bf16 v[92:95], v[156:159], v[204:207], v[92:95]
	v_mfma_f32_16x16x32_bf16 v[88:91], v[164:167], v[204:207], v[88:91]
	v_mfma_f32_16x16x32_bf16 v[76:79], v[156:159], v[212:215], v[76:79]
	v_mfma_f32_16x16x32_bf16 v[72:75], v[164:167], v[212:215], v[72:75]
	v_mfma_f32_16x16x32_bf16 v[116:119], v[168:171], v[184:187], v[116:119]
	v_mfma_f32_16x16x32_bf16 v[112:115], v[176:179], v[184:187], v[112:115]
	v_mfma_f32_16x16x32_bf16 v[100:103], v[168:171], v[192:195], v[100:103]
	v_mfma_f32_16x16x32_bf16 v[96:99], v[176:179], v[192:195], v[96:99]
	v_mfma_f32_16x16x32_bf16 v[84:87], v[168:171], v[200:203], v[84:87]
	v_mfma_f32_16x16x32_bf16 v[80:83], v[176:179], v[200:203], v[80:83]
	v_mfma_f32_16x16x32_bf16 v[68:71], v[168:171], v[208:211], v[68:71]
	v_mfma_f32_16x16x32_bf16 v[64:67], v[176:179], v[208:211], v[64:67]
	v_mfma_f32_16x16x32_bf16 v[116:119], v[172:175], v[188:191], v[116:119]
	v_mfma_f32_16x16x32_bf16 v[112:115], v[180:183], v[188:191], v[112:115]
	v_mfma_f32_16x16x32_bf16 v[100:103], v[172:175], v[196:199], v[100:103]
	v_mfma_f32_16x16x32_bf16 v[96:99], v[180:183], v[196:199], v[96:99]
	v_mfma_f32_16x16x32_bf16 v[84:87], v[172:175], v[204:207], v[84:87]
	v_mfma_f32_16x16x32_bf16 v[80:83], v[180:183], v[204:207], v[80:83]
	v_mfma_f32_16x16x32_bf16 v[68:71], v[172:175], v[212:215], v[68:71]
	v_mfma_f32_16x16x32_bf16 v[64:67], v[180:183], v[212:215], v[64:67]
	s_barrier
	s_add_i32 s26, s59, s33
	v_lshl_add_u64 v[146:147], v[146:147], 0, s[8:9]
	s_mov_b32 m0, s26
	ds_read_b128 v[184:187], v151 offset:49152
	ds_read_b128 v[188:191], v151 offset:50176
	ds_read_b128 v[192:195], v151 offset:51200
	ds_read_b128 v[196:199], v151 offset:52224
	ds_read_b128 v[200:203], v151 offset:53248
	ds_read_b128 v[204:207], v151 offset:54272
	ds_read_b128 v[208:211], v151 offset:55296
	ds_read_b128 v[212:215], v151 offset:56320
	global_load_lds_dwordx4 v[146:147], off
	s_add_i32 m0, s26, 0x2000
	s_add_u32 s24, s24, 0x40080
	v_lshl_add_u64 v[146:147], v[216:217], 0, s[8:9]
	s_addc_u32 s25, s25, 0
	s_add_i32 s26, s60, s33
	global_load_lds_dwordx4 v[146:147], off
	v_lshl_add_u64 v[146:147], s[24:25], 0, v[132:133]
	s_mov_b32 m0, s26
	s_nop 0
	global_load_lds_dwordx4 v[146:147], off
	v_lshl_add_u64 v[146:147], s[24:25], 0, v[128:129]
	s_add_i32 m0, s26, 0x2000
	s_nop 0
	global_load_lds_dwordx4 v[146:147], off
	v_lshl_add_u64 v[146:147], v[218:219], 0, s[8:9]
	s_mov_b32 m0, s41
	s_nop 0
	global_load_lds_dwordx4 v[146:147], off
	v_lshl_add_u64 v[146:147], v[220:221], 0, s[8:9]
	s_mov_b32 m0, s42
	s_nop 0
	global_load_lds_dwordx4 v[146:147], off
	s_waitcnt vmcnt(8)
	s_waitcnt lgkmcnt(0)
	s_barrier
	s_waitcnt lgkmcnt(0)
	v_mfma_f32_16x16x32_bf16 v[60:63], v[152:155], v[184:187], v[60:63]
	v_mfma_f32_16x16x32_bf16 v[56:59], v[160:163], v[184:187], v[56:59]
	v_mfma_f32_16x16x32_bf16 v[44:47], v[152:155], v[192:195], v[44:47]
	v_mfma_f32_16x16x32_bf16 v[40:43], v[160:163], v[192:195], v[40:43]
	v_mfma_f32_16x16x32_bf16 v[28:31], v[152:155], v[200:203], v[28:31]
	v_mfma_f32_16x16x32_bf16 v[24:27], v[160:163], v[200:203], v[24:27]
	v_mfma_f32_16x16x32_bf16 v[12:15], v[152:155], v[208:211], v[12:15]
	v_mfma_f32_16x16x32_bf16 v[8:11], v[160:163], v[208:211], v[8:11]
	v_mfma_f32_16x16x32_bf16 v[60:63], v[156:159], v[188:191], v[60:63]
	v_mfma_f32_16x16x32_bf16 v[56:59], v[164:167], v[188:191], v[56:59]
	v_mfma_f32_16x16x32_bf16 v[44:47], v[156:159], v[196:199], v[44:47]
	v_mfma_f32_16x16x32_bf16 v[40:43], v[164:167], v[196:199], v[40:43]
	v_mfma_f32_16x16x32_bf16 v[28:31], v[156:159], v[204:207], v[28:31]
	v_mfma_f32_16x16x32_bf16 v[24:27], v[164:167], v[204:207], v[24:27]
	v_mfma_f32_16x16x32_bf16 v[12:15], v[156:159], v[212:215], v[12:15]
	v_mfma_f32_16x16x32_bf16 v[8:11], v[164:167], v[212:215], v[8:11]
	v_mfma_f32_16x16x32_bf16 v[52:55], v[168:171], v[184:187], v[52:55]
	v_mfma_f32_16x16x32_bf16 v[48:51], v[176:179], v[184:187], v[48:51]
	v_mfma_f32_16x16x32_bf16 v[36:39], v[168:171], v[192:195], v[36:39]
	v_mfma_f32_16x16x32_bf16 v[32:35], v[176:179], v[192:195], v[32:35]
	v_mfma_f32_16x16x32_bf16 v[20:23], v[168:171], v[200:203], v[20:23]
	v_mfma_f32_16x16x32_bf16 v[16:19], v[176:179], v[200:203], v[16:19]
	v_mfma_f32_16x16x32_bf16 v[4:7], v[168:171], v[208:211], v[4:7]
	v_mfma_f32_16x16x32_bf16 v[0:3], v[176:179], v[208:211], v[0:3]
	v_mfma_f32_16x16x32_bf16 v[52:55], v[172:175], v[188:191], v[52:55]
	v_mfma_f32_16x16x32_bf16 v[48:51], v[180:183], v[188:191], v[48:51]
	v_mfma_f32_16x16x32_bf16 v[36:39], v[172:175], v[196:199], v[36:39]
	v_mfma_f32_16x16x32_bf16 v[32:35], v[180:183], v[196:199], v[32:35]
	v_mfma_f32_16x16x32_bf16 v[20:23], v[172:175], v[204:207], v[20:23]
	v_mfma_f32_16x16x32_bf16 v[16:19], v[180:183], v[204:207], v[16:19]
	v_mfma_f32_16x16x32_bf16 v[4:7], v[172:175], v[212:215], v[4:7]
	v_mfma_f32_16x16x32_bf16 v[0:3], v[180:183], v[212:215], v[0:3]
	s_barrier
	s_add_i32 s58, s58, 2
	s_add_u32 s56, s56, 0x100
	s_addc_u32 s57, s57, 0
	s_add_u32 s22, s22, 0x100
	s_addc_u32 s23, s23, 0
	s_cmp_lt_u32 s58, 14
.LBB12_9:
	ds_read_b128 v[152:155], v149
	ds_read_b128 v[156:159], v149 offset:1024
	ds_read_b128 v[160:163], v149 offset:2048
	ds_read_b128 v[164:167], v149 offset:3072
	ds_read_b128 v[168:171], v150
	ds_read_b128 v[172:175], v150 offset:1024
	ds_read_b128 v[176:179], v150 offset:2048
	ds_read_b128 v[180:183], v150 offset:3072
	s_add_u32 s24, s22, 0xfffc0080
	s_addc_u32 s25, s23, -1
	s_cmp_eq_u32 s58, 12
	s_cselect_b32 s27, s15, s25
	s_cselect_b32 s26, s54, s24
	s_cselect_b32 s25, s13, s57
	s_cselect_b32 s24, s55, s56
	v_lshl_add_u64 v[146:147], s[22:23], 0, v[140:141]
	s_add_i32 m0, s36, 0xc000
	ds_read_b128 v[184:187], v151
	ds_read_b128 v[188:191], v151 offset:1024
	ds_read_b128 v[192:195], v151 offset:2048
	ds_read_b128 v[196:199], v151 offset:3072
	ds_read_b128 v[200:203], v151 offset:4096
	ds_read_b128 v[204:207], v151 offset:5120
	ds_read_b128 v[208:211], v151 offset:6144
	ds_read_b128 v[212:215], v151 offset:7168
	global_load_lds_dwordx4 v[146:147], off
	v_lshl_add_u64 v[146:147], s[22:23], 0, v[138:139]
	s_add_i32 m0, s36, 0xe000
	s_nop 0
	global_load_lds_dwordx4 v[146:147], off
	s_waitcnt vmcnt(8)
	s_waitcnt lgkmcnt(0)
	s_barrier
	s_waitcnt lgkmcnt(0)
	v_mfma_f32_16x16x32_bf16 v[124:127], v[152:155], v[184:187], v[124:127]
	v_mfma_f32_16x16x32_bf16 v[120:123], v[160:163], v[184:187], v[120:123]
	v_mfma_f32_16x16x32_bf16 v[108:111], v[152:155], v[192:195], v[108:111]
	v_mfma_f32_16x16x32_bf16 v[104:107], v[160:163], v[192:195], v[104:107]
	v_mfma_f32_16x16x32_bf16 v[92:95], v[152:155], v[200:203], v[92:95]
	v_mfma_f32_16x16x32_bf16 v[88:91], v[160:163], v[200:203], v[88:91]
	v_mfma_f32_16x16x32_bf16 v[76:79], v[152:155], v[208:211], v[76:79]
	v_mfma_f32_16x16x32_bf16 v[72:75], v[160:163], v[208:211], v[72:75]
	v_mfma_f32_16x16x32_bf16 v[124:127], v[156:159], v[188:191], v[124:127]
	v_mfma_f32_16x16x32_bf16 v[120:123], v[164:167], v[188:191], v[120:123]
	v_mfma_f32_16x16x32_bf16 v[108:111], v[156:159], v[196:199], v[108:111]
	v_mfma_f32_16x16x32_bf16 v[104:107], v[164:167], v[196:199], v[104:107]
	v_mfma_f32_16x16x32_bf16 v[92:95], v[156:159], v[204:207], v[92:95]
	v_mfma_f32_16x16x32_bf16 v[88:91], v[164:167], v[204:207], v[88:91]
	v_mfma_f32_16x16x32_bf16 v[76:79], v[156:159], v[212:215], v[76:79]
	v_mfma_f32_16x16x32_bf16 v[72:75], v[164:167], v[212:215], v[72:75]
	v_mfma_f32_16x16x32_bf16 v[116:119], v[168:171], v[184:187], v[116:119]
	v_mfma_f32_16x16x32_bf16 v[112:115], v[176:179], v[184:187], v[112:115]
	v_mfma_f32_16x16x32_bf16 v[100:103], v[168:171], v[192:195], v[100:103]
	v_mfma_f32_16x16x32_bf16 v[96:99], v[176:179], v[192:195], v[96:99]
	v_mfma_f32_16x16x32_bf16 v[84:87], v[168:171], v[200:203], v[84:87]
	v_mfma_f32_16x16x32_bf16 v[80:83], v[176:179], v[200:203], v[80:83]
	v_mfma_f32_16x16x32_bf16 v[68:71], v[168:171], v[208:211], v[68:71]
	v_mfma_f32_16x16x32_bf16 v[64:67], v[176:179], v[208:211], v[64:67]
	v_mfma_f32_16x16x32_bf16 v[116:119], v[172:175], v[188:191], v[116:119]
	v_mfma_f32_16x16x32_bf16 v[112:115], v[180:183], v[188:191], v[112:115]
	v_mfma_f32_16x16x32_bf16 v[100:103], v[172:175], v[196:199], v[100:103]
	v_mfma_f32_16x16x32_bf16 v[96:99], v[180:183], v[196:199], v[96:99]
	v_mfma_f32_16x16x32_bf16 v[84:87], v[172:175], v[204:207], v[84:87]
	v_mfma_f32_16x16x32_bf16 v[80:83], v[180:183], v[204:207], v[80:83]
	v_mfma_f32_16x16x32_bf16 v[68:71], v[172:175], v[212:215], v[68:71]
	v_mfma_f32_16x16x32_bf16 v[64:67], v[180:183], v[212:215], v[64:67]
	s_barrier
	s_add_i32 s59, s44, s33
	v_lshl_add_u64 v[146:147], s[24:25], 0, v[132:133]
	s_mov_b32 m0, s59
	ds_read_b128 v[184:187], v151 offset:16384
	ds_read_b128 v[188:191], v151 offset:17408
	ds_read_b128 v[192:195], v151 offset:18432
	ds_read_b128 v[196:199], v151 offset:19456
	ds_read_b128 v[200:203], v151 offset:20480
	ds_read_b128 v[204:207], v151 offset:21504
	ds_read_b128 v[208:211], v151 offset:22528
	ds_read_b128 v[212:215], v151 offset:23552
	global_load_lds_dwordx4 v[146:147], off
	s_add_i32 m0, s59, 0x2000
	s_add_u32 s60, s24, 0x40000
	v_lshl_add_u64 v[216:217], s[24:25], 0, v[128:129]
	s_addc_u32 s61, s25, 0
	s_add_i32 s59, s45, s33
	global_load_lds_dwordx4 v[216:217], off
	v_lshl_add_u64 v[218:219], s[60:61], 0, v[132:133]
	s_mov_b32 m0, s59
	v_lshl_add_u64 v[220:221], s[26:27], 0, v[130:131]
	global_load_lds_dwordx4 v[218:219], off
	v_lshl_add_u64 v[218:219], s[60:61], 0, v[128:129]
	s_add_i32 m0, s59, 0x2000
	s_nop 0
	global_load_lds_dwordx4 v[218:219], off
	v_lshl_add_u64 v[218:219], s[26:27], 0, v[134:135]
	s_mov_b32 m0, s36
	s_nop 0
	global_load_lds_dwordx4 v[218:219], off
	s_mov_b32 m0, s37
	s_nop 0
	global_load_lds_dwordx4 v[220:221], off
	s_waitcnt vmcnt(8)
	s_waitcnt lgkmcnt(0)
	s_barrier
	s_waitcnt lgkmcnt(0)
	v_mfma_f32_16x16x32_bf16 v[60:63], v[152:155], v[184:187], v[60:63]
	v_mfma_f32_16x16x32_bf16 v[56:59], v[160:163], v[184:187], v[56:59]
	v_mfma_f32_16x16x32_bf16 v[44:47], v[152:155], v[192:195], v[44:47]
	v_mfma_f32_16x16x32_bf16 v[40:43], v[160:163], v[192:195], v[40:43]
	v_mfma_f32_16x16x32_bf16 v[28:31], v[152:155], v[200:203], v[28:31]
	v_mfma_f32_16x16x32_bf16 v[24:27], v[160:163], v[200:203], v[24:27]
	v_mfma_f32_16x16x32_bf16 v[12:15], v[152:155], v[208:211], v[12:15]
	v_mfma_f32_16x16x32_bf16 v[8:11], v[160:163], v[208:211], v[8:11]
	v_mfma_f32_16x16x32_bf16 v[60:63], v[156:159], v[188:191], v[60:63]
	v_mfma_f32_16x16x32_bf16 v[56:59], v[164:167], v[188:191], v[56:59]
	v_mfma_f32_16x16x32_bf16 v[44:47], v[156:159], v[196:199], v[44:47]
	v_mfma_f32_16x16x32_bf16 v[40:43], v[164:167], v[196:199], v[40:43]
	v_mfma_f32_16x16x32_bf16 v[28:31], v[156:159], v[204:207], v[28:31]
	v_mfma_f32_16x16x32_bf16 v[24:27], v[164:167], v[204:207], v[24:27]
	v_mfma_f32_16x16x32_bf16 v[12:15], v[156:159], v[212:215], v[12:15]
	v_mfma_f32_16x16x32_bf16 v[8:11], v[164:167], v[212:215], v[8:11]
	v_mfma_f32_16x16x32_bf16 v[52:55], v[168:171], v[184:187], v[52:55]
	v_mfma_f32_16x16x32_bf16 v[48:51], v[176:179], v[184:187], v[48:51]
	v_mfma_f32_16x16x32_bf16 v[36:39], v[168:171], v[192:195], v[36:39]
	v_mfma_f32_16x16x32_bf16 v[32:35], v[176:179], v[192:195], v[32:35]
	v_mfma_f32_16x16x32_bf16 v[20:23], v[168:171], v[200:203], v[20:23]
	v_mfma_f32_16x16x32_bf16 v[16:19], v[176:179], v[200:203], v[16:19]
	v_mfma_f32_16x16x32_bf16 v[4:7], v[168:171], v[208:211], v[4:7]
	v_mfma_f32_16x16x32_bf16 v[0:3], v[176:179], v[208:211], v[0:3]
	v_mfma_f32_16x16x32_bf16 v[52:55], v[172:175], v[188:191], v[52:55]
	v_mfma_f32_16x16x32_bf16 v[48:51], v[180:183], v[188:191], v[48:51]
	v_mfma_f32_16x16x32_bf16 v[36:39], v[172:175], v[196:199], v[36:39]
	v_mfma_f32_16x16x32_bf16 v[32:35], v[180:183], v[196:199], v[32:35]
	v_mfma_f32_16x16x32_bf16 v[20:23], v[172:175], v[204:207], v[20:23]
	v_mfma_f32_16x16x32_bf16 v[16:19], v[180:183], v[204:207], v[16:19]
	v_mfma_f32_16x16x32_bf16 v[4:7], v[172:175], v[212:215], v[4:7]
	v_mfma_f32_16x16x32_bf16 v[0:3], v[180:183], v[212:215], v[0:3]
	s_barrier
	s_add_i32 s59, 0, 0x18000
	s_add_i32 s60, 0, 0x1c000
	v_add_u32_e32 v164, s59, v148
	v_add_u32_e32 v180, s60, v148
	ds_read_b128 v[152:155], v164
	ds_read_b128 v[156:159], v164 offset:1024
	ds_read_b128 v[160:163], v164 offset:2048
	ds_read_b128 v[164:167], v164 offset:3072
	ds_read_b128 v[168:171], v180
	ds_read_b128 v[172:175], v180 offset:1024
	ds_read_b128 v[176:179], v180 offset:2048
	ds_read_b128 v[180:183], v180 offset:3072
	s_add_u32 s26, s26, 0x40000
	s_addc_u32 s27, s27, 0
	s_mov_b32 m0, s38
	v_lshl_add_u64 v[222:223], s[26:27], 0, v[134:135]
	ds_read_b128 v[184:187], v151 offset:32768
	ds_read_b128 v[188:191], v151 offset:33792
	ds_read_b128 v[192:195], v151 offset:34816
	ds_read_b128 v[196:199], v151 offset:35840
	ds_read_b128 v[200:203], v151 offset:36864
	ds_read_b128 v[204:207], v151 offset:37888
	ds_read_b128 v[208:211], v151 offset:38912
	ds_read_b128 v[212:215], v151 offset:39936
	global_load_lds_dwordx4 v[222:223], off
	v_lshl_add_u64 v[222:223], s[26:27], 0, v[130:131]
	s_mov_b32 m0, s39
	s_nop 0
	global_load_lds_dwordx4 v[222:223], off
	s_waitcnt vmcnt(8)
	s_waitcnt lgkmcnt(0)
	s_barrier
	s_waitcnt lgkmcnt(0)
	v_mfma_f32_16x16x32_bf16 v[124:127], v[152:155], v[184:187], v[124:127]
	v_mfma_f32_16x16x32_bf16 v[120:123], v[160:163], v[184:187], v[120:123]
	v_mfma_f32_16x16x32_bf16 v[108:111], v[152:155], v[192:195], v[108:111]
	v_mfma_f32_16x16x32_bf16 v[104:107], v[160:163], v[192:195], v[104:107]
	v_mfma_f32_16x16x32_bf16 v[92:95], v[152:155], v[200:203], v[92:95]
	v_mfma_f32_16x16x32_bf16 v[88:91], v[160:163], v[200:203], v[88:91]
	v_mfma_f32_16x16x32_bf16 v[76:79], v[152:155], v[208:211], v[76:79]
	v_mfma_f32_16x16x32_bf16 v[72:75], v[160:163], v[208:211], v[72:75]
	v_mfma_f32_16x16x32_bf16 v[124:127], v[156:159], v[188:191], v[124:127]
	v_mfma_f32_16x16x32_bf16 v[120:123], v[164:167], v[188:191], v[120:123]
	v_mfma_f32_16x16x32_bf16 v[108:111], v[156:159], v[196:199], v[108:111]
	v_mfma_f32_16x16x32_bf16 v[104:107], v[164:167], v[196:199], v[104:107]
	v_mfma_f32_16x16x32_bf16 v[92:95], v[156:159], v[204:207], v[92:95]
	v_mfma_f32_16x16x32_bf16 v[88:91], v[164:167], v[204:207], v[88:91]
	v_mfma_f32_16x16x32_bf16 v[76:79], v[156:159], v[212:215], v[76:79]
	v_mfma_f32_16x16x32_bf16 v[72:75], v[164:167], v[212:215], v[72:75]
	v_mfma_f32_16x16x32_bf16 v[116:119], v[168:171], v[184:187], v[116:119]
	v_mfma_f32_16x16x32_bf16 v[112:115], v[176:179], v[184:187], v[112:115]
	v_mfma_f32_16x16x32_bf16 v[100:103], v[168:171], v[192:195], v[100:103]
	v_mfma_f32_16x16x32_bf16 v[96:99], v[176:179], v[192:195], v[96:99]
	v_mfma_f32_16x16x32_bf16 v[84:87], v[168:171], v[200:203], v[84:87]
	v_mfma_f32_16x16x32_bf16 v[80:83], v[176:179], v[200:203], v[80:83]
	v_mfma_f32_16x16x32_bf16 v[68:71], v[168:171], v[208:211], v[68:71]
	v_mfma_f32_16x16x32_bf16 v[64:67], v[176:179], v[208:211], v[64:67]
	v_mfma_f32_16x16x32_bf16 v[116:119], v[172:175], v[188:191], v[116:119]
	v_mfma_f32_16x16x32_bf16 v[112:115], v[180:183], v[188:191], v[112:115]
	v_mfma_f32_16x16x32_bf16 v[100:103], v[172:175], v[196:199], v[100:103]
	v_mfma_f32_16x16x32_bf16 v[96:99], v[180:183], v[196:199], v[96:99]
	v_mfma_f32_16x16x32_bf16 v[84:87], v[172:175], v[204:207], v[84:87]
	v_mfma_f32_16x16x32_bf16 v[80:83], v[180:183], v[204:207], v[80:83]
	v_mfma_f32_16x16x32_bf16 v[68:71], v[172:175], v[212:215], v[68:71]
	v_mfma_f32_16x16x32_bf16 v[64:67], v[180:183], v[212:215], v[64:67]
	s_barrier
	s_add_i32 s26, s59, s33
	v_lshl_add_u64 v[146:147], v[146:147], 0, s[8:9]
	s_mov_b32 m0, s26
	ds_read_b128 v[184:187], v151 offset:49152
	ds_read_b128 v[188:191], v151 offset:50176
	ds_read_b128 v[192:195], v151 offset:51200
	ds_read_b128 v[196:199], v151 offset:52224
	ds_read_b128 v[200:203], v151 offset:53248
	ds_read_b128 v[204:207], v151 offset:54272
	ds_read_b128 v[208:211], v151 offset:55296
	ds_read_b128 v[212:215], v151 offset:56320
	global_load_lds_dwordx4 v[146:147], off
	s_add_i32 m0, s26, 0x2000
	s_add_u32 s24, s24, 0x40080
	v_lshl_add_u64 v[146:147], v[216:217], 0, s[8:9]
	s_addc_u32 s25, s25, 0
	s_add_i32 s26, s60, s33
	global_load_lds_dwordx4 v[146:147], off
	v_lshl_add_u64 v[146:147], s[24:25], 0, v[132:133]
	s_mov_b32 m0, s26
	s_nop 0
	global_load_lds_dwordx4 v[146:147], off
	v_lshl_add_u64 v[146:147], s[24:25], 0, v[128:129]
	s_add_i32 m0, s26, 0x2000
	s_nop 0
	global_load_lds_dwordx4 v[146:147], off
	v_lshl_add_u64 v[146:147], v[218:219], 0, s[8:9]
	s_mov_b32 m0, s41
	s_nop 0
	global_load_lds_dwordx4 v[146:147], off
	v_lshl_add_u64 v[146:147], v[220:221], 0, s[8:9]
	s_mov_b32 m0, s42
	s_nop 0
	global_load_lds_dwordx4 v[146:147], off
	s_waitcnt vmcnt(8)
	s_waitcnt lgkmcnt(0)
	s_barrier
	s_waitcnt lgkmcnt(0)
	v_mfma_f32_16x16x32_bf16 v[60:63], v[152:155], v[184:187], v[60:63]
	v_mfma_f32_16x16x32_bf16 v[56:59], v[160:163], v[184:187], v[56:59]
	v_mfma_f32_16x16x32_bf16 v[44:47], v[152:155], v[192:195], v[44:47]
	v_mfma_f32_16x16x32_bf16 v[40:43], v[160:163], v[192:195], v[40:43]
	v_mfma_f32_16x16x32_bf16 v[28:31], v[152:155], v[200:203], v[28:31]
	v_mfma_f32_16x16x32_bf16 v[24:27], v[160:163], v[200:203], v[24:27]
	v_mfma_f32_16x16x32_bf16 v[12:15], v[152:155], v[208:211], v[12:15]
	v_mfma_f32_16x16x32_bf16 v[8:11], v[160:163], v[208:211], v[8:11]
	v_mfma_f32_16x16x32_bf16 v[60:63], v[156:159], v[188:191], v[60:63]
	v_mfma_f32_16x16x32_bf16 v[56:59], v[164:167], v[188:191], v[56:59]
	v_mfma_f32_16x16x32_bf16 v[44:47], v[156:159], v[196:199], v[44:47]
	v_mfma_f32_16x16x32_bf16 v[40:43], v[164:167], v[196:199], v[40:43]
	v_mfma_f32_16x16x32_bf16 v[28:31], v[156:159], v[204:207], v[28:31]
	v_mfma_f32_16x16x32_bf16 v[24:27], v[164:167], v[204:207], v[24:27]
	v_mfma_f32_16x16x32_bf16 v[12:15], v[156:159], v[212:215], v[12:15]
	v_mfma_f32_16x16x32_bf16 v[8:11], v[164:167], v[212:215], v[8:11]
	v_mfma_f32_16x16x32_bf16 v[52:55], v[168:171], v[184:187], v[52:55]
	v_mfma_f32_16x16x32_bf16 v[48:51], v[176:179], v[184:187], v[48:51]
	v_mfma_f32_16x16x32_bf16 v[36:39], v[168:171], v[192:195], v[36:39]
	v_mfma_f32_16x16x32_bf16 v[32:35], v[176:179], v[192:195], v[32:35]
	v_mfma_f32_16x16x32_bf16 v[20:23], v[168:171], v[200:203], v[20:23]
	v_mfma_f32_16x16x32_bf16 v[16:19], v[176:179], v[200:203], v[16:19]
	v_mfma_f32_16x16x32_bf16 v[4:7], v[168:171], v[208:211], v[4:7]
	v_mfma_f32_16x16x32_bf16 v[0:3], v[176:179], v[208:211], v[0:3]
	v_mfma_f32_16x16x32_bf16 v[52:55], v[172:175], v[188:191], v[52:55]
	v_mfma_f32_16x16x32_bf16 v[48:51], v[180:183], v[188:191], v[48:51]
	v_mfma_f32_16x16x32_bf16 v[36:39], v[172:175], v[196:199], v[36:39]
	v_mfma_f32_16x16x32_bf16 v[32:35], v[180:183], v[196:199], v[32:35]
	v_mfma_f32_16x16x32_bf16 v[20:23], v[172:175], v[204:207], v[20:23]
	v_mfma_f32_16x16x32_bf16 v[16:19], v[180:183], v[204:207], v[16:19]
	v_mfma_f32_16x16x32_bf16 v[4:7], v[172:175], v[212:215], v[4:7]
	v_mfma_f32_16x16x32_bf16 v[0:3], v[180:183], v[212:215], v[0:3]
	s_barrier
	s_add_i32 s58, s58, 2
	s_add_u32 s56, s56, 0x100
	s_addc_u32 s57, s57, 0
	s_add_u32 s22, s22, 0x100
	s_addc_u32 s23, s23, 0
	s_cmp_lt_u32 s58, 14
	s_cbranch_scc1 .LBB12_9
	s_andn2_b64 vcc, exec, s[10:11]
	s_cbranch_vccnz .LBB12_12
	s_barrier

.LBB13_8:
	v_bfe_i32 v3, v0, 27, 1
	v_lshlrev_b32_e32 v2, 4, v0
	v_lshrrev_b32_e32 v3, 22, v3
	v_add_u32_e32 v3, v2, v3
	v_and_b32_e32 v3, 0xfffffc00, v3
	v_sub_u32_e32 v3, v2, v3
	v_lshrrev_b32_e32 v4, 4, v3
	v_ashrrev_i32_e32 v1, 31, v0
	v_bitop3_b32 v3, v4, v3, 32 bitop3:0x6c
	v_lshrrev_b32_e32 v1, 26, v1
	v_ashrrev_i32_e32 v5, 31, v3
	v_add_u32_e32 v1, v0, v1
	v_lshrrev_b32_e32 v5, 26, v5
	v_ashrrev_i32_e32 v1, 6, v1
	v_add_u32_e32 v5, v3, v5
	v_lshlrev_b32_e32 v4, 3, v1
	v_ashrrev_i32_e32 v10, 6, v5
	v_and_b32_e32 v5, 0xc0, v5
	v_and_b32_e32 v4, -16, v4
	v_sub_u32_e32 v3, v3, v5
	v_mov_b32_e32 v5, 1
	v_add_u32_e32 v4, v10, v4
	v_ashrrev_i16_sdwa v3, v5, sext(v3) dst_sel:DWORD dst_unused:UNUSED_PAD src0_sel:DWORD src1_sel:BYTE_0
	v_lshlrev_b32_e32 v6, 5, v1
	v_bfe_i32 v11, v3, 0, 16
	v_lshlrev_b32_e32 v3, 1, v4
	v_lshrrev_b32_e32 v7, 2, v4
	v_and_b32_e32 v8, 3, v10
	s_mov_b32 s9, 0x7ffe0
	v_and_b32_e32 v6, 32, v6
	v_and_b32_e32 v3, 24, v3
	v_and_b32_e32 v7, 4, v7
	v_and_or_b32 v8, v4, s9, v8
	v_or3_b32 v3, v8, v7, v3
	v_add_lshl_u32 v6, v6, v11, 1
	v_add_u32_e32 v2, 0x2000, v2
	v_lshl_add_u32 v130, v3, 13, v6
	v_ashrrev_i32_e32 v3, 31, v2
	v_lshrrev_b32_e32 v3, 22, v3
	v_add_u32_e32 v3, v2, v3
	v_ashrrev_i32_e32 v12, 10, v3
	v_mul_i32_i24_e32 v3, 0x400, v12
	v_sub_u32_e32 v2, v2, v3
	v_lshrrev_b32_e32 v3, 4, v2
	v_bitop3_b32 v2, v3, v2, 32 bitop3:0x6c
	s_ashr_i32 s10, s13, 6
	s_ashr_i32 s6, s13, 8
	v_lshl_add_u32 v128, v4, 13, v6
	v_ashrrev_i32_e32 v4, 31, v2
	s_lshl_b32 s31, s10, 10
	v_lshrrev_b32_e32 v4, 26, v4
	s_add_u32 s33, s0, 0x7400000
	v_add_u32_e32 v4, v2, v4
	s_addc_u32 s34, s1, 0
	s_add_i32 s7, s8, s7
	v_lshlrev_b32_e32 v3, 3, v12
	v_ashrrev_i32_e32 v13, 6, v4
	v_and_b32_e32 v4, 0xc0, v4
	s_ashr_i32 s8, s7, 31
	v_and_b32_e32 v3, -16, v3
	v_sub_u32_e32 v2, v2, v4
	s_lshr_b32 s8, s8, 27
	v_add_u32_e32 v3, v13, v3
	v_ashrrev_i16_sdwa v2, v5, sext(v2) dst_sel:DWORD dst_unused:UNUSED_PAD src0_sel:DWORD src1_sel:BYTE_0
	v_and_b32_e32 v5, 3, v13
	s_add_i32 s8, s7, s8
	v_and_or_b32 v5, v3, s9, v5
	s_ashr_i32 s9, s8, 5
	s_and_b32 s8, s8, 0xffe0
	s_sub_i32 s7, s7, s8
	s_bfe_i32 s8, s7, 0x80000
	s_bfe_u32 s8, s8, 0x3000c
	s_add_i32 s8, s7, s8
	s_bfe_i32 s11, s8, 0x80000
	s_and_b32 s8, s8, 0xf8
	s_sub_i32 s7, s7, s8
	s_lshl_b32 s9, s9, 3
	s_sext_i32_i16 s11, s11
	s_sext_i32_i8 s7, s7
	s_lshr_b32 s12, s11, 3
	s_add_i32 s22, s9, s7
	s_ashr_i32 s23, s22, 31
	s_bfe_i64 s[14:15], s[12:13], 0x100000
	s_lshl_b64 s[8:9], s[22:23], 21
	s_lshl_b64 s[14:15], s[14:15], 21
	s_add_u32 s24, s4, s14
	v_lshlrev_b32_e32 v6, 5, v12
	v_bfe_i32 v14, v2, 0, 16
	v_lshlrev_b32_e32 v2, 1, v3
	v_lshrrev_b32_e32 v4, 2, v3
	s_addc_u32 s25, s5, s15
	s_add_i32 s35, s31, 0
	v_and_b32_e32 v6, 32, v6
	v_and_b32_e32 v2, 24, v2
	v_and_b32_e32 v4, 4, v4
	s_add_i32 m0, s35, 0x10000
	v_or3_b32 v2, v5, v4, v2
	v_add_lshl_u32 v4, v6, v14, 1
	global_load_lds_dwordx4 v130, s[24:25]
	s_add_i32 m0, s35, 0x12000
	v_lshl_add_u32 v134, v2, 13, v4
	s_add_u32 s14, s24, 0x100000
	global_load_lds_dwordx4 v134, s[24:25]
	s_addc_u32 s15, s25, 0
	s_add_i32 m0, s35, 0x14000
	v_lshl_add_u32 v132, v3, 13, v4
	global_load_lds_dwordx4 v130, s[14:15]
	s_add_i32 m0, s35, 0x16000
	s_add_u32 s26, s33, s8
	s_addc_u32 s27, s34, s9
	s_add_i32 s36, s35, 0x2000
	global_load_lds_dwordx4 v134, s[14:15]
	s_mov_b32 m0, s35
	s_add_u32 s8, s26, 0x100000
	global_load_lds_dwordx4 v128, s[26:27]
	s_mov_b32 m0, s36
	s_addc_u32 s9, s27, 0
	s_add_i32 s37, s35, 0x4000
	global_load_lds_dwordx4 v132, s[26:27]
	s_mov_b32 m0, s37
	s_add_i32 s38, s35, 0x6000
	global_load_lds_dwordx4 v128, s[8:9]
	s_mov_b32 m0, s38
	v_mov_b32_e32 v131, 0
	global_load_lds_dwordx4 v132, s[8:9]
	v_mov_b32_e32 v135, v131
	v_mov_b32_e32 v129, v131
	v_mov_b32_e32 v133, v131
	s_cmp_eq_u32 s6, 1
	s_mov_b32 s7, 0
	s_mov_b32 s39, 0x10000
	v_lshl_add_u64 v[8:9], s[24:25], 0, v[130:131]
	v_lshl_add_u64 v[6:7], s[24:25], 0, v[134:135]
	v_lshl_add_u64 v[2:3], s[26:27], 0, v[128:129]
	s_cselect_b64 s[8:9], -1, 0
	s_cmp_lg_u32 s6, 1
	v_lshl_add_u64 v[4:5], s[26:27], 0, v[132:133]
	s_cbranch_scc1 .LBB13_10
	s_barrier
	s_setprio 1

.LBB13_19:
	s_ashr_i32 s17, s16, 31
	v_cmp_lt_i64_e32 vcc, s[0:1], v[142:143]
	s_lshl_b64 s[0:1], s[16:17], 21
	s_add_u32 s18, s33, s0
	s_addc_u32 s19, s34, s1
	s_and_b64 s[0:1], vcc, exec
	s_cselect_b32 s17, s19, s27
	s_cselect_b32 s53, s18, s26
	s_ashr_i32 s15, s14, 31
	s_lshl_b64 s[0:1], s[14:15], 21
	s_add_u32 s20, s4, s0
	s_addc_u32 s21, s5, s1
	s_and_b64 s[0:1], vcc, exec
	s_cselect_b32 s15, s21, s25
	s_cselect_b32 s54, s20, s24
	s_add_u32 s55, s24, 0x100
	s_addc_u32 s56, s25, 0
	s_add_u32 s24, s26, 0x100080
	s_addc_u32 s25, s27, 0
	s_mov_b32 s57, -2
	ds_read_b128 v[152:155], v149
	ds_read_b128 v[156:159], v149 offset:1024
	ds_read_b128 v[160:163], v149 offset:2048
	ds_read_b128 v[164:167], v149 offset:3072
	ds_read_b128 v[168:171], v150
	ds_read_b128 v[172:175], v150 offset:1024
	ds_read_b128 v[176:179], v150 offset:2048
	ds_read_b128 v[180:183], v150 offset:3072
	s_add_u32 s26, s24, 0xfff00080
	s_addc_u32 s27, s25, -1
	s_cmp_eq_u32 s57, 60
	s_cselect_b32 s29, s17, s27
	s_cselect_b32 s28, s53, s26
	s_cselect_b32 s27, s15, s56
	s_cselect_b32 s26, s54, s55
	v_lshl_add_u64 v[146:147], s[24:25], 0, v[140:141]
	s_add_i32 m0, s35, 0xc000
	ds_read_b128 v[184:187], v151
	ds_read_b128 v[188:191], v151 offset:1024
	ds_read_b128 v[192:195], v151 offset:2048
	ds_read_b128 v[196:199], v151 offset:3072
	ds_read_b128 v[200:203], v151 offset:4096
	ds_read_b128 v[204:207], v151 offset:5120
	ds_read_b128 v[208:211], v151 offset:6144
	ds_read_b128 v[212:215], v151 offset:7168
	global_load_lds_dwordx4 v[146:147], off
	v_lshl_add_u64 v[146:147], s[24:25], 0, v[138:139]
	s_add_i32 m0, s35, 0xe000
	s_nop 0
	global_load_lds_dwordx4 v[146:147], off
	s_waitcnt vmcnt(8)
	s_waitcnt lgkmcnt(0)
	s_barrier
	s_waitcnt lgkmcnt(0)
	v_mfma_f32_16x16x32_bf16 v[124:127], v[152:155], v[184:187], 0
	v_mfma_f32_16x16x32_bf16 v[120:123], v[160:163], v[184:187], 0
	v_mfma_f32_16x16x32_bf16 v[116:119], v[152:155], v[192:195], 0
	v_mfma_f32_16x16x32_bf16 v[108:111], v[160:163], v[192:195], 0
	v_mfma_f32_16x16x32_bf16 v[100:103], v[152:155], v[200:203], 0
	v_mfma_f32_16x16x32_bf16 v[92:95], v[160:163], v[200:203], 0
	v_mfma_f32_16x16x32_bf16 v[84:87], v[152:155], v[208:211], 0
	v_mfma_f32_16x16x32_bf16 v[76:79], v[160:163], v[208:211], 0
	v_mfma_f32_16x16x32_bf16 v[124:127], v[156:159], v[188:191], v[124:127]
	v_mfma_f32_16x16x32_bf16 v[120:123], v[164:167], v[188:191], v[120:123]
	v_mfma_f32_16x16x32_bf16 v[116:119], v[156:159], v[196:199], v[116:119]
	v_mfma_f32_16x16x32_bf16 v[108:111], v[164:167], v[196:199], v[108:111]
	v_mfma_f32_16x16x32_bf16 v[100:103], v[156:159], v[204:207], v[100:103]
	v_mfma_f32_16x16x32_bf16 v[92:95], v[164:167], v[204:207], v[92:95]
	v_mfma_f32_16x16x32_bf16 v[84:87], v[156:159], v[212:215], v[84:87]
	v_mfma_f32_16x16x32_bf16 v[76:79], v[164:167], v[212:215], v[76:79]
	v_mfma_f32_16x16x32_bf16 v[112:115], v[168:171], v[184:187], 0
	v_mfma_f32_16x16x32_bf16 v[104:107], v[176:179], v[184:187], 0
	v_mfma_f32_16x16x32_bf16 v[96:99], v[168:171], v[192:195], 0
	v_mfma_f32_16x16x32_bf16 v[88:91], v[176:179], v[192:195], 0
	v_mfma_f32_16x16x32_bf16 v[80:83], v[168:171], v[200:203], 0
	v_mfma_f32_16x16x32_bf16 v[72:75], v[176:179], v[200:203], 0
	v_mfma_f32_16x16x32_bf16 v[68:71], v[168:171], v[208:211], 0
	v_mfma_f32_16x16x32_bf16 v[64:67], v[176:179], v[208:211], 0
	v_mfma_f32_16x16x32_bf16 v[112:115], v[172:175], v[188:191], v[112:115]
	v_mfma_f32_16x16x32_bf16 v[104:107], v[180:183], v[188:191], v[104:107]
	v_mfma_f32_16x16x32_bf16 v[96:99], v[172:175], v[196:199], v[96:99]
	v_mfma_f32_16x16x32_bf16 v[88:91], v[180:183], v[196:199], v[88:91]
	v_mfma_f32_16x16x32_bf16 v[80:83], v[172:175], v[204:207], v[80:83]
	v_mfma_f32_16x16x32_bf16 v[72:75], v[180:183], v[204:207], v[72:75]
	v_mfma_f32_16x16x32_bf16 v[68:71], v[172:175], v[212:215], v[68:71]
	v_mfma_f32_16x16x32_bf16 v[64:67], v[180:183], v[212:215], v[64:67]
	s_barrier
	s_add_i32 s58, s46, s31
	v_lshl_add_u64 v[146:147], s[26:27], 0, v[130:131]
	s_mov_b32 m0, s58
	ds_read_b128 v[184:187], v151 offset:16384
	ds_read_b128 v[188:191], v151 offset:17408
	ds_read_b128 v[192:195], v151 offset:18432
	ds_read_b128 v[196:199], v151 offset:19456
	ds_read_b128 v[200:203], v151 offset:20480
	ds_read_b128 v[204:207], v151 offset:21504
	ds_read_b128 v[208:211], v151 offset:22528
	ds_read_b128 v[212:215], v151 offset:23552
	global_load_lds_dwordx4 v[146:147], off
	s_add_i32 m0, s58, 0x2000
	s_add_u32 s58, s26, 0x100000
	v_lshl_add_u64 v[216:217], s[26:27], 0, v[134:135]
	s_addc_u32 s59, s27, 0
	s_add_i32 s60, s47, s31
	global_load_lds_dwordx4 v[216:217], off
	v_lshl_add_u64 v[218:219], s[58:59], 0, v[130:131]
	s_mov_b32 m0, s60
	v_lshl_add_u64 v[220:221], s[28:29], 0, v[132:133]
	global_load_lds_dwordx4 v[218:219], off
	v_lshl_add_u64 v[218:219], s[58:59], 0, v[134:135]
	s_add_i32 m0, s60, 0x2000
	s_nop 0
	global_load_lds_dwordx4 v[218:219], off
	v_lshl_add_u64 v[218:219], s[28:29], 0, v[128:129]
	s_mov_b32 m0, s35
	s_nop 0
	global_load_lds_dwordx4 v[218:219], off
	s_mov_b32 m0, s36
	s_nop 0
	global_load_lds_dwordx4 v[220:221], off
	s_waitcnt vmcnt(8)
	s_waitcnt lgkmcnt(0)
	s_barrier
	s_waitcnt lgkmcnt(0)
	v_mfma_f32_16x16x32_bf16 v[60:63], v[152:155], v[184:187], 0
	v_mfma_f32_16x16x32_bf16 v[56:59], v[160:163], v[184:187], 0
	v_mfma_f32_16x16x32_bf16 v[52:55], v[152:155], v[192:195], 0
	v_mfma_f32_16x16x32_bf16 v[44:47], v[160:163], v[192:195], 0
	v_mfma_f32_16x16x32_bf16 v[36:39], v[152:155], v[200:203], 0
	v_mfma_f32_16x16x32_bf16 v[28:31], v[160:163], v[200:203], 0
	v_mfma_f32_16x16x32_bf16 v[20:23], v[152:155], v[208:211], 0
	v_mfma_f32_16x16x32_bf16 v[12:15], v[160:163], v[208:211], 0
	v_mfma_f32_16x16x32_bf16 v[60:63], v[156:159], v[188:191], v[60:63]
	v_mfma_f32_16x16x32_bf16 v[56:59], v[164:167], v[188:191], v[56:59]
	v_mfma_f32_16x16x32_bf16 v[52:55], v[156:159], v[196:199], v[52:55]
	v_mfma_f32_16x16x32_bf16 v[44:47], v[164:167], v[196:199], v[44:47]
	v_mfma_f32_16x16x32_bf16 v[36:39], v[156:159], v[204:207], v[36:39]
	v_mfma_f32_16x16x32_bf16 v[28:31], v[164:167], v[204:207], v[28:31]
	v_mfma_f32_16x16x32_bf16 v[20:23], v[156:159], v[212:215], v[20:23]
	v_mfma_f32_16x16x32_bf16 v[12:15], v[164:167], v[212:215], v[12:15]
	v_mfma_f32_16x16x32_bf16 v[48:51], v[168:171], v[184:187], 0
	v_mfma_f32_16x16x32_bf16 v[40:43], v[176:179], v[184:187], 0
	v_mfma_f32_16x16x32_bf16 v[32:35], v[168:171], v[192:195], 0
	v_mfma_f32_16x16x32_bf16 v[24:27], v[176:179], v[192:195], 0
	v_mfma_f32_16x16x32_bf16 v[16:19], v[168:171], v[200:203], 0
	v_mfma_f32_16x16x32_bf16 v[8:11], v[176:179], v[200:203], 0
	v_mfma_f32_16x16x32_bf16 v[4:7], v[168:171], v[208:211], 0
	v_mfma_f32_16x16x32_bf16 v[0:3], v[176:179], v[208:211], 0
	v_mfma_f32_16x16x32_bf16 v[48:51], v[172:175], v[188:191], v[48:51]
	v_mfma_f32_16x16x32_bf16 v[40:43], v[180:183], v[188:191], v[40:43]
	v_mfma_f32_16x16x32_bf16 v[32:35], v[172:175], v[196:199], v[32:35]
	v_mfma_f32_16x16x32_bf16 v[24:27], v[180:183], v[196:199], v[24:27]
	v_mfma_f32_16x16x32_bf16 v[16:19], v[172:175], v[204:207], v[16:19]
	v_mfma_f32_16x16x32_bf16 v[8:11], v[180:183], v[204:207], v[8:11]
	v_mfma_f32_16x16x32_bf16 v[4:7], v[172:175], v[212:215], v[4:7]
	v_mfma_f32_16x16x32_bf16 v[0:3], v[180:183], v[212:215], v[0:3]
	s_barrier
	s_add_i32 s58, 0, 0x18000
	s_add_i32 s59, 0, 0x1c000
	v_add_u32_e32 v164, s58, v148
	v_add_u32_e32 v180, s59, v148
	ds_read_b128 v[152:155], v164
	ds_read_b128 v[156:159], v164 offset:1024
	ds_read_b128 v[160:163], v164 offset:2048
	ds_read_b128 v[164:167], v164 offset:3072
	ds_read_b128 v[168:171], v180
	ds_read_b128 v[172:175], v180 offset:1024
	ds_read_b128 v[176:179], v180 offset:2048
	ds_read_b128 v[180:183], v180 offset:3072
	s_add_u32 s28, s28, 0x100000
	s_addc_u32 s29, s29, 0
	s_mov_b32 m0, s37
	v_lshl_add_u64 v[222:223], s[28:29], 0, v[128:129]
	ds_read_b128 v[184:187], v151 offset:32768
	ds_read_b128 v[188:191], v151 offset:33792
	ds_read_b128 v[192:195], v151 offset:34816
	ds_read_b128 v[196:199], v151 offset:35840
	ds_read_b128 v[200:203], v151 offset:36864
	ds_read_b128 v[204:207], v151 offset:37888
	ds_read_b128 v[208:211], v151 offset:38912
	ds_read_b128 v[212:215], v151 offset:39936
	global_load_lds_dwordx4 v[222:223], off
	v_lshl_add_u64 v[222:223], s[28:29], 0, v[132:133]
	s_mov_b32 m0, s38
	s_nop 0
	global_load_lds_dwordx4 v[222:223], off
	s_waitcnt vmcnt(8)
	s_waitcnt lgkmcnt(0)
	s_barrier
	s_waitcnt lgkmcnt(0)
	v_mfma_f32_16x16x32_bf16 v[124:127], v[152:155], v[184:187], v[124:127]
	v_mfma_f32_16x16x32_bf16 v[120:123], v[160:163], v[184:187], v[120:123]
	v_mfma_f32_16x16x32_bf16 v[116:119], v[152:155], v[192:195], v[116:119]
	v_mfma_f32_16x16x32_bf16 v[108:111], v[160:163], v[192:195], v[108:111]
	v_mfma_f32_16x16x32_bf16 v[100:103], v[152:155], v[200:203], v[100:103]
	v_mfma_f32_16x16x32_bf16 v[92:95], v[160:163], v[200:203], v[92:95]
	v_mfma_f32_16x16x32_bf16 v[84:87], v[152:155], v[208:211], v[84:87]
	v_mfma_f32_16x16x32_bf16 v[76:79], v[160:163], v[208:211], v[76:79]
	v_mfma_f32_16x16x32_bf16 v[124:127], v[156:159], v[188:191], v[124:127]
	v_mfma_f32_16x16x32_bf16 v[120:123], v[164:167], v[188:191], v[120:123]
	v_mfma_f32_16x16x32_bf16 v[116:119], v[156:159], v[196:199], v[116:119]
	v_mfma_f32_16x16x32_bf16 v[108:111], v[164:167], v[196:199], v[108:111]
	v_mfma_f32_16x16x32_bf16 v[100:103], v[156:159], v[204:207], v[100:103]
	v_mfma_f32_16x16x32_bf16 v[92:95], v[164:167], v[204:207], v[92:95]
	v_mfma_f32_16x16x32_bf16 v[84:87], v[156:159], v[212:215], v[84:87]
	v_mfma_f32_16x16x32_bf16 v[76:79], v[164:167], v[212:215], v[76:79]
	v_mfma_f32_16x16x32_bf16 v[112:115], v[168:171], v[184:187], v[112:115]
	v_mfma_f32_16x16x32_bf16 v[104:107], v[176:179], v[184:187], v[104:107]
	v_mfma_f32_16x16x32_bf16 v[96:99], v[168:171], v[192:195], v[96:99]
	v_mfma_f32_16x16x32_bf16 v[88:91], v[176:179], v[192:195], v[88:91]
	v_mfma_f32_16x16x32_bf16 v[80:83], v[168:171], v[200:203], v[80:83]
	v_mfma_f32_16x16x32_bf16 v[72:75], v[176:179], v[200:203], v[72:75]
	v_mfma_f32_16x16x32_bf16 v[68:71], v[168:171], v[208:211], v[68:71]
	v_mfma_f32_16x16x32_bf16 v[64:67], v[176:179], v[208:211], v[64:67]
	v_mfma_f32_16x16x32_bf16 v[112:115], v[172:175], v[188:191], v[112:115]
	v_mfma_f32_16x16x32_bf16 v[104:107], v[180:183], v[188:191], v[104:107]
	v_mfma_f32_16x16x32_bf16 v[96:99], v[172:175], v[196:199], v[96:99]
	v_mfma_f32_16x16x32_bf16 v[88:91], v[180:183], v[196:199], v[88:91]
	v_mfma_f32_16x16x32_bf16 v[80:83], v[172:175], v[204:207], v[80:83]
	v_mfma_f32_16x16x32_bf16 v[72:75], v[180:183], v[204:207], v[72:75]
	v_mfma_f32_16x16x32_bf16 v[68:71], v[172:175], v[212:215], v[68:71]
	v_mfma_f32_16x16x32_bf16 v[64:67], v[180:183], v[212:215], v[64:67]
	s_barrier
	s_add_i32 s28, s58, s31
	v_lshl_add_u64 v[146:147], v[146:147], 0, s[10:11]
	s_mov_b32 m0, s28
	ds_read_b128 v[184:187], v151 offset:49152
	ds_read_b128 v[188:191], v151 offset:50176
	ds_read_b128 v[192:195], v151 offset:51200
	ds_read_b128 v[196:199], v151 offset:52224
	ds_read_b128 v[200:203], v151 offset:53248
	ds_read_b128 v[204:207], v151 offset:54272
	ds_read_b128 v[208:211], v151 offset:55296
	ds_read_b128 v[212:215], v151 offset:56320
	global_load_lds_dwordx4 v[146:147], off
	s_add_i32 m0, s28, 0x2000
	s_add_u32 s26, s26, 0x100080
	v_lshl_add_u64 v[146:147], v[216:217], 0, s[10:11]
	s_addc_u32 s27, s27, 0
	s_add_i32 s28, s59, s31
	global_load_lds_dwordx4 v[146:147], off
	v_lshl_add_u64 v[146:147], s[26:27], 0, v[130:131]
	s_mov_b32 m0, s28
	s_nop 0
	global_load_lds_dwordx4 v[146:147], off
	v_lshl_add_u64 v[146:147], s[26:27], 0, v[134:135]
	s_add_i32 m0, s28, 0x2000
	s_nop 0
	global_load_lds_dwordx4 v[146:147], off
	v_lshl_add_u64 v[146:147], v[218:219], 0, s[10:11]
	s_mov_b32 m0, s41
	s_nop 0
	global_load_lds_dwordx4 v[146:147], off
	v_lshl_add_u64 v[146:147], v[220:221], 0, s[10:11]
	s_mov_b32 m0, s42
	s_nop 0
	global_load_lds_dwordx4 v[146:147], off
	s_waitcnt vmcnt(8)
	s_waitcnt lgkmcnt(0)
	s_barrier
	s_waitcnt lgkmcnt(0)
	v_mfma_f32_16x16x32_bf16 v[60:63], v[152:155], v[184:187], v[60:63]
	v_mfma_f32_16x16x32_bf16 v[56:59], v[160:163], v[184:187], v[56:59]
	v_mfma_f32_16x16x32_bf16 v[52:55], v[152:155], v[192:195], v[52:55]
	v_mfma_f32_16x16x32_bf16 v[44:47], v[160:163], v[192:195], v[44:47]
	v_mfma_f32_16x16x32_bf16 v[36:39], v[152:155], v[200:203], v[36:39]
	v_mfma_f32_16x16x32_bf16 v[28:31], v[160:163], v[200:203], v[28:31]
	v_mfma_f32_16x16x32_bf16 v[20:23], v[152:155], v[208:211], v[20:23]
	v_mfma_f32_16x16x32_bf16 v[12:15], v[160:163], v[208:211], v[12:15]
	v_mfma_f32_16x16x32_bf16 v[60:63], v[156:159], v[188:191], v[60:63]
	v_mfma_f32_16x16x32_bf16 v[56:59], v[164:167], v[188:191], v[56:59]
	v_mfma_f32_16x16x32_bf16 v[52:55], v[156:159], v[196:199], v[52:55]
	v_mfma_f32_16x16x32_bf16 v[44:47], v[164:167], v[196:199], v[44:47]
	v_mfma_f32_16x16x32_bf16 v[36:39], v[156:159], v[204:207], v[36:39]
	v_mfma_f32_16x16x32_bf16 v[28:31], v[164:167], v[204:207], v[28:31]
	v_mfma_f32_16x16x32_bf16 v[20:23], v[156:159], v[212:215], v[20:23]
	v_mfma_f32_16x16x32_bf16 v[12:15], v[164:167], v[212:215], v[12:15]
	v_mfma_f32_16x16x32_bf16 v[48:51], v[168:171], v[184:187], v[48:51]
	v_mfma_f32_16x16x32_bf16 v[40:43], v[176:179], v[184:187], v[40:43]
	v_mfma_f32_16x16x32_bf16 v[32:35], v[168:171], v[192:195], v[32:35]
	v_mfma_f32_16x16x32_bf16 v[24:27], v[176:179], v[192:195], v[24:27]
	v_mfma_f32_16x16x32_bf16 v[16:19], v[168:171], v[200:203], v[16:19]
	v_mfma_f32_16x16x32_bf16 v[8:11], v[176:179], v[200:203], v[8:11]
	v_mfma_f32_16x16x32_bf16 v[4:7], v[168:171], v[208:211], v[4:7]
	v_mfma_f32_16x16x32_bf16 v[0:3], v[176:179], v[208:211], v[0:3]
	v_mfma_f32_16x16x32_bf16 v[48:51], v[172:175], v[188:191], v[48:51]
	v_mfma_f32_16x16x32_bf16 v[40:43], v[180:183], v[188:191], v[40:43]
	v_mfma_f32_16x16x32_bf16 v[32:35], v[172:175], v[196:199], v[32:35]
	v_mfma_f32_16x16x32_bf16 v[24:27], v[180:183], v[196:199], v[24:27]
	v_mfma_f32_16x16x32_bf16 v[16:19], v[172:175], v[204:207], v[16:19]
	v_mfma_f32_16x16x32_bf16 v[8:11], v[180:183], v[204:207], v[8:11]
	v_mfma_f32_16x16x32_bf16 v[4:7], v[172:175], v[212:215], v[4:7]
	v_mfma_f32_16x16x32_bf16 v[0:3], v[180:183], v[212:215], v[0:3]
	s_barrier
	s_add_i32 s57, s57, 2
	s_add_u32 s55, s55, 0x100
	s_addc_u32 s56, s56, 0
	s_add_u32 s24, s24, 0x100
	s_addc_u32 s25, s25, 0
	s_cmp_lt_u32 s57, 62
.LBB13_20:
	ds_read_b128 v[152:155], v149
	ds_read_b128 v[156:159], v149 offset:1024
	ds_read_b128 v[160:163], v149 offset:2048
	ds_read_b128 v[164:167], v149 offset:3072
	ds_read_b128 v[168:171], v150
	ds_read_b128 v[172:175], v150 offset:1024
	ds_read_b128 v[176:179], v150 offset:2048
	ds_read_b128 v[180:183], v150 offset:3072
	s_add_u32 s26, s24, 0xfff00080
	s_addc_u32 s27, s25, -1
	s_cmp_eq_u32 s57, 60
	s_cselect_b32 s29, s17, s27
	s_cselect_b32 s28, s53, s26
	s_cselect_b32 s27, s15, s56
	s_cselect_b32 s26, s54, s55
	v_lshl_add_u64 v[146:147], s[24:25], 0, v[140:141]
	s_add_i32 m0, s35, 0xc000
	ds_read_b128 v[184:187], v151
	ds_read_b128 v[188:191], v151 offset:1024
	ds_read_b128 v[192:195], v151 offset:2048
	ds_read_b128 v[196:199], v151 offset:3072
	ds_read_b128 v[200:203], v151 offset:4096
	ds_read_b128 v[204:207], v151 offset:5120
	ds_read_b128 v[208:211], v151 offset:6144
	ds_read_b128 v[212:215], v151 offset:7168
	global_load_lds_dwordx4 v[146:147], off
	v_lshl_add_u64 v[146:147], s[24:25], 0, v[138:139]
	s_add_i32 m0, s35, 0xe000
	s_nop 0
	global_load_lds_dwordx4 v[146:147], off
	s_waitcnt vmcnt(8)
	s_waitcnt lgkmcnt(0)
	s_barrier
	s_waitcnt lgkmcnt(0)
	v_mfma_f32_16x16x32_bf16 v[124:127], v[152:155], v[184:187], v[124:127]
	v_mfma_f32_16x16x32_bf16 v[120:123], v[160:163], v[184:187], v[120:123]
	v_mfma_f32_16x16x32_bf16 v[116:119], v[152:155], v[192:195], v[116:119]
	v_mfma_f32_16x16x32_bf16 v[108:111], v[160:163], v[192:195], v[108:111]
	v_mfma_f32_16x16x32_bf16 v[100:103], v[152:155], v[200:203], v[100:103]
	v_mfma_f32_16x16x32_bf16 v[92:95], v[160:163], v[200:203], v[92:95]
	v_mfma_f32_16x16x32_bf16 v[84:87], v[152:155], v[208:211], v[84:87]
	v_mfma_f32_16x16x32_bf16 v[76:79], v[160:163], v[208:211], v[76:79]
	v_mfma_f32_16x16x32_bf16 v[124:127], v[156:159], v[188:191], v[124:127]
	v_mfma_f32_16x16x32_bf16 v[120:123], v[164:167], v[188:191], v[120:123]
	v_mfma_f32_16x16x32_bf16 v[116:119], v[156:159], v[196:199], v[116:119]
	v_mfma_f32_16x16x32_bf16 v[108:111], v[164:167], v[196:199], v[108:111]
	v_mfma_f32_16x16x32_bf16 v[100:103], v[156:159], v[204:207], v[100:103]
	v_mfma_f32_16x16x32_bf16 v[92:95], v[164:167], v[204:207], v[92:95]
	v_mfma_f32_16x16x32_bf16 v[84:87], v[156:159], v[212:215], v[84:87]
	v_mfma_f32_16x16x32_bf16 v[76:79], v[164:167], v[212:215], v[76:79]
	v_mfma_f32_16x16x32_bf16 v[112:115], v[168:171], v[184:187], v[112:115]
	v_mfma_f32_16x16x32_bf16 v[104:107], v[176:179], v[184:187], v[104:107]
	v_mfma_f32_16x16x32_bf16 v[96:99], v[168:171], v[192:195], v[96:99]
	v_mfma_f32_16x16x32_bf16 v[88:91], v[176:179], v[192:195], v[88:91]
	v_mfma_f32_16x16x32_bf16 v[80:83], v[168:171], v[200:203], v[80:83]
	v_mfma_f32_16x16x32_bf16 v[72:75], v[176:179], v[200:203], v[72:75]
	v_mfma_f32_16x16x32_bf16 v[68:71], v[168:171], v[208:211], v[68:71]
	v_mfma_f32_16x16x32_bf16 v[64:67], v[176:179], v[208:211], v[64:67]
	v_mfma_f32_16x16x32_bf16 v[112:115], v[172:175], v[188:191], v[112:115]
	v_mfma_f32_16x16x32_bf16 v[104:107], v[180:183], v[188:191], v[104:107]
	v_mfma_f32_16x16x32_bf16 v[96:99], v[172:175], v[196:199], v[96:99]
	v_mfma_f32_16x16x32_bf16 v[88:91], v[180:183], v[196:199], v[88:91]
	v_mfma_f32_16x16x32_bf16 v[80:83], v[172:175], v[204:207], v[80:83]
	v_mfma_f32_16x16x32_bf16 v[72:75], v[180:183], v[204:207], v[72:75]
	v_mfma_f32_16x16x32_bf16 v[68:71], v[172:175], v[212:215], v[68:71]
	v_mfma_f32_16x16x32_bf16 v[64:67], v[180:183], v[212:215], v[64:67]
	s_barrier
	s_add_i32 s58, s46, s31
	v_lshl_add_u64 v[146:147], s[26:27], 0, v[130:131]
	s_mov_b32 m0, s58
	ds_read_b128 v[184:187], v151 offset:16384
	ds_read_b128 v[188:191], v151 offset:17408
	ds_read_b128 v[192:195], v151 offset:18432
	ds_read_b128 v[196:199], v151 offset:19456
	ds_read_b128 v[200:203], v151 offset:20480
	ds_read_b128 v[204:207], v151 offset:21504
	ds_read_b128 v[208:211], v151 offset:22528
	ds_read_b128 v[212:215], v151 offset:23552
	global_load_lds_dwordx4 v[146:147], off
	s_add_i32 m0, s58, 0x2000
	s_add_u32 s58, s26, 0x100000
	v_lshl_add_u64 v[216:217], s[26:27], 0, v[134:135]
	s_addc_u32 s59, s27, 0
	s_add_i32 s60, s47, s31
	global_load_lds_dwordx4 v[216:217], off
	v_lshl_add_u64 v[218:219], s[58:59], 0, v[130:131]
	s_mov_b32 m0, s60
	v_lshl_add_u64 v[220:221], s[28:29], 0, v[132:133]
	global_load_lds_dwordx4 v[218:219], off
	v_lshl_add_u64 v[218:219], s[58:59], 0, v[134:135]
	s_add_i32 m0, s60, 0x2000
	s_nop 0
	global_load_lds_dwordx4 v[218:219], off
	v_lshl_add_u64 v[218:219], s[28:29], 0, v[128:129]
	s_mov_b32 m0, s35
	s_nop 0
	global_load_lds_dwordx4 v[218:219], off
	s_mov_b32 m0, s36
	s_nop 0
	global_load_lds_dwordx4 v[220:221], off
	s_waitcnt vmcnt(8)
	s_waitcnt lgkmcnt(0)
	s_barrier
	s_waitcnt lgkmcnt(0)
	v_mfma_f32_16x16x32_bf16 v[60:63], v[152:155], v[184:187], v[60:63]
	v_mfma_f32_16x16x32_bf16 v[56:59], v[160:163], v[184:187], v[56:59]
	v_mfma_f32_16x16x32_bf16 v[52:55], v[152:155], v[192:195], v[52:55]
	v_mfma_f32_16x16x32_bf16 v[44:47], v[160:163], v[192:195], v[44:47]
	v_mfma_f32_16x16x32_bf16 v[36:39], v[152:155], v[200:203], v[36:39]
	v_mfma_f32_16x16x32_bf16 v[28:31], v[160:163], v[200:203], v[28:31]
	v_mfma_f32_16x16x32_bf16 v[20:23], v[152:155], v[208:211], v[20:23]
	v_mfma_f32_16x16x32_bf16 v[12:15], v[160:163], v[208:211], v[12:15]
	v_mfma_f32_16x16x32_bf16 v[60:63], v[156:159], v[188:191], v[60:63]
	v_mfma_f32_16x16x32_bf16 v[56:59], v[164:167], v[188:191], v[56:59]
	v_mfma_f32_16x16x32_bf16 v[52:55], v[156:159], v[196:199], v[52:55]
	v_mfma_f32_16x16x32_bf16 v[44:47], v[164:167], v[196:199], v[44:47]
	v_mfma_f32_16x16x32_bf16 v[36:39], v[156:159], v[204:207], v[36:39]
	v_mfma_f32_16x16x32_bf16 v[28:31], v[164:167], v[204:207], v[28:31]
	v_mfma_f32_16x16x32_bf16 v[20:23], v[156:159], v[212:215], v[20:23]
	v_mfma_f32_16x16x32_bf16 v[12:15], v[164:167], v[212:215], v[12:15]
	v_mfma_f32_16x16x32_bf16 v[48:51], v[168:171], v[184:187], v[48:51]
	v_mfma_f32_16x16x32_bf16 v[40:43], v[176:179], v[184:187], v[40:43]
	v_mfma_f32_16x16x32_bf16 v[32:35], v[168:171], v[192:195], v[32:35]
	v_mfma_f32_16x16x32_bf16 v[24:27], v[176:179], v[192:195], v[24:27]
	v_mfma_f32_16x16x32_bf16 v[16:19], v[168:171], v[200:203], v[16:19]
	v_mfma_f32_16x16x32_bf16 v[8:11], v[176:179], v[200:203], v[8:11]
	v_mfma_f32_16x16x32_bf16 v[4:7], v[168:171], v[208:211], v[4:7]
	v_mfma_f32_16x16x32_bf16 v[0:3], v[176:179], v[208:211], v[0:3]
	v_mfma_f32_16x16x32_bf16 v[48:51], v[172:175], v[188:191], v[48:51]
	v_mfma_f32_16x16x32_bf16 v[40:43], v[180:183], v[188:191], v[40:43]
	v_mfma_f32_16x16x32_bf16 v[32:35], v[172:175], v[196:199], v[32:35]
	v_mfma_f32_16x16x32_bf16 v[24:27], v[180:183], v[196:199], v[24:27]
	v_mfma_f32_16x16x32_bf16 v[16:19], v[172:175], v[204:207], v[16:19]
	v_mfma_f32_16x16x32_bf16 v[8:11], v[180:183], v[204:207], v[8:11]
	v_mfma_f32_16x16x32_bf16 v[4:7], v[172:175], v[212:215], v[4:7]
	v_mfma_f32_16x16x32_bf16 v[0:3], v[180:183], v[212:215], v[0:3]
	s_barrier
	s_add_i32 s58, 0, 0x18000
	s_add_i32 s59, 0, 0x1c000
	v_add_u32_e32 v164, s58, v148
	v_add_u32_e32 v180, s59, v148
	ds_read_b128 v[152:155], v164
	ds_read_b128 v[156:159], v164 offset:1024
	ds_read_b128 v[160:163], v164 offset:2048
	ds_read_b128 v[164:167], v164 offset:3072
	ds_read_b128 v[168:171], v180
	ds_read_b128 v[172:175], v180 offset:1024
	ds_read_b128 v[176:179], v180 offset:2048
	ds_read_b128 v[180:183], v180 offset:3072
	s_add_u32 s28, s28, 0x100000
	s_addc_u32 s29, s29, 0
	s_mov_b32 m0, s37
	v_lshl_add_u64 v[222:223], s[28:29], 0, v[128:129]
	ds_read_b128 v[184:187], v151 offset:32768
	ds_read_b128 v[188:191], v151 offset:33792
	ds_read_b128 v[192:195], v151 offset:34816
	ds_read_b128 v[196:199], v151 offset:35840
	ds_read_b128 v[200:203], v151 offset:36864
	ds_read_b128 v[204:207], v151 offset:37888
	ds_read_b128 v[208:211], v151 offset:38912
	ds_read_b128 v[212:215], v151 offset:39936
	global_load_lds_dwordx4 v[222:223], off
	v_lshl_add_u64 v[222:223], s[28:29], 0, v[132:133]
	s_mov_b32 m0, s38
	s_nop 0
	global_load_lds_dwordx4 v[222:223], off
	s_waitcnt vmcnt(8)
	s_waitcnt lgkmcnt(0)
	s_barrier
	s_waitcnt lgkmcnt(0)
	v_mfma_f32_16x16x32_bf16 v[124:127], v[152:155], v[184:187], v[124:127]
	v_mfma_f32_16x16x32_bf16 v[120:123], v[160:163], v[184:187], v[120:123]
	v_mfma_f32_16x16x32_bf16 v[116:119], v[152:155], v[192:195], v[116:119]
	v_mfma_f32_16x16x32_bf16 v[108:111], v[160:163], v[192:195], v[108:111]
	v_mfma_f32_16x16x32_bf16 v[100:103], v[152:155], v[200:203], v[100:103]
	v_mfma_f32_16x16x32_bf16 v[92:95], v[160:163], v[200:203], v[92:95]
	v_mfma_f32_16x16x32_bf16 v[84:87], v[152:155], v[208:211], v[84:87]
	v_mfma_f32_16x16x32_bf16 v[76:79], v[160:163], v[208:211], v[76:79]
	v_mfma_f32_16x16x32_bf16 v[124:127], v[156:159], v[188:191], v[124:127]
	v_mfma_f32_16x16x32_bf16 v[120:123], v[164:167], v[188:191], v[120:123]
	v_mfma_f32_16x16x32_bf16 v[116:119], v[156:159], v[196:199], v[116:119]
	v_mfma_f32_16x16x32_bf16 v[108:111], v[164:167], v[196:199], v[108:111]
	v_mfma_f32_16x16x32_bf16 v[100:103], v[156:159], v[204:207], v[100:103]
	v_mfma_f32_16x16x32_bf16 v[92:95], v[164:167], v[204:207], v[92:95]
	v_mfma_f32_16x16x32_bf16 v[84:87], v[156:159], v[212:215], v[84:87]
	v_mfma_f32_16x16x32_bf16 v[76:79], v[164:167], v[212:215], v[76:79]
	v_mfma_f32_16x16x32_bf16 v[112:115], v[168:171], v[184:187], v[112:115]
	v_mfma_f32_16x16x32_bf16 v[104:107], v[176:179], v[184:187], v[104:107]
	v_mfma_f32_16x16x32_bf16 v[96:99], v[168:171], v[192:195], v[96:99]
	v_mfma_f32_16x16x32_bf16 v[88:91], v[176:179], v[192:195], v[88:91]
	v_mfma_f32_16x16x32_bf16 v[80:83], v[168:171], v[200:203], v[80:83]
	v_mfma_f32_16x16x32_bf16 v[72:75], v[176:179], v[200:203], v[72:75]
	v_mfma_f32_16x16x32_bf16 v[68:71], v[168:171], v[208:211], v[68:71]
	v_mfma_f32_16x16x32_bf16 v[64:67], v[176:179], v[208:211], v[64:67]
	v_mfma_f32_16x16x32_bf16 v[112:115], v[172:175], v[188:191], v[112:115]
	v_mfma_f32_16x16x32_bf16 v[104:107], v[180:183], v[188:191], v[104:107]
	v_mfma_f32_16x16x32_bf16 v[96:99], v[172:175], v[196:199], v[96:99]
	v_mfma_f32_16x16x32_bf16 v[88:91], v[180:183], v[196:199], v[88:91]
	v_mfma_f32_16x16x32_bf16 v[80:83], v[172:175], v[204:207], v[80:83]
	v_mfma_f32_16x16x32_bf16 v[72:75], v[180:183], v[204:207], v[72:75]
	v_mfma_f32_16x16x32_bf16 v[68:71], v[172:175], v[212:215], v[68:71]
	v_mfma_f32_16x16x32_bf16 v[64:67], v[180:183], v[212:215], v[64:67]
	s_barrier
	s_add_i32 s28, s58, s31
	v_lshl_add_u64 v[146:147], v[146:147], 0, s[10:11]
	s_mov_b32 m0, s28
	ds_read_b128 v[184:187], v151 offset:49152
	ds_read_b128 v[188:191], v151 offset:50176
	ds_read_b128 v[192:195], v151 offset:51200
	ds_read_b128 v[196:199], v151 offset:52224
	ds_read_b128 v[200:203], v151 offset:53248
	ds_read_b128 v[204:207], v151 offset:54272
	ds_read_b128 v[208:211], v151 offset:55296
	ds_read_b128 v[212:215], v151 offset:56320
	global_load_lds_dwordx4 v[146:147], off
	s_add_i32 m0, s28, 0x2000
	s_add_u32 s26, s26, 0x100080
	v_lshl_add_u64 v[146:147], v[216:217], 0, s[10:11]
	s_addc_u32 s27, s27, 0
	s_add_i32 s28, s59, s31
	global_load_lds_dwordx4 v[146:147], off
	v_lshl_add_u64 v[146:147], s[26:27], 0, v[130:131]
	s_mov_b32 m0, s28
	s_nop 0
	global_load_lds_dwordx4 v[146:147], off
	v_lshl_add_u64 v[146:147], s[26:27], 0, v[134:135]
	s_add_i32 m0, s28, 0x2000
	s_nop 0
	global_load_lds_dwordx4 v[146:147], off
	v_lshl_add_u64 v[146:147], v[218:219], 0, s[10:11]
	s_mov_b32 m0, s41
	s_nop 0
	global_load_lds_dwordx4 v[146:147], off
	v_lshl_add_u64 v[146:147], v[220:221], 0, s[10:11]
	s_mov_b32 m0, s42
	s_nop 0
	global_load_lds_dwordx4 v[146:147], off
	s_waitcnt vmcnt(8)
	s_waitcnt lgkmcnt(0)
	s_barrier
	s_waitcnt lgkmcnt(0)
	v_mfma_f32_16x16x32_bf16 v[60:63], v[152:155], v[184:187], v[60:63]
	v_mfma_f32_16x16x32_bf16 v[56:59], v[160:163], v[184:187], v[56:59]
	v_mfma_f32_16x16x32_bf16 v[52:55], v[152:155], v[192:195], v[52:55]
	v_mfma_f32_16x16x32_bf16 v[44:47], v[160:163], v[192:195], v[44:47]
	v_mfma_f32_16x16x32_bf16 v[36:39], v[152:155], v[200:203], v[36:39]
	v_mfma_f32_16x16x32_bf16 v[28:31], v[160:163], v[200:203], v[28:31]
	v_mfma_f32_16x16x32_bf16 v[20:23], v[152:155], v[208:211], v[20:23]
	v_mfma_f32_16x16x32_bf16 v[12:15], v[160:163], v[208:211], v[12:15]
	v_mfma_f32_16x16x32_bf16 v[60:63], v[156:159], v[188:191], v[60:63]
	v_mfma_f32_16x16x32_bf16 v[56:59], v[164:167], v[188:191], v[56:59]
	v_mfma_f32_16x16x32_bf16 v[52:55], v[156:159], v[196:199], v[52:55]
	v_mfma_f32_16x16x32_bf16 v[44:47], v[164:167], v[196:199], v[44:47]
	v_mfma_f32_16x16x32_bf16 v[36:39], v[156:159], v[204:207], v[36:39]
	v_mfma_f32_16x16x32_bf16 v[28:31], v[164:167], v[204:207], v[28:31]
	v_mfma_f32_16x16x32_bf16 v[20:23], v[156:159], v[212:215], v[20:23]
	v_mfma_f32_16x16x32_bf16 v[12:15], v[164:167], v[212:215], v[12:15]
	v_mfma_f32_16x16x32_bf16 v[48:51], v[168:171], v[184:187], v[48:51]
	v_mfma_f32_16x16x32_bf16 v[40:43], v[176:179], v[184:187], v[40:43]
	v_mfma_f32_16x16x32_bf16 v[32:35], v[168:171], v[192:195], v[32:35]
	v_mfma_f32_16x16x32_bf16 v[24:27], v[176:179], v[192:195], v[24:27]
	v_mfma_f32_16x16x32_bf16 v[16:19], v[168:171], v[200:203], v[16:19]
	v_mfma_f32_16x16x32_bf16 v[8:11], v[176:179], v[200:203], v[8:11]
	v_mfma_f32_16x16x32_bf16 v[4:7], v[168:171], v[208:211], v[4:7]
	v_mfma_f32_16x16x32_bf16 v[0:3], v[176:179], v[208:211], v[0:3]
	v_mfma_f32_16x16x32_bf16 v[48:51], v[172:175], v[188:191], v[48:51]
	v_mfma_f32_16x16x32_bf16 v[40:43], v[180:183], v[188:191], v[40:43]
	v_mfma_f32_16x16x32_bf16 v[32:35], v[172:175], v[196:199], v[32:35]
	v_mfma_f32_16x16x32_bf16 v[24:27], v[180:183], v[196:199], v[24:27]
	v_mfma_f32_16x16x32_bf16 v[16:19], v[172:175], v[204:207], v[16:19]
	v_mfma_f32_16x16x32_bf16 v[8:11], v[180:183], v[204:207], v[8:11]
	v_mfma_f32_16x16x32_bf16 v[4:7], v[172:175], v[212:215], v[4:7]
	v_mfma_f32_16x16x32_bf16 v[0:3], v[180:183], v[212:215], v[0:3]
	s_barrier
	s_add_i32 s57, s57, 2
	s_add_u32 s55, s55, 0x100
	s_addc_u32 s56, s56, 0
	s_add_u32 s24, s24, 0x100
	s_addc_u32 s25, s25, 0
	s_cmp_lt_u32 s57, 62
	s_cbranch_scc1 .LBB13_20
	s_andn2_b64 vcc, exec, s[12:13]
	s_cbranch_vccnz .LBB13_23
	s_barrier
